# P56: gemv17 K-loops (adaLN + 3 bias variants) unrolled with all K-step weight loads in flight (7/6 register sets)
# speedup vs baseline: 1.0096x; 1.0096x over previous
.LBB0_63:
	s_mov_b32 s101, 0
	s_mov_b32 s100, 0x60000
	v_lshl_add_u64 v[250:251], v[64:65], 0, s[100:101]
	global_load_dword v138, v[250:251], off
	global_load_dword v139, v[250:251], off offset:128
	s_add_u32 s100, s64, 0x60000
	v_lshl_add_u64 v[252:253], v[64:65], 0, s[100:101]
	global_load_dword v140, v[252:253], off
	global_load_dword v148, v[252:253], off offset:128
	s_add_u32 s100, s62, 0x60000
	v_lshl_add_u64 v[250:251], v[64:65], 0, s[100:101]
	global_load_dword v141, v[250:251], off
	global_load_dword v147, v[250:251], off offset:128
	s_add_u32 s100, s63, 0x60000
	v_lshl_add_u64 v[252:253], v[64:65], 0, s[100:101]
	global_load_dword v142, v[252:253], off
	global_load_dword v149, v[252:253], off offset:128
	s_add_u32 s100, s67, 0x60000
	v_lshl_add_u64 v[250:251], v[64:65], 0, s[100:101]
	global_load_dword v143, v[250:251], off
	global_load_dword v151, v[250:251], off offset:128
	s_add_u32 s100, s65, 0x60000
	v_lshl_add_u64 v[252:253], v[64:65], 0, s[100:101]
	global_load_dword v144, v[252:253], off
	global_load_dword v153, v[252:253], off offset:128
	s_add_u32 s100, s68, 0x60000
	v_lshl_add_u64 v[250:251], v[64:65], 0, s[100:101]
	global_load_dword v145, v[250:251], off
	global_load_dword v150, v[250:251], off offset:128
	s_add_u32 s100, s66, 0x60000
	v_lshl_add_u64 v[252:253], v[64:65], 0, s[100:101]
	global_load_dword v146, v[252:253], off
	global_load_dword v152, v[252:253], off offset:128
	s_mov_b32 s101, 0
	s_mov_b32 s100, 0xc0000
	v_lshl_add_u64 v[250:251], v[64:65], 0, s[100:101]
	global_load_dword v154, v[250:251], off
	global_load_dword v155, v[250:251], off offset:128
	s_add_u32 s100, s64, 0xc0000
	v_lshl_add_u64 v[252:253], v[64:65], 0, s[100:101]
	global_load_dword v156, v[252:253], off
	global_load_dword v164, v[252:253], off offset:128
	s_add_u32 s100, s62, 0xc0000
	v_lshl_add_u64 v[250:251], v[64:65], 0, s[100:101]
	global_load_dword v157, v[250:251], off
	global_load_dword v163, v[250:251], off offset:128
	s_add_u32 s100, s63, 0xc0000
	v_lshl_add_u64 v[252:253], v[64:65], 0, s[100:101]
	global_load_dword v158, v[252:253], off
	global_load_dword v165, v[252:253], off offset:128
	s_add_u32 s100, s67, 0xc0000
	v_lshl_add_u64 v[250:251], v[64:65], 0, s[100:101]
	global_load_dword v159, v[250:251], off
	global_load_dword v167, v[250:251], off offset:128
	s_add_u32 s100, s65, 0xc0000
	v_lshl_add_u64 v[252:253], v[64:65], 0, s[100:101]
	global_load_dword v160, v[252:253], off
	global_load_dword v169, v[252:253], off offset:128
	s_add_u32 s100, s68, 0xc0000
	v_lshl_add_u64 v[250:251], v[64:65], 0, s[100:101]
	global_load_dword v161, v[250:251], off
	global_load_dword v166, v[250:251], off offset:128
	s_add_u32 s100, s66, 0xc0000
	v_lshl_add_u64 v[252:253], v[64:65], 0, s[100:101]
	global_load_dword v162, v[252:253], off
	global_load_dword v168, v[252:253], off offset:128
	s_mov_b32 s101, 0
	s_mov_b32 s100, 0x120000
	v_lshl_add_u64 v[250:251], v[64:65], 0, s[100:101]
	global_load_dword v170, v[250:251], off
	global_load_dword v171, v[250:251], off offset:128
	s_add_u32 s100, s64, 0x120000
	v_lshl_add_u64 v[252:253], v[64:65], 0, s[100:101]
	global_load_dword v172, v[252:253], off
	global_load_dword v180, v[252:253], off offset:128
	s_add_u32 s100, s62, 0x120000
	v_lshl_add_u64 v[250:251], v[64:65], 0, s[100:101]
	global_load_dword v173, v[250:251], off
	global_load_dword v179, v[250:251], off offset:128
	s_add_u32 s100, s63, 0x120000
	v_lshl_add_u64 v[252:253], v[64:65], 0, s[100:101]
	global_load_dword v174, v[252:253], off
	global_load_dword v181, v[252:253], off offset:128
	s_add_u32 s100, s67, 0x120000
	v_lshl_add_u64 v[250:251], v[64:65], 0, s[100:101]
	global_load_dword v175, v[250:251], off
	global_load_dword v183, v[250:251], off offset:128
	s_add_u32 s100, s65, 0x120000
	v_lshl_add_u64 v[252:253], v[64:65], 0, s[100:101]
	global_load_dword v176, v[252:253], off
	global_load_dword v185, v[252:253], off offset:128
	s_add_u32 s100, s68, 0x120000
	v_lshl_add_u64 v[250:251], v[64:65], 0, s[100:101]
	global_load_dword v177, v[250:251], off
	global_load_dword v182, v[250:251], off offset:128
	s_add_u32 s100, s66, 0x120000
	v_lshl_add_u64 v[252:253], v[64:65], 0, s[100:101]
	global_load_dword v178, v[252:253], off
	global_load_dword v184, v[252:253], off offset:128
	s_mov_b32 s101, 0
	s_mov_b32 s100, 0x180000
	v_lshl_add_u64 v[250:251], v[64:65], 0, s[100:101]
	global_load_dword v186, v[250:251], off
	global_load_dword v187, v[250:251], off offset:128
	s_add_u32 s100, s64, 0x180000
	v_lshl_add_u64 v[252:253], v[64:65], 0, s[100:101]
	global_load_dword v188, v[252:253], off
	global_load_dword v196, v[252:253], off offset:128
	s_add_u32 s100, s62, 0x180000
	v_lshl_add_u64 v[250:251], v[64:65], 0, s[100:101]
	global_load_dword v189, v[250:251], off
	global_load_dword v195, v[250:251], off offset:128
	s_add_u32 s100, s63, 0x180000
	v_lshl_add_u64 v[252:253], v[64:65], 0, s[100:101]
	global_load_dword v190, v[252:253], off
	global_load_dword v197, v[252:253], off offset:128
	s_add_u32 s100, s67, 0x180000
	v_lshl_add_u64 v[250:251], v[64:65], 0, s[100:101]
	global_load_dword v191, v[250:251], off
	global_load_dword v199, v[250:251], off offset:128
	s_add_u32 s100, s65, 0x180000
	v_lshl_add_u64 v[252:253], v[64:65], 0, s[100:101]
	global_load_dword v192, v[252:253], off
	global_load_dword v201, v[252:253], off offset:128
	s_add_u32 s100, s68, 0x180000
	v_lshl_add_u64 v[250:251], v[64:65], 0, s[100:101]
	global_load_dword v193, v[250:251], off
	global_load_dword v198, v[250:251], off offset:128
	s_add_u32 s100, s66, 0x180000
	v_lshl_add_u64 v[252:253], v[64:65], 0, s[100:101]
	global_load_dword v194, v[252:253], off
	global_load_dword v200, v[252:253], off offset:128
	s_mov_b32 s101, 0
	s_mov_b32 s100, 0x1e0000
	v_lshl_add_u64 v[250:251], v[64:65], 0, s[100:101]
	global_load_dword v202, v[250:251], off
	global_load_dword v203, v[250:251], off offset:128
	s_add_u32 s100, s64, 0x1e0000
	v_lshl_add_u64 v[252:253], v[64:65], 0, s[100:101]
	global_load_dword v204, v[252:253], off
	global_load_dword v212, v[252:253], off offset:128
	s_add_u32 s100, s62, 0x1e0000
	v_lshl_add_u64 v[250:251], v[64:65], 0, s[100:101]
	global_load_dword v205, v[250:251], off
	global_load_dword v211, v[250:251], off offset:128
	s_add_u32 s100, s63, 0x1e0000
	v_lshl_add_u64 v[252:253], v[64:65], 0, s[100:101]
	global_load_dword v206, v[252:253], off
	global_load_dword v213, v[252:253], off offset:128
	s_add_u32 s100, s67, 0x1e0000
	v_lshl_add_u64 v[250:251], v[64:65], 0, s[100:101]
	global_load_dword v207, v[250:251], off
	global_load_dword v215, v[250:251], off offset:128
	s_add_u32 s100, s65, 0x1e0000
	v_lshl_add_u64 v[252:253], v[64:65], 0, s[100:101]
	global_load_dword v208, v[252:253], off
	global_load_dword v217, v[252:253], off offset:128
	s_add_u32 s100, s68, 0x1e0000
	v_lshl_add_u64 v[250:251], v[64:65], 0, s[100:101]
	global_load_dword v209, v[250:251], off
	global_load_dword v214, v[250:251], off offset:128
	s_add_u32 s100, s66, 0x1e0000
	v_lshl_add_u64 v[252:253], v[64:65], 0, s[100:101]
	global_load_dword v210, v[252:253], off
	global_load_dword v216, v[252:253], off offset:128
	s_mov_b32 s101, 0
	s_mov_b32 s100, 0x240000
	v_lshl_add_u64 v[250:251], v[64:65], 0, s[100:101]
	global_load_dword v218, v[250:251], off
	global_load_dword v219, v[250:251], off offset:128
	s_add_u32 s100, s64, 0x240000
	v_lshl_add_u64 v[252:253], v[64:65], 0, s[100:101]
	global_load_dword v220, v[252:253], off
	global_load_dword v228, v[252:253], off offset:128
	s_add_u32 s100, s62, 0x240000
	v_lshl_add_u64 v[250:251], v[64:65], 0, s[100:101]
	global_load_dword v221, v[250:251], off
	global_load_dword v227, v[250:251], off offset:128
	s_add_u32 s100, s63, 0x240000
	v_lshl_add_u64 v[252:253], v[64:65], 0, s[100:101]
	global_load_dword v222, v[252:253], off
	global_load_dword v229, v[252:253], off offset:128
	s_add_u32 s100, s67, 0x240000
	v_lshl_add_u64 v[250:251], v[64:65], 0, s[100:101]
	global_load_dword v223, v[250:251], off
	global_load_dword v231, v[250:251], off offset:128
	s_add_u32 s100, s65, 0x240000
	v_lshl_add_u64 v[252:253], v[64:65], 0, s[100:101]
	global_load_dword v224, v[252:253], off
	global_load_dword v233, v[252:253], off offset:128
	s_add_u32 s100, s68, 0x240000
	v_lshl_add_u64 v[250:251], v[64:65], 0, s[100:101]
	global_load_dword v225, v[250:251], off
	global_load_dword v230, v[250:251], off offset:128
	s_add_u32 s100, s66, 0x240000
	v_lshl_add_u64 v[252:253], v[64:65], 0, s[100:101]
	global_load_dword v226, v[252:253], off
	global_load_dword v232, v[252:253], off offset:128
	s_mov_b32 s101, 0
	s_mov_b32 s100, 0x2a0000
	v_lshl_add_u64 v[250:251], v[64:65], 0, s[100:101]
	global_load_dword v234, v[250:251], off
	global_load_dword v235, v[250:251], off offset:128
	s_add_u32 s100, s64, 0x2a0000
	v_lshl_add_u64 v[252:253], v[64:65], 0, s[100:101]
	global_load_dword v236, v[252:253], off
	global_load_dword v244, v[252:253], off offset:128
	s_add_u32 s100, s62, 0x2a0000
	v_lshl_add_u64 v[250:251], v[64:65], 0, s[100:101]
	global_load_dword v237, v[250:251], off
	global_load_dword v243, v[250:251], off offset:128
	s_add_u32 s100, s63, 0x2a0000
	v_lshl_add_u64 v[252:253], v[64:65], 0, s[100:101]
	global_load_dword v238, v[252:253], off
	global_load_dword v245, v[252:253], off offset:128
	s_add_u32 s100, s67, 0x2a0000
	v_lshl_add_u64 v[250:251], v[64:65], 0, s[100:101]
	global_load_dword v239, v[250:251], off
	global_load_dword v247, v[250:251], off offset:128
	s_add_u32 s100, s65, 0x2a0000
	v_lshl_add_u64 v[252:253], v[64:65], 0, s[100:101]
	global_load_dword v240, v[252:253], off
	global_load_dword v249, v[252:253], off offset:128
	s_add_u32 s100, s68, 0x2a0000
	v_lshl_add_u64 v[250:251], v[64:65], 0, s[100:101]
	global_load_dword v241, v[250:251], off
	global_load_dword v246, v[250:251], off offset:128
	s_add_u32 s100, s66, 0x2a0000
	v_lshl_add_u64 v[252:253], v[64:65], 0, s[100:101]
	global_load_dword v242, v[252:253], off
	global_load_dword v248, v[252:253], off offset:128
	v_lshl_add_u64 v[66:67], v[64:65], 0, s[58:59]
	v_add_co_u32_e32 v78, vcc, s63, v66
	ds_read_b128 v[34:37], v40
	ds_read_b128 v[106:109], v40 offset:16
	v_addc_co_u32_e32 v79, vcc, 0, v67, vcc
	v_add_co_u32_e32 v80, vcc, s64, v66
	s_waitcnt lgkmcnt(1)
	v_cndmask_b32_e64 v37, 0, v37, s[2:3]
	v_addc_co_u32_e32 v81, vcc, 0, v67, vcc
	v_add_co_u32_e32 v74, vcc, s62, v66
	s_waitcnt lgkmcnt(0)
	v_cndmask_b32_e64 v109, 0, v109, s[2:3]
	v_addc_co_u32_e32 v75, vcc, 0, v67, vcc
	v_add_co_u32_e32 v110, vcc, s65, v66
	v_and_b32_sdwa v63, v37, v104 dst_sel:DWORD dst_unused:UNUSED_PAD src0_sel:WORD_1 src1_sel:DWORD
	s_nop 0
	v_addc_co_u32_e32 v111, vcc, 0, v67, vcc
	v_add_co_u32_e32 v112, vcc, s66, v66
	s_nop 0
	v_addc_co_u32_e32 v113, vcc, 0, v67, vcc
	v_add_co_u32_e32 v114, vcc, s67, v66
	s_nop 0
	v_addc_co_u32_e32 v115, vcc, 0, v67, vcc
	v_add_co_u32_e32 v116, vcc, s68, v66
	s_nop 0
	v_addc_co_u32_e32 v117, vcc, 0, v67, vcc
	global_load_dword v70, v[66:67], off
	s_nop 0
	global_load_dword v66, v[66:67], off offset:128
	s_nop 0
	global_load_dword v71, v[80:81], off
	global_load_dword v69, v[74:75], off
	global_load_dword v68, v[78:79], off
	global_load_dword v73, v[114:115], off
	global_load_dword v72, v[110:111], off
	global_load_dword v77, v[116:117], off
	global_load_dword v76, v[112:113], off
	s_nop 0
	global_load_dword v75, v[74:75], off offset:128
	s_nop 0
	global_load_dword v67, v[80:81], off offset:128
	global_load_dword v74, v[78:79], off offset:128
	s_nop 0
	global_load_dword v79, v[116:117], off offset:128
	global_load_dword v81, v[114:115], off offset:128
	global_load_dword v78, v[112:113], off offset:128
	global_load_dword v80, v[110:111], off offset:128
	v_cndmask_b32_e64 v111, 0, v36, s[2:3]
	v_cndmask_b32_e64 v110, 0, v34, s[2:3]
	v_cndmask_b32_e64 v36, 0, v35, s[2:3]
	v_cndmask_b32_e64 v113, 0, v108, s[2:3]
	v_cndmask_b32_e64 v112, 0, v106, s[2:3]
	v_cndmask_b32_e64 v108, 0, v107, s[2:3]
	v_and_b32_sdwa v34, v111, v104 dst_sel:DWORD dst_unused:UNUSED_PAD src0_sel:WORD_1 src1_sel:DWORD
	v_and_b32_sdwa v35, v110, v104 dst_sel:DWORD dst_unused:UNUSED_PAD src0_sel:WORD_1 src1_sel:DWORD
	v_and_b32_sdwa v105, v36, v104 dst_sel:DWORD dst_unused:UNUSED_PAD src0_sel:WORD_1 src1_sel:DWORD
	v_and_b32_sdwa v106, v113, v104 dst_sel:DWORD dst_unused:UNUSED_PAD src0_sel:WORD_1 src1_sel:DWORD
	v_and_b32_sdwa v107, v112, v104 dst_sel:DWORD dst_unused:UNUSED_PAD src0_sel:WORD_1 src1_sel:DWORD
	v_and_b32_sdwa v114, v109, v104 dst_sel:DWORD dst_unused:UNUSED_PAD src0_sel:WORD_1 src1_sel:DWORD
	v_and_b32_sdwa v115, v108, v104 dst_sel:DWORD dst_unused:UNUSED_PAD src0_sel:WORD_1 src1_sel:DWORD
	v_add3_u32 v120, v111, v34, s69
	v_add3_u32 v34, v110, v35, s69
	v_add3_u32 v35, v37, v63, s69
	v_add3_u32 v63, v36, v105, s69
	v_add3_u32 v105, v113, v106, s69
	v_add3_u32 v121, v112, v107, s69
	v_add3_u32 v116, v109, v114, s69
	v_add3_u32 v118, v108, v115, s69
	v_and_b32_e32 v107, 0xffff0000, v35
	v_and_b32_e32 v106, 0xffff0000, v63
	v_and_b32_e32 v115, 0xffff0000, v120
	v_and_b32_e32 v114, 0xffff0000, v34
	v_and_b32_e32 v117, 0xffff0000, v116
	v_and_b32_e32 v116, 0xffff0000, v118
	v_and_b32_e32 v119, 0xffff0000, v105
	v_and_b32_e32 v118, 0xffff0000, v121
	v_or_b32_sdwa v34, v106, v34 dst_sel:DWORD dst_unused:UNUSED_PAD src0_sel:DWORD src1_sel:WORD_1
	v_pk_add_f32 v[110:111], v[110:111], v[114:115] neg_lo:[0,1] neg_hi:[0,1]
	v_pk_add_f32 v[114:115], v[36:37], v[106:107] neg_lo:[0,1] neg_hi:[0,1]
	v_or_b32_sdwa v35, v107, v120 dst_sel:DWORD dst_unused:UNUSED_PAD src0_sel:DWORD src1_sel:WORD_1
	v_pk_add_f32 v[106:107], v[112:113], v[118:119] neg_lo:[0,1] neg_hi:[0,1]
	v_pk_add_f32 v[108:109], v[108:109], v[116:117] neg_lo:[0,1] neg_hi:[0,1]
	v_or_b32_sdwa v37, v117, v105 dst_sel:DWORD dst_unused:UNUSED_PAD src0_sel:DWORD src1_sel:WORD_1
	v_bfe_u32 v105, v108, 16, 1
	v_bfe_u32 v117, v111, 16, 1
	v_bfe_u32 v118, v106, 16, 1
	v_bfe_u32 v119, v107, 16, 1
	v_or_b32_sdwa v36, v116, v121 dst_sel:DWORD dst_unused:UNUSED_PAD src0_sel:DWORD src1_sel:WORD_1
	v_bfe_u32 v63, v109, 16, 1
	v_bfe_u32 v116, v110, 16, 1
	v_add3_u32 v105, v108, v105, s69
	v_add3_u32 v107, v107, v119, s69
	v_add3_u32 v106, v106, v118, s69
	v_add3_u32 v108, v111, v117, s69
	v_bfe_u32 v112, v115, 16, 1
	v_bfe_u32 v113, v114, 16, 1
	v_add3_u32 v63, v109, v63, s69
	v_add3_u32 v109, v110, v116, s69
	v_lshrrev_b32_e32 v127, 16, v108
	v_lshrrev_b32_e32 v108, 16, v106
	v_lshrrev_b32_e32 v106, 16, v107
	v_add3_u32 v124, v114, v113, s69
	v_add3_u32 v125, v115, v112, s69
	v_lshrrev_b32_e32 v126, 16, v109
	v_and_or_b32 v109, v63, s70, v106
	v_and_or_b32 v108, v105, s70, v108
	v_add_u32_e32 v40, 64, v40
	s_waitcnt vmcnt(15)
	v_and_b32_sdwa v63, v70, v104 dst_sel:DWORD dst_unused:UNUSED_PAD src0_sel:WORD_1 src1_sel:DWORD
	s_waitcnt vmcnt(14)
	v_and_b32_sdwa v106, v66, v104 dst_sel:DWORD dst_unused:UNUSED_PAD src0_sel:WORD_1 src1_sel:DWORD
	s_waitcnt vmcnt(13)
	v_and_b32_sdwa v107, v71, v104 dst_sel:DWORD dst_unused:UNUSED_PAD src0_sel:WORD_1 src1_sel:DWORD
	s_waitcnt vmcnt(12)
	v_and_b32_sdwa v110, v69, v104 dst_sel:DWORD dst_unused:UNUSED_PAD src0_sel:WORD_1 src1_sel:DWORD
	s_waitcnt vmcnt(11)
	v_and_b32_sdwa v111, v68, v104 dst_sel:DWORD dst_unused:UNUSED_PAD src0_sel:WORD_1 src1_sel:DWORD
	s_waitcnt vmcnt(10)
	v_and_b32_sdwa v112, v73, v104 dst_sel:DWORD dst_unused:UNUSED_PAD src0_sel:WORD_1 src1_sel:DWORD
	s_waitcnt vmcnt(9)
	v_and_b32_sdwa v113, v72, v104 dst_sel:DWORD dst_unused:UNUSED_PAD src0_sel:WORD_1 src1_sel:DWORD
	s_waitcnt vmcnt(8)
	v_and_b32_sdwa v114, v77, v104 dst_sel:DWORD dst_unused:UNUSED_PAD src0_sel:WORD_1 src1_sel:DWORD
	s_waitcnt vmcnt(7)
	v_and_b32_sdwa v115, v76, v104 dst_sel:DWORD dst_unused:UNUSED_PAD src0_sel:WORD_1 src1_sel:DWORD
	v_add3_u32 v63, v70, v63, s69
	s_waitcnt vmcnt(5)
	v_and_b32_sdwa v116, v67, v104 dst_sel:DWORD dst_unused:UNUSED_PAD src0_sel:WORD_1 src1_sel:DWORD
	v_and_b32_sdwa v117, v75, v104 dst_sel:DWORD dst_unused:UNUSED_PAD src0_sel:WORD_1 src1_sel:DWORD
	v_add3_u32 v129, v71, v107, s69
	v_add3_u32 v107, v69, v110, s69
	v_add3_u32 v111, v68, v111, s69
	v_add3_u32 v130, v73, v112, s69
	v_add3_u32 v131, v72, v113, s69
	v_add3_u32 v123, v77, v114, s69
	v_add3_u32 v132, v76, v115, s69
	v_add3_u32 v128, v66, v106, s69
	s_waitcnt vmcnt(4)
	v_and_b32_sdwa v118, v74, v104 dst_sel:DWORD dst_unused:UNUSED_PAD src0_sel:WORD_1 src1_sel:DWORD
	s_waitcnt vmcnt(3)
	v_and_b32_sdwa v121, v79, v104 dst_sel:DWORD dst_unused:UNUSED_PAD src0_sel:WORD_1 src1_sel:DWORD
	s_waitcnt vmcnt(1)
	v_and_b32_sdwa v122, v78, v104 dst_sel:DWORD dst_unused:UNUSED_PAD src0_sel:WORD_1 src1_sel:DWORD
	v_and_b32_e32 v106, 0xffff0000, v63
	v_add3_u32 v133, v67, v116, s69
	v_add3_u32 v134, v75, v117, s69
	v_and_b32_e32 v113, 0xffff0000, v107
	v_and_b32_e32 v112, 0xffff0000, v111
	v_and_b32_e32 v107, 0xffff0000, v129
	v_and_b32_e32 v115, 0xffff0000, v130
	v_and_b32_e32 v114, 0xffff0000, v131
	v_and_b32_e32 v117, 0xffff0000, v123
	v_and_b32_e32 v116, 0xffff0000, v132
	v_and_b32_sdwa v119, v81, v104 dst_sel:DWORD dst_unused:UNUSED_PAD src0_sel:WORD_1 src1_sel:DWORD
	s_waitcnt vmcnt(0)
	v_and_b32_sdwa v120, v80, v104 dst_sel:DWORD dst_unused:UNUSED_PAD src0_sel:WORD_1 src1_sel:DWORD
	v_add3_u32 v118, v74, v118, s69
	v_add3_u32 v137, v79, v121, s69
	v_add3_u32 v122, v78, v122, s69
	v_pk_add_f32 v[106:107], v[70:71], v[106:107] neg_lo:[0,1] neg_hi:[0,1]
	v_or_b32_sdwa v70, v112, v63 dst_sel:DWORD dst_unused:UNUSED_PAD src0_sel:DWORD src1_sel:WORD_1
	v_or_b32_sdwa v71, v113, v129 dst_sel:DWORD dst_unused:UNUSED_PAD src0_sel:DWORD src1_sel:WORD_1
	v_pk_add_f32 v[114:115], v[72:73], v[114:115] neg_lo:[0,1] neg_hi:[0,1]
	v_or_b32_sdwa v72, v116, v131 dst_sel:DWORD dst_unused:UNUSED_PAD src0_sel:DWORD src1_sel:WORD_1
	v_or_b32_sdwa v73, v117, v130 dst_sel:DWORD dst_unused:UNUSED_PAD src0_sel:DWORD src1_sel:WORD_1
	v_and_b32_e32 v110, 0xffff0000, v128
	v_add3_u32 v135, v81, v119, s69
	v_add3_u32 v136, v80, v120, s69
	v_and_b32_e32 v119, 0xffff0000, v134
	v_and_b32_e32 v118, 0xffff0000, v118
	v_and_b32_e32 v111, 0xffff0000, v133
	v_and_b32_e32 v123, 0xffff0000, v137
	v_and_b32_e32 v122, 0xffff0000, v122
	v_mfma_f32_32x32x16_bf16 v[2:17], v[34:37], v[70:73], v[2:17]
	v_add_f32_e64 v112, v68, -v112
	v_add_f32_e64 v113, v69, -v113
	v_add_f32_e64 v110, v66, -v110
	v_add_f32_e64 v111, v67, -v111
	v_or_b32_sdwa v66, v118, v128 dst_sel:DWORD dst_unused:UNUSED_PAD src0_sel:DWORD src1_sel:WORD_1
	v_or_b32_sdwa v67, v119, v133 dst_sel:DWORD dst_unused:UNUSED_PAD src0_sel:DWORD src1_sel:WORD_1
	v_or_b32_sdwa v68, v122, v136 dst_sel:DWORD dst_unused:UNUSED_PAD src0_sel:DWORD src1_sel:WORD_1
	v_or_b32_sdwa v69, v123, v135 dst_sel:DWORD dst_unused:UNUSED_PAD src0_sel:DWORD src1_sel:WORD_1
	v_and_b32_e32 v121, 0xffff0000, v135
	v_and_b32_e32 v120, 0xffff0000, v136
	v_mfma_f32_32x32x16_bf16 v[18:33], v[34:37], v[66:69], v[18:33]
	v_add_f32_e64 v76, v76, -v116
	v_add_f32_e64 v77, v77, -v117
	v_add_f32_e64 v74, v74, -v118
	v_add_f32_e64 v75, v75, -v119
	v_add_f32_e64 v80, v80, -v120
	v_add_f32_e64 v81, v81, -v121
	v_pk_add_f32 v[78:79], v[78:79], v[122:123] neg_lo:[0,1] neg_hi:[0,1]
	v_bfe_u32 v63, v113, 16, 1
	v_bfe_u32 v119, v114, 16, 1
	v_bfe_u32 v120, v115, 16, 1
	v_bfe_u32 v121, v106, 16, 1
	v_bfe_u32 v122, v107, 16, 1
	v_bfe_u32 v116, v112, 16, 1
	v_bfe_u32 v117, v77, 16, 1
	v_bfe_u32 v118, v76, 16, 1
	v_bfe_u32 v123, v75, 16, 1
	v_bfe_u32 v128, v74, 16, 1
	v_bfe_u32 v131, v80, 16, 1
	v_bfe_u32 v134, v111, 16, 1
	v_add3_u32 v63, v113, v63, s69
	v_add3_u32 v113, v115, v120, s69
	v_add3_u32 v114, v114, v119, s69
	v_add3_u32 v107, v107, v122, s69
	v_add3_u32 v106, v106, v121, s69
	v_bfe_u32 v132, v81, 16, 1
	v_bfe_u32 v133, v110, 16, 1
	v_add3_u32 v112, v112, v116, s69
	v_add3_u32 v76, v76, v118, s69
	v_add3_u32 v77, v77, v117, s69
	v_add3_u32 v115, v74, v128, s69
	v_add3_u32 v116, v75, v123, s69
	v_add3_u32 v74, v80, v131, s69
	v_add3_u32 v80, v111, v134, s69
	v_lshrrev_b32_e32 v75, 16, v114
	v_lshrrev_b32_e32 v111, 16, v113
	v_lshrrev_b32_e32 v106, 16, v106
	v_lshrrev_b32_e32 v107, 16, v107
	v_bfe_u32 v129, v79, 16, 1
	v_bfe_u32 v130, v78, 16, 1
	v_add3_u32 v81, v81, v132, s69
	v_add3_u32 v110, v110, v133, s69
	v_lshrrev_b32_e32 v113, 16, v74
	v_and_or_b32 v77, v77, s70, v111
	v_and_or_b32 v76, v76, s70, v75
	v_and_or_b32 v75, v63, s70, v107
	v_and_or_b32 v74, v112, s70, v106
	v_add3_u32 v78, v78, v130, s69
	v_add3_u32 v79, v79, v129, s69
	v_mfma_f32_32x32x16_bf16 v[2:17], v[34:37], v[74:77], v[2:17]
	v_lshrrev_b32_e32 v63, 16, v81
	v_lshrrev_b32_e32 v74, 16, v110
	v_lshrrev_b32_e32 v75, 16, v80
	v_and_or_b32 v77, v79, s70, v63
	v_and_or_b32 v76, v78, s70, v113
	v_and_or_b32 v75, v116, s70, v75
	v_and_or_b32 v74, v115, s70, v74
	v_and_or_b32 v107, v125, s70, v127
	v_and_or_b32 v106, v124, s70, v126
	v_mfma_f32_32x32x16_bf16 v[18:33], v[34:37], v[74:77], v[18:33]
	s_nop 0
	v_mfma_f32_32x32x16_bf16 v[2:17], v[106:109], v[70:73], v[2:17]
	v_mfma_f32_32x32x16_bf16 v[18:33], v[106:109], v[66:69], v[18:33]
	ds_read_b128 v[34:37], v40
	ds_read_b128 v[106:109], v40 offset:16
	s_waitcnt lgkmcnt(1)
	v_cndmask_b32_e64 v37, 0, v37, s[2:3]
	s_waitcnt lgkmcnt(0)
	v_cndmask_b32_e64 v109, 0, v109, s[2:3]
	v_and_b32_sdwa v63, v37, v104 dst_sel:DWORD dst_unused:UNUSED_PAD src0_sel:WORD_1 src1_sel:DWORD
	s_nop 0
	s_nop 0
	s_nop 0
	s_nop 0
	v_mov_b32_e32 v70, v138
	s_nop 0
	v_mov_b32_e32 v66, v139
	s_nop 0
	v_mov_b32_e32 v71, v140
	v_mov_b32_e32 v69, v141
	v_mov_b32_e32 v68, v142
	v_mov_b32_e32 v73, v143
	v_mov_b32_e32 v72, v144
	v_mov_b32_e32 v77, v145
	v_mov_b32_e32 v76, v146
	s_nop 0
	v_mov_b32_e32 v75, v147
	s_nop 0
	v_mov_b32_e32 v67, v148
	v_mov_b32_e32 v74, v149
	s_nop 0
	v_mov_b32_e32 v79, v150
	v_mov_b32_e32 v81, v151
	v_mov_b32_e32 v78, v152
	v_mov_b32_e32 v80, v153
	v_cndmask_b32_e64 v111, 0, v36, s[2:3]
	v_cndmask_b32_e64 v110, 0, v34, s[2:3]
	v_cndmask_b32_e64 v36, 0, v35, s[2:3]
	v_cndmask_b32_e64 v113, 0, v108, s[2:3]
	v_cndmask_b32_e64 v112, 0, v106, s[2:3]
	v_cndmask_b32_e64 v108, 0, v107, s[2:3]
	v_and_b32_sdwa v34, v111, v104 dst_sel:DWORD dst_unused:UNUSED_PAD src0_sel:WORD_1 src1_sel:DWORD
	v_and_b32_sdwa v35, v110, v104 dst_sel:DWORD dst_unused:UNUSED_PAD src0_sel:WORD_1 src1_sel:DWORD
	v_and_b32_sdwa v105, v36, v104 dst_sel:DWORD dst_unused:UNUSED_PAD src0_sel:WORD_1 src1_sel:DWORD
	v_and_b32_sdwa v106, v113, v104 dst_sel:DWORD dst_unused:UNUSED_PAD src0_sel:WORD_1 src1_sel:DWORD
	v_and_b32_sdwa v107, v112, v104 dst_sel:DWORD dst_unused:UNUSED_PAD src0_sel:WORD_1 src1_sel:DWORD
	v_and_b32_sdwa v114, v109, v104 dst_sel:DWORD dst_unused:UNUSED_PAD src0_sel:WORD_1 src1_sel:DWORD
	v_and_b32_sdwa v115, v108, v104 dst_sel:DWORD dst_unused:UNUSED_PAD src0_sel:WORD_1 src1_sel:DWORD
	v_add3_u32 v120, v111, v34, s69
	v_add3_u32 v34, v110, v35, s69
	v_add3_u32 v35, v37, v63, s69
	v_add3_u32 v63, v36, v105, s69
	v_add3_u32 v105, v113, v106, s69
	v_add3_u32 v121, v112, v107, s69
	v_add3_u32 v116, v109, v114, s69
	v_add3_u32 v118, v108, v115, s69
	v_and_b32_e32 v107, 0xffff0000, v35
	v_and_b32_e32 v106, 0xffff0000, v63
	v_and_b32_e32 v115, 0xffff0000, v120
	v_and_b32_e32 v114, 0xffff0000, v34
	v_and_b32_e32 v117, 0xffff0000, v116
	v_and_b32_e32 v116, 0xffff0000, v118
	v_and_b32_e32 v119, 0xffff0000, v105
	v_and_b32_e32 v118, 0xffff0000, v121
	v_or_b32_sdwa v34, v106, v34 dst_sel:DWORD dst_unused:UNUSED_PAD src0_sel:DWORD src1_sel:WORD_1
	v_pk_add_f32 v[110:111], v[110:111], v[114:115] neg_lo:[0,1] neg_hi:[0,1]
	v_pk_add_f32 v[114:115], v[36:37], v[106:107] neg_lo:[0,1] neg_hi:[0,1]
	v_or_b32_sdwa v35, v107, v120 dst_sel:DWORD dst_unused:UNUSED_PAD src0_sel:DWORD src1_sel:WORD_1
	v_pk_add_f32 v[106:107], v[112:113], v[118:119] neg_lo:[0,1] neg_hi:[0,1]
	v_pk_add_f32 v[108:109], v[108:109], v[116:117] neg_lo:[0,1] neg_hi:[0,1]
	v_or_b32_sdwa v37, v117, v105 dst_sel:DWORD dst_unused:UNUSED_PAD src0_sel:DWORD src1_sel:WORD_1
	v_bfe_u32 v105, v108, 16, 1
	v_bfe_u32 v117, v111, 16, 1
	v_bfe_u32 v118, v106, 16, 1
	v_bfe_u32 v119, v107, 16, 1
	v_or_b32_sdwa v36, v116, v121 dst_sel:DWORD dst_unused:UNUSED_PAD src0_sel:DWORD src1_sel:WORD_1
	v_bfe_u32 v63, v109, 16, 1
	v_bfe_u32 v116, v110, 16, 1
	v_add3_u32 v105, v108, v105, s69
	v_add3_u32 v107, v107, v119, s69
	v_add3_u32 v106, v106, v118, s69
	v_add3_u32 v108, v111, v117, s69
	v_bfe_u32 v112, v115, 16, 1
	v_bfe_u32 v113, v114, 16, 1
	v_add3_u32 v63, v109, v63, s69
	v_add3_u32 v109, v110, v116, s69
	v_lshrrev_b32_e32 v127, 16, v108
	v_lshrrev_b32_e32 v108, 16, v106
	v_lshrrev_b32_e32 v106, 16, v107
	v_add3_u32 v124, v114, v113, s69
	v_add3_u32 v125, v115, v112, s69
	v_lshrrev_b32_e32 v126, 16, v109
	v_and_or_b32 v109, v63, s70, v106
	v_and_or_b32 v108, v105, s70, v108
	v_add_u32_e32 v40, 64, v40
	v_and_b32_sdwa v63, v70, v104 dst_sel:DWORD dst_unused:UNUSED_PAD src0_sel:WORD_1 src1_sel:DWORD
	v_and_b32_sdwa v106, v66, v104 dst_sel:DWORD dst_unused:UNUSED_PAD src0_sel:WORD_1 src1_sel:DWORD
	v_and_b32_sdwa v107, v71, v104 dst_sel:DWORD dst_unused:UNUSED_PAD src0_sel:WORD_1 src1_sel:DWORD
	v_and_b32_sdwa v110, v69, v104 dst_sel:DWORD dst_unused:UNUSED_PAD src0_sel:WORD_1 src1_sel:DWORD
	v_and_b32_sdwa v111, v68, v104 dst_sel:DWORD dst_unused:UNUSED_PAD src0_sel:WORD_1 src1_sel:DWORD
	v_and_b32_sdwa v112, v73, v104 dst_sel:DWORD dst_unused:UNUSED_PAD src0_sel:WORD_1 src1_sel:DWORD
	v_and_b32_sdwa v113, v72, v104 dst_sel:DWORD dst_unused:UNUSED_PAD src0_sel:WORD_1 src1_sel:DWORD
	v_and_b32_sdwa v114, v77, v104 dst_sel:DWORD dst_unused:UNUSED_PAD src0_sel:WORD_1 src1_sel:DWORD
	v_and_b32_sdwa v115, v76, v104 dst_sel:DWORD dst_unused:UNUSED_PAD src0_sel:WORD_1 src1_sel:DWORD
	v_add3_u32 v63, v70, v63, s69
	v_and_b32_sdwa v116, v67, v104 dst_sel:DWORD dst_unused:UNUSED_PAD src0_sel:WORD_1 src1_sel:DWORD
	v_and_b32_sdwa v117, v75, v104 dst_sel:DWORD dst_unused:UNUSED_PAD src0_sel:WORD_1 src1_sel:DWORD
	v_add3_u32 v129, v71, v107, s69
	v_add3_u32 v107, v69, v110, s69
	v_add3_u32 v111, v68, v111, s69
	v_add3_u32 v130, v73, v112, s69
	v_add3_u32 v131, v72, v113, s69
	v_add3_u32 v123, v77, v114, s69
	v_add3_u32 v132, v76, v115, s69
	v_add3_u32 v128, v66, v106, s69
	v_and_b32_sdwa v118, v74, v104 dst_sel:DWORD dst_unused:UNUSED_PAD src0_sel:WORD_1 src1_sel:DWORD
	v_and_b32_sdwa v121, v79, v104 dst_sel:DWORD dst_unused:UNUSED_PAD src0_sel:WORD_1 src1_sel:DWORD
	v_and_b32_sdwa v122, v78, v104 dst_sel:DWORD dst_unused:UNUSED_PAD src0_sel:WORD_1 src1_sel:DWORD
	v_and_b32_e32 v106, 0xffff0000, v63
	v_add3_u32 v133, v67, v116, s69
	v_add3_u32 v134, v75, v117, s69
	v_and_b32_e32 v113, 0xffff0000, v107
	v_and_b32_e32 v112, 0xffff0000, v111
	v_and_b32_e32 v107, 0xffff0000, v129
	v_and_b32_e32 v115, 0xffff0000, v130
	v_and_b32_e32 v114, 0xffff0000, v131
	v_and_b32_e32 v117, 0xffff0000, v123
	v_and_b32_e32 v116, 0xffff0000, v132
	v_and_b32_sdwa v119, v81, v104 dst_sel:DWORD dst_unused:UNUSED_PAD src0_sel:WORD_1 src1_sel:DWORD
	v_and_b32_sdwa v120, v80, v104 dst_sel:DWORD dst_unused:UNUSED_PAD src0_sel:WORD_1 src1_sel:DWORD
	v_add3_u32 v118, v74, v118, s69
	v_add3_u32 v137, v79, v121, s69
	v_add3_u32 v122, v78, v122, s69
	v_pk_add_f32 v[106:107], v[70:71], v[106:107] neg_lo:[0,1] neg_hi:[0,1]
	v_or_b32_sdwa v70, v112, v63 dst_sel:DWORD dst_unused:UNUSED_PAD src0_sel:DWORD src1_sel:WORD_1
	v_or_b32_sdwa v71, v113, v129 dst_sel:DWORD dst_unused:UNUSED_PAD src0_sel:DWORD src1_sel:WORD_1
	v_pk_add_f32 v[114:115], v[72:73], v[114:115] neg_lo:[0,1] neg_hi:[0,1]
	v_or_b32_sdwa v72, v116, v131 dst_sel:DWORD dst_unused:UNUSED_PAD src0_sel:DWORD src1_sel:WORD_1
	v_or_b32_sdwa v73, v117, v130 dst_sel:DWORD dst_unused:UNUSED_PAD src0_sel:DWORD src1_sel:WORD_1
	v_and_b32_e32 v110, 0xffff0000, v128
	v_add3_u32 v135, v81, v119, s69
	v_add3_u32 v136, v80, v120, s69
	v_and_b32_e32 v119, 0xffff0000, v134
	v_and_b32_e32 v118, 0xffff0000, v118
	v_and_b32_e32 v111, 0xffff0000, v133
	v_and_b32_e32 v123, 0xffff0000, v137
	v_and_b32_e32 v122, 0xffff0000, v122
	v_mfma_f32_32x32x16_bf16 v[2:17], v[34:37], v[70:73], v[2:17]
	v_add_f32_e64 v112, v68, -v112
	v_add_f32_e64 v113, v69, -v113
	v_add_f32_e64 v110, v66, -v110
	v_add_f32_e64 v111, v67, -v111
	v_or_b32_sdwa v66, v118, v128 dst_sel:DWORD dst_unused:UNUSED_PAD src0_sel:DWORD src1_sel:WORD_1
	v_or_b32_sdwa v67, v119, v133 dst_sel:DWORD dst_unused:UNUSED_PAD src0_sel:DWORD src1_sel:WORD_1
	v_or_b32_sdwa v68, v122, v136 dst_sel:DWORD dst_unused:UNUSED_PAD src0_sel:DWORD src1_sel:WORD_1
	v_or_b32_sdwa v69, v123, v135 dst_sel:DWORD dst_unused:UNUSED_PAD src0_sel:DWORD src1_sel:WORD_1
	v_and_b32_e32 v121, 0xffff0000, v135
	v_and_b32_e32 v120, 0xffff0000, v136
	v_mfma_f32_32x32x16_bf16 v[18:33], v[34:37], v[66:69], v[18:33]
	v_add_f32_e64 v76, v76, -v116
	v_add_f32_e64 v77, v77, -v117
	v_add_f32_e64 v74, v74, -v118
	v_add_f32_e64 v75, v75, -v119
	v_add_f32_e64 v80, v80, -v120
	v_add_f32_e64 v81, v81, -v121
	v_pk_add_f32 v[78:79], v[78:79], v[122:123] neg_lo:[0,1] neg_hi:[0,1]
	v_bfe_u32 v63, v113, 16, 1
	v_bfe_u32 v119, v114, 16, 1
	v_bfe_u32 v120, v115, 16, 1
	v_bfe_u32 v121, v106, 16, 1
	v_bfe_u32 v122, v107, 16, 1
	v_bfe_u32 v116, v112, 16, 1
	v_bfe_u32 v117, v77, 16, 1
	v_bfe_u32 v118, v76, 16, 1
	v_bfe_u32 v123, v75, 16, 1
	v_bfe_u32 v128, v74, 16, 1
	v_bfe_u32 v131, v80, 16, 1
	v_bfe_u32 v134, v111, 16, 1
	v_add3_u32 v63, v113, v63, s69
	v_add3_u32 v113, v115, v120, s69
	v_add3_u32 v114, v114, v119, s69
	v_add3_u32 v107, v107, v122, s69
	v_add3_u32 v106, v106, v121, s69
	v_bfe_u32 v132, v81, 16, 1
	v_bfe_u32 v133, v110, 16, 1
	v_add3_u32 v112, v112, v116, s69
	v_add3_u32 v76, v76, v118, s69
	v_add3_u32 v77, v77, v117, s69
	v_add3_u32 v115, v74, v128, s69
	v_add3_u32 v116, v75, v123, s69
	v_add3_u32 v74, v80, v131, s69
	v_add3_u32 v80, v111, v134, s69
	v_lshrrev_b32_e32 v75, 16, v114
	v_lshrrev_b32_e32 v111, 16, v113
	v_lshrrev_b32_e32 v106, 16, v106
	v_lshrrev_b32_e32 v107, 16, v107
	v_bfe_u32 v129, v79, 16, 1
	v_bfe_u32 v130, v78, 16, 1
	v_add3_u32 v81, v81, v132, s69
	v_add3_u32 v110, v110, v133, s69
	v_lshrrev_b32_e32 v113, 16, v74
	v_and_or_b32 v77, v77, s70, v111
	v_and_or_b32 v76, v76, s70, v75
	v_and_or_b32 v75, v63, s70, v107
	v_and_or_b32 v74, v112, s70, v106
	v_add3_u32 v78, v78, v130, s69
	v_add3_u32 v79, v79, v129, s69
	v_mfma_f32_32x32x16_bf16 v[2:17], v[34:37], v[74:77], v[2:17]
	v_lshrrev_b32_e32 v63, 16, v81
	v_lshrrev_b32_e32 v74, 16, v110
	v_lshrrev_b32_e32 v75, 16, v80
	v_and_or_b32 v77, v79, s70, v63
	v_and_or_b32 v76, v78, s70, v113
	v_and_or_b32 v75, v116, s70, v75
	v_and_or_b32 v74, v115, s70, v74
	v_and_or_b32 v107, v125, s70, v127
	v_and_or_b32 v106, v124, s70, v126
	v_mfma_f32_32x32x16_bf16 v[18:33], v[34:37], v[74:77], v[18:33]
	s_nop 0
	v_mfma_f32_32x32x16_bf16 v[2:17], v[106:109], v[70:73], v[2:17]
	v_mfma_f32_32x32x16_bf16 v[18:33], v[106:109], v[66:69], v[18:33]
	ds_read_b128 v[34:37], v40
	ds_read_b128 v[106:109], v40 offset:16
	s_waitcnt lgkmcnt(1)
	v_cndmask_b32_e64 v37, 0, v37, s[2:3]
	s_waitcnt lgkmcnt(0)
	v_cndmask_b32_e64 v109, 0, v109, s[2:3]
	v_and_b32_sdwa v63, v37, v104 dst_sel:DWORD dst_unused:UNUSED_PAD src0_sel:WORD_1 src1_sel:DWORD
	s_nop 0
	s_nop 0
	s_nop 0
	s_nop 0
	v_mov_b32_e32 v70, v154
	s_nop 0
	v_mov_b32_e32 v66, v155
	s_nop 0
	v_mov_b32_e32 v71, v156
	v_mov_b32_e32 v69, v157
	v_mov_b32_e32 v68, v158
	v_mov_b32_e32 v73, v159
	v_mov_b32_e32 v72, v160
	v_mov_b32_e32 v77, v161
	v_mov_b32_e32 v76, v162
	s_nop 0
	v_mov_b32_e32 v75, v163
	s_nop 0
	v_mov_b32_e32 v67, v164
	v_mov_b32_e32 v74, v165
	s_nop 0
	v_mov_b32_e32 v79, v166
	v_mov_b32_e32 v81, v167
	v_mov_b32_e32 v78, v168
	v_mov_b32_e32 v80, v169
	v_cndmask_b32_e64 v111, 0, v36, s[2:3]
	v_cndmask_b32_e64 v110, 0, v34, s[2:3]
	v_cndmask_b32_e64 v36, 0, v35, s[2:3]
	v_cndmask_b32_e64 v113, 0, v108, s[2:3]
	v_cndmask_b32_e64 v112, 0, v106, s[2:3]
	v_cndmask_b32_e64 v108, 0, v107, s[2:3]
	v_and_b32_sdwa v34, v111, v104 dst_sel:DWORD dst_unused:UNUSED_PAD src0_sel:WORD_1 src1_sel:DWORD
	v_and_b32_sdwa v35, v110, v104 dst_sel:DWORD dst_unused:UNUSED_PAD src0_sel:WORD_1 src1_sel:DWORD
	v_and_b32_sdwa v105, v36, v104 dst_sel:DWORD dst_unused:UNUSED_PAD src0_sel:WORD_1 src1_sel:DWORD
	v_and_b32_sdwa v106, v113, v104 dst_sel:DWORD dst_unused:UNUSED_PAD src0_sel:WORD_1 src1_sel:DWORD
	v_and_b32_sdwa v107, v112, v104 dst_sel:DWORD dst_unused:UNUSED_PAD src0_sel:WORD_1 src1_sel:DWORD
	v_and_b32_sdwa v114, v109, v104 dst_sel:DWORD dst_unused:UNUSED_PAD src0_sel:WORD_1 src1_sel:DWORD
	v_and_b32_sdwa v115, v108, v104 dst_sel:DWORD dst_unused:UNUSED_PAD src0_sel:WORD_1 src1_sel:DWORD
	v_add3_u32 v120, v111, v34, s69
	v_add3_u32 v34, v110, v35, s69
	v_add3_u32 v35, v37, v63, s69
	v_add3_u32 v63, v36, v105, s69
	v_add3_u32 v105, v113, v106, s69
	v_add3_u32 v121, v112, v107, s69
	v_add3_u32 v116, v109, v114, s69
	v_add3_u32 v118, v108, v115, s69
	v_and_b32_e32 v107, 0xffff0000, v35
	v_and_b32_e32 v106, 0xffff0000, v63
	v_and_b32_e32 v115, 0xffff0000, v120
	v_and_b32_e32 v114, 0xffff0000, v34
	v_and_b32_e32 v117, 0xffff0000, v116
	v_and_b32_e32 v116, 0xffff0000, v118
	v_and_b32_e32 v119, 0xffff0000, v105
	v_and_b32_e32 v118, 0xffff0000, v121
	v_or_b32_sdwa v34, v106, v34 dst_sel:DWORD dst_unused:UNUSED_PAD src0_sel:DWORD src1_sel:WORD_1
	v_pk_add_f32 v[110:111], v[110:111], v[114:115] neg_lo:[0,1] neg_hi:[0,1]
	v_pk_add_f32 v[114:115], v[36:37], v[106:107] neg_lo:[0,1] neg_hi:[0,1]
	v_or_b32_sdwa v35, v107, v120 dst_sel:DWORD dst_unused:UNUSED_PAD src0_sel:DWORD src1_sel:WORD_1
	v_pk_add_f32 v[106:107], v[112:113], v[118:119] neg_lo:[0,1] neg_hi:[0,1]
	v_pk_add_f32 v[108:109], v[108:109], v[116:117] neg_lo:[0,1] neg_hi:[0,1]
	v_or_b32_sdwa v37, v117, v105 dst_sel:DWORD dst_unused:UNUSED_PAD src0_sel:DWORD src1_sel:WORD_1
	v_bfe_u32 v105, v108, 16, 1
	v_bfe_u32 v117, v111, 16, 1
	v_bfe_u32 v118, v106, 16, 1
	v_bfe_u32 v119, v107, 16, 1
	v_or_b32_sdwa v36, v116, v121 dst_sel:DWORD dst_unused:UNUSED_PAD src0_sel:DWORD src1_sel:WORD_1
	v_bfe_u32 v63, v109, 16, 1
	v_bfe_u32 v116, v110, 16, 1
	v_add3_u32 v105, v108, v105, s69
	v_add3_u32 v107, v107, v119, s69
	v_add3_u32 v106, v106, v118, s69
	v_add3_u32 v108, v111, v117, s69
	v_bfe_u32 v112, v115, 16, 1
	v_bfe_u32 v113, v114, 16, 1
	v_add3_u32 v63, v109, v63, s69
	v_add3_u32 v109, v110, v116, s69
	v_lshrrev_b32_e32 v127, 16, v108
	v_lshrrev_b32_e32 v108, 16, v106
	v_lshrrev_b32_e32 v106, 16, v107
	v_add3_u32 v124, v114, v113, s69
	v_add3_u32 v125, v115, v112, s69
	v_lshrrev_b32_e32 v126, 16, v109
	v_and_or_b32 v109, v63, s70, v106
	v_and_or_b32 v108, v105, s70, v108
	v_add_u32_e32 v40, 64, v40
	v_and_b32_sdwa v63, v70, v104 dst_sel:DWORD dst_unused:UNUSED_PAD src0_sel:WORD_1 src1_sel:DWORD
	v_and_b32_sdwa v106, v66, v104 dst_sel:DWORD dst_unused:UNUSED_PAD src0_sel:WORD_1 src1_sel:DWORD
	v_and_b32_sdwa v107, v71, v104 dst_sel:DWORD dst_unused:UNUSED_PAD src0_sel:WORD_1 src1_sel:DWORD
	v_and_b32_sdwa v110, v69, v104 dst_sel:DWORD dst_unused:UNUSED_PAD src0_sel:WORD_1 src1_sel:DWORD
	v_and_b32_sdwa v111, v68, v104 dst_sel:DWORD dst_unused:UNUSED_PAD src0_sel:WORD_1 src1_sel:DWORD
	v_and_b32_sdwa v112, v73, v104 dst_sel:DWORD dst_unused:UNUSED_PAD src0_sel:WORD_1 src1_sel:DWORD
	v_and_b32_sdwa v113, v72, v104 dst_sel:DWORD dst_unused:UNUSED_PAD src0_sel:WORD_1 src1_sel:DWORD
	v_and_b32_sdwa v114, v77, v104 dst_sel:DWORD dst_unused:UNUSED_PAD src0_sel:WORD_1 src1_sel:DWORD
	v_and_b32_sdwa v115, v76, v104 dst_sel:DWORD dst_unused:UNUSED_PAD src0_sel:WORD_1 src1_sel:DWORD
	v_add3_u32 v63, v70, v63, s69
	v_and_b32_sdwa v116, v67, v104 dst_sel:DWORD dst_unused:UNUSED_PAD src0_sel:WORD_1 src1_sel:DWORD
	v_and_b32_sdwa v117, v75, v104 dst_sel:DWORD dst_unused:UNUSED_PAD src0_sel:WORD_1 src1_sel:DWORD
	v_add3_u32 v129, v71, v107, s69
	v_add3_u32 v107, v69, v110, s69
	v_add3_u32 v111, v68, v111, s69
	v_add3_u32 v130, v73, v112, s69
	v_add3_u32 v131, v72, v113, s69
	v_add3_u32 v123, v77, v114, s69
	v_add3_u32 v132, v76, v115, s69
	v_add3_u32 v128, v66, v106, s69
	v_and_b32_sdwa v118, v74, v104 dst_sel:DWORD dst_unused:UNUSED_PAD src0_sel:WORD_1 src1_sel:DWORD
	v_and_b32_sdwa v121, v79, v104 dst_sel:DWORD dst_unused:UNUSED_PAD src0_sel:WORD_1 src1_sel:DWORD
	v_and_b32_sdwa v122, v78, v104 dst_sel:DWORD dst_unused:UNUSED_PAD src0_sel:WORD_1 src1_sel:DWORD
	v_and_b32_e32 v106, 0xffff0000, v63
	v_add3_u32 v133, v67, v116, s69
	v_add3_u32 v134, v75, v117, s69
	v_and_b32_e32 v113, 0xffff0000, v107
	v_and_b32_e32 v112, 0xffff0000, v111
	v_and_b32_e32 v107, 0xffff0000, v129
	v_and_b32_e32 v115, 0xffff0000, v130
	v_and_b32_e32 v114, 0xffff0000, v131
	v_and_b32_e32 v117, 0xffff0000, v123
	v_and_b32_e32 v116, 0xffff0000, v132
	v_and_b32_sdwa v119, v81, v104 dst_sel:DWORD dst_unused:UNUSED_PAD src0_sel:WORD_1 src1_sel:DWORD
	v_and_b32_sdwa v120, v80, v104 dst_sel:DWORD dst_unused:UNUSED_PAD src0_sel:WORD_1 src1_sel:DWORD
	v_add3_u32 v118, v74, v118, s69
	v_add3_u32 v137, v79, v121, s69
	v_add3_u32 v122, v78, v122, s69
	v_pk_add_f32 v[106:107], v[70:71], v[106:107] neg_lo:[0,1] neg_hi:[0,1]
	v_or_b32_sdwa v70, v112, v63 dst_sel:DWORD dst_unused:UNUSED_PAD src0_sel:DWORD src1_sel:WORD_1
	v_or_b32_sdwa v71, v113, v129 dst_sel:DWORD dst_unused:UNUSED_PAD src0_sel:DWORD src1_sel:WORD_1
	v_pk_add_f32 v[114:115], v[72:73], v[114:115] neg_lo:[0,1] neg_hi:[0,1]
	v_or_b32_sdwa v72, v116, v131 dst_sel:DWORD dst_unused:UNUSED_PAD src0_sel:DWORD src1_sel:WORD_1
	v_or_b32_sdwa v73, v117, v130 dst_sel:DWORD dst_unused:UNUSED_PAD src0_sel:DWORD src1_sel:WORD_1
	v_and_b32_e32 v110, 0xffff0000, v128
	v_add3_u32 v135, v81, v119, s69
	v_add3_u32 v136, v80, v120, s69
	v_and_b32_e32 v119, 0xffff0000, v134
	v_and_b32_e32 v118, 0xffff0000, v118
	v_and_b32_e32 v111, 0xffff0000, v133
	v_and_b32_e32 v123, 0xffff0000, v137
	v_and_b32_e32 v122, 0xffff0000, v122
	v_mfma_f32_32x32x16_bf16 v[2:17], v[34:37], v[70:73], v[2:17]
	v_add_f32_e64 v112, v68, -v112
	v_add_f32_e64 v113, v69, -v113
	v_add_f32_e64 v110, v66, -v110
	v_add_f32_e64 v111, v67, -v111
	v_or_b32_sdwa v66, v118, v128 dst_sel:DWORD dst_unused:UNUSED_PAD src0_sel:DWORD src1_sel:WORD_1
	v_or_b32_sdwa v67, v119, v133 dst_sel:DWORD dst_unused:UNUSED_PAD src0_sel:DWORD src1_sel:WORD_1
	v_or_b32_sdwa v68, v122, v136 dst_sel:DWORD dst_unused:UNUSED_PAD src0_sel:DWORD src1_sel:WORD_1
	v_or_b32_sdwa v69, v123, v135 dst_sel:DWORD dst_unused:UNUSED_PAD src0_sel:DWORD src1_sel:WORD_1
	v_and_b32_e32 v121, 0xffff0000, v135
	v_and_b32_e32 v120, 0xffff0000, v136
	v_mfma_f32_32x32x16_bf16 v[18:33], v[34:37], v[66:69], v[18:33]
	v_add_f32_e64 v76, v76, -v116
	v_add_f32_e64 v77, v77, -v117
	v_add_f32_e64 v74, v74, -v118
	v_add_f32_e64 v75, v75, -v119
	v_add_f32_e64 v80, v80, -v120
	v_add_f32_e64 v81, v81, -v121
	v_pk_add_f32 v[78:79], v[78:79], v[122:123] neg_lo:[0,1] neg_hi:[0,1]
	v_bfe_u32 v63, v113, 16, 1
	v_bfe_u32 v119, v114, 16, 1
	v_bfe_u32 v120, v115, 16, 1
	v_bfe_u32 v121, v106, 16, 1
	v_bfe_u32 v122, v107, 16, 1
	v_bfe_u32 v116, v112, 16, 1
	v_bfe_u32 v117, v77, 16, 1
	v_bfe_u32 v118, v76, 16, 1
	v_bfe_u32 v123, v75, 16, 1
	v_bfe_u32 v128, v74, 16, 1
	v_bfe_u32 v131, v80, 16, 1
	v_bfe_u32 v134, v111, 16, 1
	v_add3_u32 v63, v113, v63, s69
	v_add3_u32 v113, v115, v120, s69
	v_add3_u32 v114, v114, v119, s69
	v_add3_u32 v107, v107, v122, s69
	v_add3_u32 v106, v106, v121, s69
	v_bfe_u32 v132, v81, 16, 1
	v_bfe_u32 v133, v110, 16, 1
	v_add3_u32 v112, v112, v116, s69
	v_add3_u32 v76, v76, v118, s69
	v_add3_u32 v77, v77, v117, s69
	v_add3_u32 v115, v74, v128, s69
	v_add3_u32 v116, v75, v123, s69
	v_add3_u32 v74, v80, v131, s69
	v_add3_u32 v80, v111, v134, s69
	v_lshrrev_b32_e32 v75, 16, v114
	v_lshrrev_b32_e32 v111, 16, v113
	v_lshrrev_b32_e32 v106, 16, v106
	v_lshrrev_b32_e32 v107, 16, v107
	v_bfe_u32 v129, v79, 16, 1
	v_bfe_u32 v130, v78, 16, 1
	v_add3_u32 v81, v81, v132, s69
	v_add3_u32 v110, v110, v133, s69
	v_lshrrev_b32_e32 v113, 16, v74
	v_and_or_b32 v77, v77, s70, v111
	v_and_or_b32 v76, v76, s70, v75
	v_and_or_b32 v75, v63, s70, v107
	v_and_or_b32 v74, v112, s70, v106
	v_add3_u32 v78, v78, v130, s69
	v_add3_u32 v79, v79, v129, s69
	v_mfma_f32_32x32x16_bf16 v[2:17], v[34:37], v[74:77], v[2:17]
	v_lshrrev_b32_e32 v63, 16, v81
	v_lshrrev_b32_e32 v74, 16, v110
	v_lshrrev_b32_e32 v75, 16, v80
	v_and_or_b32 v77, v79, s70, v63
	v_and_or_b32 v76, v78, s70, v113
	v_and_or_b32 v75, v116, s70, v75
	v_and_or_b32 v74, v115, s70, v74
	v_and_or_b32 v107, v125, s70, v127
	v_and_or_b32 v106, v124, s70, v126
	v_mfma_f32_32x32x16_bf16 v[18:33], v[34:37], v[74:77], v[18:33]
	s_nop 0
	v_mfma_f32_32x32x16_bf16 v[2:17], v[106:109], v[70:73], v[2:17]
	v_mfma_f32_32x32x16_bf16 v[18:33], v[106:109], v[66:69], v[18:33]
	ds_read_b128 v[34:37], v40
	ds_read_b128 v[106:109], v40 offset:16
	s_waitcnt lgkmcnt(1)
	v_cndmask_b32_e64 v37, 0, v37, s[2:3]
	s_waitcnt lgkmcnt(0)
	v_cndmask_b32_e64 v109, 0, v109, s[2:3]
	v_and_b32_sdwa v63, v37, v104 dst_sel:DWORD dst_unused:UNUSED_PAD src0_sel:WORD_1 src1_sel:DWORD
	s_nop 0
	s_nop 0
	s_nop 0
	s_nop 0
	v_mov_b32_e32 v70, v170
	s_nop 0
	v_mov_b32_e32 v66, v171
	s_nop 0
	v_mov_b32_e32 v71, v172
	v_mov_b32_e32 v69, v173
	v_mov_b32_e32 v68, v174
	v_mov_b32_e32 v73, v175
	v_mov_b32_e32 v72, v176
	v_mov_b32_e32 v77, v177
	v_mov_b32_e32 v76, v178
	s_nop 0
	v_mov_b32_e32 v75, v179
	s_nop 0
	v_mov_b32_e32 v67, v180
	v_mov_b32_e32 v74, v181
	s_nop 0
	v_mov_b32_e32 v79, v182
	v_mov_b32_e32 v81, v183
	v_mov_b32_e32 v78, v184
	v_mov_b32_e32 v80, v185
	v_cndmask_b32_e64 v111, 0, v36, s[2:3]
	v_cndmask_b32_e64 v110, 0, v34, s[2:3]
	v_cndmask_b32_e64 v36, 0, v35, s[2:3]
	v_cndmask_b32_e64 v113, 0, v108, s[2:3]
	v_cndmask_b32_e64 v112, 0, v106, s[2:3]
	v_cndmask_b32_e64 v108, 0, v107, s[2:3]
	v_and_b32_sdwa v34, v111, v104 dst_sel:DWORD dst_unused:UNUSED_PAD src0_sel:WORD_1 src1_sel:DWORD
	v_and_b32_sdwa v35, v110, v104 dst_sel:DWORD dst_unused:UNUSED_PAD src0_sel:WORD_1 src1_sel:DWORD
	v_and_b32_sdwa v105, v36, v104 dst_sel:DWORD dst_unused:UNUSED_PAD src0_sel:WORD_1 src1_sel:DWORD
	v_and_b32_sdwa v106, v113, v104 dst_sel:DWORD dst_unused:UNUSED_PAD src0_sel:WORD_1 src1_sel:DWORD
	v_and_b32_sdwa v107, v112, v104 dst_sel:DWORD dst_unused:UNUSED_PAD src0_sel:WORD_1 src1_sel:DWORD
	v_and_b32_sdwa v114, v109, v104 dst_sel:DWORD dst_unused:UNUSED_PAD src0_sel:WORD_1 src1_sel:DWORD
	v_and_b32_sdwa v115, v108, v104 dst_sel:DWORD dst_unused:UNUSED_PAD src0_sel:WORD_1 src1_sel:DWORD
	v_add3_u32 v120, v111, v34, s69
	v_add3_u32 v34, v110, v35, s69
	v_add3_u32 v35, v37, v63, s69
	v_add3_u32 v63, v36, v105, s69
	v_add3_u32 v105, v113, v106, s69
	v_add3_u32 v121, v112, v107, s69
	v_add3_u32 v116, v109, v114, s69
	v_add3_u32 v118, v108, v115, s69
	v_and_b32_e32 v107, 0xffff0000, v35
	v_and_b32_e32 v106, 0xffff0000, v63
	v_and_b32_e32 v115, 0xffff0000, v120
	v_and_b32_e32 v114, 0xffff0000, v34
	v_and_b32_e32 v117, 0xffff0000, v116
	v_and_b32_e32 v116, 0xffff0000, v118
	v_and_b32_e32 v119, 0xffff0000, v105
	v_and_b32_e32 v118, 0xffff0000, v121
	v_or_b32_sdwa v34, v106, v34 dst_sel:DWORD dst_unused:UNUSED_PAD src0_sel:DWORD src1_sel:WORD_1
	v_pk_add_f32 v[110:111], v[110:111], v[114:115] neg_lo:[0,1] neg_hi:[0,1]
	v_pk_add_f32 v[114:115], v[36:37], v[106:107] neg_lo:[0,1] neg_hi:[0,1]
	v_or_b32_sdwa v35, v107, v120 dst_sel:DWORD dst_unused:UNUSED_PAD src0_sel:DWORD src1_sel:WORD_1
	v_pk_add_f32 v[106:107], v[112:113], v[118:119] neg_lo:[0,1] neg_hi:[0,1]
	v_pk_add_f32 v[108:109], v[108:109], v[116:117] neg_lo:[0,1] neg_hi:[0,1]
	v_or_b32_sdwa v37, v117, v105 dst_sel:DWORD dst_unused:UNUSED_PAD src0_sel:DWORD src1_sel:WORD_1
	v_bfe_u32 v105, v108, 16, 1
	v_bfe_u32 v117, v111, 16, 1
	v_bfe_u32 v118, v106, 16, 1
	v_bfe_u32 v119, v107, 16, 1
	v_or_b32_sdwa v36, v116, v121 dst_sel:DWORD dst_unused:UNUSED_PAD src0_sel:DWORD src1_sel:WORD_1
	v_bfe_u32 v63, v109, 16, 1
	v_bfe_u32 v116, v110, 16, 1
	v_add3_u32 v105, v108, v105, s69
	v_add3_u32 v107, v107, v119, s69
	v_add3_u32 v106, v106, v118, s69
	v_add3_u32 v108, v111, v117, s69
	v_bfe_u32 v112, v115, 16, 1
	v_bfe_u32 v113, v114, 16, 1
	v_add3_u32 v63, v109, v63, s69
	v_add3_u32 v109, v110, v116, s69
	v_lshrrev_b32_e32 v127, 16, v108
	v_lshrrev_b32_e32 v108, 16, v106
	v_lshrrev_b32_e32 v106, 16, v107
	v_add3_u32 v124, v114, v113, s69
	v_add3_u32 v125, v115, v112, s69
	v_lshrrev_b32_e32 v126, 16, v109
	v_and_or_b32 v109, v63, s70, v106
	v_and_or_b32 v108, v105, s70, v108
	v_add_u32_e32 v40, 64, v40
	v_and_b32_sdwa v63, v70, v104 dst_sel:DWORD dst_unused:UNUSED_PAD src0_sel:WORD_1 src1_sel:DWORD
	v_and_b32_sdwa v106, v66, v104 dst_sel:DWORD dst_unused:UNUSED_PAD src0_sel:WORD_1 src1_sel:DWORD
	v_and_b32_sdwa v107, v71, v104 dst_sel:DWORD dst_unused:UNUSED_PAD src0_sel:WORD_1 src1_sel:DWORD
	v_and_b32_sdwa v110, v69, v104 dst_sel:DWORD dst_unused:UNUSED_PAD src0_sel:WORD_1 src1_sel:DWORD
	v_and_b32_sdwa v111, v68, v104 dst_sel:DWORD dst_unused:UNUSED_PAD src0_sel:WORD_1 src1_sel:DWORD
	v_and_b32_sdwa v112, v73, v104 dst_sel:DWORD dst_unused:UNUSED_PAD src0_sel:WORD_1 src1_sel:DWORD
	v_and_b32_sdwa v113, v72, v104 dst_sel:DWORD dst_unused:UNUSED_PAD src0_sel:WORD_1 src1_sel:DWORD
	v_and_b32_sdwa v114, v77, v104 dst_sel:DWORD dst_unused:UNUSED_PAD src0_sel:WORD_1 src1_sel:DWORD
	v_and_b32_sdwa v115, v76, v104 dst_sel:DWORD dst_unused:UNUSED_PAD src0_sel:WORD_1 src1_sel:DWORD
	v_add3_u32 v63, v70, v63, s69
	v_and_b32_sdwa v116, v67, v104 dst_sel:DWORD dst_unused:UNUSED_PAD src0_sel:WORD_1 src1_sel:DWORD
	v_and_b32_sdwa v117, v75, v104 dst_sel:DWORD dst_unused:UNUSED_PAD src0_sel:WORD_1 src1_sel:DWORD
	v_add3_u32 v129, v71, v107, s69
	v_add3_u32 v107, v69, v110, s69
	v_add3_u32 v111, v68, v111, s69
	v_add3_u32 v130, v73, v112, s69
	v_add3_u32 v131, v72, v113, s69
	v_add3_u32 v123, v77, v114, s69
	v_add3_u32 v132, v76, v115, s69
	v_add3_u32 v128, v66, v106, s69
	v_and_b32_sdwa v118, v74, v104 dst_sel:DWORD dst_unused:UNUSED_PAD src0_sel:WORD_1 src1_sel:DWORD
	v_and_b32_sdwa v121, v79, v104 dst_sel:DWORD dst_unused:UNUSED_PAD src0_sel:WORD_1 src1_sel:DWORD
	v_and_b32_sdwa v122, v78, v104 dst_sel:DWORD dst_unused:UNUSED_PAD src0_sel:WORD_1 src1_sel:DWORD
	v_and_b32_e32 v106, 0xffff0000, v63
	v_add3_u32 v133, v67, v116, s69
	v_add3_u32 v134, v75, v117, s69
	v_and_b32_e32 v113, 0xffff0000, v107
	v_and_b32_e32 v112, 0xffff0000, v111
	v_and_b32_e32 v107, 0xffff0000, v129
	v_and_b32_e32 v115, 0xffff0000, v130
	v_and_b32_e32 v114, 0xffff0000, v131
	v_and_b32_e32 v117, 0xffff0000, v123
	v_and_b32_e32 v116, 0xffff0000, v132
	v_and_b32_sdwa v119, v81, v104 dst_sel:DWORD dst_unused:UNUSED_PAD src0_sel:WORD_1 src1_sel:DWORD
	v_and_b32_sdwa v120, v80, v104 dst_sel:DWORD dst_unused:UNUSED_PAD src0_sel:WORD_1 src1_sel:DWORD
	v_add3_u32 v118, v74, v118, s69
	v_add3_u32 v137, v79, v121, s69
	v_add3_u32 v122, v78, v122, s69
	v_pk_add_f32 v[106:107], v[70:71], v[106:107] neg_lo:[0,1] neg_hi:[0,1]
	v_or_b32_sdwa v70, v112, v63 dst_sel:DWORD dst_unused:UNUSED_PAD src0_sel:DWORD src1_sel:WORD_1
	v_or_b32_sdwa v71, v113, v129 dst_sel:DWORD dst_unused:UNUSED_PAD src0_sel:DWORD src1_sel:WORD_1
	v_pk_add_f32 v[114:115], v[72:73], v[114:115] neg_lo:[0,1] neg_hi:[0,1]
	v_or_b32_sdwa v72, v116, v131 dst_sel:DWORD dst_unused:UNUSED_PAD src0_sel:DWORD src1_sel:WORD_1
	v_or_b32_sdwa v73, v117, v130 dst_sel:DWORD dst_unused:UNUSED_PAD src0_sel:DWORD src1_sel:WORD_1
	v_and_b32_e32 v110, 0xffff0000, v128
	v_add3_u32 v135, v81, v119, s69
	v_add3_u32 v136, v80, v120, s69
	v_and_b32_e32 v119, 0xffff0000, v134
	v_and_b32_e32 v118, 0xffff0000, v118
	v_and_b32_e32 v111, 0xffff0000, v133
	v_and_b32_e32 v123, 0xffff0000, v137
	v_and_b32_e32 v122, 0xffff0000, v122
	v_mfma_f32_32x32x16_bf16 v[2:17], v[34:37], v[70:73], v[2:17]
	v_add_f32_e64 v112, v68, -v112
	v_add_f32_e64 v113, v69, -v113
	v_add_f32_e64 v110, v66, -v110
	v_add_f32_e64 v111, v67, -v111
	v_or_b32_sdwa v66, v118, v128 dst_sel:DWORD dst_unused:UNUSED_PAD src0_sel:DWORD src1_sel:WORD_1
	v_or_b32_sdwa v67, v119, v133 dst_sel:DWORD dst_unused:UNUSED_PAD src0_sel:DWORD src1_sel:WORD_1
	v_or_b32_sdwa v68, v122, v136 dst_sel:DWORD dst_unused:UNUSED_PAD src0_sel:DWORD src1_sel:WORD_1
	v_or_b32_sdwa v69, v123, v135 dst_sel:DWORD dst_unused:UNUSED_PAD src0_sel:DWORD src1_sel:WORD_1
	v_and_b32_e32 v121, 0xffff0000, v135
	v_and_b32_e32 v120, 0xffff0000, v136
	v_mfma_f32_32x32x16_bf16 v[18:33], v[34:37], v[66:69], v[18:33]
	v_add_f32_e64 v76, v76, -v116
	v_add_f32_e64 v77, v77, -v117
	v_add_f32_e64 v74, v74, -v118
	v_add_f32_e64 v75, v75, -v119
	v_add_f32_e64 v80, v80, -v120
	v_add_f32_e64 v81, v81, -v121
	v_pk_add_f32 v[78:79], v[78:79], v[122:123] neg_lo:[0,1] neg_hi:[0,1]
	v_bfe_u32 v63, v113, 16, 1
	v_bfe_u32 v119, v114, 16, 1
	v_bfe_u32 v120, v115, 16, 1
	v_bfe_u32 v121, v106, 16, 1
	v_bfe_u32 v122, v107, 16, 1
	v_bfe_u32 v116, v112, 16, 1
	v_bfe_u32 v117, v77, 16, 1
	v_bfe_u32 v118, v76, 16, 1
	v_bfe_u32 v123, v75, 16, 1
	v_bfe_u32 v128, v74, 16, 1
	v_bfe_u32 v131, v80, 16, 1
	v_bfe_u32 v134, v111, 16, 1
	v_add3_u32 v63, v113, v63, s69
	v_add3_u32 v113, v115, v120, s69
	v_add3_u32 v114, v114, v119, s69
	v_add3_u32 v107, v107, v122, s69
	v_add3_u32 v106, v106, v121, s69
	v_bfe_u32 v132, v81, 16, 1
	v_bfe_u32 v133, v110, 16, 1
	v_add3_u32 v112, v112, v116, s69
	v_add3_u32 v76, v76, v118, s69
	v_add3_u32 v77, v77, v117, s69
	v_add3_u32 v115, v74, v128, s69
	v_add3_u32 v116, v75, v123, s69
	v_add3_u32 v74, v80, v131, s69
	v_add3_u32 v80, v111, v134, s69
	v_lshrrev_b32_e32 v75, 16, v114
	v_lshrrev_b32_e32 v111, 16, v113
	v_lshrrev_b32_e32 v106, 16, v106
	v_lshrrev_b32_e32 v107, 16, v107
	v_bfe_u32 v129, v79, 16, 1
	v_bfe_u32 v130, v78, 16, 1
	v_add3_u32 v81, v81, v132, s69
	v_add3_u32 v110, v110, v133, s69
	v_lshrrev_b32_e32 v113, 16, v74
	v_and_or_b32 v77, v77, s70, v111
	v_and_or_b32 v76, v76, s70, v75
	v_and_or_b32 v75, v63, s70, v107
	v_and_or_b32 v74, v112, s70, v106
	v_add3_u32 v78, v78, v130, s69
	v_add3_u32 v79, v79, v129, s69
	v_mfma_f32_32x32x16_bf16 v[2:17], v[34:37], v[74:77], v[2:17]
	v_lshrrev_b32_e32 v63, 16, v81
	v_lshrrev_b32_e32 v74, 16, v110
	v_lshrrev_b32_e32 v75, 16, v80
	v_and_or_b32 v77, v79, s70, v63
	v_and_or_b32 v76, v78, s70, v113
	v_and_or_b32 v75, v116, s70, v75
	v_and_or_b32 v74, v115, s70, v74
	v_and_or_b32 v107, v125, s70, v127
	v_and_or_b32 v106, v124, s70, v126
	v_mfma_f32_32x32x16_bf16 v[18:33], v[34:37], v[74:77], v[18:33]
	s_nop 0
	v_mfma_f32_32x32x16_bf16 v[2:17], v[106:109], v[70:73], v[2:17]
	v_mfma_f32_32x32x16_bf16 v[18:33], v[106:109], v[66:69], v[18:33]
	ds_read_b128 v[34:37], v40
	ds_read_b128 v[106:109], v40 offset:16
	s_waitcnt lgkmcnt(1)
	v_cndmask_b32_e64 v37, 0, v37, s[2:3]
	s_waitcnt lgkmcnt(0)
	v_cndmask_b32_e64 v109, 0, v109, s[2:3]
	v_and_b32_sdwa v63, v37, v104 dst_sel:DWORD dst_unused:UNUSED_PAD src0_sel:WORD_1 src1_sel:DWORD
	s_nop 0
	s_nop 0
	s_nop 0
	s_nop 0
	v_mov_b32_e32 v70, v186
	s_nop 0
	v_mov_b32_e32 v66, v187
	s_nop 0
	v_mov_b32_e32 v71, v188
	v_mov_b32_e32 v69, v189
	v_mov_b32_e32 v68, v190
	v_mov_b32_e32 v73, v191
	v_mov_b32_e32 v72, v192
	v_mov_b32_e32 v77, v193
	v_mov_b32_e32 v76, v194
	s_nop 0
	v_mov_b32_e32 v75, v195
	s_nop 0
	v_mov_b32_e32 v67, v196
	v_mov_b32_e32 v74, v197
	s_nop 0
	v_mov_b32_e32 v79, v198
	v_mov_b32_e32 v81, v199
	v_mov_b32_e32 v78, v200
	v_mov_b32_e32 v80, v201
	v_cndmask_b32_e64 v111, 0, v36, s[2:3]
	v_cndmask_b32_e64 v110, 0, v34, s[2:3]
	v_cndmask_b32_e64 v36, 0, v35, s[2:3]
	v_cndmask_b32_e64 v113, 0, v108, s[2:3]
	v_cndmask_b32_e64 v112, 0, v106, s[2:3]
	v_cndmask_b32_e64 v108, 0, v107, s[2:3]
	v_and_b32_sdwa v34, v111, v104 dst_sel:DWORD dst_unused:UNUSED_PAD src0_sel:WORD_1 src1_sel:DWORD
	v_and_b32_sdwa v35, v110, v104 dst_sel:DWORD dst_unused:UNUSED_PAD src0_sel:WORD_1 src1_sel:DWORD
	v_and_b32_sdwa v105, v36, v104 dst_sel:DWORD dst_unused:UNUSED_PAD src0_sel:WORD_1 src1_sel:DWORD
	v_and_b32_sdwa v106, v113, v104 dst_sel:DWORD dst_unused:UNUSED_PAD src0_sel:WORD_1 src1_sel:DWORD
	v_and_b32_sdwa v107, v112, v104 dst_sel:DWORD dst_unused:UNUSED_PAD src0_sel:WORD_1 src1_sel:DWORD
	v_and_b32_sdwa v114, v109, v104 dst_sel:DWORD dst_unused:UNUSED_PAD src0_sel:WORD_1 src1_sel:DWORD
	v_and_b32_sdwa v115, v108, v104 dst_sel:DWORD dst_unused:UNUSED_PAD src0_sel:WORD_1 src1_sel:DWORD
	v_add3_u32 v120, v111, v34, s69
	v_add3_u32 v34, v110, v35, s69
	v_add3_u32 v35, v37, v63, s69
	v_add3_u32 v63, v36, v105, s69
	v_add3_u32 v105, v113, v106, s69
	v_add3_u32 v121, v112, v107, s69
	v_add3_u32 v116, v109, v114, s69
	v_add3_u32 v118, v108, v115, s69
	v_and_b32_e32 v107, 0xffff0000, v35
	v_and_b32_e32 v106, 0xffff0000, v63
	v_and_b32_e32 v115, 0xffff0000, v120
	v_and_b32_e32 v114, 0xffff0000, v34
	v_and_b32_e32 v117, 0xffff0000, v116
	v_and_b32_e32 v116, 0xffff0000, v118
	v_and_b32_e32 v119, 0xffff0000, v105
	v_and_b32_e32 v118, 0xffff0000, v121
	v_or_b32_sdwa v34, v106, v34 dst_sel:DWORD dst_unused:UNUSED_PAD src0_sel:DWORD src1_sel:WORD_1
	v_pk_add_f32 v[110:111], v[110:111], v[114:115] neg_lo:[0,1] neg_hi:[0,1]
	v_pk_add_f32 v[114:115], v[36:37], v[106:107] neg_lo:[0,1] neg_hi:[0,1]
	v_or_b32_sdwa v35, v107, v120 dst_sel:DWORD dst_unused:UNUSED_PAD src0_sel:DWORD src1_sel:WORD_1
	v_pk_add_f32 v[106:107], v[112:113], v[118:119] neg_lo:[0,1] neg_hi:[0,1]
	v_pk_add_f32 v[108:109], v[108:109], v[116:117] neg_lo:[0,1] neg_hi:[0,1]
	v_or_b32_sdwa v37, v117, v105 dst_sel:DWORD dst_unused:UNUSED_PAD src0_sel:DWORD src1_sel:WORD_1
	v_bfe_u32 v105, v108, 16, 1
	v_bfe_u32 v117, v111, 16, 1
	v_bfe_u32 v118, v106, 16, 1
	v_bfe_u32 v119, v107, 16, 1
	v_or_b32_sdwa v36, v116, v121 dst_sel:DWORD dst_unused:UNUSED_PAD src0_sel:DWORD src1_sel:WORD_1
	v_bfe_u32 v63, v109, 16, 1
	v_bfe_u32 v116, v110, 16, 1
	v_add3_u32 v105, v108, v105, s69
	v_add3_u32 v107, v107, v119, s69
	v_add3_u32 v106, v106, v118, s69
	v_add3_u32 v108, v111, v117, s69
	v_bfe_u32 v112, v115, 16, 1
	v_bfe_u32 v113, v114, 16, 1
	v_add3_u32 v63, v109, v63, s69
	v_add3_u32 v109, v110, v116, s69
	v_lshrrev_b32_e32 v127, 16, v108
	v_lshrrev_b32_e32 v108, 16, v106
	v_lshrrev_b32_e32 v106, 16, v107
	v_add3_u32 v124, v114, v113, s69
	v_add3_u32 v125, v115, v112, s69
	v_lshrrev_b32_e32 v126, 16, v109
	v_and_or_b32 v109, v63, s70, v106
	v_and_or_b32 v108, v105, s70, v108
	v_add_u32_e32 v40, 64, v40
	v_and_b32_sdwa v63, v70, v104 dst_sel:DWORD dst_unused:UNUSED_PAD src0_sel:WORD_1 src1_sel:DWORD
	v_and_b32_sdwa v106, v66, v104 dst_sel:DWORD dst_unused:UNUSED_PAD src0_sel:WORD_1 src1_sel:DWORD
	v_and_b32_sdwa v107, v71, v104 dst_sel:DWORD dst_unused:UNUSED_PAD src0_sel:WORD_1 src1_sel:DWORD
	v_and_b32_sdwa v110, v69, v104 dst_sel:DWORD dst_unused:UNUSED_PAD src0_sel:WORD_1 src1_sel:DWORD
	v_and_b32_sdwa v111, v68, v104 dst_sel:DWORD dst_unused:UNUSED_PAD src0_sel:WORD_1 src1_sel:DWORD
	v_and_b32_sdwa v112, v73, v104 dst_sel:DWORD dst_unused:UNUSED_PAD src0_sel:WORD_1 src1_sel:DWORD
	v_and_b32_sdwa v113, v72, v104 dst_sel:DWORD dst_unused:UNUSED_PAD src0_sel:WORD_1 src1_sel:DWORD
	v_and_b32_sdwa v114, v77, v104 dst_sel:DWORD dst_unused:UNUSED_PAD src0_sel:WORD_1 src1_sel:DWORD
	v_and_b32_sdwa v115, v76, v104 dst_sel:DWORD dst_unused:UNUSED_PAD src0_sel:WORD_1 src1_sel:DWORD
	v_add3_u32 v63, v70, v63, s69
	v_and_b32_sdwa v116, v67, v104 dst_sel:DWORD dst_unused:UNUSED_PAD src0_sel:WORD_1 src1_sel:DWORD
	v_and_b32_sdwa v117, v75, v104 dst_sel:DWORD dst_unused:UNUSED_PAD src0_sel:WORD_1 src1_sel:DWORD
	v_add3_u32 v129, v71, v107, s69
	v_add3_u32 v107, v69, v110, s69
	v_add3_u32 v111, v68, v111, s69
	v_add3_u32 v130, v73, v112, s69
	v_add3_u32 v131, v72, v113, s69
	v_add3_u32 v123, v77, v114, s69
	v_add3_u32 v132, v76, v115, s69
	v_add3_u32 v128, v66, v106, s69
	v_and_b32_sdwa v118, v74, v104 dst_sel:DWORD dst_unused:UNUSED_PAD src0_sel:WORD_1 src1_sel:DWORD
	v_and_b32_sdwa v121, v79, v104 dst_sel:DWORD dst_unused:UNUSED_PAD src0_sel:WORD_1 src1_sel:DWORD
	v_and_b32_sdwa v122, v78, v104 dst_sel:DWORD dst_unused:UNUSED_PAD src0_sel:WORD_1 src1_sel:DWORD
	v_and_b32_e32 v106, 0xffff0000, v63
	v_add3_u32 v133, v67, v116, s69
	v_add3_u32 v134, v75, v117, s69
	v_and_b32_e32 v113, 0xffff0000, v107
	v_and_b32_e32 v112, 0xffff0000, v111
	v_and_b32_e32 v107, 0xffff0000, v129
	v_and_b32_e32 v115, 0xffff0000, v130
	v_and_b32_e32 v114, 0xffff0000, v131
	v_and_b32_e32 v117, 0xffff0000, v123
	v_and_b32_e32 v116, 0xffff0000, v132
	v_and_b32_sdwa v119, v81, v104 dst_sel:DWORD dst_unused:UNUSED_PAD src0_sel:WORD_1 src1_sel:DWORD
	v_and_b32_sdwa v120, v80, v104 dst_sel:DWORD dst_unused:UNUSED_PAD src0_sel:WORD_1 src1_sel:DWORD
	v_add3_u32 v118, v74, v118, s69
	v_add3_u32 v137, v79, v121, s69
	v_add3_u32 v122, v78, v122, s69
	v_pk_add_f32 v[106:107], v[70:71], v[106:107] neg_lo:[0,1] neg_hi:[0,1]
	v_or_b32_sdwa v70, v112, v63 dst_sel:DWORD dst_unused:UNUSED_PAD src0_sel:DWORD src1_sel:WORD_1
	v_or_b32_sdwa v71, v113, v129 dst_sel:DWORD dst_unused:UNUSED_PAD src0_sel:DWORD src1_sel:WORD_1
	v_pk_add_f32 v[114:115], v[72:73], v[114:115] neg_lo:[0,1] neg_hi:[0,1]
	v_or_b32_sdwa v72, v116, v131 dst_sel:DWORD dst_unused:UNUSED_PAD src0_sel:DWORD src1_sel:WORD_1
	v_or_b32_sdwa v73, v117, v130 dst_sel:DWORD dst_unused:UNUSED_PAD src0_sel:DWORD src1_sel:WORD_1
	v_and_b32_e32 v110, 0xffff0000, v128
	v_add3_u32 v135, v81, v119, s69
	v_add3_u32 v136, v80, v120, s69
	v_and_b32_e32 v119, 0xffff0000, v134
	v_and_b32_e32 v118, 0xffff0000, v118
	v_and_b32_e32 v111, 0xffff0000, v133
	v_and_b32_e32 v123, 0xffff0000, v137
	v_and_b32_e32 v122, 0xffff0000, v122
	v_mfma_f32_32x32x16_bf16 v[2:17], v[34:37], v[70:73], v[2:17]
	v_add_f32_e64 v112, v68, -v112
	v_add_f32_e64 v113, v69, -v113
	v_add_f32_e64 v110, v66, -v110
	v_add_f32_e64 v111, v67, -v111
	v_or_b32_sdwa v66, v118, v128 dst_sel:DWORD dst_unused:UNUSED_PAD src0_sel:DWORD src1_sel:WORD_1
	v_or_b32_sdwa v67, v119, v133 dst_sel:DWORD dst_unused:UNUSED_PAD src0_sel:DWORD src1_sel:WORD_1
	v_or_b32_sdwa v68, v122, v136 dst_sel:DWORD dst_unused:UNUSED_PAD src0_sel:DWORD src1_sel:WORD_1
	v_or_b32_sdwa v69, v123, v135 dst_sel:DWORD dst_unused:UNUSED_PAD src0_sel:DWORD src1_sel:WORD_1
	v_and_b32_e32 v121, 0xffff0000, v135
	v_and_b32_e32 v120, 0xffff0000, v136
	v_mfma_f32_32x32x16_bf16 v[18:33], v[34:37], v[66:69], v[18:33]
	v_add_f32_e64 v76, v76, -v116
	v_add_f32_e64 v77, v77, -v117
	v_add_f32_e64 v74, v74, -v118
	v_add_f32_e64 v75, v75, -v119
	v_add_f32_e64 v80, v80, -v120
	v_add_f32_e64 v81, v81, -v121
	v_pk_add_f32 v[78:79], v[78:79], v[122:123] neg_lo:[0,1] neg_hi:[0,1]
	v_bfe_u32 v63, v113, 16, 1
	v_bfe_u32 v119, v114, 16, 1
	v_bfe_u32 v120, v115, 16, 1
	v_bfe_u32 v121, v106, 16, 1
	v_bfe_u32 v122, v107, 16, 1
	v_bfe_u32 v116, v112, 16, 1
	v_bfe_u32 v117, v77, 16, 1
	v_bfe_u32 v118, v76, 16, 1
	v_bfe_u32 v123, v75, 16, 1
	v_bfe_u32 v128, v74, 16, 1
	v_bfe_u32 v131, v80, 16, 1
	v_bfe_u32 v134, v111, 16, 1
	v_add3_u32 v63, v113, v63, s69
	v_add3_u32 v113, v115, v120, s69
	v_add3_u32 v114, v114, v119, s69
	v_add3_u32 v107, v107, v122, s69
	v_add3_u32 v106, v106, v121, s69
	v_bfe_u32 v132, v81, 16, 1
	v_bfe_u32 v133, v110, 16, 1
	v_add3_u32 v112, v112, v116, s69
	v_add3_u32 v76, v76, v118, s69
	v_add3_u32 v77, v77, v117, s69
	v_add3_u32 v115, v74, v128, s69
	v_add3_u32 v116, v75, v123, s69
	v_add3_u32 v74, v80, v131, s69
	v_add3_u32 v80, v111, v134, s69
	v_lshrrev_b32_e32 v75, 16, v114
	v_lshrrev_b32_e32 v111, 16, v113
	v_lshrrev_b32_e32 v106, 16, v106
	v_lshrrev_b32_e32 v107, 16, v107
	v_bfe_u32 v129, v79, 16, 1
	v_bfe_u32 v130, v78, 16, 1
	v_add3_u32 v81, v81, v132, s69
	v_add3_u32 v110, v110, v133, s69
	v_lshrrev_b32_e32 v113, 16, v74
	v_and_or_b32 v77, v77, s70, v111
	v_and_or_b32 v76, v76, s70, v75
	v_and_or_b32 v75, v63, s70, v107
	v_and_or_b32 v74, v112, s70, v106
	v_add3_u32 v78, v78, v130, s69
	v_add3_u32 v79, v79, v129, s69
	v_mfma_f32_32x32x16_bf16 v[2:17], v[34:37], v[74:77], v[2:17]
	v_lshrrev_b32_e32 v63, 16, v81
	v_lshrrev_b32_e32 v74, 16, v110
	v_lshrrev_b32_e32 v75, 16, v80
	v_and_or_b32 v77, v79, s70, v63
	v_and_or_b32 v76, v78, s70, v113
	v_and_or_b32 v75, v116, s70, v75
	v_and_or_b32 v74, v115, s70, v74
	v_and_or_b32 v107, v125, s70, v127
	v_and_or_b32 v106, v124, s70, v126
	v_mfma_f32_32x32x16_bf16 v[18:33], v[34:37], v[74:77], v[18:33]
	s_nop 0
	v_mfma_f32_32x32x16_bf16 v[2:17], v[106:109], v[70:73], v[2:17]
	v_mfma_f32_32x32x16_bf16 v[18:33], v[106:109], v[66:69], v[18:33]
	ds_read_b128 v[34:37], v40
	ds_read_b128 v[106:109], v40 offset:16
	s_waitcnt lgkmcnt(1)
	v_cndmask_b32_e64 v37, 0, v37, s[2:3]
	s_waitcnt lgkmcnt(0)
	v_cndmask_b32_e64 v109, 0, v109, s[2:3]
	v_and_b32_sdwa v63, v37, v104 dst_sel:DWORD dst_unused:UNUSED_PAD src0_sel:WORD_1 src1_sel:DWORD
	s_nop 0
	s_nop 0
	s_nop 0
	s_nop 0
	v_mov_b32_e32 v70, v202
	s_nop 0
	v_mov_b32_e32 v66, v203
	s_nop 0
	v_mov_b32_e32 v71, v204
	v_mov_b32_e32 v69, v205
	v_mov_b32_e32 v68, v206
	v_mov_b32_e32 v73, v207
	v_mov_b32_e32 v72, v208
	v_mov_b32_e32 v77, v209
	v_mov_b32_e32 v76, v210
	s_nop 0
	v_mov_b32_e32 v75, v211
	s_nop 0
	v_mov_b32_e32 v67, v212
	v_mov_b32_e32 v74, v213
	s_nop 0
	v_mov_b32_e32 v79, v214
	v_mov_b32_e32 v81, v215
	v_mov_b32_e32 v78, v216
	v_mov_b32_e32 v80, v217
	v_cndmask_b32_e64 v111, 0, v36, s[2:3]
	v_cndmask_b32_e64 v110, 0, v34, s[2:3]
	v_cndmask_b32_e64 v36, 0, v35, s[2:3]
	v_cndmask_b32_e64 v113, 0, v108, s[2:3]
	v_cndmask_b32_e64 v112, 0, v106, s[2:3]
	v_cndmask_b32_e64 v108, 0, v107, s[2:3]
	v_and_b32_sdwa v34, v111, v104 dst_sel:DWORD dst_unused:UNUSED_PAD src0_sel:WORD_1 src1_sel:DWORD
	v_and_b32_sdwa v35, v110, v104 dst_sel:DWORD dst_unused:UNUSED_PAD src0_sel:WORD_1 src1_sel:DWORD
	v_and_b32_sdwa v105, v36, v104 dst_sel:DWORD dst_unused:UNUSED_PAD src0_sel:WORD_1 src1_sel:DWORD
	v_and_b32_sdwa v106, v113, v104 dst_sel:DWORD dst_unused:UNUSED_PAD src0_sel:WORD_1 src1_sel:DWORD
	v_and_b32_sdwa v107, v112, v104 dst_sel:DWORD dst_unused:UNUSED_PAD src0_sel:WORD_1 src1_sel:DWORD
	v_and_b32_sdwa v114, v109, v104 dst_sel:DWORD dst_unused:UNUSED_PAD src0_sel:WORD_1 src1_sel:DWORD
	v_and_b32_sdwa v115, v108, v104 dst_sel:DWORD dst_unused:UNUSED_PAD src0_sel:WORD_1 src1_sel:DWORD
	v_add3_u32 v120, v111, v34, s69
	v_add3_u32 v34, v110, v35, s69
	v_add3_u32 v35, v37, v63, s69
	v_add3_u32 v63, v36, v105, s69
	v_add3_u32 v105, v113, v106, s69
	v_add3_u32 v121, v112, v107, s69
	v_add3_u32 v116, v109, v114, s69
	v_add3_u32 v118, v108, v115, s69
	v_and_b32_e32 v107, 0xffff0000, v35
	v_and_b32_e32 v106, 0xffff0000, v63
	v_and_b32_e32 v115, 0xffff0000, v120
	v_and_b32_e32 v114, 0xffff0000, v34
	v_and_b32_e32 v117, 0xffff0000, v116
	v_and_b32_e32 v116, 0xffff0000, v118
	v_and_b32_e32 v119, 0xffff0000, v105
	v_and_b32_e32 v118, 0xffff0000, v121
	v_or_b32_sdwa v34, v106, v34 dst_sel:DWORD dst_unused:UNUSED_PAD src0_sel:DWORD src1_sel:WORD_1
	v_pk_add_f32 v[110:111], v[110:111], v[114:115] neg_lo:[0,1] neg_hi:[0,1]
	v_pk_add_f32 v[114:115], v[36:37], v[106:107] neg_lo:[0,1] neg_hi:[0,1]
	v_or_b32_sdwa v35, v107, v120 dst_sel:DWORD dst_unused:UNUSED_PAD src0_sel:DWORD src1_sel:WORD_1
	v_pk_add_f32 v[106:107], v[112:113], v[118:119] neg_lo:[0,1] neg_hi:[0,1]
	v_pk_add_f32 v[108:109], v[108:109], v[116:117] neg_lo:[0,1] neg_hi:[0,1]
	v_or_b32_sdwa v37, v117, v105 dst_sel:DWORD dst_unused:UNUSED_PAD src0_sel:DWORD src1_sel:WORD_1
	v_bfe_u32 v105, v108, 16, 1
	v_bfe_u32 v117, v111, 16, 1
	v_bfe_u32 v118, v106, 16, 1
	v_bfe_u32 v119, v107, 16, 1
	v_or_b32_sdwa v36, v116, v121 dst_sel:DWORD dst_unused:UNUSED_PAD src0_sel:DWORD src1_sel:WORD_1
	v_bfe_u32 v63, v109, 16, 1
	v_bfe_u32 v116, v110, 16, 1
	v_add3_u32 v105, v108, v105, s69
	v_add3_u32 v107, v107, v119, s69
	v_add3_u32 v106, v106, v118, s69
	v_add3_u32 v108, v111, v117, s69
	v_bfe_u32 v112, v115, 16, 1
	v_bfe_u32 v113, v114, 16, 1
	v_add3_u32 v63, v109, v63, s69
	v_add3_u32 v109, v110, v116, s69
	v_lshrrev_b32_e32 v127, 16, v108
	v_lshrrev_b32_e32 v108, 16, v106
	v_lshrrev_b32_e32 v106, 16, v107
	v_add3_u32 v124, v114, v113, s69
	v_add3_u32 v125, v115, v112, s69
	v_lshrrev_b32_e32 v126, 16, v109
	v_and_or_b32 v109, v63, s70, v106
	v_and_or_b32 v108, v105, s70, v108
	v_add_u32_e32 v40, 64, v40
	v_and_b32_sdwa v63, v70, v104 dst_sel:DWORD dst_unused:UNUSED_PAD src0_sel:WORD_1 src1_sel:DWORD
	v_and_b32_sdwa v106, v66, v104 dst_sel:DWORD dst_unused:UNUSED_PAD src0_sel:WORD_1 src1_sel:DWORD
	v_and_b32_sdwa v107, v71, v104 dst_sel:DWORD dst_unused:UNUSED_PAD src0_sel:WORD_1 src1_sel:DWORD
	v_and_b32_sdwa v110, v69, v104 dst_sel:DWORD dst_unused:UNUSED_PAD src0_sel:WORD_1 src1_sel:DWORD
	v_and_b32_sdwa v111, v68, v104 dst_sel:DWORD dst_unused:UNUSED_PAD src0_sel:WORD_1 src1_sel:DWORD
	v_and_b32_sdwa v112, v73, v104 dst_sel:DWORD dst_unused:UNUSED_PAD src0_sel:WORD_1 src1_sel:DWORD
	v_and_b32_sdwa v113, v72, v104 dst_sel:DWORD dst_unused:UNUSED_PAD src0_sel:WORD_1 src1_sel:DWORD
	v_and_b32_sdwa v114, v77, v104 dst_sel:DWORD dst_unused:UNUSED_PAD src0_sel:WORD_1 src1_sel:DWORD
	v_and_b32_sdwa v115, v76, v104 dst_sel:DWORD dst_unused:UNUSED_PAD src0_sel:WORD_1 src1_sel:DWORD
	v_add3_u32 v63, v70, v63, s69
	v_and_b32_sdwa v116, v67, v104 dst_sel:DWORD dst_unused:UNUSED_PAD src0_sel:WORD_1 src1_sel:DWORD
	v_and_b32_sdwa v117, v75, v104 dst_sel:DWORD dst_unused:UNUSED_PAD src0_sel:WORD_1 src1_sel:DWORD
	v_add3_u32 v129, v71, v107, s69
	v_add3_u32 v107, v69, v110, s69
	v_add3_u32 v111, v68, v111, s69
	v_add3_u32 v130, v73, v112, s69
	v_add3_u32 v131, v72, v113, s69
	v_add3_u32 v123, v77, v114, s69
	v_add3_u32 v132, v76, v115, s69
	v_add3_u32 v128, v66, v106, s69
	v_and_b32_sdwa v118, v74, v104 dst_sel:DWORD dst_unused:UNUSED_PAD src0_sel:WORD_1 src1_sel:DWORD
	v_and_b32_sdwa v121, v79, v104 dst_sel:DWORD dst_unused:UNUSED_PAD src0_sel:WORD_1 src1_sel:DWORD
	v_and_b32_sdwa v122, v78, v104 dst_sel:DWORD dst_unused:UNUSED_PAD src0_sel:WORD_1 src1_sel:DWORD
	v_and_b32_e32 v106, 0xffff0000, v63
	v_add3_u32 v133, v67, v116, s69
	v_add3_u32 v134, v75, v117, s69
	v_and_b32_e32 v113, 0xffff0000, v107
	v_and_b32_e32 v112, 0xffff0000, v111
	v_and_b32_e32 v107, 0xffff0000, v129
	v_and_b32_e32 v115, 0xffff0000, v130
	v_and_b32_e32 v114, 0xffff0000, v131
	v_and_b32_e32 v117, 0xffff0000, v123
	v_and_b32_e32 v116, 0xffff0000, v132
	v_and_b32_sdwa v119, v81, v104 dst_sel:DWORD dst_unused:UNUSED_PAD src0_sel:WORD_1 src1_sel:DWORD
	v_and_b32_sdwa v120, v80, v104 dst_sel:DWORD dst_unused:UNUSED_PAD src0_sel:WORD_1 src1_sel:DWORD
	v_add3_u32 v118, v74, v118, s69
	v_add3_u32 v137, v79, v121, s69
	v_add3_u32 v122, v78, v122, s69
	v_pk_add_f32 v[106:107], v[70:71], v[106:107] neg_lo:[0,1] neg_hi:[0,1]
	v_or_b32_sdwa v70, v112, v63 dst_sel:DWORD dst_unused:UNUSED_PAD src0_sel:DWORD src1_sel:WORD_1
	v_or_b32_sdwa v71, v113, v129 dst_sel:DWORD dst_unused:UNUSED_PAD src0_sel:DWORD src1_sel:WORD_1
	v_pk_add_f32 v[114:115], v[72:73], v[114:115] neg_lo:[0,1] neg_hi:[0,1]
	v_or_b32_sdwa v72, v116, v131 dst_sel:DWORD dst_unused:UNUSED_PAD src0_sel:DWORD src1_sel:WORD_1
	v_or_b32_sdwa v73, v117, v130 dst_sel:DWORD dst_unused:UNUSED_PAD src0_sel:DWORD src1_sel:WORD_1
	v_and_b32_e32 v110, 0xffff0000, v128
	v_add3_u32 v135, v81, v119, s69
	v_add3_u32 v136, v80, v120, s69
	v_and_b32_e32 v119, 0xffff0000, v134
	v_and_b32_e32 v118, 0xffff0000, v118
	v_and_b32_e32 v111, 0xffff0000, v133
	v_and_b32_e32 v123, 0xffff0000, v137
	v_and_b32_e32 v122, 0xffff0000, v122
	v_mfma_f32_32x32x16_bf16 v[2:17], v[34:37], v[70:73], v[2:17]
	v_add_f32_e64 v112, v68, -v112
	v_add_f32_e64 v113, v69, -v113
	v_add_f32_e64 v110, v66, -v110
	v_add_f32_e64 v111, v67, -v111
	v_or_b32_sdwa v66, v118, v128 dst_sel:DWORD dst_unused:UNUSED_PAD src0_sel:DWORD src1_sel:WORD_1
	v_or_b32_sdwa v67, v119, v133 dst_sel:DWORD dst_unused:UNUSED_PAD src0_sel:DWORD src1_sel:WORD_1
	v_or_b32_sdwa v68, v122, v136 dst_sel:DWORD dst_unused:UNUSED_PAD src0_sel:DWORD src1_sel:WORD_1
	v_or_b32_sdwa v69, v123, v135 dst_sel:DWORD dst_unused:UNUSED_PAD src0_sel:DWORD src1_sel:WORD_1
	v_and_b32_e32 v121, 0xffff0000, v135
	v_and_b32_e32 v120, 0xffff0000, v136
	v_mfma_f32_32x32x16_bf16 v[18:33], v[34:37], v[66:69], v[18:33]
	v_add_f32_e64 v76, v76, -v116
	v_add_f32_e64 v77, v77, -v117
	v_add_f32_e64 v74, v74, -v118
	v_add_f32_e64 v75, v75, -v119
	v_add_f32_e64 v80, v80, -v120
	v_add_f32_e64 v81, v81, -v121
	v_pk_add_f32 v[78:79], v[78:79], v[122:123] neg_lo:[0,1] neg_hi:[0,1]
	v_bfe_u32 v63, v113, 16, 1
	v_bfe_u32 v119, v114, 16, 1
	v_bfe_u32 v120, v115, 16, 1
	v_bfe_u32 v121, v106, 16, 1
	v_bfe_u32 v122, v107, 16, 1
	v_bfe_u32 v116, v112, 16, 1
	v_bfe_u32 v117, v77, 16, 1
	v_bfe_u32 v118, v76, 16, 1
	v_bfe_u32 v123, v75, 16, 1
	v_bfe_u32 v128, v74, 16, 1
	v_bfe_u32 v131, v80, 16, 1
	v_bfe_u32 v134, v111, 16, 1
	v_add3_u32 v63, v113, v63, s69
	v_add3_u32 v113, v115, v120, s69
	v_add3_u32 v114, v114, v119, s69
	v_add3_u32 v107, v107, v122, s69
	v_add3_u32 v106, v106, v121, s69
	v_bfe_u32 v132, v81, 16, 1
	v_bfe_u32 v133, v110, 16, 1
	v_add3_u32 v112, v112, v116, s69
	v_add3_u32 v76, v76, v118, s69
	v_add3_u32 v77, v77, v117, s69
	v_add3_u32 v115, v74, v128, s69
	v_add3_u32 v116, v75, v123, s69
	v_add3_u32 v74, v80, v131, s69
	v_add3_u32 v80, v111, v134, s69
	v_lshrrev_b32_e32 v75, 16, v114
	v_lshrrev_b32_e32 v111, 16, v113
	v_lshrrev_b32_e32 v106, 16, v106
	v_lshrrev_b32_e32 v107, 16, v107
	v_bfe_u32 v129, v79, 16, 1
	v_bfe_u32 v130, v78, 16, 1
	v_add3_u32 v81, v81, v132, s69
	v_add3_u32 v110, v110, v133, s69
	v_lshrrev_b32_e32 v113, 16, v74
	v_and_or_b32 v77, v77, s70, v111
	v_and_or_b32 v76, v76, s70, v75
	v_and_or_b32 v75, v63, s70, v107
	v_and_or_b32 v74, v112, s70, v106
	v_add3_u32 v78, v78, v130, s69
	v_add3_u32 v79, v79, v129, s69
	v_mfma_f32_32x32x16_bf16 v[2:17], v[34:37], v[74:77], v[2:17]
	v_lshrrev_b32_e32 v63, 16, v81
	v_lshrrev_b32_e32 v74, 16, v110
	v_lshrrev_b32_e32 v75, 16, v80
	v_and_or_b32 v77, v79, s70, v63
	v_and_or_b32 v76, v78, s70, v113
	v_and_or_b32 v75, v116, s70, v75
	v_and_or_b32 v74, v115, s70, v74
	v_and_or_b32 v107, v125, s70, v127
	v_and_or_b32 v106, v124, s70, v126
	v_mfma_f32_32x32x16_bf16 v[18:33], v[34:37], v[74:77], v[18:33]
	s_nop 0
	v_mfma_f32_32x32x16_bf16 v[2:17], v[106:109], v[70:73], v[2:17]
	v_mfma_f32_32x32x16_bf16 v[18:33], v[106:109], v[66:69], v[18:33]
	ds_read_b128 v[34:37], v40
	ds_read_b128 v[106:109], v40 offset:16
	s_waitcnt lgkmcnt(1)
	v_cndmask_b32_e64 v37, 0, v37, s[2:3]
	s_waitcnt lgkmcnt(0)
	v_cndmask_b32_e64 v109, 0, v109, s[2:3]
	v_and_b32_sdwa v63, v37, v104 dst_sel:DWORD dst_unused:UNUSED_PAD src0_sel:WORD_1 src1_sel:DWORD
	s_nop 0
	s_nop 0
	s_nop 0
	s_nop 0
	v_mov_b32_e32 v70, v218
	s_nop 0
	v_mov_b32_e32 v66, v219
	s_nop 0
	v_mov_b32_e32 v71, v220
	v_mov_b32_e32 v69, v221
	v_mov_b32_e32 v68, v222
	v_mov_b32_e32 v73, v223
	v_mov_b32_e32 v72, v224
	v_mov_b32_e32 v77, v225
	v_mov_b32_e32 v76, v226
	s_nop 0
	v_mov_b32_e32 v75, v227
	s_nop 0
	v_mov_b32_e32 v67, v228
	v_mov_b32_e32 v74, v229
	s_nop 0
	v_mov_b32_e32 v79, v230
	v_mov_b32_e32 v81, v231
	v_mov_b32_e32 v78, v232
	v_mov_b32_e32 v80, v233
	v_cndmask_b32_e64 v111, 0, v36, s[2:3]
	v_cndmask_b32_e64 v110, 0, v34, s[2:3]
	v_cndmask_b32_e64 v36, 0, v35, s[2:3]
	v_cndmask_b32_e64 v113, 0, v108, s[2:3]
	v_cndmask_b32_e64 v112, 0, v106, s[2:3]
	v_cndmask_b32_e64 v108, 0, v107, s[2:3]
	v_and_b32_sdwa v34, v111, v104 dst_sel:DWORD dst_unused:UNUSED_PAD src0_sel:WORD_1 src1_sel:DWORD
	v_and_b32_sdwa v35, v110, v104 dst_sel:DWORD dst_unused:UNUSED_PAD src0_sel:WORD_1 src1_sel:DWORD
	v_and_b32_sdwa v105, v36, v104 dst_sel:DWORD dst_unused:UNUSED_PAD src0_sel:WORD_1 src1_sel:DWORD
	v_and_b32_sdwa v106, v113, v104 dst_sel:DWORD dst_unused:UNUSED_PAD src0_sel:WORD_1 src1_sel:DWORD
	v_and_b32_sdwa v107, v112, v104 dst_sel:DWORD dst_unused:UNUSED_PAD src0_sel:WORD_1 src1_sel:DWORD
	v_and_b32_sdwa v114, v109, v104 dst_sel:DWORD dst_unused:UNUSED_PAD src0_sel:WORD_1 src1_sel:DWORD
	v_and_b32_sdwa v115, v108, v104 dst_sel:DWORD dst_unused:UNUSED_PAD src0_sel:WORD_1 src1_sel:DWORD
	v_add3_u32 v120, v111, v34, s69
	v_add3_u32 v34, v110, v35, s69
	v_add3_u32 v35, v37, v63, s69
	v_add3_u32 v63, v36, v105, s69
	v_add3_u32 v105, v113, v106, s69
	v_add3_u32 v121, v112, v107, s69
	v_add3_u32 v116, v109, v114, s69
	v_add3_u32 v118, v108, v115, s69
	v_and_b32_e32 v107, 0xffff0000, v35
	v_and_b32_e32 v106, 0xffff0000, v63
	v_and_b32_e32 v115, 0xffff0000, v120
	v_and_b32_e32 v114, 0xffff0000, v34
	v_and_b32_e32 v117, 0xffff0000, v116
	v_and_b32_e32 v116, 0xffff0000, v118
	v_and_b32_e32 v119, 0xffff0000, v105
	v_and_b32_e32 v118, 0xffff0000, v121
	v_or_b32_sdwa v34, v106, v34 dst_sel:DWORD dst_unused:UNUSED_PAD src0_sel:DWORD src1_sel:WORD_1
	v_pk_add_f32 v[110:111], v[110:111], v[114:115] neg_lo:[0,1] neg_hi:[0,1]
	v_pk_add_f32 v[114:115], v[36:37], v[106:107] neg_lo:[0,1] neg_hi:[0,1]
	v_or_b32_sdwa v35, v107, v120 dst_sel:DWORD dst_unused:UNUSED_PAD src0_sel:DWORD src1_sel:WORD_1
	v_pk_add_f32 v[106:107], v[112:113], v[118:119] neg_lo:[0,1] neg_hi:[0,1]
	v_pk_add_f32 v[108:109], v[108:109], v[116:117] neg_lo:[0,1] neg_hi:[0,1]
	v_or_b32_sdwa v37, v117, v105 dst_sel:DWORD dst_unused:UNUSED_PAD src0_sel:DWORD src1_sel:WORD_1
	v_bfe_u32 v105, v108, 16, 1
	v_bfe_u32 v117, v111, 16, 1
	v_bfe_u32 v118, v106, 16, 1
	v_bfe_u32 v119, v107, 16, 1
	v_or_b32_sdwa v36, v116, v121 dst_sel:DWORD dst_unused:UNUSED_PAD src0_sel:DWORD src1_sel:WORD_1
	v_bfe_u32 v63, v109, 16, 1
	v_bfe_u32 v116, v110, 16, 1
	v_add3_u32 v105, v108, v105, s69
	v_add3_u32 v107, v107, v119, s69
	v_add3_u32 v106, v106, v118, s69
	v_add3_u32 v108, v111, v117, s69
	v_bfe_u32 v112, v115, 16, 1
	v_bfe_u32 v113, v114, 16, 1
	v_add3_u32 v63, v109, v63, s69
	v_add3_u32 v109, v110, v116, s69
	v_lshrrev_b32_e32 v127, 16, v108
	v_lshrrev_b32_e32 v108, 16, v106
	v_lshrrev_b32_e32 v106, 16, v107
	v_add3_u32 v124, v114, v113, s69
	v_add3_u32 v125, v115, v112, s69
	v_lshrrev_b32_e32 v126, 16, v109
	v_and_or_b32 v109, v63, s70, v106
	v_and_or_b32 v108, v105, s70, v108
	v_add_u32_e32 v40, 64, v40
	v_and_b32_sdwa v63, v70, v104 dst_sel:DWORD dst_unused:UNUSED_PAD src0_sel:WORD_1 src1_sel:DWORD
	v_and_b32_sdwa v106, v66, v104 dst_sel:DWORD dst_unused:UNUSED_PAD src0_sel:WORD_1 src1_sel:DWORD
	v_and_b32_sdwa v107, v71, v104 dst_sel:DWORD dst_unused:UNUSED_PAD src0_sel:WORD_1 src1_sel:DWORD
	v_and_b32_sdwa v110, v69, v104 dst_sel:DWORD dst_unused:UNUSED_PAD src0_sel:WORD_1 src1_sel:DWORD
	v_and_b32_sdwa v111, v68, v104 dst_sel:DWORD dst_unused:UNUSED_PAD src0_sel:WORD_1 src1_sel:DWORD
	v_and_b32_sdwa v112, v73, v104 dst_sel:DWORD dst_unused:UNUSED_PAD src0_sel:WORD_1 src1_sel:DWORD
	v_and_b32_sdwa v113, v72, v104 dst_sel:DWORD dst_unused:UNUSED_PAD src0_sel:WORD_1 src1_sel:DWORD
	v_and_b32_sdwa v114, v77, v104 dst_sel:DWORD dst_unused:UNUSED_PAD src0_sel:WORD_1 src1_sel:DWORD
	v_and_b32_sdwa v115, v76, v104 dst_sel:DWORD dst_unused:UNUSED_PAD src0_sel:WORD_1 src1_sel:DWORD
	v_add3_u32 v63, v70, v63, s69
	v_and_b32_sdwa v116, v67, v104 dst_sel:DWORD dst_unused:UNUSED_PAD src0_sel:WORD_1 src1_sel:DWORD
	v_and_b32_sdwa v117, v75, v104 dst_sel:DWORD dst_unused:UNUSED_PAD src0_sel:WORD_1 src1_sel:DWORD
	v_add3_u32 v129, v71, v107, s69
	v_add3_u32 v107, v69, v110, s69
	v_add3_u32 v111, v68, v111, s69
	v_add3_u32 v130, v73, v112, s69
	v_add3_u32 v131, v72, v113, s69
	v_add3_u32 v123, v77, v114, s69
	v_add3_u32 v132, v76, v115, s69
	v_add3_u32 v128, v66, v106, s69
	v_and_b32_sdwa v118, v74, v104 dst_sel:DWORD dst_unused:UNUSED_PAD src0_sel:WORD_1 src1_sel:DWORD
	v_and_b32_sdwa v121, v79, v104 dst_sel:DWORD dst_unused:UNUSED_PAD src0_sel:WORD_1 src1_sel:DWORD
	v_and_b32_sdwa v122, v78, v104 dst_sel:DWORD dst_unused:UNUSED_PAD src0_sel:WORD_1 src1_sel:DWORD
	v_and_b32_e32 v106, 0xffff0000, v63
	v_add3_u32 v133, v67, v116, s69
	v_add3_u32 v134, v75, v117, s69
	v_and_b32_e32 v113, 0xffff0000, v107
	v_and_b32_e32 v112, 0xffff0000, v111
	v_and_b32_e32 v107, 0xffff0000, v129
	v_and_b32_e32 v115, 0xffff0000, v130
	v_and_b32_e32 v114, 0xffff0000, v131
	v_and_b32_e32 v117, 0xffff0000, v123
	v_and_b32_e32 v116, 0xffff0000, v132
	v_and_b32_sdwa v119, v81, v104 dst_sel:DWORD dst_unused:UNUSED_PAD src0_sel:WORD_1 src1_sel:DWORD
	v_and_b32_sdwa v120, v80, v104 dst_sel:DWORD dst_unused:UNUSED_PAD src0_sel:WORD_1 src1_sel:DWORD
	v_add3_u32 v118, v74, v118, s69
	v_add3_u32 v137, v79, v121, s69
	v_add3_u32 v122, v78, v122, s69
	v_pk_add_f32 v[106:107], v[70:71], v[106:107] neg_lo:[0,1] neg_hi:[0,1]
	v_or_b32_sdwa v70, v112, v63 dst_sel:DWORD dst_unused:UNUSED_PAD src0_sel:DWORD src1_sel:WORD_1
	v_or_b32_sdwa v71, v113, v129 dst_sel:DWORD dst_unused:UNUSED_PAD src0_sel:DWORD src1_sel:WORD_1
	v_pk_add_f32 v[114:115], v[72:73], v[114:115] neg_lo:[0,1] neg_hi:[0,1]
	v_or_b32_sdwa v72, v116, v131 dst_sel:DWORD dst_unused:UNUSED_PAD src0_sel:DWORD src1_sel:WORD_1
	v_or_b32_sdwa v73, v117, v130 dst_sel:DWORD dst_unused:UNUSED_PAD src0_sel:DWORD src1_sel:WORD_1
	v_and_b32_e32 v110, 0xffff0000, v128
	v_add3_u32 v135, v81, v119, s69
	v_add3_u32 v136, v80, v120, s69
	v_and_b32_e32 v119, 0xffff0000, v134
	v_and_b32_e32 v118, 0xffff0000, v118
	v_and_b32_e32 v111, 0xffff0000, v133
	v_and_b32_e32 v123, 0xffff0000, v137
	v_and_b32_e32 v122, 0xffff0000, v122
	v_mfma_f32_32x32x16_bf16 v[2:17], v[34:37], v[70:73], v[2:17]
	v_add_f32_e64 v112, v68, -v112
	v_add_f32_e64 v113, v69, -v113
	v_add_f32_e64 v110, v66, -v110
	v_add_f32_e64 v111, v67, -v111
	v_or_b32_sdwa v66, v118, v128 dst_sel:DWORD dst_unused:UNUSED_PAD src0_sel:DWORD src1_sel:WORD_1
	v_or_b32_sdwa v67, v119, v133 dst_sel:DWORD dst_unused:UNUSED_PAD src0_sel:DWORD src1_sel:WORD_1
	v_or_b32_sdwa v68, v122, v136 dst_sel:DWORD dst_unused:UNUSED_PAD src0_sel:DWORD src1_sel:WORD_1
	v_or_b32_sdwa v69, v123, v135 dst_sel:DWORD dst_unused:UNUSED_PAD src0_sel:DWORD src1_sel:WORD_1
	v_and_b32_e32 v121, 0xffff0000, v135
	v_and_b32_e32 v120, 0xffff0000, v136
	v_mfma_f32_32x32x16_bf16 v[18:33], v[34:37], v[66:69], v[18:33]
	v_add_f32_e64 v76, v76, -v116
	v_add_f32_e64 v77, v77, -v117
	v_add_f32_e64 v74, v74, -v118
	v_add_f32_e64 v75, v75, -v119
	v_add_f32_e64 v80, v80, -v120
	v_add_f32_e64 v81, v81, -v121
	v_pk_add_f32 v[78:79], v[78:79], v[122:123] neg_lo:[0,1] neg_hi:[0,1]
	v_bfe_u32 v63, v113, 16, 1
	v_bfe_u32 v119, v114, 16, 1
	v_bfe_u32 v120, v115, 16, 1
	v_bfe_u32 v121, v106, 16, 1
	v_bfe_u32 v122, v107, 16, 1
	v_bfe_u32 v116, v112, 16, 1
	v_bfe_u32 v117, v77, 16, 1
	v_bfe_u32 v118, v76, 16, 1
	v_bfe_u32 v123, v75, 16, 1
	v_bfe_u32 v128, v74, 16, 1
	v_bfe_u32 v131, v80, 16, 1
	v_bfe_u32 v134, v111, 16, 1
	v_add3_u32 v63, v113, v63, s69
	v_add3_u32 v113, v115, v120, s69
	v_add3_u32 v114, v114, v119, s69
	v_add3_u32 v107, v107, v122, s69
	v_add3_u32 v106, v106, v121, s69
	v_bfe_u32 v132, v81, 16, 1
	v_bfe_u32 v133, v110, 16, 1
	v_add3_u32 v112, v112, v116, s69
	v_add3_u32 v76, v76, v118, s69
	v_add3_u32 v77, v77, v117, s69
	v_add3_u32 v115, v74, v128, s69
	v_add3_u32 v116, v75, v123, s69
	v_add3_u32 v74, v80, v131, s69
	v_add3_u32 v80, v111, v134, s69
	v_lshrrev_b32_e32 v75, 16, v114
	v_lshrrev_b32_e32 v111, 16, v113
	v_lshrrev_b32_e32 v106, 16, v106
	v_lshrrev_b32_e32 v107, 16, v107
	v_bfe_u32 v129, v79, 16, 1
	v_bfe_u32 v130, v78, 16, 1
	v_add3_u32 v81, v81, v132, s69
	v_add3_u32 v110, v110, v133, s69
	v_lshrrev_b32_e32 v113, 16, v74
	v_and_or_b32 v77, v77, s70, v111
	v_and_or_b32 v76, v76, s70, v75
	v_and_or_b32 v75, v63, s70, v107
	v_and_or_b32 v74, v112, s70, v106
	v_add3_u32 v78, v78, v130, s69
	v_add3_u32 v79, v79, v129, s69
	v_mfma_f32_32x32x16_bf16 v[2:17], v[34:37], v[74:77], v[2:17]
	v_lshrrev_b32_e32 v63, 16, v81
	v_lshrrev_b32_e32 v74, 16, v110
	v_lshrrev_b32_e32 v75, 16, v80
	v_and_or_b32 v77, v79, s70, v63
	v_and_or_b32 v76, v78, s70, v113
	v_and_or_b32 v75, v116, s70, v75
	v_and_or_b32 v74, v115, s70, v74
	v_and_or_b32 v107, v125, s70, v127
	v_and_or_b32 v106, v124, s70, v126
	v_mfma_f32_32x32x16_bf16 v[18:33], v[34:37], v[74:77], v[18:33]
	s_nop 0
	v_mfma_f32_32x32x16_bf16 v[2:17], v[106:109], v[70:73], v[2:17]
	v_mfma_f32_32x32x16_bf16 v[18:33], v[106:109], v[66:69], v[18:33]
	ds_read_b128 v[34:37], v40
	ds_read_b128 v[106:109], v40 offset:16
	s_waitcnt lgkmcnt(1)
	v_cndmask_b32_e64 v37, 0, v37, s[2:3]
	s_waitcnt lgkmcnt(0)
	v_cndmask_b32_e64 v109, 0, v109, s[2:3]
	v_and_b32_sdwa v63, v37, v104 dst_sel:DWORD dst_unused:UNUSED_PAD src0_sel:WORD_1 src1_sel:DWORD
	s_nop 0
	s_nop 0
	s_nop 0
	s_nop 0
	v_mov_b32_e32 v70, v234
	s_nop 0
	v_mov_b32_e32 v66, v235
	s_nop 0
	v_mov_b32_e32 v71, v236
	v_mov_b32_e32 v69, v237
	v_mov_b32_e32 v68, v238
	v_mov_b32_e32 v73, v239
	v_mov_b32_e32 v72, v240
	v_mov_b32_e32 v77, v241
	v_mov_b32_e32 v76, v242
	s_nop 0
	v_mov_b32_e32 v75, v243
	s_nop 0
	v_mov_b32_e32 v67, v244
	v_mov_b32_e32 v74, v245
	s_nop 0
	v_mov_b32_e32 v79, v246
	v_mov_b32_e32 v81, v247
	v_mov_b32_e32 v78, v248
	v_mov_b32_e32 v80, v249
	v_cndmask_b32_e64 v111, 0, v36, s[2:3]
	v_cndmask_b32_e64 v110, 0, v34, s[2:3]
	v_cndmask_b32_e64 v36, 0, v35, s[2:3]
	v_cndmask_b32_e64 v113, 0, v108, s[2:3]
	v_cndmask_b32_e64 v112, 0, v106, s[2:3]
	v_cndmask_b32_e64 v108, 0, v107, s[2:3]
	v_and_b32_sdwa v34, v111, v104 dst_sel:DWORD dst_unused:UNUSED_PAD src0_sel:WORD_1 src1_sel:DWORD
	v_and_b32_sdwa v35, v110, v104 dst_sel:DWORD dst_unused:UNUSED_PAD src0_sel:WORD_1 src1_sel:DWORD
	v_and_b32_sdwa v105, v36, v104 dst_sel:DWORD dst_unused:UNUSED_PAD src0_sel:WORD_1 src1_sel:DWORD
	v_and_b32_sdwa v106, v113, v104 dst_sel:DWORD dst_unused:UNUSED_PAD src0_sel:WORD_1 src1_sel:DWORD
	v_and_b32_sdwa v107, v112, v104 dst_sel:DWORD dst_unused:UNUSED_PAD src0_sel:WORD_1 src1_sel:DWORD
	v_and_b32_sdwa v114, v109, v104 dst_sel:DWORD dst_unused:UNUSED_PAD src0_sel:WORD_1 src1_sel:DWORD
	v_and_b32_sdwa v115, v108, v104 dst_sel:DWORD dst_unused:UNUSED_PAD src0_sel:WORD_1 src1_sel:DWORD
	v_add3_u32 v120, v111, v34, s69
	v_add3_u32 v34, v110, v35, s69
	v_add3_u32 v35, v37, v63, s69
	v_add3_u32 v63, v36, v105, s69
	v_add3_u32 v105, v113, v106, s69
	v_add3_u32 v121, v112, v107, s69
	v_add3_u32 v116, v109, v114, s69
	v_add3_u32 v118, v108, v115, s69
	v_and_b32_e32 v107, 0xffff0000, v35
	v_and_b32_e32 v106, 0xffff0000, v63
	v_and_b32_e32 v115, 0xffff0000, v120
	v_and_b32_e32 v114, 0xffff0000, v34
	v_and_b32_e32 v117, 0xffff0000, v116
	v_and_b32_e32 v116, 0xffff0000, v118
	v_and_b32_e32 v119, 0xffff0000, v105
	v_and_b32_e32 v118, 0xffff0000, v121
	v_or_b32_sdwa v34, v106, v34 dst_sel:DWORD dst_unused:UNUSED_PAD src0_sel:DWORD src1_sel:WORD_1
	v_pk_add_f32 v[110:111], v[110:111], v[114:115] neg_lo:[0,1] neg_hi:[0,1]
	v_pk_add_f32 v[114:115], v[36:37], v[106:107] neg_lo:[0,1] neg_hi:[0,1]
	v_or_b32_sdwa v35, v107, v120 dst_sel:DWORD dst_unused:UNUSED_PAD src0_sel:DWORD src1_sel:WORD_1
	v_pk_add_f32 v[106:107], v[112:113], v[118:119] neg_lo:[0,1] neg_hi:[0,1]
	v_pk_add_f32 v[108:109], v[108:109], v[116:117] neg_lo:[0,1] neg_hi:[0,1]
	v_or_b32_sdwa v37, v117, v105 dst_sel:DWORD dst_unused:UNUSED_PAD src0_sel:DWORD src1_sel:WORD_1
	v_bfe_u32 v105, v108, 16, 1
	v_bfe_u32 v117, v111, 16, 1
	v_bfe_u32 v118, v106, 16, 1
	v_bfe_u32 v119, v107, 16, 1
	v_or_b32_sdwa v36, v116, v121 dst_sel:DWORD dst_unused:UNUSED_PAD src0_sel:DWORD src1_sel:WORD_1
	v_bfe_u32 v63, v109, 16, 1
	v_bfe_u32 v116, v110, 16, 1
	v_add3_u32 v105, v108, v105, s69
	v_add3_u32 v107, v107, v119, s69
	v_add3_u32 v106, v106, v118, s69
	v_add3_u32 v108, v111, v117, s69
	v_bfe_u32 v112, v115, 16, 1
	v_bfe_u32 v113, v114, 16, 1
	v_add3_u32 v63, v109, v63, s69
	v_add3_u32 v109, v110, v116, s69
	v_lshrrev_b32_e32 v127, 16, v108
	v_lshrrev_b32_e32 v108, 16, v106
	v_lshrrev_b32_e32 v106, 16, v107
	v_add3_u32 v124, v114, v113, s69
	v_add3_u32 v125, v115, v112, s69
	v_lshrrev_b32_e32 v126, 16, v109
	v_and_or_b32 v109, v63, s70, v106
	v_and_or_b32 v108, v105, s70, v108
	v_add_u32_e32 v40, 64, v40
	v_and_b32_sdwa v63, v70, v104 dst_sel:DWORD dst_unused:UNUSED_PAD src0_sel:WORD_1 src1_sel:DWORD
	v_and_b32_sdwa v106, v66, v104 dst_sel:DWORD dst_unused:UNUSED_PAD src0_sel:WORD_1 src1_sel:DWORD
	v_and_b32_sdwa v107, v71, v104 dst_sel:DWORD dst_unused:UNUSED_PAD src0_sel:WORD_1 src1_sel:DWORD
	v_and_b32_sdwa v110, v69, v104 dst_sel:DWORD dst_unused:UNUSED_PAD src0_sel:WORD_1 src1_sel:DWORD
	v_and_b32_sdwa v111, v68, v104 dst_sel:DWORD dst_unused:UNUSED_PAD src0_sel:WORD_1 src1_sel:DWORD
	v_and_b32_sdwa v112, v73, v104 dst_sel:DWORD dst_unused:UNUSED_PAD src0_sel:WORD_1 src1_sel:DWORD
	v_and_b32_sdwa v113, v72, v104 dst_sel:DWORD dst_unused:UNUSED_PAD src0_sel:WORD_1 src1_sel:DWORD
	v_and_b32_sdwa v114, v77, v104 dst_sel:DWORD dst_unused:UNUSED_PAD src0_sel:WORD_1 src1_sel:DWORD
	v_and_b32_sdwa v115, v76, v104 dst_sel:DWORD dst_unused:UNUSED_PAD src0_sel:WORD_1 src1_sel:DWORD
	v_add3_u32 v63, v70, v63, s69
	v_and_b32_sdwa v116, v67, v104 dst_sel:DWORD dst_unused:UNUSED_PAD src0_sel:WORD_1 src1_sel:DWORD
	v_and_b32_sdwa v117, v75, v104 dst_sel:DWORD dst_unused:UNUSED_PAD src0_sel:WORD_1 src1_sel:DWORD
	v_add3_u32 v129, v71, v107, s69
	v_add3_u32 v107, v69, v110, s69
	v_add3_u32 v111, v68, v111, s69
	v_add3_u32 v130, v73, v112, s69
	v_add3_u32 v131, v72, v113, s69
	v_add3_u32 v123, v77, v114, s69
	v_add3_u32 v132, v76, v115, s69
	v_add3_u32 v128, v66, v106, s69
	v_and_b32_sdwa v118, v74, v104 dst_sel:DWORD dst_unused:UNUSED_PAD src0_sel:WORD_1 src1_sel:DWORD
	v_and_b32_sdwa v121, v79, v104 dst_sel:DWORD dst_unused:UNUSED_PAD src0_sel:WORD_1 src1_sel:DWORD
	v_and_b32_sdwa v122, v78, v104 dst_sel:DWORD dst_unused:UNUSED_PAD src0_sel:WORD_1 src1_sel:DWORD
	v_and_b32_e32 v106, 0xffff0000, v63
	v_add3_u32 v133, v67, v116, s69
	v_add3_u32 v134, v75, v117, s69
	v_and_b32_e32 v113, 0xffff0000, v107
	v_and_b32_e32 v112, 0xffff0000, v111
	v_and_b32_e32 v107, 0xffff0000, v129
	v_and_b32_e32 v115, 0xffff0000, v130
	v_and_b32_e32 v114, 0xffff0000, v131
	v_and_b32_e32 v117, 0xffff0000, v123
	v_and_b32_e32 v116, 0xffff0000, v132
	v_and_b32_sdwa v119, v81, v104 dst_sel:DWORD dst_unused:UNUSED_PAD src0_sel:WORD_1 src1_sel:DWORD
	v_and_b32_sdwa v120, v80, v104 dst_sel:DWORD dst_unused:UNUSED_PAD src0_sel:WORD_1 src1_sel:DWORD
	v_add3_u32 v118, v74, v118, s69
	v_add3_u32 v137, v79, v121, s69
	v_add3_u32 v122, v78, v122, s69
	v_pk_add_f32 v[106:107], v[70:71], v[106:107] neg_lo:[0,1] neg_hi:[0,1]
	v_or_b32_sdwa v70, v112, v63 dst_sel:DWORD dst_unused:UNUSED_PAD src0_sel:DWORD src1_sel:WORD_1
	v_or_b32_sdwa v71, v113, v129 dst_sel:DWORD dst_unused:UNUSED_PAD src0_sel:DWORD src1_sel:WORD_1
	v_pk_add_f32 v[114:115], v[72:73], v[114:115] neg_lo:[0,1] neg_hi:[0,1]
	v_or_b32_sdwa v72, v116, v131 dst_sel:DWORD dst_unused:UNUSED_PAD src0_sel:DWORD src1_sel:WORD_1
	v_or_b32_sdwa v73, v117, v130 dst_sel:DWORD dst_unused:UNUSED_PAD src0_sel:DWORD src1_sel:WORD_1
	v_and_b32_e32 v110, 0xffff0000, v128
	v_add3_u32 v135, v81, v119, s69
	v_add3_u32 v136, v80, v120, s69
	v_and_b32_e32 v119, 0xffff0000, v134
	v_and_b32_e32 v118, 0xffff0000, v118
	v_and_b32_e32 v111, 0xffff0000, v133
	v_and_b32_e32 v123, 0xffff0000, v137
	v_and_b32_e32 v122, 0xffff0000, v122
	v_mfma_f32_32x32x16_bf16 v[2:17], v[34:37], v[70:73], v[2:17]
	v_add_f32_e64 v112, v68, -v112
	v_add_f32_e64 v113, v69, -v113
	v_add_f32_e64 v110, v66, -v110
	v_add_f32_e64 v111, v67, -v111
	v_or_b32_sdwa v66, v118, v128 dst_sel:DWORD dst_unused:UNUSED_PAD src0_sel:DWORD src1_sel:WORD_1
	v_or_b32_sdwa v67, v119, v133 dst_sel:DWORD dst_unused:UNUSED_PAD src0_sel:DWORD src1_sel:WORD_1
	v_or_b32_sdwa v68, v122, v136 dst_sel:DWORD dst_unused:UNUSED_PAD src0_sel:DWORD src1_sel:WORD_1
	v_or_b32_sdwa v69, v123, v135 dst_sel:DWORD dst_unused:UNUSED_PAD src0_sel:DWORD src1_sel:WORD_1
	v_and_b32_e32 v121, 0xffff0000, v135
	v_and_b32_e32 v120, 0xffff0000, v136
	v_mfma_f32_32x32x16_bf16 v[18:33], v[34:37], v[66:69], v[18:33]
	v_add_f32_e64 v76, v76, -v116
	v_add_f32_e64 v77, v77, -v117
	v_add_f32_e64 v74, v74, -v118
	v_add_f32_e64 v75, v75, -v119
	v_add_f32_e64 v80, v80, -v120
	v_add_f32_e64 v81, v81, -v121
	v_pk_add_f32 v[78:79], v[78:79], v[122:123] neg_lo:[0,1] neg_hi:[0,1]
	v_bfe_u32 v63, v113, 16, 1
	v_bfe_u32 v119, v114, 16, 1
	v_bfe_u32 v120, v115, 16, 1
	v_bfe_u32 v121, v106, 16, 1
	v_bfe_u32 v122, v107, 16, 1
	v_bfe_u32 v116, v112, 16, 1
	v_bfe_u32 v117, v77, 16, 1
	v_bfe_u32 v118, v76, 16, 1
	v_bfe_u32 v123, v75, 16, 1
	v_bfe_u32 v128, v74, 16, 1
	v_bfe_u32 v131, v80, 16, 1
	v_bfe_u32 v134, v111, 16, 1
	v_add3_u32 v63, v113, v63, s69
	v_add3_u32 v113, v115, v120, s69
	v_add3_u32 v114, v114, v119, s69
	v_add3_u32 v107, v107, v122, s69
	v_add3_u32 v106, v106, v121, s69
	v_bfe_u32 v132, v81, 16, 1
	v_bfe_u32 v133, v110, 16, 1
	v_add3_u32 v112, v112, v116, s69
	v_add3_u32 v76, v76, v118, s69
	v_add3_u32 v77, v77, v117, s69
	v_add3_u32 v115, v74, v128, s69
	v_add3_u32 v116, v75, v123, s69
	v_add3_u32 v74, v80, v131, s69
	v_add3_u32 v80, v111, v134, s69
	v_lshrrev_b32_e32 v75, 16, v114
	v_lshrrev_b32_e32 v111, 16, v113
	v_lshrrev_b32_e32 v106, 16, v106
	v_lshrrev_b32_e32 v107, 16, v107
	v_bfe_u32 v129, v79, 16, 1
	v_bfe_u32 v130, v78, 16, 1
	v_add3_u32 v81, v81, v132, s69
	v_add3_u32 v110, v110, v133, s69
	v_lshrrev_b32_e32 v113, 16, v74
	v_and_or_b32 v77, v77, s70, v111
	v_and_or_b32 v76, v76, s70, v75
	v_and_or_b32 v75, v63, s70, v107
	v_and_or_b32 v74, v112, s70, v106
	v_add3_u32 v78, v78, v130, s69
	v_add3_u32 v79, v79, v129, s69
	v_mfma_f32_32x32x16_bf16 v[2:17], v[34:37], v[74:77], v[2:17]
	v_lshrrev_b32_e32 v63, 16, v81
	v_lshrrev_b32_e32 v74, 16, v110
	v_lshrrev_b32_e32 v75, 16, v80
	v_and_or_b32 v77, v79, s70, v63
	v_and_or_b32 v76, v78, s70, v113
	v_and_or_b32 v75, v116, s70, v75
	v_and_or_b32 v74, v115, s70, v74
	v_and_or_b32 v107, v125, s70, v127
	v_and_or_b32 v106, v124, s70, v126
	v_mfma_f32_32x32x16_bf16 v[18:33], v[34:37], v[74:77], v[18:33]
	s_nop 0
	v_mfma_f32_32x32x16_bf16 v[2:17], v[106:109], v[70:73], v[2:17]
	v_mfma_f32_32x32x16_bf16 v[18:33], v[106:109], v[66:69], v[18:33]
	s_mul_i32 s58, s61, 17
	s_nop 8
	v_add_u32_e32 v11, s58, v85
	v_lshl_add_u32 v11, v11, 8, v86
	ds_write2_b32 v11, v2, v18 offset1:32
	v_add_u32_e32 v2, s58, v87
	v_lshl_add_u32 v2, v2, 8, v86
	ds_write2_b32 v2, v3, v19 offset1:32
	v_add_u32_e32 v2, s58, v88
	v_lshl_add_u32 v2, v2, 8, v86
	ds_write2_b32 v2, v4, v20 offset1:32
	v_add_u32_e32 v2, s58, v89
	v_lshl_add_u32 v2, v2, 8, v86
	ds_write2_b32 v2, v5, v21 offset1:32
	v_add_u32_e32 v2, s58, v90
	v_lshl_add_u32 v2, v2, 8, v86
	ds_write2_b32 v2, v6, v22 offset1:32
	v_add_u32_e32 v2, s58, v91
	v_lshl_add_u32 v2, v2, 8, v86
	ds_write2_b32 v2, v7, v23 offset1:32
	v_add_u32_e32 v2, s58, v92
	v_lshl_add_u32 v2, v2, 8, v86
	ds_write2_b32 v2, v8, v24 offset1:32
	v_add_u32_e32 v2, s58, v93
	v_lshl_add_u32 v2, v2, 8, v86
	ds_write2_b32 v2, v9, v25 offset1:32
	s_and_saveexec_b64 s[58:59], s[4:5]
	s_mulk_i32 s61, 0x1100
	v_add_u32_e32 v2, s61, v86
	v_add_u32_e32 v2, 0x1000, v2
	ds_write2_b32 v2, v10, v26 offset1:32
	s_or_b64 exec, exec, s[58:59]
	s_waitcnt lgkmcnt(0)
	s_barrier
	s_and_saveexec_b64 s[58:59], s[6:7]
	s_cbranch_execz .LBB0_7
	s_mul_i32 s73, s60, 0x66000
	s_mul_hi_i32 s61, s60, 0x66000
	s_add_u32 s73, s1, s73
	s_mul_hi_i32 s74, s60, 0x6000
	s_mulk_i32 s60, 0x6000
	s_addc_u32 s75, s33, s61
	s_add_u32 s60, s50, s60
	s_addc_u32 s61, s51, s74
	s_add_u32 s60, s60, s48
	s_addc_u32 s61, s61, s49
	s_add_u32 s48, s73, s48
	s_addc_u32 s49, s75, s49
	v_mov_b32_e32 v63, v41
	v_readlane_b32 s73, v254, 0
	v_lshl_add_u64 v[2:3], s[60:61], 0, v[62:63]
	v_lshl_add_u64 v[4:5], s[48:49], 0, v[62:63]
	s_mov_b64 s[48:49], 0
	v_mov_b32_e32 v6, v82
	s_branch .LBB0_69

.LBB0_173:
	s_mov_b32 s101, 0
	s_mov_b32 s100, 0x2c000
	v_lshl_add_u64 v[250:251], v[38:39], 0, s[100:101]
	global_load_dword v148, v[250:251], off
	global_load_dword v149, v[250:251], off offset:128
	s_add_u32 s100, s63, 0x2c000
	v_lshl_add_u64 v[252:253], v[38:39], 0, s[100:101]
	global_load_dword v150, v[252:253], off offset:2048
	global_load_dword v157, v[252:253], off offset:2176
	s_add_u32 s100, s64, 0x2c000
	v_lshl_add_u64 v[250:251], v[38:39], 0, s[100:101]
	global_load_dword v151, v[250:251], off offset:1024
	global_load_dword v158, v[250:251], off offset:1152
	s_add_u32 s100, s62, 0x2c000
	v_lshl_add_u64 v[252:253], v[38:39], 0, s[100:101]
	global_load_dword v152, v[252:253], off offset:3072
	global_load_dword v159, v[252:253], off offset:3200
	s_add_u32 s100, s67, 0x2c000
	v_lshl_add_u64 v[250:251], v[38:39], 0, s[100:101]
	global_load_dword v153, v[250:251], off offset:2048
	global_load_dword v160, v[250:251], off offset:2176
	s_add_u32 s100, s65, 0x2c000
	v_lshl_add_u64 v[252:253], v[38:39], 0, s[100:101]
	global_load_dword v154, v[252:253], off
	global_load_dword v161, v[252:253], off offset:128
	s_add_u32 s100, s68, 0x2c000
	v_lshl_add_u64 v[250:251], v[38:39], 0, s[100:101]
	global_load_dword v155, v[250:251], off offset:1024
	global_load_dword v162, v[250:251], off offset:1152
	s_add_u32 s100, s66, 0x2c000
	v_lshl_add_u64 v[252:253], v[38:39], 0, s[100:101]
	global_load_dword v156, v[252:253], off offset:3072
	global_load_dword v163, v[252:253], off offset:3200
	s_mov_b32 s101, 0
	s_mov_b32 s100, 0x58000
	v_lshl_add_u64 v[250:251], v[38:39], 0, s[100:101]
	global_load_dword v164, v[250:251], off
	global_load_dword v165, v[250:251], off offset:128
	s_add_u32 s100, s63, 0x58000
	v_lshl_add_u64 v[252:253], v[38:39], 0, s[100:101]
	global_load_dword v166, v[252:253], off offset:2048
	global_load_dword v173, v[252:253], off offset:2176
	s_add_u32 s100, s64, 0x58000
	v_lshl_add_u64 v[250:251], v[38:39], 0, s[100:101]
	global_load_dword v167, v[250:251], off offset:1024
	global_load_dword v174, v[250:251], off offset:1152
	s_add_u32 s100, s62, 0x58000
	v_lshl_add_u64 v[252:253], v[38:39], 0, s[100:101]
	global_load_dword v168, v[252:253], off offset:3072
	global_load_dword v175, v[252:253], off offset:3200
	s_add_u32 s100, s67, 0x58000
	v_lshl_add_u64 v[250:251], v[38:39], 0, s[100:101]
	global_load_dword v169, v[250:251], off offset:2048
	global_load_dword v176, v[250:251], off offset:2176
	s_add_u32 s100, s65, 0x58000
	v_lshl_add_u64 v[252:253], v[38:39], 0, s[100:101]
	global_load_dword v170, v[252:253], off
	global_load_dword v177, v[252:253], off offset:128
	s_add_u32 s100, s68, 0x58000
	v_lshl_add_u64 v[250:251], v[38:39], 0, s[100:101]
	global_load_dword v171, v[250:251], off offset:1024
	global_load_dword v178, v[250:251], off offset:1152
	s_add_u32 s100, s66, 0x58000
	v_lshl_add_u64 v[252:253], v[38:39], 0, s[100:101]
	global_load_dword v172, v[252:253], off offset:3072
	global_load_dword v179, v[252:253], off offset:3200
	s_mov_b32 s101, 0
	s_mov_b32 s100, 0x84000
	v_lshl_add_u64 v[250:251], v[38:39], 0, s[100:101]
	global_load_dword v180, v[250:251], off
	global_load_dword v181, v[250:251], off offset:128
	s_add_u32 s100, s63, 0x84000
	v_lshl_add_u64 v[252:253], v[38:39], 0, s[100:101]
	global_load_dword v182, v[252:253], off offset:2048
	global_load_dword v189, v[252:253], off offset:2176
	s_add_u32 s100, s64, 0x84000
	v_lshl_add_u64 v[250:251], v[38:39], 0, s[100:101]
	global_load_dword v183, v[250:251], off offset:1024
	global_load_dword v190, v[250:251], off offset:1152
	s_add_u32 s100, s62, 0x84000
	v_lshl_add_u64 v[252:253], v[38:39], 0, s[100:101]
	global_load_dword v184, v[252:253], off offset:3072
	global_load_dword v191, v[252:253], off offset:3200
	s_add_u32 s100, s67, 0x84000
	v_lshl_add_u64 v[250:251], v[38:39], 0, s[100:101]
	global_load_dword v185, v[250:251], off offset:2048
	global_load_dword v192, v[250:251], off offset:2176
	s_add_u32 s100, s65, 0x84000
	v_lshl_add_u64 v[252:253], v[38:39], 0, s[100:101]
	global_load_dword v186, v[252:253], off
	global_load_dword v193, v[252:253], off offset:128
	s_add_u32 s100, s68, 0x84000
	v_lshl_add_u64 v[250:251], v[38:39], 0, s[100:101]
	global_load_dword v187, v[250:251], off offset:1024
	global_load_dword v194, v[250:251], off offset:1152
	s_add_u32 s100, s66, 0x84000
	v_lshl_add_u64 v[252:253], v[38:39], 0, s[100:101]
	global_load_dword v188, v[252:253], off offset:3072
	global_load_dword v195, v[252:253], off offset:3200
	s_mov_b32 s101, 0
	s_mov_b32 s100, 0xb0000
	v_lshl_add_u64 v[250:251], v[38:39], 0, s[100:101]
	global_load_dword v196, v[250:251], off
	global_load_dword v197, v[250:251], off offset:128
	s_add_u32 s100, s63, 0xb0000
	v_lshl_add_u64 v[252:253], v[38:39], 0, s[100:101]
	global_load_dword v198, v[252:253], off offset:2048
	global_load_dword v205, v[252:253], off offset:2176
	s_add_u32 s100, s64, 0xb0000
	v_lshl_add_u64 v[250:251], v[38:39], 0, s[100:101]
	global_load_dword v199, v[250:251], off offset:1024
	global_load_dword v206, v[250:251], off offset:1152
	s_add_u32 s100, s62, 0xb0000
	v_lshl_add_u64 v[252:253], v[38:39], 0, s[100:101]
	global_load_dword v200, v[252:253], off offset:3072
	global_load_dword v207, v[252:253], off offset:3200
	s_add_u32 s100, s67, 0xb0000
	v_lshl_add_u64 v[250:251], v[38:39], 0, s[100:101]
	global_load_dword v201, v[250:251], off offset:2048
	global_load_dword v208, v[250:251], off offset:2176
	s_add_u32 s100, s65, 0xb0000
	v_lshl_add_u64 v[252:253], v[38:39], 0, s[100:101]
	global_load_dword v202, v[252:253], off
	global_load_dword v209, v[252:253], off offset:128
	s_add_u32 s100, s68, 0xb0000
	v_lshl_add_u64 v[250:251], v[38:39], 0, s[100:101]
	global_load_dword v203, v[250:251], off offset:1024
	global_load_dword v210, v[250:251], off offset:1152
	s_add_u32 s100, s66, 0xb0000
	v_lshl_add_u64 v[252:253], v[38:39], 0, s[100:101]
	global_load_dword v204, v[252:253], off offset:3072
	global_load_dword v211, v[252:253], off offset:3200
	s_mov_b32 s101, 0
	s_mov_b32 s100, 0xdc000
	v_lshl_add_u64 v[250:251], v[38:39], 0, s[100:101]
	global_load_dword v212, v[250:251], off
	global_load_dword v213, v[250:251], off offset:128
	s_add_u32 s100, s63, 0xdc000
	v_lshl_add_u64 v[252:253], v[38:39], 0, s[100:101]
	global_load_dword v214, v[252:253], off offset:2048
	global_load_dword v221, v[252:253], off offset:2176
	s_add_u32 s100, s64, 0xdc000
	v_lshl_add_u64 v[250:251], v[38:39], 0, s[100:101]
	global_load_dword v215, v[250:251], off offset:1024
	global_load_dword v222, v[250:251], off offset:1152
	s_add_u32 s100, s62, 0xdc000
	v_lshl_add_u64 v[252:253], v[38:39], 0, s[100:101]
	global_load_dword v216, v[252:253], off offset:3072
	global_load_dword v223, v[252:253], off offset:3200
	s_add_u32 s100, s67, 0xdc000
	v_lshl_add_u64 v[250:251], v[38:39], 0, s[100:101]
	global_load_dword v217, v[250:251], off offset:2048
	global_load_dword v224, v[250:251], off offset:2176
	s_add_u32 s100, s65, 0xdc000
	v_lshl_add_u64 v[252:253], v[38:39], 0, s[100:101]
	global_load_dword v218, v[252:253], off
	global_load_dword v225, v[252:253], off offset:128
	s_add_u32 s100, s68, 0xdc000
	v_lshl_add_u64 v[250:251], v[38:39], 0, s[100:101]
	global_load_dword v219, v[250:251], off offset:1024
	global_load_dword v226, v[250:251], off offset:1152
	s_add_u32 s100, s66, 0xdc000
	v_lshl_add_u64 v[252:253], v[38:39], 0, s[100:101]
	global_load_dword v220, v[252:253], off offset:3072
	global_load_dword v227, v[252:253], off offset:3200
	s_mov_b32 s101, 0
	s_mov_b32 s100, 0x108000
	v_lshl_add_u64 v[250:251], v[38:39], 0, s[100:101]
	global_load_dword v228, v[250:251], off
	global_load_dword v229, v[250:251], off offset:128
	s_add_u32 s100, s63, 0x108000
	v_lshl_add_u64 v[252:253], v[38:39], 0, s[100:101]
	global_load_dword v230, v[252:253], off offset:2048
	global_load_dword v237, v[252:253], off offset:2176
	s_add_u32 s100, s64, 0x108000
	v_lshl_add_u64 v[250:251], v[38:39], 0, s[100:101]
	global_load_dword v231, v[250:251], off offset:1024
	global_load_dword v238, v[250:251], off offset:1152
	s_add_u32 s100, s62, 0x108000
	v_lshl_add_u64 v[252:253], v[38:39], 0, s[100:101]
	global_load_dword v232, v[252:253], off offset:3072
	global_load_dword v239, v[252:253], off offset:3200
	s_add_u32 s100, s67, 0x108000
	v_lshl_add_u64 v[250:251], v[38:39], 0, s[100:101]
	global_load_dword v233, v[250:251], off offset:2048
	global_load_dword v240, v[250:251], off offset:2176
	s_add_u32 s100, s65, 0x108000
	v_lshl_add_u64 v[252:253], v[38:39], 0, s[100:101]
	global_load_dword v234, v[252:253], off
	global_load_dword v241, v[252:253], off offset:128
	s_add_u32 s100, s68, 0x108000
	v_lshl_add_u64 v[250:251], v[38:39], 0, s[100:101]
	global_load_dword v235, v[250:251], off offset:1024
	global_load_dword v242, v[250:251], off offset:1152
	s_add_u32 s100, s66, 0x108000
	v_lshl_add_u64 v[252:253], v[38:39], 0, s[100:101]
	global_load_dword v236, v[252:253], off offset:3072
	global_load_dword v243, v[252:253], off offset:3200
	v_lshl_add_u64 v[36:37], v[38:39], 0, s[50:51]
	v_add_co_u32_e32 v42, vcc, s62, v36
	ds_read_b128 v[32:35], v88
	ds_read_b128 v[116:119], v88 offset:16
	v_addc_co_u32_e32 v43, vcc, 0, v37, vcc
	v_add_co_u32_e32 v46, vcc, s63, v36
	s_waitcnt lgkmcnt(1)
	v_cndmask_b32_e64 v35, 0, v35, s[2:3]
	v_addc_co_u32_e32 v47, vcc, 0, v37, vcc
	v_add_co_u32_e32 v84, vcc, s64, v36
	s_waitcnt lgkmcnt(0)
	v_cndmask_b32_e64 v119, 0, v119, s[2:3]
	v_addc_co_u32_e32 v85, vcc, 0, v37, vcc
	v_add_co_u32_e32 v120, vcc, s65, v36
	v_and_b32_sdwa v89, v35, v115 dst_sel:DWORD dst_unused:UNUSED_PAD src0_sel:WORD_1 src1_sel:DWORD
	s_nop 0
	v_addc_co_u32_e32 v121, vcc, 0, v37, vcc
	v_add_co_u32_e32 v122, vcc, s66, v36
	s_nop 0
	v_addc_co_u32_e32 v123, vcc, 0, v37, vcc
	v_add_co_u32_e32 v124, vcc, s67, v36
	s_nop 0
	v_addc_co_u32_e32 v125, vcc, 0, v37, vcc
	v_add_co_u32_e32 v126, vcc, s68, v36
	s_nop 0
	v_addc_co_u32_e32 v127, vcc, 0, v37, vcc
	global_load_dword v44, v[36:37], off
	global_load_dword v40, v[36:37], off offset:128
	global_load_dword v45, v[46:47], off offset:2048
	global_load_dword v83, v[84:85], off offset:1024
	global_load_dword v82, v[42:43], off offset:3072
	global_load_dword v81, v[124:125], off offset:2048
	global_load_dword v80, v[120:121], off
	global_load_dword v87, v[126:127], off offset:1024
	global_load_dword v86, v[122:123], off offset:3072
	global_load_dword v41, v[46:47], off offset:2176
	s_nop 0
	global_load_dword v85, v[84:85], off offset:1152
	s_nop 0
	global_load_dword v84, v[42:43], off offset:3200
	s_nop 0
	global_load_dword v43, v[124:125], off offset:2176
	global_load_dword v42, v[120:121], off offset:128
	global_load_dword v47, v[126:127], off offset:1152
	global_load_dword v46, v[122:123], off offset:3200
	v_cndmask_b32_e64 v37, 0, v34, s[2:3]
	v_cndmask_b32_e64 v36, 0, v32, s[2:3]
	v_cndmask_b32_e64 v34, 0, v33, s[2:3]
	v_cndmask_b32_e64 v121, 0, v118, s[2:3]
	v_cndmask_b32_e64 v120, 0, v116, s[2:3]
	v_cndmask_b32_e64 v118, 0, v117, s[2:3]
	v_and_b32_sdwa v32, v37, v115 dst_sel:DWORD dst_unused:UNUSED_PAD src0_sel:WORD_1 src1_sel:DWORD
	v_and_b32_sdwa v33, v36, v115 dst_sel:DWORD dst_unused:UNUSED_PAD src0_sel:WORD_1 src1_sel:DWORD
	v_and_b32_sdwa v116, v34, v115 dst_sel:DWORD dst_unused:UNUSED_PAD src0_sel:WORD_1 src1_sel:DWORD
	v_and_b32_sdwa v117, v121, v115 dst_sel:DWORD dst_unused:UNUSED_PAD src0_sel:WORD_1 src1_sel:DWORD
	v_and_b32_sdwa v122, v120, v115 dst_sel:DWORD dst_unused:UNUSED_PAD src0_sel:WORD_1 src1_sel:DWORD
	v_and_b32_sdwa v123, v119, v115 dst_sel:DWORD dst_unused:UNUSED_PAD src0_sel:WORD_1 src1_sel:DWORD
	v_and_b32_sdwa v124, v118, v115 dst_sel:DWORD dst_unused:UNUSED_PAD src0_sel:WORD_1 src1_sel:DWORD
	v_add3_u32 v128, v37, v32, s69
	v_add3_u32 v32, v36, v33, s69
	v_add3_u32 v33, v35, v89, s69
	v_add3_u32 v89, v34, v116, s69
	v_add3_u32 v129, v121, v117, s69
	v_add3_u32 v130, v120, v122, s69
	v_add3_u32 v125, v119, v123, s69
	v_add3_u32 v124, v118, v124, s69
	v_and_b32_e32 v117, 0xffff0000, v33
	v_and_b32_e32 v116, 0xffff0000, v89
	v_and_b32_e32 v123, 0xffff0000, v128
	v_and_b32_e32 v122, 0xffff0000, v32
	v_and_b32_e32 v127, 0xffff0000, v129
	v_and_b32_e32 v126, 0xffff0000, v130
	v_and_b32_e32 v125, 0xffff0000, v125
	v_and_b32_e32 v124, 0xffff0000, v124
	v_or_b32_sdwa v32, v116, v32 dst_sel:DWORD dst_unused:UNUSED_PAD src0_sel:DWORD src1_sel:WORD_1
	v_pk_add_f32 v[36:37], v[36:37], v[122:123] neg_lo:[0,1] neg_hi:[0,1]
	v_pk_add_f32 v[122:123], v[34:35], v[116:117] neg_lo:[0,1] neg_hi:[0,1]
	v_or_b32_sdwa v33, v117, v128 dst_sel:DWORD dst_unused:UNUSED_PAD src0_sel:DWORD src1_sel:WORD_1
	v_pk_add_f32 v[116:117], v[120:121], v[126:127] neg_lo:[0,1] neg_hi:[0,1]
	v_pk_add_f32 v[118:119], v[118:119], v[124:125] neg_lo:[0,1] neg_hi:[0,1]
	v_bfe_u32 v126, v37, 16, 1
	v_bfe_u32 v128, v117, 16, 1
	v_or_b32_sdwa v35, v125, v129 dst_sel:DWORD dst_unused:UNUSED_PAD src0_sel:DWORD src1_sel:WORD_1
	v_bfe_u32 v89, v119, 16, 1
	v_bfe_u32 v125, v36, 16, 1
	v_bfe_u32 v127, v116, 16, 1
	v_add3_u32 v117, v117, v128, s69
	v_add3_u32 v37, v37, v126, s69
	v_or_b32_sdwa v34, v124, v130 dst_sel:DWORD dst_unused:UNUSED_PAD src0_sel:DWORD src1_sel:WORD_1
	v_bfe_u32 v120, v118, 16, 1
	v_bfe_u32 v121, v123, 16, 1
	v_bfe_u32 v124, v122, 16, 1
	v_add3_u32 v89, v119, v89, s69
	v_add3_u32 v116, v116, v127, s69
	v_add3_u32 v36, v36, v125, s69
	v_lshrrev_b32_e32 v140, 16, v37
	v_lshrrev_b32_e32 v37, 16, v117
	v_add3_u32 v136, v122, v124, s69
	v_add3_u32 v137, v123, v121, s69
	v_add3_u32 v138, v118, v120, s69
	v_lshrrev_b32_e32 v139, 16, v36
	v_lshrrev_b32_e32 v36, 16, v116
	v_and_or_b32 v37, v89, s70, v37
	v_and_or_b32 v36, v138, s70, v36
	v_add_u32_e32 v88, 64, v88
	s_waitcnt vmcnt(15)
	v_and_b32_sdwa v89, v44, v115 dst_sel:DWORD dst_unused:UNUSED_PAD src0_sel:WORD_1 src1_sel:DWORD
	s_waitcnt vmcnt(14)
	v_and_b32_sdwa v116, v40, v115 dst_sel:DWORD dst_unused:UNUSED_PAD src0_sel:WORD_1 src1_sel:DWORD
	s_waitcnt vmcnt(13)
	v_and_b32_sdwa v117, v45, v115 dst_sel:DWORD dst_unused:UNUSED_PAD src0_sel:WORD_1 src1_sel:DWORD
	s_waitcnt vmcnt(12)
	v_and_b32_sdwa v118, v83, v115 dst_sel:DWORD dst_unused:UNUSED_PAD src0_sel:WORD_1 src1_sel:DWORD
	s_waitcnt vmcnt(11)
	v_and_b32_sdwa v119, v82, v115 dst_sel:DWORD dst_unused:UNUSED_PAD src0_sel:WORD_1 src1_sel:DWORD
	v_add3_u32 v89, v44, v89, s69
	s_waitcnt vmcnt(9)
	v_and_b32_sdwa v121, v80, v115 dst_sel:DWORD dst_unused:UNUSED_PAD src0_sel:WORD_1 src1_sel:DWORD
	s_waitcnt vmcnt(8)
	v_and_b32_sdwa v122, v87, v115 dst_sel:DWORD dst_unused:UNUSED_PAD src0_sel:WORD_1 src1_sel:DWORD
	s_waitcnt vmcnt(7)
	v_and_b32_sdwa v123, v86, v115 dst_sel:DWORD dst_unused:UNUSED_PAD src0_sel:WORD_1 src1_sel:DWORD
	v_and_b32_sdwa v120, v81, v115 dst_sel:DWORD dst_unused:UNUSED_PAD src0_sel:WORD_1 src1_sel:DWORD
	s_waitcnt vmcnt(6)
	v_and_b32_sdwa v124, v41, v115 dst_sel:DWORD dst_unused:UNUSED_PAD src0_sel:WORD_1 src1_sel:DWORD
	v_add3_u32 v141, v40, v116, s69
	s_waitcnt vmcnt(5)
	v_and_b32_sdwa v116, v85, v115 dst_sel:DWORD dst_unused:UNUSED_PAD src0_sel:WORD_1 src1_sel:DWORD
	s_waitcnt vmcnt(4)
	v_and_b32_sdwa v125, v84, v115 dst_sel:DWORD dst_unused:UNUSED_PAD src0_sel:WORD_1 src1_sel:DWORD
	v_add3_u32 v117, v45, v117, s69
	v_add3_u32 v130, v83, v118, s69
	v_add3_u32 v119, v82, v119, s69
	v_add3_u32 v143, v80, v121, s69
	v_add3_u32 v121, v87, v122, s69
	v_add3_u32 v131, v86, v123, s69
	s_waitcnt vmcnt(1)
	v_and_b32_sdwa v128, v47, v115 dst_sel:DWORD dst_unused:UNUSED_PAD src0_sel:WORD_1 src1_sel:DWORD
	s_waitcnt vmcnt(0)
	v_and_b32_sdwa v129, v46, v115 dst_sel:DWORD dst_unused:UNUSED_PAD src0_sel:WORD_1 src1_sel:DWORD
	v_and_b32_e32 v118, 0xffff0000, v89
	v_add3_u32 v142, v81, v120, s69
	v_add3_u32 v144, v41, v124, s69
	v_add3_u32 v116, v85, v116, s69
	v_add3_u32 v132, v84, v125, s69
	v_and_b32_e32 v123, 0xffff0000, v130
	v_and_b32_e32 v122, 0xffff0000, v119
	v_and_b32_e32 v119, 0xffff0000, v117
	v_and_b32_e32 v125, 0xffff0000, v121
	v_and_b32_e32 v124, 0xffff0000, v131
	v_and_b32_sdwa v126, v43, v115 dst_sel:DWORD dst_unused:UNUSED_PAD src0_sel:WORD_1 src1_sel:DWORD
	v_and_b32_sdwa v127, v42, v115 dst_sel:DWORD dst_unused:UNUSED_PAD src0_sel:WORD_1 src1_sel:DWORD
	v_add3_u32 v133, v47, v128, s69
	v_add3_u32 v134, v46, v129, s69
	v_and_b32_e32 v129, 0xffff0000, v116
	v_or_b32_sdwa v116, v122, v89 dst_sel:DWORD dst_unused:UNUSED_PAD src0_sel:DWORD src1_sel:WORD_1
	v_pk_add_f32 v[44:45], v[44:45], v[118:119] neg_lo:[0,1] neg_hi:[0,1]
	v_or_b32_sdwa v117, v123, v117 dst_sel:DWORD dst_unused:UNUSED_PAD src0_sel:DWORD src1_sel:WORD_1
	v_or_b32_sdwa v118, v124, v143 dst_sel:DWORD dst_unused:UNUSED_PAD src0_sel:DWORD src1_sel:WORD_1
	v_or_b32_sdwa v119, v125, v142 dst_sel:DWORD dst_unused:UNUSED_PAD src0_sel:DWORD src1_sel:WORD_1
	v_add3_u32 v145, v43, v126, s69
	v_add3_u32 v146, v42, v127, s69
	v_and_b32_e32 v127, 0xffff0000, v142
	v_and_b32_e32 v126, 0xffff0000, v143
	v_and_b32_e32 v128, 0xffff0000, v132
	v_and_b32_e32 v131, 0xffff0000, v133
	v_and_b32_e32 v130, 0xffff0000, v134
	v_mfma_f32_32x32x16_bf16 v[0:15], v[32:35], v[116:119], v[0:15]
	v_add_f32_e64 v134, v82, -v122
	v_add_f32_e64 v135, v83, -v123
	v_add_f32_e64 v122, v80, -v126
	v_add_f32_e64 v123, v81, -v127
	v_or_b32_sdwa v80, v128, v141 dst_sel:DWORD dst_unused:UNUSED_PAD src0_sel:DWORD src1_sel:WORD_1
	v_or_b32_sdwa v81, v129, v144 dst_sel:DWORD dst_unused:UNUSED_PAD src0_sel:DWORD src1_sel:WORD_1
	v_or_b32_sdwa v82, v130, v146 dst_sel:DWORD dst_unused:UNUSED_PAD src0_sel:DWORD src1_sel:WORD_1
	v_or_b32_sdwa v83, v131, v145 dst_sel:DWORD dst_unused:UNUSED_PAD src0_sel:DWORD src1_sel:WORD_1
	v_and_b32_e32 v120, 0xffff0000, v141
	v_and_b32_e32 v121, 0xffff0000, v144
	v_mfma_f32_32x32x16_bf16 v[16:31], v[32:35], v[80:83], v[16:31]
	v_and_b32_e32 v133, 0xffff0000, v145
	v_and_b32_e32 v132, 0xffff0000, v146
	v_add_f32_e64 v86, v86, -v124
	v_add_f32_e64 v87, v87, -v125
	v_add_f32_e64 v40, v40, -v120
	v_add_f32_e64 v41, v41, -v121
	v_pk_add_f32 v[84:85], v[84:85], v[128:129] neg_lo:[0,1] neg_hi:[0,1]
	v_pk_add_f32 v[42:43], v[42:43], v[132:133] neg_lo:[0,1] neg_hi:[0,1]
	v_bfe_u32 v89, v87, 16, 1
	v_bfe_u32 v120, v86, 16, 1
	v_bfe_u32 v125, v122, 16, 1
	v_bfe_u32 v126, v123, 16, 1
	v_bfe_u32 v127, v44, 16, 1
	v_bfe_u32 v128, v45, 16, 1
	v_bfe_u32 v121, v135, 16, 1
	v_bfe_u32 v124, v134, 16, 1
	v_bfe_u32 v133, v42, 16, 1
	v_bfe_u32 v142, v40, 16, 1
	v_bfe_u32 v143, v41, 16, 1
	v_add3_u32 v86, v86, v120, s69
	v_add3_u32 v87, v87, v89, s69
	v_add3_u32 v89, v123, v126, s69
	v_add3_u32 v120, v122, v125, s69
	v_add3_u32 v45, v45, v128, s69
	v_add3_u32 v44, v44, v127, s69
	v_pk_add_f32 v[46:47], v[46:47], v[130:131] neg_lo:[0,1] neg_hi:[0,1]
	v_bfe_u32 v141, v43, 16, 1
	v_add3_u32 v124, v134, v124, s69
	v_add3_u32 v121, v135, v121, s69
	v_add3_u32 v42, v42, v133, s69
	v_add3_u32 v123, v41, v143, s69
	v_add3_u32 v125, v40, v142, s69
	v_lshrrev_b32_e32 v40, 16, v120
	v_lshrrev_b32_e32 v41, 16, v89
	v_lshrrev_b32_e32 v44, 16, v44
	v_lshrrev_b32_e32 v45, 16, v45
	v_bfe_u32 v129, v47, 16, 1
	v_bfe_u32 v130, v46, 16, 1
	v_bfe_u32 v131, v85, 16, 1
	v_bfe_u32 v132, v84, 16, 1
	v_add3_u32 v122, v43, v141, s69
	v_lshrrev_b32_e32 v89, 16, v42
	v_and_or_b32 v43, v87, s70, v41
	v_and_or_b32 v42, v86, s70, v40
	v_and_or_b32 v41, v121, s70, v45
	v_and_or_b32 v40, v124, s70, v44
	v_add3_u32 v84, v84, v132, s69
	v_add3_u32 v85, v85, v131, s69
	v_add3_u32 v46, v46, v130, s69
	v_add3_u32 v47, v47, v129, s69
	v_mfma_f32_32x32x16_bf16 v[0:15], v[32:35], v[40:43], v[0:15]
	v_lshrrev_b32_e32 v40, 16, v122
	v_lshrrev_b32_e32 v44, 16, v125
	v_lshrrev_b32_e32 v41, 16, v123
	v_and_or_b32 v43, v47, s70, v40
	v_and_or_b32 v42, v46, s70, v89
	v_and_or_b32 v41, v85, s70, v41
	v_and_or_b32 v40, v84, s70, v44
	s_nop 1
	v_mfma_f32_32x32x16_bf16 v[16:31], v[32:35], v[40:43], v[16:31]
	v_and_or_b32 v35, v137, s70, v140
	v_and_or_b32 v34, v136, s70, v139
	s_nop 1
	v_mfma_f32_32x32x16_bf16 v[0:15], v[34:37], v[116:119], v[0:15]
	v_mfma_f32_32x32x16_bf16 v[16:31], v[34:37], v[80:83], v[16:31]
	ds_read_b128 v[32:35], v88
	ds_read_b128 v[116:119], v88 offset:16
	s_waitcnt lgkmcnt(1)
	v_cndmask_b32_e64 v35, 0, v35, s[2:3]
	s_waitcnt lgkmcnt(0)
	v_cndmask_b32_e64 v119, 0, v119, s[2:3]
	v_and_b32_sdwa v89, v35, v115 dst_sel:DWORD dst_unused:UNUSED_PAD src0_sel:WORD_1 src1_sel:DWORD
	s_nop 0
	s_nop 0
	s_nop 0
	s_nop 0
	v_mov_b32_e32 v44, v148
	v_mov_b32_e32 v40, v149
	v_mov_b32_e32 v45, v150
	v_mov_b32_e32 v83, v151
	v_mov_b32_e32 v82, v152
	v_mov_b32_e32 v81, v153
	v_mov_b32_e32 v80, v154
	v_mov_b32_e32 v87, v155
	v_mov_b32_e32 v86, v156
	v_mov_b32_e32 v41, v157
	s_nop 0
	v_mov_b32_e32 v85, v158
	s_nop 0
	v_mov_b32_e32 v84, v159
	s_nop 0
	v_mov_b32_e32 v43, v160
	v_mov_b32_e32 v42, v161
	v_mov_b32_e32 v47, v162
	v_mov_b32_e32 v46, v163
	s_mov_b32 s101, 0
	s_mov_b32 s100, 0x134000
	v_lshl_add_u64 v[250:251], v[38:39], 0, s[100:101]
	global_load_dword v148, v[250:251], off
	global_load_dword v149, v[250:251], off offset:128
	s_add_u32 s100, s63, 0x134000
	v_lshl_add_u64 v[252:253], v[38:39], 0, s[100:101]
	global_load_dword v150, v[252:253], off offset:2048
	global_load_dword v157, v[252:253], off offset:2176
	s_add_u32 s100, s64, 0x134000
	v_lshl_add_u64 v[250:251], v[38:39], 0, s[100:101]
	global_load_dword v151, v[250:251], off offset:1024
	global_load_dword v158, v[250:251], off offset:1152
	s_add_u32 s100, s62, 0x134000
	v_lshl_add_u64 v[252:253], v[38:39], 0, s[100:101]
	global_load_dword v152, v[252:253], off offset:3072
	global_load_dword v159, v[252:253], off offset:3200
	s_add_u32 s100, s67, 0x134000
	v_lshl_add_u64 v[250:251], v[38:39], 0, s[100:101]
	global_load_dword v153, v[250:251], off offset:2048
	global_load_dword v160, v[250:251], off offset:2176
	s_add_u32 s100, s65, 0x134000
	v_lshl_add_u64 v[252:253], v[38:39], 0, s[100:101]
	global_load_dword v154, v[252:253], off
	global_load_dword v161, v[252:253], off offset:128
	s_add_u32 s100, s68, 0x134000
	v_lshl_add_u64 v[250:251], v[38:39], 0, s[100:101]
	global_load_dword v155, v[250:251], off offset:1024
	global_load_dword v162, v[250:251], off offset:1152
	s_add_u32 s100, s66, 0x134000
	v_lshl_add_u64 v[252:253], v[38:39], 0, s[100:101]
	global_load_dword v156, v[252:253], off offset:3072
	global_load_dword v163, v[252:253], off offset:3200
	v_cndmask_b32_e64 v37, 0, v34, s[2:3]
	v_cndmask_b32_e64 v36, 0, v32, s[2:3]
	v_cndmask_b32_e64 v34, 0, v33, s[2:3]
	v_cndmask_b32_e64 v121, 0, v118, s[2:3]
	v_cndmask_b32_e64 v120, 0, v116, s[2:3]
	v_cndmask_b32_e64 v118, 0, v117, s[2:3]
	v_and_b32_sdwa v32, v37, v115 dst_sel:DWORD dst_unused:UNUSED_PAD src0_sel:WORD_1 src1_sel:DWORD
	v_and_b32_sdwa v33, v36, v115 dst_sel:DWORD dst_unused:UNUSED_PAD src0_sel:WORD_1 src1_sel:DWORD
	v_and_b32_sdwa v116, v34, v115 dst_sel:DWORD dst_unused:UNUSED_PAD src0_sel:WORD_1 src1_sel:DWORD
	v_and_b32_sdwa v117, v121, v115 dst_sel:DWORD dst_unused:UNUSED_PAD src0_sel:WORD_1 src1_sel:DWORD
	v_and_b32_sdwa v122, v120, v115 dst_sel:DWORD dst_unused:UNUSED_PAD src0_sel:WORD_1 src1_sel:DWORD
	v_and_b32_sdwa v123, v119, v115 dst_sel:DWORD dst_unused:UNUSED_PAD src0_sel:WORD_1 src1_sel:DWORD
	v_and_b32_sdwa v124, v118, v115 dst_sel:DWORD dst_unused:UNUSED_PAD src0_sel:WORD_1 src1_sel:DWORD
	v_add3_u32 v128, v37, v32, s69
	v_add3_u32 v32, v36, v33, s69
	v_add3_u32 v33, v35, v89, s69
	v_add3_u32 v89, v34, v116, s69
	v_add3_u32 v129, v121, v117, s69
	v_add3_u32 v130, v120, v122, s69
	v_add3_u32 v125, v119, v123, s69
	v_add3_u32 v124, v118, v124, s69
	v_and_b32_e32 v117, 0xffff0000, v33
	v_and_b32_e32 v116, 0xffff0000, v89
	v_and_b32_e32 v123, 0xffff0000, v128
	v_and_b32_e32 v122, 0xffff0000, v32
	v_and_b32_e32 v127, 0xffff0000, v129
	v_and_b32_e32 v126, 0xffff0000, v130
	v_and_b32_e32 v125, 0xffff0000, v125
	v_and_b32_e32 v124, 0xffff0000, v124
	v_or_b32_sdwa v32, v116, v32 dst_sel:DWORD dst_unused:UNUSED_PAD src0_sel:DWORD src1_sel:WORD_1
	v_pk_add_f32 v[36:37], v[36:37], v[122:123] neg_lo:[0,1] neg_hi:[0,1]
	v_pk_add_f32 v[122:123], v[34:35], v[116:117] neg_lo:[0,1] neg_hi:[0,1]
	v_or_b32_sdwa v33, v117, v128 dst_sel:DWORD dst_unused:UNUSED_PAD src0_sel:DWORD src1_sel:WORD_1
	v_pk_add_f32 v[116:117], v[120:121], v[126:127] neg_lo:[0,1] neg_hi:[0,1]
	v_pk_add_f32 v[118:119], v[118:119], v[124:125] neg_lo:[0,1] neg_hi:[0,1]
	v_bfe_u32 v126, v37, 16, 1
	v_bfe_u32 v128, v117, 16, 1
	v_or_b32_sdwa v35, v125, v129 dst_sel:DWORD dst_unused:UNUSED_PAD src0_sel:DWORD src1_sel:WORD_1
	v_bfe_u32 v89, v119, 16, 1
	v_bfe_u32 v125, v36, 16, 1
	v_bfe_u32 v127, v116, 16, 1
	v_add3_u32 v117, v117, v128, s69
	v_add3_u32 v37, v37, v126, s69
	v_or_b32_sdwa v34, v124, v130 dst_sel:DWORD dst_unused:UNUSED_PAD src0_sel:DWORD src1_sel:WORD_1
	v_bfe_u32 v120, v118, 16, 1
	v_bfe_u32 v121, v123, 16, 1
	v_bfe_u32 v124, v122, 16, 1
	v_add3_u32 v89, v119, v89, s69
	v_add3_u32 v116, v116, v127, s69
	v_add3_u32 v36, v36, v125, s69
	v_lshrrev_b32_e32 v140, 16, v37
	v_lshrrev_b32_e32 v37, 16, v117
	v_add3_u32 v136, v122, v124, s69
	v_add3_u32 v137, v123, v121, s69
	v_add3_u32 v138, v118, v120, s69
	v_lshrrev_b32_e32 v139, 16, v36
	v_lshrrev_b32_e32 v36, 16, v116
	v_and_or_b32 v37, v89, s70, v37
	v_and_or_b32 v36, v138, s70, v36
	v_add_u32_e32 v88, 64, v88
	v_and_b32_sdwa v89, v44, v115 dst_sel:DWORD dst_unused:UNUSED_PAD src0_sel:WORD_1 src1_sel:DWORD
	v_and_b32_sdwa v116, v40, v115 dst_sel:DWORD dst_unused:UNUSED_PAD src0_sel:WORD_1 src1_sel:DWORD
	v_and_b32_sdwa v117, v45, v115 dst_sel:DWORD dst_unused:UNUSED_PAD src0_sel:WORD_1 src1_sel:DWORD
	v_and_b32_sdwa v118, v83, v115 dst_sel:DWORD dst_unused:UNUSED_PAD src0_sel:WORD_1 src1_sel:DWORD
	v_and_b32_sdwa v119, v82, v115 dst_sel:DWORD dst_unused:UNUSED_PAD src0_sel:WORD_1 src1_sel:DWORD
	v_add3_u32 v89, v44, v89, s69
	v_and_b32_sdwa v121, v80, v115 dst_sel:DWORD dst_unused:UNUSED_PAD src0_sel:WORD_1 src1_sel:DWORD
	v_and_b32_sdwa v122, v87, v115 dst_sel:DWORD dst_unused:UNUSED_PAD src0_sel:WORD_1 src1_sel:DWORD
	v_and_b32_sdwa v123, v86, v115 dst_sel:DWORD dst_unused:UNUSED_PAD src0_sel:WORD_1 src1_sel:DWORD
	v_and_b32_sdwa v120, v81, v115 dst_sel:DWORD dst_unused:UNUSED_PAD src0_sel:WORD_1 src1_sel:DWORD
	v_and_b32_sdwa v124, v41, v115 dst_sel:DWORD dst_unused:UNUSED_PAD src0_sel:WORD_1 src1_sel:DWORD
	v_add3_u32 v141, v40, v116, s69
	v_and_b32_sdwa v116, v85, v115 dst_sel:DWORD dst_unused:UNUSED_PAD src0_sel:WORD_1 src1_sel:DWORD
	v_and_b32_sdwa v125, v84, v115 dst_sel:DWORD dst_unused:UNUSED_PAD src0_sel:WORD_1 src1_sel:DWORD
	v_add3_u32 v117, v45, v117, s69
	v_add3_u32 v130, v83, v118, s69
	v_add3_u32 v119, v82, v119, s69
	v_add3_u32 v143, v80, v121, s69
	v_add3_u32 v121, v87, v122, s69
	v_add3_u32 v131, v86, v123, s69
	v_and_b32_sdwa v128, v47, v115 dst_sel:DWORD dst_unused:UNUSED_PAD src0_sel:WORD_1 src1_sel:DWORD
	v_and_b32_sdwa v129, v46, v115 dst_sel:DWORD dst_unused:UNUSED_PAD src0_sel:WORD_1 src1_sel:DWORD
	v_and_b32_e32 v118, 0xffff0000, v89
	v_add3_u32 v142, v81, v120, s69
	v_add3_u32 v144, v41, v124, s69
	v_add3_u32 v116, v85, v116, s69
	v_add3_u32 v132, v84, v125, s69
	v_and_b32_e32 v123, 0xffff0000, v130
	v_and_b32_e32 v122, 0xffff0000, v119
	v_and_b32_e32 v119, 0xffff0000, v117
	v_and_b32_e32 v125, 0xffff0000, v121
	v_and_b32_e32 v124, 0xffff0000, v131
	v_and_b32_sdwa v126, v43, v115 dst_sel:DWORD dst_unused:UNUSED_PAD src0_sel:WORD_1 src1_sel:DWORD
	v_and_b32_sdwa v127, v42, v115 dst_sel:DWORD dst_unused:UNUSED_PAD src0_sel:WORD_1 src1_sel:DWORD
	v_add3_u32 v133, v47, v128, s69
	v_add3_u32 v134, v46, v129, s69
	v_and_b32_e32 v129, 0xffff0000, v116
	v_or_b32_sdwa v116, v122, v89 dst_sel:DWORD dst_unused:UNUSED_PAD src0_sel:DWORD src1_sel:WORD_1
	v_pk_add_f32 v[44:45], v[44:45], v[118:119] neg_lo:[0,1] neg_hi:[0,1]
	v_or_b32_sdwa v117, v123, v117 dst_sel:DWORD dst_unused:UNUSED_PAD src0_sel:DWORD src1_sel:WORD_1
	v_or_b32_sdwa v118, v124, v143 dst_sel:DWORD dst_unused:UNUSED_PAD src0_sel:DWORD src1_sel:WORD_1
	v_or_b32_sdwa v119, v125, v142 dst_sel:DWORD dst_unused:UNUSED_PAD src0_sel:DWORD src1_sel:WORD_1
	v_add3_u32 v145, v43, v126, s69
	v_add3_u32 v146, v42, v127, s69
	v_and_b32_e32 v127, 0xffff0000, v142
	v_and_b32_e32 v126, 0xffff0000, v143
	v_and_b32_e32 v128, 0xffff0000, v132
	v_and_b32_e32 v131, 0xffff0000, v133
	v_and_b32_e32 v130, 0xffff0000, v134
	v_mfma_f32_32x32x16_bf16 v[0:15], v[32:35], v[116:119], v[0:15]
	v_add_f32_e64 v134, v82, -v122
	v_add_f32_e64 v135, v83, -v123
	v_add_f32_e64 v122, v80, -v126
	v_add_f32_e64 v123, v81, -v127
	v_or_b32_sdwa v80, v128, v141 dst_sel:DWORD dst_unused:UNUSED_PAD src0_sel:DWORD src1_sel:WORD_1
	v_or_b32_sdwa v81, v129, v144 dst_sel:DWORD dst_unused:UNUSED_PAD src0_sel:DWORD src1_sel:WORD_1
	v_or_b32_sdwa v82, v130, v146 dst_sel:DWORD dst_unused:UNUSED_PAD src0_sel:DWORD src1_sel:WORD_1
	v_or_b32_sdwa v83, v131, v145 dst_sel:DWORD dst_unused:UNUSED_PAD src0_sel:DWORD src1_sel:WORD_1
	v_and_b32_e32 v120, 0xffff0000, v141
	v_and_b32_e32 v121, 0xffff0000, v144
	v_mfma_f32_32x32x16_bf16 v[16:31], v[32:35], v[80:83], v[16:31]
	v_and_b32_e32 v133, 0xffff0000, v145
	v_and_b32_e32 v132, 0xffff0000, v146
	v_add_f32_e64 v86, v86, -v124
	v_add_f32_e64 v87, v87, -v125
	v_add_f32_e64 v40, v40, -v120
	v_add_f32_e64 v41, v41, -v121
	v_pk_add_f32 v[84:85], v[84:85], v[128:129] neg_lo:[0,1] neg_hi:[0,1]
	v_pk_add_f32 v[42:43], v[42:43], v[132:133] neg_lo:[0,1] neg_hi:[0,1]
	v_bfe_u32 v89, v87, 16, 1
	v_bfe_u32 v120, v86, 16, 1
	v_bfe_u32 v125, v122, 16, 1
	v_bfe_u32 v126, v123, 16, 1
	v_bfe_u32 v127, v44, 16, 1
	v_bfe_u32 v128, v45, 16, 1
	v_bfe_u32 v121, v135, 16, 1
	v_bfe_u32 v124, v134, 16, 1
	v_bfe_u32 v133, v42, 16, 1
	v_bfe_u32 v142, v40, 16, 1
	v_bfe_u32 v143, v41, 16, 1
	v_add3_u32 v86, v86, v120, s69
	v_add3_u32 v87, v87, v89, s69
	v_add3_u32 v89, v123, v126, s69
	v_add3_u32 v120, v122, v125, s69
	v_add3_u32 v45, v45, v128, s69
	v_add3_u32 v44, v44, v127, s69
	v_pk_add_f32 v[46:47], v[46:47], v[130:131] neg_lo:[0,1] neg_hi:[0,1]
	v_bfe_u32 v141, v43, 16, 1
	v_add3_u32 v124, v134, v124, s69
	v_add3_u32 v121, v135, v121, s69
	v_add3_u32 v42, v42, v133, s69
	v_add3_u32 v123, v41, v143, s69
	v_add3_u32 v125, v40, v142, s69
	v_lshrrev_b32_e32 v40, 16, v120
	v_lshrrev_b32_e32 v41, 16, v89
	v_lshrrev_b32_e32 v44, 16, v44
	v_lshrrev_b32_e32 v45, 16, v45
	v_bfe_u32 v129, v47, 16, 1
	v_bfe_u32 v130, v46, 16, 1
	v_bfe_u32 v131, v85, 16, 1
	v_bfe_u32 v132, v84, 16, 1
	v_add3_u32 v122, v43, v141, s69
	v_lshrrev_b32_e32 v89, 16, v42
	v_and_or_b32 v43, v87, s70, v41
	v_and_or_b32 v42, v86, s70, v40
	v_and_or_b32 v41, v121, s70, v45
	v_and_or_b32 v40, v124, s70, v44
	v_add3_u32 v84, v84, v132, s69
	v_add3_u32 v85, v85, v131, s69
	v_add3_u32 v46, v46, v130, s69
	v_add3_u32 v47, v47, v129, s69
	v_mfma_f32_32x32x16_bf16 v[0:15], v[32:35], v[40:43], v[0:15]
	v_lshrrev_b32_e32 v40, 16, v122
	v_lshrrev_b32_e32 v44, 16, v125
	v_lshrrev_b32_e32 v41, 16, v123
	v_and_or_b32 v43, v47, s70, v40
	v_and_or_b32 v42, v46, s70, v89
	v_and_or_b32 v41, v85, s70, v41
	v_and_or_b32 v40, v84, s70, v44
	s_nop 1
	v_mfma_f32_32x32x16_bf16 v[16:31], v[32:35], v[40:43], v[16:31]
	v_and_or_b32 v35, v137, s70, v140
	v_and_or_b32 v34, v136, s70, v139
	s_nop 1
	v_mfma_f32_32x32x16_bf16 v[0:15], v[34:37], v[116:119], v[0:15]
	v_mfma_f32_32x32x16_bf16 v[16:31], v[34:37], v[80:83], v[16:31]
	ds_read_b128 v[32:35], v88
	ds_read_b128 v[116:119], v88 offset:16
	s_waitcnt lgkmcnt(1)
	v_cndmask_b32_e64 v35, 0, v35, s[2:3]
	s_waitcnt lgkmcnt(0)
	v_cndmask_b32_e64 v119, 0, v119, s[2:3]
	v_and_b32_sdwa v89, v35, v115 dst_sel:DWORD dst_unused:UNUSED_PAD src0_sel:WORD_1 src1_sel:DWORD
	s_nop 0
	s_nop 0
	s_nop 0
	s_nop 0
	v_mov_b32_e32 v44, v164
	v_mov_b32_e32 v40, v165
	v_mov_b32_e32 v45, v166
	v_mov_b32_e32 v83, v167
	v_mov_b32_e32 v82, v168
	v_mov_b32_e32 v81, v169
	v_mov_b32_e32 v80, v170
	v_mov_b32_e32 v87, v171
	v_mov_b32_e32 v86, v172
	v_mov_b32_e32 v41, v173
	s_nop 0
	v_mov_b32_e32 v85, v174
	s_nop 0
	v_mov_b32_e32 v84, v175
	s_nop 0
	v_mov_b32_e32 v43, v176
	v_mov_b32_e32 v42, v177
	v_mov_b32_e32 v47, v178
	v_mov_b32_e32 v46, v179
	v_cndmask_b32_e64 v37, 0, v34, s[2:3]
	v_cndmask_b32_e64 v36, 0, v32, s[2:3]
	v_cndmask_b32_e64 v34, 0, v33, s[2:3]
	v_cndmask_b32_e64 v121, 0, v118, s[2:3]
	v_cndmask_b32_e64 v120, 0, v116, s[2:3]
	v_cndmask_b32_e64 v118, 0, v117, s[2:3]
	v_and_b32_sdwa v32, v37, v115 dst_sel:DWORD dst_unused:UNUSED_PAD src0_sel:WORD_1 src1_sel:DWORD
	v_and_b32_sdwa v33, v36, v115 dst_sel:DWORD dst_unused:UNUSED_PAD src0_sel:WORD_1 src1_sel:DWORD
	v_and_b32_sdwa v116, v34, v115 dst_sel:DWORD dst_unused:UNUSED_PAD src0_sel:WORD_1 src1_sel:DWORD
	v_and_b32_sdwa v117, v121, v115 dst_sel:DWORD dst_unused:UNUSED_PAD src0_sel:WORD_1 src1_sel:DWORD
	v_and_b32_sdwa v122, v120, v115 dst_sel:DWORD dst_unused:UNUSED_PAD src0_sel:WORD_1 src1_sel:DWORD
	v_and_b32_sdwa v123, v119, v115 dst_sel:DWORD dst_unused:UNUSED_PAD src0_sel:WORD_1 src1_sel:DWORD
	v_and_b32_sdwa v124, v118, v115 dst_sel:DWORD dst_unused:UNUSED_PAD src0_sel:WORD_1 src1_sel:DWORD
	v_add3_u32 v128, v37, v32, s69
	v_add3_u32 v32, v36, v33, s69
	v_add3_u32 v33, v35, v89, s69
	v_add3_u32 v89, v34, v116, s69
	v_add3_u32 v129, v121, v117, s69
	v_add3_u32 v130, v120, v122, s69
	v_add3_u32 v125, v119, v123, s69
	v_add3_u32 v124, v118, v124, s69
	v_and_b32_e32 v117, 0xffff0000, v33
	v_and_b32_e32 v116, 0xffff0000, v89
	v_and_b32_e32 v123, 0xffff0000, v128
	v_and_b32_e32 v122, 0xffff0000, v32
	v_and_b32_e32 v127, 0xffff0000, v129
	v_and_b32_e32 v126, 0xffff0000, v130
	v_and_b32_e32 v125, 0xffff0000, v125
	v_and_b32_e32 v124, 0xffff0000, v124
	v_or_b32_sdwa v32, v116, v32 dst_sel:DWORD dst_unused:UNUSED_PAD src0_sel:DWORD src1_sel:WORD_1
	v_pk_add_f32 v[36:37], v[36:37], v[122:123] neg_lo:[0,1] neg_hi:[0,1]
	v_pk_add_f32 v[122:123], v[34:35], v[116:117] neg_lo:[0,1] neg_hi:[0,1]
	v_or_b32_sdwa v33, v117, v128 dst_sel:DWORD dst_unused:UNUSED_PAD src0_sel:DWORD src1_sel:WORD_1
	v_pk_add_f32 v[116:117], v[120:121], v[126:127] neg_lo:[0,1] neg_hi:[0,1]
	v_pk_add_f32 v[118:119], v[118:119], v[124:125] neg_lo:[0,1] neg_hi:[0,1]
	v_bfe_u32 v126, v37, 16, 1
	v_bfe_u32 v128, v117, 16, 1
	v_or_b32_sdwa v35, v125, v129 dst_sel:DWORD dst_unused:UNUSED_PAD src0_sel:DWORD src1_sel:WORD_1
	v_bfe_u32 v89, v119, 16, 1
	v_bfe_u32 v125, v36, 16, 1
	v_bfe_u32 v127, v116, 16, 1
	v_add3_u32 v117, v117, v128, s69
	v_add3_u32 v37, v37, v126, s69
	v_or_b32_sdwa v34, v124, v130 dst_sel:DWORD dst_unused:UNUSED_PAD src0_sel:DWORD src1_sel:WORD_1
	v_bfe_u32 v120, v118, 16, 1
	v_bfe_u32 v121, v123, 16, 1
	v_bfe_u32 v124, v122, 16, 1
	v_add3_u32 v89, v119, v89, s69
	v_add3_u32 v116, v116, v127, s69
	v_add3_u32 v36, v36, v125, s69
	v_lshrrev_b32_e32 v140, 16, v37
	v_lshrrev_b32_e32 v37, 16, v117
	v_add3_u32 v136, v122, v124, s69
	v_add3_u32 v137, v123, v121, s69
	v_add3_u32 v138, v118, v120, s69
	v_lshrrev_b32_e32 v139, 16, v36
	v_lshrrev_b32_e32 v36, 16, v116
	v_and_or_b32 v37, v89, s70, v37
	v_and_or_b32 v36, v138, s70, v36
	v_add_u32_e32 v88, 64, v88
	v_and_b32_sdwa v89, v44, v115 dst_sel:DWORD dst_unused:UNUSED_PAD src0_sel:WORD_1 src1_sel:DWORD
	v_and_b32_sdwa v116, v40, v115 dst_sel:DWORD dst_unused:UNUSED_PAD src0_sel:WORD_1 src1_sel:DWORD
	v_and_b32_sdwa v117, v45, v115 dst_sel:DWORD dst_unused:UNUSED_PAD src0_sel:WORD_1 src1_sel:DWORD
	v_and_b32_sdwa v118, v83, v115 dst_sel:DWORD dst_unused:UNUSED_PAD src0_sel:WORD_1 src1_sel:DWORD
	v_and_b32_sdwa v119, v82, v115 dst_sel:DWORD dst_unused:UNUSED_PAD src0_sel:WORD_1 src1_sel:DWORD
	v_add3_u32 v89, v44, v89, s69
	v_and_b32_sdwa v121, v80, v115 dst_sel:DWORD dst_unused:UNUSED_PAD src0_sel:WORD_1 src1_sel:DWORD
	v_and_b32_sdwa v122, v87, v115 dst_sel:DWORD dst_unused:UNUSED_PAD src0_sel:WORD_1 src1_sel:DWORD
	v_and_b32_sdwa v123, v86, v115 dst_sel:DWORD dst_unused:UNUSED_PAD src0_sel:WORD_1 src1_sel:DWORD
	v_and_b32_sdwa v120, v81, v115 dst_sel:DWORD dst_unused:UNUSED_PAD src0_sel:WORD_1 src1_sel:DWORD
	v_and_b32_sdwa v124, v41, v115 dst_sel:DWORD dst_unused:UNUSED_PAD src0_sel:WORD_1 src1_sel:DWORD
	v_add3_u32 v141, v40, v116, s69
	v_and_b32_sdwa v116, v85, v115 dst_sel:DWORD dst_unused:UNUSED_PAD src0_sel:WORD_1 src1_sel:DWORD
	v_and_b32_sdwa v125, v84, v115 dst_sel:DWORD dst_unused:UNUSED_PAD src0_sel:WORD_1 src1_sel:DWORD
	v_add3_u32 v117, v45, v117, s69
	v_add3_u32 v130, v83, v118, s69
	v_add3_u32 v119, v82, v119, s69
	v_add3_u32 v143, v80, v121, s69
	v_add3_u32 v121, v87, v122, s69
	v_add3_u32 v131, v86, v123, s69
	v_and_b32_sdwa v128, v47, v115 dst_sel:DWORD dst_unused:UNUSED_PAD src0_sel:WORD_1 src1_sel:DWORD
	v_and_b32_sdwa v129, v46, v115 dst_sel:DWORD dst_unused:UNUSED_PAD src0_sel:WORD_1 src1_sel:DWORD
	v_and_b32_e32 v118, 0xffff0000, v89
	v_add3_u32 v142, v81, v120, s69
	v_add3_u32 v144, v41, v124, s69
	v_add3_u32 v116, v85, v116, s69
	v_add3_u32 v132, v84, v125, s69
	v_and_b32_e32 v123, 0xffff0000, v130
	v_and_b32_e32 v122, 0xffff0000, v119
	v_and_b32_e32 v119, 0xffff0000, v117
	v_and_b32_e32 v125, 0xffff0000, v121
	v_and_b32_e32 v124, 0xffff0000, v131
	v_and_b32_sdwa v126, v43, v115 dst_sel:DWORD dst_unused:UNUSED_PAD src0_sel:WORD_1 src1_sel:DWORD
	v_and_b32_sdwa v127, v42, v115 dst_sel:DWORD dst_unused:UNUSED_PAD src0_sel:WORD_1 src1_sel:DWORD
	v_add3_u32 v133, v47, v128, s69
	v_add3_u32 v134, v46, v129, s69
	v_and_b32_e32 v129, 0xffff0000, v116
	v_or_b32_sdwa v116, v122, v89 dst_sel:DWORD dst_unused:UNUSED_PAD src0_sel:DWORD src1_sel:WORD_1
	v_pk_add_f32 v[44:45], v[44:45], v[118:119] neg_lo:[0,1] neg_hi:[0,1]
	v_or_b32_sdwa v117, v123, v117 dst_sel:DWORD dst_unused:UNUSED_PAD src0_sel:DWORD src1_sel:WORD_1
	v_or_b32_sdwa v118, v124, v143 dst_sel:DWORD dst_unused:UNUSED_PAD src0_sel:DWORD src1_sel:WORD_1
	v_or_b32_sdwa v119, v125, v142 dst_sel:DWORD dst_unused:UNUSED_PAD src0_sel:DWORD src1_sel:WORD_1
	v_add3_u32 v145, v43, v126, s69
	v_add3_u32 v146, v42, v127, s69
	v_and_b32_e32 v127, 0xffff0000, v142
	v_and_b32_e32 v126, 0xffff0000, v143
	v_and_b32_e32 v128, 0xffff0000, v132
	v_and_b32_e32 v131, 0xffff0000, v133
	v_and_b32_e32 v130, 0xffff0000, v134
	v_mfma_f32_32x32x16_bf16 v[0:15], v[32:35], v[116:119], v[0:15]
	v_add_f32_e64 v134, v82, -v122
	v_add_f32_e64 v135, v83, -v123
	v_add_f32_e64 v122, v80, -v126
	v_add_f32_e64 v123, v81, -v127
	v_or_b32_sdwa v80, v128, v141 dst_sel:DWORD dst_unused:UNUSED_PAD src0_sel:DWORD src1_sel:WORD_1
	v_or_b32_sdwa v81, v129, v144 dst_sel:DWORD dst_unused:UNUSED_PAD src0_sel:DWORD src1_sel:WORD_1
	v_or_b32_sdwa v82, v130, v146 dst_sel:DWORD dst_unused:UNUSED_PAD src0_sel:DWORD src1_sel:WORD_1
	v_or_b32_sdwa v83, v131, v145 dst_sel:DWORD dst_unused:UNUSED_PAD src0_sel:DWORD src1_sel:WORD_1
	v_and_b32_e32 v120, 0xffff0000, v141
	v_and_b32_e32 v121, 0xffff0000, v144
	v_mfma_f32_32x32x16_bf16 v[16:31], v[32:35], v[80:83], v[16:31]
	v_and_b32_e32 v133, 0xffff0000, v145
	v_and_b32_e32 v132, 0xffff0000, v146
	v_add_f32_e64 v86, v86, -v124
	v_add_f32_e64 v87, v87, -v125
	v_add_f32_e64 v40, v40, -v120
	v_add_f32_e64 v41, v41, -v121
	v_pk_add_f32 v[84:85], v[84:85], v[128:129] neg_lo:[0,1] neg_hi:[0,1]
	v_pk_add_f32 v[42:43], v[42:43], v[132:133] neg_lo:[0,1] neg_hi:[0,1]
	v_bfe_u32 v89, v87, 16, 1
	v_bfe_u32 v120, v86, 16, 1
	v_bfe_u32 v125, v122, 16, 1
	v_bfe_u32 v126, v123, 16, 1
	v_bfe_u32 v127, v44, 16, 1
	v_bfe_u32 v128, v45, 16, 1
	v_bfe_u32 v121, v135, 16, 1
	v_bfe_u32 v124, v134, 16, 1
	v_bfe_u32 v133, v42, 16, 1
	v_bfe_u32 v142, v40, 16, 1
	v_bfe_u32 v143, v41, 16, 1
	v_add3_u32 v86, v86, v120, s69
	v_add3_u32 v87, v87, v89, s69
	v_add3_u32 v89, v123, v126, s69
	v_add3_u32 v120, v122, v125, s69
	v_add3_u32 v45, v45, v128, s69
	v_add3_u32 v44, v44, v127, s69
	v_pk_add_f32 v[46:47], v[46:47], v[130:131] neg_lo:[0,1] neg_hi:[0,1]
	v_bfe_u32 v141, v43, 16, 1
	v_add3_u32 v124, v134, v124, s69
	v_add3_u32 v121, v135, v121, s69
	v_add3_u32 v42, v42, v133, s69
	v_add3_u32 v123, v41, v143, s69
	v_add3_u32 v125, v40, v142, s69
	v_lshrrev_b32_e32 v40, 16, v120
	v_lshrrev_b32_e32 v41, 16, v89
	v_lshrrev_b32_e32 v44, 16, v44
	v_lshrrev_b32_e32 v45, 16, v45
	v_bfe_u32 v129, v47, 16, 1
	v_bfe_u32 v130, v46, 16, 1
	v_bfe_u32 v131, v85, 16, 1
	v_bfe_u32 v132, v84, 16, 1
	v_add3_u32 v122, v43, v141, s69
	v_lshrrev_b32_e32 v89, 16, v42
	v_and_or_b32 v43, v87, s70, v41
	v_and_or_b32 v42, v86, s70, v40
	v_and_or_b32 v41, v121, s70, v45
	v_and_or_b32 v40, v124, s70, v44
	v_add3_u32 v84, v84, v132, s69
	v_add3_u32 v85, v85, v131, s69
	v_add3_u32 v46, v46, v130, s69
	v_add3_u32 v47, v47, v129, s69
	v_mfma_f32_32x32x16_bf16 v[0:15], v[32:35], v[40:43], v[0:15]
	v_lshrrev_b32_e32 v40, 16, v122
	v_lshrrev_b32_e32 v44, 16, v125
	v_lshrrev_b32_e32 v41, 16, v123
	v_and_or_b32 v43, v47, s70, v40
	v_and_or_b32 v42, v46, s70, v89
	v_and_or_b32 v41, v85, s70, v41
	v_and_or_b32 v40, v84, s70, v44
	s_nop 1
	v_mfma_f32_32x32x16_bf16 v[16:31], v[32:35], v[40:43], v[16:31]
	v_and_or_b32 v35, v137, s70, v140
	v_and_or_b32 v34, v136, s70, v139
	s_nop 1
	v_mfma_f32_32x32x16_bf16 v[0:15], v[34:37], v[116:119], v[0:15]
	v_mfma_f32_32x32x16_bf16 v[16:31], v[34:37], v[80:83], v[16:31]
	ds_read_b128 v[32:35], v88
	ds_read_b128 v[116:119], v88 offset:16
	s_waitcnt lgkmcnt(1)
	v_cndmask_b32_e64 v35, 0, v35, s[2:3]
	s_waitcnt lgkmcnt(0)
	v_cndmask_b32_e64 v119, 0, v119, s[2:3]
	v_and_b32_sdwa v89, v35, v115 dst_sel:DWORD dst_unused:UNUSED_PAD src0_sel:WORD_1 src1_sel:DWORD
	s_nop 0
	s_nop 0
	s_nop 0
	s_nop 0
	v_mov_b32_e32 v44, v180
	v_mov_b32_e32 v40, v181
	v_mov_b32_e32 v45, v182
	v_mov_b32_e32 v83, v183
	v_mov_b32_e32 v82, v184
	v_mov_b32_e32 v81, v185
	v_mov_b32_e32 v80, v186
	v_mov_b32_e32 v87, v187
	v_mov_b32_e32 v86, v188
	v_mov_b32_e32 v41, v189
	s_nop 0
	v_mov_b32_e32 v85, v190
	s_nop 0
	v_mov_b32_e32 v84, v191
	s_nop 0
	v_mov_b32_e32 v43, v192
	v_mov_b32_e32 v42, v193
	v_mov_b32_e32 v47, v194
	v_mov_b32_e32 v46, v195
	v_cndmask_b32_e64 v37, 0, v34, s[2:3]
	v_cndmask_b32_e64 v36, 0, v32, s[2:3]
	v_cndmask_b32_e64 v34, 0, v33, s[2:3]
	v_cndmask_b32_e64 v121, 0, v118, s[2:3]
	v_cndmask_b32_e64 v120, 0, v116, s[2:3]
	v_cndmask_b32_e64 v118, 0, v117, s[2:3]
	v_and_b32_sdwa v32, v37, v115 dst_sel:DWORD dst_unused:UNUSED_PAD src0_sel:WORD_1 src1_sel:DWORD
	v_and_b32_sdwa v33, v36, v115 dst_sel:DWORD dst_unused:UNUSED_PAD src0_sel:WORD_1 src1_sel:DWORD
	v_and_b32_sdwa v116, v34, v115 dst_sel:DWORD dst_unused:UNUSED_PAD src0_sel:WORD_1 src1_sel:DWORD
	v_and_b32_sdwa v117, v121, v115 dst_sel:DWORD dst_unused:UNUSED_PAD src0_sel:WORD_1 src1_sel:DWORD
	v_and_b32_sdwa v122, v120, v115 dst_sel:DWORD dst_unused:UNUSED_PAD src0_sel:WORD_1 src1_sel:DWORD
	v_and_b32_sdwa v123, v119, v115 dst_sel:DWORD dst_unused:UNUSED_PAD src0_sel:WORD_1 src1_sel:DWORD
	v_and_b32_sdwa v124, v118, v115 dst_sel:DWORD dst_unused:UNUSED_PAD src0_sel:WORD_1 src1_sel:DWORD
	v_add3_u32 v128, v37, v32, s69
	v_add3_u32 v32, v36, v33, s69
	v_add3_u32 v33, v35, v89, s69
	v_add3_u32 v89, v34, v116, s69
	v_add3_u32 v129, v121, v117, s69
	v_add3_u32 v130, v120, v122, s69
	v_add3_u32 v125, v119, v123, s69
	v_add3_u32 v124, v118, v124, s69
	v_and_b32_e32 v117, 0xffff0000, v33
	v_and_b32_e32 v116, 0xffff0000, v89
	v_and_b32_e32 v123, 0xffff0000, v128
	v_and_b32_e32 v122, 0xffff0000, v32
	v_and_b32_e32 v127, 0xffff0000, v129
	v_and_b32_e32 v126, 0xffff0000, v130
	v_and_b32_e32 v125, 0xffff0000, v125
	v_and_b32_e32 v124, 0xffff0000, v124
	v_or_b32_sdwa v32, v116, v32 dst_sel:DWORD dst_unused:UNUSED_PAD src0_sel:DWORD src1_sel:WORD_1
	v_pk_add_f32 v[36:37], v[36:37], v[122:123] neg_lo:[0,1] neg_hi:[0,1]
	v_pk_add_f32 v[122:123], v[34:35], v[116:117] neg_lo:[0,1] neg_hi:[0,1]
	v_or_b32_sdwa v33, v117, v128 dst_sel:DWORD dst_unused:UNUSED_PAD src0_sel:DWORD src1_sel:WORD_1
	v_pk_add_f32 v[116:117], v[120:121], v[126:127] neg_lo:[0,1] neg_hi:[0,1]
	v_pk_add_f32 v[118:119], v[118:119], v[124:125] neg_lo:[0,1] neg_hi:[0,1]
	v_bfe_u32 v126, v37, 16, 1
	v_bfe_u32 v128, v117, 16, 1
	v_or_b32_sdwa v35, v125, v129 dst_sel:DWORD dst_unused:UNUSED_PAD src0_sel:DWORD src1_sel:WORD_1
	v_bfe_u32 v89, v119, 16, 1
	v_bfe_u32 v125, v36, 16, 1
	v_bfe_u32 v127, v116, 16, 1
	v_add3_u32 v117, v117, v128, s69
	v_add3_u32 v37, v37, v126, s69
	v_or_b32_sdwa v34, v124, v130 dst_sel:DWORD dst_unused:UNUSED_PAD src0_sel:DWORD src1_sel:WORD_1
	v_bfe_u32 v120, v118, 16, 1
	v_bfe_u32 v121, v123, 16, 1
	v_bfe_u32 v124, v122, 16, 1
	v_add3_u32 v89, v119, v89, s69
	v_add3_u32 v116, v116, v127, s69
	v_add3_u32 v36, v36, v125, s69
	v_lshrrev_b32_e32 v140, 16, v37
	v_lshrrev_b32_e32 v37, 16, v117
	v_add3_u32 v136, v122, v124, s69
	v_add3_u32 v137, v123, v121, s69
	v_add3_u32 v138, v118, v120, s69
	v_lshrrev_b32_e32 v139, 16, v36
	v_lshrrev_b32_e32 v36, 16, v116
	v_and_or_b32 v37, v89, s70, v37
	v_and_or_b32 v36, v138, s70, v36
	v_add_u32_e32 v88, 64, v88
	v_and_b32_sdwa v89, v44, v115 dst_sel:DWORD dst_unused:UNUSED_PAD src0_sel:WORD_1 src1_sel:DWORD
	v_and_b32_sdwa v116, v40, v115 dst_sel:DWORD dst_unused:UNUSED_PAD src0_sel:WORD_1 src1_sel:DWORD
	v_and_b32_sdwa v117, v45, v115 dst_sel:DWORD dst_unused:UNUSED_PAD src0_sel:WORD_1 src1_sel:DWORD
	v_and_b32_sdwa v118, v83, v115 dst_sel:DWORD dst_unused:UNUSED_PAD src0_sel:WORD_1 src1_sel:DWORD
	v_and_b32_sdwa v119, v82, v115 dst_sel:DWORD dst_unused:UNUSED_PAD src0_sel:WORD_1 src1_sel:DWORD
	v_add3_u32 v89, v44, v89, s69
	v_and_b32_sdwa v121, v80, v115 dst_sel:DWORD dst_unused:UNUSED_PAD src0_sel:WORD_1 src1_sel:DWORD
	v_and_b32_sdwa v122, v87, v115 dst_sel:DWORD dst_unused:UNUSED_PAD src0_sel:WORD_1 src1_sel:DWORD
	v_and_b32_sdwa v123, v86, v115 dst_sel:DWORD dst_unused:UNUSED_PAD src0_sel:WORD_1 src1_sel:DWORD
	v_and_b32_sdwa v120, v81, v115 dst_sel:DWORD dst_unused:UNUSED_PAD src0_sel:WORD_1 src1_sel:DWORD
	v_and_b32_sdwa v124, v41, v115 dst_sel:DWORD dst_unused:UNUSED_PAD src0_sel:WORD_1 src1_sel:DWORD
	v_add3_u32 v141, v40, v116, s69
	v_and_b32_sdwa v116, v85, v115 dst_sel:DWORD dst_unused:UNUSED_PAD src0_sel:WORD_1 src1_sel:DWORD
	v_and_b32_sdwa v125, v84, v115 dst_sel:DWORD dst_unused:UNUSED_PAD src0_sel:WORD_1 src1_sel:DWORD
	v_add3_u32 v117, v45, v117, s69
	v_add3_u32 v130, v83, v118, s69
	v_add3_u32 v119, v82, v119, s69
	v_add3_u32 v143, v80, v121, s69
	v_add3_u32 v121, v87, v122, s69
	v_add3_u32 v131, v86, v123, s69
	v_and_b32_sdwa v128, v47, v115 dst_sel:DWORD dst_unused:UNUSED_PAD src0_sel:WORD_1 src1_sel:DWORD
	v_and_b32_sdwa v129, v46, v115 dst_sel:DWORD dst_unused:UNUSED_PAD src0_sel:WORD_1 src1_sel:DWORD
	v_and_b32_e32 v118, 0xffff0000, v89
	v_add3_u32 v142, v81, v120, s69
	v_add3_u32 v144, v41, v124, s69
	v_add3_u32 v116, v85, v116, s69
	v_add3_u32 v132, v84, v125, s69
	v_and_b32_e32 v123, 0xffff0000, v130
	v_and_b32_e32 v122, 0xffff0000, v119
	v_and_b32_e32 v119, 0xffff0000, v117
	v_and_b32_e32 v125, 0xffff0000, v121
	v_and_b32_e32 v124, 0xffff0000, v131
	v_and_b32_sdwa v126, v43, v115 dst_sel:DWORD dst_unused:UNUSED_PAD src0_sel:WORD_1 src1_sel:DWORD
	v_and_b32_sdwa v127, v42, v115 dst_sel:DWORD dst_unused:UNUSED_PAD src0_sel:WORD_1 src1_sel:DWORD
	v_add3_u32 v133, v47, v128, s69
	v_add3_u32 v134, v46, v129, s69
	v_and_b32_e32 v129, 0xffff0000, v116
	v_or_b32_sdwa v116, v122, v89 dst_sel:DWORD dst_unused:UNUSED_PAD src0_sel:DWORD src1_sel:WORD_1
	v_pk_add_f32 v[44:45], v[44:45], v[118:119] neg_lo:[0,1] neg_hi:[0,1]
	v_or_b32_sdwa v117, v123, v117 dst_sel:DWORD dst_unused:UNUSED_PAD src0_sel:DWORD src1_sel:WORD_1
	v_or_b32_sdwa v118, v124, v143 dst_sel:DWORD dst_unused:UNUSED_PAD src0_sel:DWORD src1_sel:WORD_1
	v_or_b32_sdwa v119, v125, v142 dst_sel:DWORD dst_unused:UNUSED_PAD src0_sel:DWORD src1_sel:WORD_1
	v_add3_u32 v145, v43, v126, s69
	v_add3_u32 v146, v42, v127, s69
	v_and_b32_e32 v127, 0xffff0000, v142
	v_and_b32_e32 v126, 0xffff0000, v143
	v_and_b32_e32 v128, 0xffff0000, v132
	v_and_b32_e32 v131, 0xffff0000, v133
	v_and_b32_e32 v130, 0xffff0000, v134
	v_mfma_f32_32x32x16_bf16 v[0:15], v[32:35], v[116:119], v[0:15]
	v_add_f32_e64 v134, v82, -v122
	v_add_f32_e64 v135, v83, -v123
	v_add_f32_e64 v122, v80, -v126
	v_add_f32_e64 v123, v81, -v127
	v_or_b32_sdwa v80, v128, v141 dst_sel:DWORD dst_unused:UNUSED_PAD src0_sel:DWORD src1_sel:WORD_1
	v_or_b32_sdwa v81, v129, v144 dst_sel:DWORD dst_unused:UNUSED_PAD src0_sel:DWORD src1_sel:WORD_1
	v_or_b32_sdwa v82, v130, v146 dst_sel:DWORD dst_unused:UNUSED_PAD src0_sel:DWORD src1_sel:WORD_1
	v_or_b32_sdwa v83, v131, v145 dst_sel:DWORD dst_unused:UNUSED_PAD src0_sel:DWORD src1_sel:WORD_1
	v_and_b32_e32 v120, 0xffff0000, v141
	v_and_b32_e32 v121, 0xffff0000, v144
	v_mfma_f32_32x32x16_bf16 v[16:31], v[32:35], v[80:83], v[16:31]
	v_and_b32_e32 v133, 0xffff0000, v145
	v_and_b32_e32 v132, 0xffff0000, v146
	v_add_f32_e64 v86, v86, -v124
	v_add_f32_e64 v87, v87, -v125
	v_add_f32_e64 v40, v40, -v120
	v_add_f32_e64 v41, v41, -v121
	v_pk_add_f32 v[84:85], v[84:85], v[128:129] neg_lo:[0,1] neg_hi:[0,1]
	v_pk_add_f32 v[42:43], v[42:43], v[132:133] neg_lo:[0,1] neg_hi:[0,1]
	v_bfe_u32 v89, v87, 16, 1
	v_bfe_u32 v120, v86, 16, 1
	v_bfe_u32 v125, v122, 16, 1
	v_bfe_u32 v126, v123, 16, 1
	v_bfe_u32 v127, v44, 16, 1
	v_bfe_u32 v128, v45, 16, 1
	v_bfe_u32 v121, v135, 16, 1
	v_bfe_u32 v124, v134, 16, 1
	v_bfe_u32 v133, v42, 16, 1
	v_bfe_u32 v142, v40, 16, 1
	v_bfe_u32 v143, v41, 16, 1
	v_add3_u32 v86, v86, v120, s69
	v_add3_u32 v87, v87, v89, s69
	v_add3_u32 v89, v123, v126, s69
	v_add3_u32 v120, v122, v125, s69
	v_add3_u32 v45, v45, v128, s69
	v_add3_u32 v44, v44, v127, s69
	v_pk_add_f32 v[46:47], v[46:47], v[130:131] neg_lo:[0,1] neg_hi:[0,1]
	v_bfe_u32 v141, v43, 16, 1
	v_add3_u32 v124, v134, v124, s69
	v_add3_u32 v121, v135, v121, s69
	v_add3_u32 v42, v42, v133, s69
	v_add3_u32 v123, v41, v143, s69
	v_add3_u32 v125, v40, v142, s69
	v_lshrrev_b32_e32 v40, 16, v120
	v_lshrrev_b32_e32 v41, 16, v89
	v_lshrrev_b32_e32 v44, 16, v44
	v_lshrrev_b32_e32 v45, 16, v45
	v_bfe_u32 v129, v47, 16, 1
	v_bfe_u32 v130, v46, 16, 1
	v_bfe_u32 v131, v85, 16, 1
	v_bfe_u32 v132, v84, 16, 1
	v_add3_u32 v122, v43, v141, s69
	v_lshrrev_b32_e32 v89, 16, v42
	v_and_or_b32 v43, v87, s70, v41
	v_and_or_b32 v42, v86, s70, v40
	v_and_or_b32 v41, v121, s70, v45
	v_and_or_b32 v40, v124, s70, v44
	v_add3_u32 v84, v84, v132, s69
	v_add3_u32 v85, v85, v131, s69
	v_add3_u32 v46, v46, v130, s69
	v_add3_u32 v47, v47, v129, s69
	v_mfma_f32_32x32x16_bf16 v[0:15], v[32:35], v[40:43], v[0:15]
	v_lshrrev_b32_e32 v40, 16, v122
	v_lshrrev_b32_e32 v44, 16, v125
	v_lshrrev_b32_e32 v41, 16, v123
	v_and_or_b32 v43, v47, s70, v40
	v_and_or_b32 v42, v46, s70, v89
	v_and_or_b32 v41, v85, s70, v41
	v_and_or_b32 v40, v84, s70, v44
	s_nop 1
	v_mfma_f32_32x32x16_bf16 v[16:31], v[32:35], v[40:43], v[16:31]
	v_and_or_b32 v35, v137, s70, v140
	v_and_or_b32 v34, v136, s70, v139
	s_nop 1
	v_mfma_f32_32x32x16_bf16 v[0:15], v[34:37], v[116:119], v[0:15]
	v_mfma_f32_32x32x16_bf16 v[16:31], v[34:37], v[80:83], v[16:31]
	ds_read_b128 v[32:35], v88
	ds_read_b128 v[116:119], v88 offset:16
	s_waitcnt lgkmcnt(1)
	v_cndmask_b32_e64 v35, 0, v35, s[2:3]
	s_waitcnt lgkmcnt(0)
	v_cndmask_b32_e64 v119, 0, v119, s[2:3]
	v_and_b32_sdwa v89, v35, v115 dst_sel:DWORD dst_unused:UNUSED_PAD src0_sel:WORD_1 src1_sel:DWORD
	s_nop 0
	s_nop 0
	s_nop 0
	s_nop 0
	v_mov_b32_e32 v44, v196
	v_mov_b32_e32 v40, v197
	v_mov_b32_e32 v45, v198
	v_mov_b32_e32 v83, v199
	v_mov_b32_e32 v82, v200
	v_mov_b32_e32 v81, v201
	v_mov_b32_e32 v80, v202
	v_mov_b32_e32 v87, v203
	v_mov_b32_e32 v86, v204
	v_mov_b32_e32 v41, v205
	s_nop 0
	v_mov_b32_e32 v85, v206
	s_nop 0
	v_mov_b32_e32 v84, v207
	s_nop 0
	v_mov_b32_e32 v43, v208
	v_mov_b32_e32 v42, v209
	v_mov_b32_e32 v47, v210
	v_mov_b32_e32 v46, v211
	v_cndmask_b32_e64 v37, 0, v34, s[2:3]
	v_cndmask_b32_e64 v36, 0, v32, s[2:3]
	v_cndmask_b32_e64 v34, 0, v33, s[2:3]
	v_cndmask_b32_e64 v121, 0, v118, s[2:3]
	v_cndmask_b32_e64 v120, 0, v116, s[2:3]
	v_cndmask_b32_e64 v118, 0, v117, s[2:3]
	v_and_b32_sdwa v32, v37, v115 dst_sel:DWORD dst_unused:UNUSED_PAD src0_sel:WORD_1 src1_sel:DWORD
	v_and_b32_sdwa v33, v36, v115 dst_sel:DWORD dst_unused:UNUSED_PAD src0_sel:WORD_1 src1_sel:DWORD
	v_and_b32_sdwa v116, v34, v115 dst_sel:DWORD dst_unused:UNUSED_PAD src0_sel:WORD_1 src1_sel:DWORD
	v_and_b32_sdwa v117, v121, v115 dst_sel:DWORD dst_unused:UNUSED_PAD src0_sel:WORD_1 src1_sel:DWORD
	v_and_b32_sdwa v122, v120, v115 dst_sel:DWORD dst_unused:UNUSED_PAD src0_sel:WORD_1 src1_sel:DWORD
	v_and_b32_sdwa v123, v119, v115 dst_sel:DWORD dst_unused:UNUSED_PAD src0_sel:WORD_1 src1_sel:DWORD
	v_and_b32_sdwa v124, v118, v115 dst_sel:DWORD dst_unused:UNUSED_PAD src0_sel:WORD_1 src1_sel:DWORD
	v_add3_u32 v128, v37, v32, s69
	v_add3_u32 v32, v36, v33, s69
	v_add3_u32 v33, v35, v89, s69
	v_add3_u32 v89, v34, v116, s69
	v_add3_u32 v129, v121, v117, s69
	v_add3_u32 v130, v120, v122, s69
	v_add3_u32 v125, v119, v123, s69
	v_add3_u32 v124, v118, v124, s69
	v_and_b32_e32 v117, 0xffff0000, v33
	v_and_b32_e32 v116, 0xffff0000, v89
	v_and_b32_e32 v123, 0xffff0000, v128
	v_and_b32_e32 v122, 0xffff0000, v32
	v_and_b32_e32 v127, 0xffff0000, v129
	v_and_b32_e32 v126, 0xffff0000, v130
	v_and_b32_e32 v125, 0xffff0000, v125
	v_and_b32_e32 v124, 0xffff0000, v124
	v_or_b32_sdwa v32, v116, v32 dst_sel:DWORD dst_unused:UNUSED_PAD src0_sel:DWORD src1_sel:WORD_1
	v_pk_add_f32 v[36:37], v[36:37], v[122:123] neg_lo:[0,1] neg_hi:[0,1]
	v_pk_add_f32 v[122:123], v[34:35], v[116:117] neg_lo:[0,1] neg_hi:[0,1]
	v_or_b32_sdwa v33, v117, v128 dst_sel:DWORD dst_unused:UNUSED_PAD src0_sel:DWORD src1_sel:WORD_1
	v_pk_add_f32 v[116:117], v[120:121], v[126:127] neg_lo:[0,1] neg_hi:[0,1]
	v_pk_add_f32 v[118:119], v[118:119], v[124:125] neg_lo:[0,1] neg_hi:[0,1]
	v_bfe_u32 v126, v37, 16, 1
	v_bfe_u32 v128, v117, 16, 1
	v_or_b32_sdwa v35, v125, v129 dst_sel:DWORD dst_unused:UNUSED_PAD src0_sel:DWORD src1_sel:WORD_1
	v_bfe_u32 v89, v119, 16, 1
	v_bfe_u32 v125, v36, 16, 1
	v_bfe_u32 v127, v116, 16, 1
	v_add3_u32 v117, v117, v128, s69
	v_add3_u32 v37, v37, v126, s69
	v_or_b32_sdwa v34, v124, v130 dst_sel:DWORD dst_unused:UNUSED_PAD src0_sel:DWORD src1_sel:WORD_1
	v_bfe_u32 v120, v118, 16, 1
	v_bfe_u32 v121, v123, 16, 1
	v_bfe_u32 v124, v122, 16, 1
	v_add3_u32 v89, v119, v89, s69
	v_add3_u32 v116, v116, v127, s69
	v_add3_u32 v36, v36, v125, s69
	v_lshrrev_b32_e32 v140, 16, v37
	v_lshrrev_b32_e32 v37, 16, v117
	v_add3_u32 v136, v122, v124, s69
	v_add3_u32 v137, v123, v121, s69
	v_add3_u32 v138, v118, v120, s69
	v_lshrrev_b32_e32 v139, 16, v36
	v_lshrrev_b32_e32 v36, 16, v116
	v_and_or_b32 v37, v89, s70, v37
	v_and_or_b32 v36, v138, s70, v36
	v_add_u32_e32 v88, 64, v88
	v_and_b32_sdwa v89, v44, v115 dst_sel:DWORD dst_unused:UNUSED_PAD src0_sel:WORD_1 src1_sel:DWORD
	v_and_b32_sdwa v116, v40, v115 dst_sel:DWORD dst_unused:UNUSED_PAD src0_sel:WORD_1 src1_sel:DWORD
	v_and_b32_sdwa v117, v45, v115 dst_sel:DWORD dst_unused:UNUSED_PAD src0_sel:WORD_1 src1_sel:DWORD
	v_and_b32_sdwa v118, v83, v115 dst_sel:DWORD dst_unused:UNUSED_PAD src0_sel:WORD_1 src1_sel:DWORD
	v_and_b32_sdwa v119, v82, v115 dst_sel:DWORD dst_unused:UNUSED_PAD src0_sel:WORD_1 src1_sel:DWORD
	v_add3_u32 v89, v44, v89, s69
	v_and_b32_sdwa v121, v80, v115 dst_sel:DWORD dst_unused:UNUSED_PAD src0_sel:WORD_1 src1_sel:DWORD
	v_and_b32_sdwa v122, v87, v115 dst_sel:DWORD dst_unused:UNUSED_PAD src0_sel:WORD_1 src1_sel:DWORD
	v_and_b32_sdwa v123, v86, v115 dst_sel:DWORD dst_unused:UNUSED_PAD src0_sel:WORD_1 src1_sel:DWORD
	v_and_b32_sdwa v120, v81, v115 dst_sel:DWORD dst_unused:UNUSED_PAD src0_sel:WORD_1 src1_sel:DWORD
	v_and_b32_sdwa v124, v41, v115 dst_sel:DWORD dst_unused:UNUSED_PAD src0_sel:WORD_1 src1_sel:DWORD
	v_add3_u32 v141, v40, v116, s69
	v_and_b32_sdwa v116, v85, v115 dst_sel:DWORD dst_unused:UNUSED_PAD src0_sel:WORD_1 src1_sel:DWORD
	v_and_b32_sdwa v125, v84, v115 dst_sel:DWORD dst_unused:UNUSED_PAD src0_sel:WORD_1 src1_sel:DWORD
	v_add3_u32 v117, v45, v117, s69
	v_add3_u32 v130, v83, v118, s69
	v_add3_u32 v119, v82, v119, s69
	v_add3_u32 v143, v80, v121, s69
	v_add3_u32 v121, v87, v122, s69
	v_add3_u32 v131, v86, v123, s69
	v_and_b32_sdwa v128, v47, v115 dst_sel:DWORD dst_unused:UNUSED_PAD src0_sel:WORD_1 src1_sel:DWORD
	v_and_b32_sdwa v129, v46, v115 dst_sel:DWORD dst_unused:UNUSED_PAD src0_sel:WORD_1 src1_sel:DWORD
	v_and_b32_e32 v118, 0xffff0000, v89
	v_add3_u32 v142, v81, v120, s69
	v_add3_u32 v144, v41, v124, s69
	v_add3_u32 v116, v85, v116, s69
	v_add3_u32 v132, v84, v125, s69
	v_and_b32_e32 v123, 0xffff0000, v130
	v_and_b32_e32 v122, 0xffff0000, v119
	v_and_b32_e32 v119, 0xffff0000, v117
	v_and_b32_e32 v125, 0xffff0000, v121
	v_and_b32_e32 v124, 0xffff0000, v131
	v_and_b32_sdwa v126, v43, v115 dst_sel:DWORD dst_unused:UNUSED_PAD src0_sel:WORD_1 src1_sel:DWORD
	v_and_b32_sdwa v127, v42, v115 dst_sel:DWORD dst_unused:UNUSED_PAD src0_sel:WORD_1 src1_sel:DWORD
	v_add3_u32 v133, v47, v128, s69
	v_add3_u32 v134, v46, v129, s69
	v_and_b32_e32 v129, 0xffff0000, v116
	v_or_b32_sdwa v116, v122, v89 dst_sel:DWORD dst_unused:UNUSED_PAD src0_sel:DWORD src1_sel:WORD_1
	v_pk_add_f32 v[44:45], v[44:45], v[118:119] neg_lo:[0,1] neg_hi:[0,1]
	v_or_b32_sdwa v117, v123, v117 dst_sel:DWORD dst_unused:UNUSED_PAD src0_sel:DWORD src1_sel:WORD_1
	v_or_b32_sdwa v118, v124, v143 dst_sel:DWORD dst_unused:UNUSED_PAD src0_sel:DWORD src1_sel:WORD_1
	v_or_b32_sdwa v119, v125, v142 dst_sel:DWORD dst_unused:UNUSED_PAD src0_sel:DWORD src1_sel:WORD_1
	v_add3_u32 v145, v43, v126, s69
	v_add3_u32 v146, v42, v127, s69
	v_and_b32_e32 v127, 0xffff0000, v142
	v_and_b32_e32 v126, 0xffff0000, v143
	v_and_b32_e32 v128, 0xffff0000, v132
	v_and_b32_e32 v131, 0xffff0000, v133
	v_and_b32_e32 v130, 0xffff0000, v134
	v_mfma_f32_32x32x16_bf16 v[0:15], v[32:35], v[116:119], v[0:15]
	v_add_f32_e64 v134, v82, -v122
	v_add_f32_e64 v135, v83, -v123
	v_add_f32_e64 v122, v80, -v126
	v_add_f32_e64 v123, v81, -v127
	v_or_b32_sdwa v80, v128, v141 dst_sel:DWORD dst_unused:UNUSED_PAD src0_sel:DWORD src1_sel:WORD_1
	v_or_b32_sdwa v81, v129, v144 dst_sel:DWORD dst_unused:UNUSED_PAD src0_sel:DWORD src1_sel:WORD_1
	v_or_b32_sdwa v82, v130, v146 dst_sel:DWORD dst_unused:UNUSED_PAD src0_sel:DWORD src1_sel:WORD_1
	v_or_b32_sdwa v83, v131, v145 dst_sel:DWORD dst_unused:UNUSED_PAD src0_sel:DWORD src1_sel:WORD_1
	v_and_b32_e32 v120, 0xffff0000, v141
	v_and_b32_e32 v121, 0xffff0000, v144
	v_mfma_f32_32x32x16_bf16 v[16:31], v[32:35], v[80:83], v[16:31]
	v_and_b32_e32 v133, 0xffff0000, v145
	v_and_b32_e32 v132, 0xffff0000, v146
	v_add_f32_e64 v86, v86, -v124
	v_add_f32_e64 v87, v87, -v125
	v_add_f32_e64 v40, v40, -v120
	v_add_f32_e64 v41, v41, -v121
	v_pk_add_f32 v[84:85], v[84:85], v[128:129] neg_lo:[0,1] neg_hi:[0,1]
	v_pk_add_f32 v[42:43], v[42:43], v[132:133] neg_lo:[0,1] neg_hi:[0,1]
	v_bfe_u32 v89, v87, 16, 1
	v_bfe_u32 v120, v86, 16, 1
	v_bfe_u32 v125, v122, 16, 1
	v_bfe_u32 v126, v123, 16, 1
	v_bfe_u32 v127, v44, 16, 1
	v_bfe_u32 v128, v45, 16, 1
	v_bfe_u32 v121, v135, 16, 1
	v_bfe_u32 v124, v134, 16, 1
	v_bfe_u32 v133, v42, 16, 1
	v_bfe_u32 v142, v40, 16, 1
	v_bfe_u32 v143, v41, 16, 1
	v_add3_u32 v86, v86, v120, s69
	v_add3_u32 v87, v87, v89, s69
	v_add3_u32 v89, v123, v126, s69
	v_add3_u32 v120, v122, v125, s69
	v_add3_u32 v45, v45, v128, s69
	v_add3_u32 v44, v44, v127, s69
	v_pk_add_f32 v[46:47], v[46:47], v[130:131] neg_lo:[0,1] neg_hi:[0,1]
	v_bfe_u32 v141, v43, 16, 1
	v_add3_u32 v124, v134, v124, s69
	v_add3_u32 v121, v135, v121, s69
	v_add3_u32 v42, v42, v133, s69
	v_add3_u32 v123, v41, v143, s69
	v_add3_u32 v125, v40, v142, s69
	v_lshrrev_b32_e32 v40, 16, v120
	v_lshrrev_b32_e32 v41, 16, v89
	v_lshrrev_b32_e32 v44, 16, v44
	v_lshrrev_b32_e32 v45, 16, v45
	v_bfe_u32 v129, v47, 16, 1
	v_bfe_u32 v130, v46, 16, 1
	v_bfe_u32 v131, v85, 16, 1
	v_bfe_u32 v132, v84, 16, 1
	v_add3_u32 v122, v43, v141, s69
	v_lshrrev_b32_e32 v89, 16, v42
	v_and_or_b32 v43, v87, s70, v41
	v_and_or_b32 v42, v86, s70, v40
	v_and_or_b32 v41, v121, s70, v45
	v_and_or_b32 v40, v124, s70, v44
	v_add3_u32 v84, v84, v132, s69
	v_add3_u32 v85, v85, v131, s69
	v_add3_u32 v46, v46, v130, s69
	v_add3_u32 v47, v47, v129, s69
	v_mfma_f32_32x32x16_bf16 v[0:15], v[32:35], v[40:43], v[0:15]
	v_lshrrev_b32_e32 v40, 16, v122
	v_lshrrev_b32_e32 v44, 16, v125
	v_lshrrev_b32_e32 v41, 16, v123
	v_and_or_b32 v43, v47, s70, v40
	v_and_or_b32 v42, v46, s70, v89
	v_and_or_b32 v41, v85, s70, v41
	v_and_or_b32 v40, v84, s70, v44
	s_nop 1
	v_mfma_f32_32x32x16_bf16 v[16:31], v[32:35], v[40:43], v[16:31]
	v_and_or_b32 v35, v137, s70, v140
	v_and_or_b32 v34, v136, s70, v139
	s_nop 1
	v_mfma_f32_32x32x16_bf16 v[0:15], v[34:37], v[116:119], v[0:15]
	v_mfma_f32_32x32x16_bf16 v[16:31], v[34:37], v[80:83], v[16:31]
	ds_read_b128 v[32:35], v88
	ds_read_b128 v[116:119], v88 offset:16
	s_waitcnt lgkmcnt(1)
	v_cndmask_b32_e64 v35, 0, v35, s[2:3]
	s_waitcnt lgkmcnt(0)
	v_cndmask_b32_e64 v119, 0, v119, s[2:3]
	v_and_b32_sdwa v89, v35, v115 dst_sel:DWORD dst_unused:UNUSED_PAD src0_sel:WORD_1 src1_sel:DWORD
	s_nop 0
	s_nop 0
	s_nop 0
	s_nop 0
	v_mov_b32_e32 v44, v212
	v_mov_b32_e32 v40, v213
	v_mov_b32_e32 v45, v214
	v_mov_b32_e32 v83, v215
	v_mov_b32_e32 v82, v216
	v_mov_b32_e32 v81, v217
	v_mov_b32_e32 v80, v218
	v_mov_b32_e32 v87, v219
	v_mov_b32_e32 v86, v220
	v_mov_b32_e32 v41, v221
	s_nop 0
	v_mov_b32_e32 v85, v222
	s_nop 0
	v_mov_b32_e32 v84, v223
	s_nop 0
	v_mov_b32_e32 v43, v224
	v_mov_b32_e32 v42, v225
	v_mov_b32_e32 v47, v226
	v_mov_b32_e32 v46, v227
	v_cndmask_b32_e64 v37, 0, v34, s[2:3]
	v_cndmask_b32_e64 v36, 0, v32, s[2:3]
	v_cndmask_b32_e64 v34, 0, v33, s[2:3]
	v_cndmask_b32_e64 v121, 0, v118, s[2:3]
	v_cndmask_b32_e64 v120, 0, v116, s[2:3]
	v_cndmask_b32_e64 v118, 0, v117, s[2:3]
	v_and_b32_sdwa v32, v37, v115 dst_sel:DWORD dst_unused:UNUSED_PAD src0_sel:WORD_1 src1_sel:DWORD
	v_and_b32_sdwa v33, v36, v115 dst_sel:DWORD dst_unused:UNUSED_PAD src0_sel:WORD_1 src1_sel:DWORD
	v_and_b32_sdwa v116, v34, v115 dst_sel:DWORD dst_unused:UNUSED_PAD src0_sel:WORD_1 src1_sel:DWORD
	v_and_b32_sdwa v117, v121, v115 dst_sel:DWORD dst_unused:UNUSED_PAD src0_sel:WORD_1 src1_sel:DWORD
	v_and_b32_sdwa v122, v120, v115 dst_sel:DWORD dst_unused:UNUSED_PAD src0_sel:WORD_1 src1_sel:DWORD
	v_and_b32_sdwa v123, v119, v115 dst_sel:DWORD dst_unused:UNUSED_PAD src0_sel:WORD_1 src1_sel:DWORD
	v_and_b32_sdwa v124, v118, v115 dst_sel:DWORD dst_unused:UNUSED_PAD src0_sel:WORD_1 src1_sel:DWORD
	v_add3_u32 v128, v37, v32, s69
	v_add3_u32 v32, v36, v33, s69
	v_add3_u32 v33, v35, v89, s69
	v_add3_u32 v89, v34, v116, s69
	v_add3_u32 v129, v121, v117, s69
	v_add3_u32 v130, v120, v122, s69
	v_add3_u32 v125, v119, v123, s69
	v_add3_u32 v124, v118, v124, s69
	v_and_b32_e32 v117, 0xffff0000, v33
	v_and_b32_e32 v116, 0xffff0000, v89
	v_and_b32_e32 v123, 0xffff0000, v128
	v_and_b32_e32 v122, 0xffff0000, v32
	v_and_b32_e32 v127, 0xffff0000, v129
	v_and_b32_e32 v126, 0xffff0000, v130
	v_and_b32_e32 v125, 0xffff0000, v125
	v_and_b32_e32 v124, 0xffff0000, v124
	v_or_b32_sdwa v32, v116, v32 dst_sel:DWORD dst_unused:UNUSED_PAD src0_sel:DWORD src1_sel:WORD_1
	v_pk_add_f32 v[36:37], v[36:37], v[122:123] neg_lo:[0,1] neg_hi:[0,1]
	v_pk_add_f32 v[122:123], v[34:35], v[116:117] neg_lo:[0,1] neg_hi:[0,1]
	v_or_b32_sdwa v33, v117, v128 dst_sel:DWORD dst_unused:UNUSED_PAD src0_sel:DWORD src1_sel:WORD_1
	v_pk_add_f32 v[116:117], v[120:121], v[126:127] neg_lo:[0,1] neg_hi:[0,1]
	v_pk_add_f32 v[118:119], v[118:119], v[124:125] neg_lo:[0,1] neg_hi:[0,1]
	v_bfe_u32 v126, v37, 16, 1
	v_bfe_u32 v128, v117, 16, 1
	v_or_b32_sdwa v35, v125, v129 dst_sel:DWORD dst_unused:UNUSED_PAD src0_sel:DWORD src1_sel:WORD_1
	v_bfe_u32 v89, v119, 16, 1
	v_bfe_u32 v125, v36, 16, 1
	v_bfe_u32 v127, v116, 16, 1
	v_add3_u32 v117, v117, v128, s69
	v_add3_u32 v37, v37, v126, s69
	v_or_b32_sdwa v34, v124, v130 dst_sel:DWORD dst_unused:UNUSED_PAD src0_sel:DWORD src1_sel:WORD_1
	v_bfe_u32 v120, v118, 16, 1
	v_bfe_u32 v121, v123, 16, 1
	v_bfe_u32 v124, v122, 16, 1
	v_add3_u32 v89, v119, v89, s69
	v_add3_u32 v116, v116, v127, s69
	v_add3_u32 v36, v36, v125, s69
	v_lshrrev_b32_e32 v140, 16, v37
	v_lshrrev_b32_e32 v37, 16, v117
	v_add3_u32 v136, v122, v124, s69
	v_add3_u32 v137, v123, v121, s69
	v_add3_u32 v138, v118, v120, s69
	v_lshrrev_b32_e32 v139, 16, v36
	v_lshrrev_b32_e32 v36, 16, v116
	v_and_or_b32 v37, v89, s70, v37
	v_and_or_b32 v36, v138, s70, v36
	v_add_u32_e32 v88, 64, v88
	v_and_b32_sdwa v89, v44, v115 dst_sel:DWORD dst_unused:UNUSED_PAD src0_sel:WORD_1 src1_sel:DWORD
	v_and_b32_sdwa v116, v40, v115 dst_sel:DWORD dst_unused:UNUSED_PAD src0_sel:WORD_1 src1_sel:DWORD
	v_and_b32_sdwa v117, v45, v115 dst_sel:DWORD dst_unused:UNUSED_PAD src0_sel:WORD_1 src1_sel:DWORD
	v_and_b32_sdwa v118, v83, v115 dst_sel:DWORD dst_unused:UNUSED_PAD src0_sel:WORD_1 src1_sel:DWORD
	v_and_b32_sdwa v119, v82, v115 dst_sel:DWORD dst_unused:UNUSED_PAD src0_sel:WORD_1 src1_sel:DWORD
	v_add3_u32 v89, v44, v89, s69
	v_and_b32_sdwa v121, v80, v115 dst_sel:DWORD dst_unused:UNUSED_PAD src0_sel:WORD_1 src1_sel:DWORD
	v_and_b32_sdwa v122, v87, v115 dst_sel:DWORD dst_unused:UNUSED_PAD src0_sel:WORD_1 src1_sel:DWORD
	v_and_b32_sdwa v123, v86, v115 dst_sel:DWORD dst_unused:UNUSED_PAD src0_sel:WORD_1 src1_sel:DWORD
	v_and_b32_sdwa v120, v81, v115 dst_sel:DWORD dst_unused:UNUSED_PAD src0_sel:WORD_1 src1_sel:DWORD
	v_and_b32_sdwa v124, v41, v115 dst_sel:DWORD dst_unused:UNUSED_PAD src0_sel:WORD_1 src1_sel:DWORD
	v_add3_u32 v141, v40, v116, s69
	v_and_b32_sdwa v116, v85, v115 dst_sel:DWORD dst_unused:UNUSED_PAD src0_sel:WORD_1 src1_sel:DWORD
	v_and_b32_sdwa v125, v84, v115 dst_sel:DWORD dst_unused:UNUSED_PAD src0_sel:WORD_1 src1_sel:DWORD
	v_add3_u32 v117, v45, v117, s69
	v_add3_u32 v130, v83, v118, s69
	v_add3_u32 v119, v82, v119, s69
	v_add3_u32 v143, v80, v121, s69
	v_add3_u32 v121, v87, v122, s69
	v_add3_u32 v131, v86, v123, s69
	v_and_b32_sdwa v128, v47, v115 dst_sel:DWORD dst_unused:UNUSED_PAD src0_sel:WORD_1 src1_sel:DWORD
	v_and_b32_sdwa v129, v46, v115 dst_sel:DWORD dst_unused:UNUSED_PAD src0_sel:WORD_1 src1_sel:DWORD
	v_and_b32_e32 v118, 0xffff0000, v89
	v_add3_u32 v142, v81, v120, s69
	v_add3_u32 v144, v41, v124, s69
	v_add3_u32 v116, v85, v116, s69
	v_add3_u32 v132, v84, v125, s69
	v_and_b32_e32 v123, 0xffff0000, v130
	v_and_b32_e32 v122, 0xffff0000, v119
	v_and_b32_e32 v119, 0xffff0000, v117
	v_and_b32_e32 v125, 0xffff0000, v121
	v_and_b32_e32 v124, 0xffff0000, v131
	v_and_b32_sdwa v126, v43, v115 dst_sel:DWORD dst_unused:UNUSED_PAD src0_sel:WORD_1 src1_sel:DWORD
	v_and_b32_sdwa v127, v42, v115 dst_sel:DWORD dst_unused:UNUSED_PAD src0_sel:WORD_1 src1_sel:DWORD
	v_add3_u32 v133, v47, v128, s69
	v_add3_u32 v134, v46, v129, s69
	v_and_b32_e32 v129, 0xffff0000, v116
	v_or_b32_sdwa v116, v122, v89 dst_sel:DWORD dst_unused:UNUSED_PAD src0_sel:DWORD src1_sel:WORD_1
	v_pk_add_f32 v[44:45], v[44:45], v[118:119] neg_lo:[0,1] neg_hi:[0,1]
	v_or_b32_sdwa v117, v123, v117 dst_sel:DWORD dst_unused:UNUSED_PAD src0_sel:DWORD src1_sel:WORD_1
	v_or_b32_sdwa v118, v124, v143 dst_sel:DWORD dst_unused:UNUSED_PAD src0_sel:DWORD src1_sel:WORD_1
	v_or_b32_sdwa v119, v125, v142 dst_sel:DWORD dst_unused:UNUSED_PAD src0_sel:DWORD src1_sel:WORD_1
	v_add3_u32 v145, v43, v126, s69
	v_add3_u32 v146, v42, v127, s69
	v_and_b32_e32 v127, 0xffff0000, v142
	v_and_b32_e32 v126, 0xffff0000, v143
	v_and_b32_e32 v128, 0xffff0000, v132
	v_and_b32_e32 v131, 0xffff0000, v133
	v_and_b32_e32 v130, 0xffff0000, v134
	v_mfma_f32_32x32x16_bf16 v[0:15], v[32:35], v[116:119], v[0:15]
	v_add_f32_e64 v134, v82, -v122
	v_add_f32_e64 v135, v83, -v123
	v_add_f32_e64 v122, v80, -v126
	v_add_f32_e64 v123, v81, -v127
	v_or_b32_sdwa v80, v128, v141 dst_sel:DWORD dst_unused:UNUSED_PAD src0_sel:DWORD src1_sel:WORD_1
	v_or_b32_sdwa v81, v129, v144 dst_sel:DWORD dst_unused:UNUSED_PAD src0_sel:DWORD src1_sel:WORD_1
	v_or_b32_sdwa v82, v130, v146 dst_sel:DWORD dst_unused:UNUSED_PAD src0_sel:DWORD src1_sel:WORD_1
	v_or_b32_sdwa v83, v131, v145 dst_sel:DWORD dst_unused:UNUSED_PAD src0_sel:DWORD src1_sel:WORD_1
	v_and_b32_e32 v120, 0xffff0000, v141
	v_and_b32_e32 v121, 0xffff0000, v144
	v_mfma_f32_32x32x16_bf16 v[16:31], v[32:35], v[80:83], v[16:31]
	v_and_b32_e32 v133, 0xffff0000, v145
	v_and_b32_e32 v132, 0xffff0000, v146
	v_add_f32_e64 v86, v86, -v124
	v_add_f32_e64 v87, v87, -v125
	v_add_f32_e64 v40, v40, -v120
	v_add_f32_e64 v41, v41, -v121
	v_pk_add_f32 v[84:85], v[84:85], v[128:129] neg_lo:[0,1] neg_hi:[0,1]
	v_pk_add_f32 v[42:43], v[42:43], v[132:133] neg_lo:[0,1] neg_hi:[0,1]
	v_bfe_u32 v89, v87, 16, 1
	v_bfe_u32 v120, v86, 16, 1
	v_bfe_u32 v125, v122, 16, 1
	v_bfe_u32 v126, v123, 16, 1
	v_bfe_u32 v127, v44, 16, 1
	v_bfe_u32 v128, v45, 16, 1
	v_bfe_u32 v121, v135, 16, 1
	v_bfe_u32 v124, v134, 16, 1
	v_bfe_u32 v133, v42, 16, 1
	v_bfe_u32 v142, v40, 16, 1
	v_bfe_u32 v143, v41, 16, 1
	v_add3_u32 v86, v86, v120, s69
	v_add3_u32 v87, v87, v89, s69
	v_add3_u32 v89, v123, v126, s69
	v_add3_u32 v120, v122, v125, s69
	v_add3_u32 v45, v45, v128, s69
	v_add3_u32 v44, v44, v127, s69
	v_pk_add_f32 v[46:47], v[46:47], v[130:131] neg_lo:[0,1] neg_hi:[0,1]
	v_bfe_u32 v141, v43, 16, 1
	v_add3_u32 v124, v134, v124, s69
	v_add3_u32 v121, v135, v121, s69
	v_add3_u32 v42, v42, v133, s69
	v_add3_u32 v123, v41, v143, s69
	v_add3_u32 v125, v40, v142, s69
	v_lshrrev_b32_e32 v40, 16, v120
	v_lshrrev_b32_e32 v41, 16, v89
	v_lshrrev_b32_e32 v44, 16, v44
	v_lshrrev_b32_e32 v45, 16, v45
	v_bfe_u32 v129, v47, 16, 1
	v_bfe_u32 v130, v46, 16, 1
	v_bfe_u32 v131, v85, 16, 1
	v_bfe_u32 v132, v84, 16, 1
	v_add3_u32 v122, v43, v141, s69
	v_lshrrev_b32_e32 v89, 16, v42
	v_and_or_b32 v43, v87, s70, v41
	v_and_or_b32 v42, v86, s70, v40
	v_and_or_b32 v41, v121, s70, v45
	v_and_or_b32 v40, v124, s70, v44
	v_add3_u32 v84, v84, v132, s69
	v_add3_u32 v85, v85, v131, s69
	v_add3_u32 v46, v46, v130, s69
	v_add3_u32 v47, v47, v129, s69
	v_mfma_f32_32x32x16_bf16 v[0:15], v[32:35], v[40:43], v[0:15]
	v_lshrrev_b32_e32 v40, 16, v122
	v_lshrrev_b32_e32 v44, 16, v125
	v_lshrrev_b32_e32 v41, 16, v123
	v_and_or_b32 v43, v47, s70, v40
	v_and_or_b32 v42, v46, s70, v89
	v_and_or_b32 v41, v85, s70, v41
	v_and_or_b32 v40, v84, s70, v44
	s_nop 1
	v_mfma_f32_32x32x16_bf16 v[16:31], v[32:35], v[40:43], v[16:31]
	v_and_or_b32 v35, v137, s70, v140
	v_and_or_b32 v34, v136, s70, v139
	s_nop 1
	v_mfma_f32_32x32x16_bf16 v[0:15], v[34:37], v[116:119], v[0:15]
	v_mfma_f32_32x32x16_bf16 v[16:31], v[34:37], v[80:83], v[16:31]
	ds_read_b128 v[32:35], v88
	ds_read_b128 v[116:119], v88 offset:16
	s_waitcnt lgkmcnt(1)
	v_cndmask_b32_e64 v35, 0, v35, s[2:3]
	s_waitcnt lgkmcnt(0)
	v_cndmask_b32_e64 v119, 0, v119, s[2:3]
	v_and_b32_sdwa v89, v35, v115 dst_sel:DWORD dst_unused:UNUSED_PAD src0_sel:WORD_1 src1_sel:DWORD
	s_nop 0
	s_nop 0
	s_nop 0
	s_nop 0
	v_mov_b32_e32 v44, v228
	v_mov_b32_e32 v40, v229
	v_mov_b32_e32 v45, v230
	v_mov_b32_e32 v83, v231
	v_mov_b32_e32 v82, v232
	v_mov_b32_e32 v81, v233
	v_mov_b32_e32 v80, v234
	v_mov_b32_e32 v87, v235
	v_mov_b32_e32 v86, v236
	v_mov_b32_e32 v41, v237
	s_nop 0
	v_mov_b32_e32 v85, v238
	s_nop 0
	v_mov_b32_e32 v84, v239
	s_nop 0
	v_mov_b32_e32 v43, v240
	v_mov_b32_e32 v42, v241
	v_mov_b32_e32 v47, v242
	v_mov_b32_e32 v46, v243
	v_cndmask_b32_e64 v37, 0, v34, s[2:3]
	v_cndmask_b32_e64 v36, 0, v32, s[2:3]
	v_cndmask_b32_e64 v34, 0, v33, s[2:3]
	v_cndmask_b32_e64 v121, 0, v118, s[2:3]
	v_cndmask_b32_e64 v120, 0, v116, s[2:3]
	v_cndmask_b32_e64 v118, 0, v117, s[2:3]
	v_and_b32_sdwa v32, v37, v115 dst_sel:DWORD dst_unused:UNUSED_PAD src0_sel:WORD_1 src1_sel:DWORD
	v_and_b32_sdwa v33, v36, v115 dst_sel:DWORD dst_unused:UNUSED_PAD src0_sel:WORD_1 src1_sel:DWORD
	v_and_b32_sdwa v116, v34, v115 dst_sel:DWORD dst_unused:UNUSED_PAD src0_sel:WORD_1 src1_sel:DWORD
	v_and_b32_sdwa v117, v121, v115 dst_sel:DWORD dst_unused:UNUSED_PAD src0_sel:WORD_1 src1_sel:DWORD
	v_and_b32_sdwa v122, v120, v115 dst_sel:DWORD dst_unused:UNUSED_PAD src0_sel:WORD_1 src1_sel:DWORD
	v_and_b32_sdwa v123, v119, v115 dst_sel:DWORD dst_unused:UNUSED_PAD src0_sel:WORD_1 src1_sel:DWORD
	v_and_b32_sdwa v124, v118, v115 dst_sel:DWORD dst_unused:UNUSED_PAD src0_sel:WORD_1 src1_sel:DWORD
	v_add3_u32 v128, v37, v32, s69
	v_add3_u32 v32, v36, v33, s69
	v_add3_u32 v33, v35, v89, s69
	v_add3_u32 v89, v34, v116, s69
	v_add3_u32 v129, v121, v117, s69
	v_add3_u32 v130, v120, v122, s69
	v_add3_u32 v125, v119, v123, s69
	v_add3_u32 v124, v118, v124, s69
	v_and_b32_e32 v117, 0xffff0000, v33
	v_and_b32_e32 v116, 0xffff0000, v89
	v_and_b32_e32 v123, 0xffff0000, v128
	v_and_b32_e32 v122, 0xffff0000, v32
	v_and_b32_e32 v127, 0xffff0000, v129
	v_and_b32_e32 v126, 0xffff0000, v130
	v_and_b32_e32 v125, 0xffff0000, v125
	v_and_b32_e32 v124, 0xffff0000, v124
	v_or_b32_sdwa v32, v116, v32 dst_sel:DWORD dst_unused:UNUSED_PAD src0_sel:DWORD src1_sel:WORD_1
	v_pk_add_f32 v[36:37], v[36:37], v[122:123] neg_lo:[0,1] neg_hi:[0,1]
	v_pk_add_f32 v[122:123], v[34:35], v[116:117] neg_lo:[0,1] neg_hi:[0,1]
	v_or_b32_sdwa v33, v117, v128 dst_sel:DWORD dst_unused:UNUSED_PAD src0_sel:DWORD src1_sel:WORD_1
	v_pk_add_f32 v[116:117], v[120:121], v[126:127] neg_lo:[0,1] neg_hi:[0,1]
	v_pk_add_f32 v[118:119], v[118:119], v[124:125] neg_lo:[0,1] neg_hi:[0,1]
	v_bfe_u32 v126, v37, 16, 1
	v_bfe_u32 v128, v117, 16, 1
	v_or_b32_sdwa v35, v125, v129 dst_sel:DWORD dst_unused:UNUSED_PAD src0_sel:DWORD src1_sel:WORD_1
	v_bfe_u32 v89, v119, 16, 1
	v_bfe_u32 v125, v36, 16, 1
	v_bfe_u32 v127, v116, 16, 1
	v_add3_u32 v117, v117, v128, s69
	v_add3_u32 v37, v37, v126, s69
	v_or_b32_sdwa v34, v124, v130 dst_sel:DWORD dst_unused:UNUSED_PAD src0_sel:DWORD src1_sel:WORD_1
	v_bfe_u32 v120, v118, 16, 1
	v_bfe_u32 v121, v123, 16, 1
	v_bfe_u32 v124, v122, 16, 1
	v_add3_u32 v89, v119, v89, s69
	v_add3_u32 v116, v116, v127, s69
	v_add3_u32 v36, v36, v125, s69
	v_lshrrev_b32_e32 v140, 16, v37
	v_lshrrev_b32_e32 v37, 16, v117
	v_add3_u32 v136, v122, v124, s69
	v_add3_u32 v137, v123, v121, s69
	v_add3_u32 v138, v118, v120, s69
	v_lshrrev_b32_e32 v139, 16, v36
	v_lshrrev_b32_e32 v36, 16, v116
	v_and_or_b32 v37, v89, s70, v37
	v_and_or_b32 v36, v138, s70, v36
	v_add_u32_e32 v88, 64, v88
	v_and_b32_sdwa v89, v44, v115 dst_sel:DWORD dst_unused:UNUSED_PAD src0_sel:WORD_1 src1_sel:DWORD
	v_and_b32_sdwa v116, v40, v115 dst_sel:DWORD dst_unused:UNUSED_PAD src0_sel:WORD_1 src1_sel:DWORD
	v_and_b32_sdwa v117, v45, v115 dst_sel:DWORD dst_unused:UNUSED_PAD src0_sel:WORD_1 src1_sel:DWORD
	v_and_b32_sdwa v118, v83, v115 dst_sel:DWORD dst_unused:UNUSED_PAD src0_sel:WORD_1 src1_sel:DWORD
	v_and_b32_sdwa v119, v82, v115 dst_sel:DWORD dst_unused:UNUSED_PAD src0_sel:WORD_1 src1_sel:DWORD
	v_add3_u32 v89, v44, v89, s69
	v_and_b32_sdwa v121, v80, v115 dst_sel:DWORD dst_unused:UNUSED_PAD src0_sel:WORD_1 src1_sel:DWORD
	v_and_b32_sdwa v122, v87, v115 dst_sel:DWORD dst_unused:UNUSED_PAD src0_sel:WORD_1 src1_sel:DWORD
	v_and_b32_sdwa v123, v86, v115 dst_sel:DWORD dst_unused:UNUSED_PAD src0_sel:WORD_1 src1_sel:DWORD
	v_and_b32_sdwa v120, v81, v115 dst_sel:DWORD dst_unused:UNUSED_PAD src0_sel:WORD_1 src1_sel:DWORD
	v_and_b32_sdwa v124, v41, v115 dst_sel:DWORD dst_unused:UNUSED_PAD src0_sel:WORD_1 src1_sel:DWORD
	v_add3_u32 v141, v40, v116, s69
	v_and_b32_sdwa v116, v85, v115 dst_sel:DWORD dst_unused:UNUSED_PAD src0_sel:WORD_1 src1_sel:DWORD
	v_and_b32_sdwa v125, v84, v115 dst_sel:DWORD dst_unused:UNUSED_PAD src0_sel:WORD_1 src1_sel:DWORD
	v_add3_u32 v117, v45, v117, s69
	v_add3_u32 v130, v83, v118, s69
	v_add3_u32 v119, v82, v119, s69
	v_add3_u32 v143, v80, v121, s69
	v_add3_u32 v121, v87, v122, s69
	v_add3_u32 v131, v86, v123, s69
	v_and_b32_sdwa v128, v47, v115 dst_sel:DWORD dst_unused:UNUSED_PAD src0_sel:WORD_1 src1_sel:DWORD
	v_and_b32_sdwa v129, v46, v115 dst_sel:DWORD dst_unused:UNUSED_PAD src0_sel:WORD_1 src1_sel:DWORD
	v_and_b32_e32 v118, 0xffff0000, v89
	v_add3_u32 v142, v81, v120, s69
	v_add3_u32 v144, v41, v124, s69
	v_add3_u32 v116, v85, v116, s69
	v_add3_u32 v132, v84, v125, s69
	v_and_b32_e32 v123, 0xffff0000, v130
	v_and_b32_e32 v122, 0xffff0000, v119
	v_and_b32_e32 v119, 0xffff0000, v117
	v_and_b32_e32 v125, 0xffff0000, v121
	v_and_b32_e32 v124, 0xffff0000, v131
	v_and_b32_sdwa v126, v43, v115 dst_sel:DWORD dst_unused:UNUSED_PAD src0_sel:WORD_1 src1_sel:DWORD
	v_and_b32_sdwa v127, v42, v115 dst_sel:DWORD dst_unused:UNUSED_PAD src0_sel:WORD_1 src1_sel:DWORD
	v_add3_u32 v133, v47, v128, s69
	v_add3_u32 v134, v46, v129, s69
	v_and_b32_e32 v129, 0xffff0000, v116
	v_or_b32_sdwa v116, v122, v89 dst_sel:DWORD dst_unused:UNUSED_PAD src0_sel:DWORD src1_sel:WORD_1
	v_pk_add_f32 v[44:45], v[44:45], v[118:119] neg_lo:[0,1] neg_hi:[0,1]
	v_or_b32_sdwa v117, v123, v117 dst_sel:DWORD dst_unused:UNUSED_PAD src0_sel:DWORD src1_sel:WORD_1
	v_or_b32_sdwa v118, v124, v143 dst_sel:DWORD dst_unused:UNUSED_PAD src0_sel:DWORD src1_sel:WORD_1
	v_or_b32_sdwa v119, v125, v142 dst_sel:DWORD dst_unused:UNUSED_PAD src0_sel:DWORD src1_sel:WORD_1
	v_add3_u32 v145, v43, v126, s69
	v_add3_u32 v146, v42, v127, s69
	v_and_b32_e32 v127, 0xffff0000, v142
	v_and_b32_e32 v126, 0xffff0000, v143
	v_and_b32_e32 v128, 0xffff0000, v132
	v_and_b32_e32 v131, 0xffff0000, v133
	v_and_b32_e32 v130, 0xffff0000, v134
	v_mfma_f32_32x32x16_bf16 v[0:15], v[32:35], v[116:119], v[0:15]
	v_add_f32_e64 v134, v82, -v122
	v_add_f32_e64 v135, v83, -v123
	v_add_f32_e64 v122, v80, -v126
	v_add_f32_e64 v123, v81, -v127
	v_or_b32_sdwa v80, v128, v141 dst_sel:DWORD dst_unused:UNUSED_PAD src0_sel:DWORD src1_sel:WORD_1
	v_or_b32_sdwa v81, v129, v144 dst_sel:DWORD dst_unused:UNUSED_PAD src0_sel:DWORD src1_sel:WORD_1
	v_or_b32_sdwa v82, v130, v146 dst_sel:DWORD dst_unused:UNUSED_PAD src0_sel:DWORD src1_sel:WORD_1
	v_or_b32_sdwa v83, v131, v145 dst_sel:DWORD dst_unused:UNUSED_PAD src0_sel:DWORD src1_sel:WORD_1
	v_and_b32_e32 v120, 0xffff0000, v141
	v_and_b32_e32 v121, 0xffff0000, v144
	v_mfma_f32_32x32x16_bf16 v[16:31], v[32:35], v[80:83], v[16:31]
	v_and_b32_e32 v133, 0xffff0000, v145
	v_and_b32_e32 v132, 0xffff0000, v146
	v_add_f32_e64 v86, v86, -v124
	v_add_f32_e64 v87, v87, -v125
	v_add_f32_e64 v40, v40, -v120
	v_add_f32_e64 v41, v41, -v121
	v_pk_add_f32 v[84:85], v[84:85], v[128:129] neg_lo:[0,1] neg_hi:[0,1]
	v_pk_add_f32 v[42:43], v[42:43], v[132:133] neg_lo:[0,1] neg_hi:[0,1]
	v_bfe_u32 v89, v87, 16, 1
	v_bfe_u32 v120, v86, 16, 1
	v_bfe_u32 v125, v122, 16, 1
	v_bfe_u32 v126, v123, 16, 1
	v_bfe_u32 v127, v44, 16, 1
	v_bfe_u32 v128, v45, 16, 1
	v_bfe_u32 v121, v135, 16, 1
	v_bfe_u32 v124, v134, 16, 1
	v_bfe_u32 v133, v42, 16, 1
	v_bfe_u32 v142, v40, 16, 1
	v_bfe_u32 v143, v41, 16, 1
	v_add3_u32 v86, v86, v120, s69
	v_add3_u32 v87, v87, v89, s69
	v_add3_u32 v89, v123, v126, s69
	v_add3_u32 v120, v122, v125, s69
	v_add3_u32 v45, v45, v128, s69
	v_add3_u32 v44, v44, v127, s69
	v_pk_add_f32 v[46:47], v[46:47], v[130:131] neg_lo:[0,1] neg_hi:[0,1]
	v_bfe_u32 v141, v43, 16, 1
	v_add3_u32 v124, v134, v124, s69
	v_add3_u32 v121, v135, v121, s69
	v_add3_u32 v42, v42, v133, s69
	v_add3_u32 v123, v41, v143, s69
	v_add3_u32 v125, v40, v142, s69
	v_lshrrev_b32_e32 v40, 16, v120
	v_lshrrev_b32_e32 v41, 16, v89
	v_lshrrev_b32_e32 v44, 16, v44
	v_lshrrev_b32_e32 v45, 16, v45
	v_bfe_u32 v129, v47, 16, 1
	v_bfe_u32 v130, v46, 16, 1
	v_bfe_u32 v131, v85, 16, 1
	v_bfe_u32 v132, v84, 16, 1
	v_add3_u32 v122, v43, v141, s69
	v_lshrrev_b32_e32 v89, 16, v42
	v_and_or_b32 v43, v87, s70, v41
	v_and_or_b32 v42, v86, s70, v40
	v_and_or_b32 v41, v121, s70, v45
	v_and_or_b32 v40, v124, s70, v44
	v_add3_u32 v84, v84, v132, s69
	v_add3_u32 v85, v85, v131, s69
	v_add3_u32 v46, v46, v130, s69
	v_add3_u32 v47, v47, v129, s69
	v_mfma_f32_32x32x16_bf16 v[0:15], v[32:35], v[40:43], v[0:15]
	v_lshrrev_b32_e32 v40, 16, v122
	v_lshrrev_b32_e32 v44, 16, v125
	v_lshrrev_b32_e32 v41, 16, v123
	v_and_or_b32 v43, v47, s70, v40
	v_and_or_b32 v42, v46, s70, v89
	v_and_or_b32 v41, v85, s70, v41
	v_and_or_b32 v40, v84, s70, v44
	s_nop 1
	v_mfma_f32_32x32x16_bf16 v[16:31], v[32:35], v[40:43], v[16:31]
	v_and_or_b32 v35, v137, s70, v140
	v_and_or_b32 v34, v136, s70, v139
	s_nop 1
	v_mfma_f32_32x32x16_bf16 v[0:15], v[34:37], v[116:119], v[0:15]
	v_mfma_f32_32x32x16_bf16 v[16:31], v[34:37], v[80:83], v[16:31]
	ds_read_b128 v[32:35], v88
	ds_read_b128 v[116:119], v88 offset:16
	s_waitcnt lgkmcnt(1)
	v_cndmask_b32_e64 v35, 0, v35, s[2:3]
	s_waitcnt lgkmcnt(0)
	v_cndmask_b32_e64 v119, 0, v119, s[2:3]
	v_and_b32_sdwa v89, v35, v115 dst_sel:DWORD dst_unused:UNUSED_PAD src0_sel:WORD_1 src1_sel:DWORD
	s_nop 0
	s_nop 0
	s_nop 0
	s_nop 0
	s_waitcnt vmcnt(0)
	v_mov_b32_e32 v44, v148
	v_mov_b32_e32 v40, v149
	v_mov_b32_e32 v45, v150
	v_mov_b32_e32 v83, v151
	v_mov_b32_e32 v82, v152
	v_mov_b32_e32 v81, v153
	v_mov_b32_e32 v80, v154
	v_mov_b32_e32 v87, v155
	v_mov_b32_e32 v86, v156
	v_mov_b32_e32 v41, v157
	s_nop 0
	v_mov_b32_e32 v85, v158
	s_nop 0
	v_mov_b32_e32 v84, v159
	s_nop 0
	v_mov_b32_e32 v43, v160
	v_mov_b32_e32 v42, v161
	v_mov_b32_e32 v47, v162
	v_mov_b32_e32 v46, v163
	v_cndmask_b32_e64 v37, 0, v34, s[2:3]
	v_cndmask_b32_e64 v36, 0, v32, s[2:3]
	v_cndmask_b32_e64 v34, 0, v33, s[2:3]
	v_cndmask_b32_e64 v121, 0, v118, s[2:3]
	v_cndmask_b32_e64 v120, 0, v116, s[2:3]
	v_cndmask_b32_e64 v118, 0, v117, s[2:3]
	v_and_b32_sdwa v32, v37, v115 dst_sel:DWORD dst_unused:UNUSED_PAD src0_sel:WORD_1 src1_sel:DWORD
	v_and_b32_sdwa v33, v36, v115 dst_sel:DWORD dst_unused:UNUSED_PAD src0_sel:WORD_1 src1_sel:DWORD
	v_and_b32_sdwa v116, v34, v115 dst_sel:DWORD dst_unused:UNUSED_PAD src0_sel:WORD_1 src1_sel:DWORD
	v_and_b32_sdwa v117, v121, v115 dst_sel:DWORD dst_unused:UNUSED_PAD src0_sel:WORD_1 src1_sel:DWORD
	v_and_b32_sdwa v122, v120, v115 dst_sel:DWORD dst_unused:UNUSED_PAD src0_sel:WORD_1 src1_sel:DWORD
	v_and_b32_sdwa v123, v119, v115 dst_sel:DWORD dst_unused:UNUSED_PAD src0_sel:WORD_1 src1_sel:DWORD
	v_and_b32_sdwa v124, v118, v115 dst_sel:DWORD dst_unused:UNUSED_PAD src0_sel:WORD_1 src1_sel:DWORD
	v_add3_u32 v128, v37, v32, s69
	v_add3_u32 v32, v36, v33, s69
	v_add3_u32 v33, v35, v89, s69
	v_add3_u32 v89, v34, v116, s69
	v_add3_u32 v129, v121, v117, s69
	v_add3_u32 v130, v120, v122, s69
	v_add3_u32 v125, v119, v123, s69
	v_add3_u32 v124, v118, v124, s69
	v_and_b32_e32 v117, 0xffff0000, v33
	v_and_b32_e32 v116, 0xffff0000, v89
	v_and_b32_e32 v123, 0xffff0000, v128
	v_and_b32_e32 v122, 0xffff0000, v32
	v_and_b32_e32 v127, 0xffff0000, v129
	v_and_b32_e32 v126, 0xffff0000, v130
	v_and_b32_e32 v125, 0xffff0000, v125
	v_and_b32_e32 v124, 0xffff0000, v124
	v_or_b32_sdwa v32, v116, v32 dst_sel:DWORD dst_unused:UNUSED_PAD src0_sel:DWORD src1_sel:WORD_1
	v_pk_add_f32 v[36:37], v[36:37], v[122:123] neg_lo:[0,1] neg_hi:[0,1]
	v_pk_add_f32 v[122:123], v[34:35], v[116:117] neg_lo:[0,1] neg_hi:[0,1]
	v_or_b32_sdwa v33, v117, v128 dst_sel:DWORD dst_unused:UNUSED_PAD src0_sel:DWORD src1_sel:WORD_1
	v_pk_add_f32 v[116:117], v[120:121], v[126:127] neg_lo:[0,1] neg_hi:[0,1]
	v_pk_add_f32 v[118:119], v[118:119], v[124:125] neg_lo:[0,1] neg_hi:[0,1]
	v_bfe_u32 v126, v37, 16, 1
	v_bfe_u32 v128, v117, 16, 1
	v_or_b32_sdwa v35, v125, v129 dst_sel:DWORD dst_unused:UNUSED_PAD src0_sel:DWORD src1_sel:WORD_1
	v_bfe_u32 v89, v119, 16, 1
	v_bfe_u32 v125, v36, 16, 1
	v_bfe_u32 v127, v116, 16, 1
	v_add3_u32 v117, v117, v128, s69
	v_add3_u32 v37, v37, v126, s69
	v_or_b32_sdwa v34, v124, v130 dst_sel:DWORD dst_unused:UNUSED_PAD src0_sel:DWORD src1_sel:WORD_1
	v_bfe_u32 v120, v118, 16, 1
	v_bfe_u32 v121, v123, 16, 1
	v_bfe_u32 v124, v122, 16, 1
	v_add3_u32 v89, v119, v89, s69
	v_add3_u32 v116, v116, v127, s69
	v_add3_u32 v36, v36, v125, s69
	v_lshrrev_b32_e32 v140, 16, v37
	v_lshrrev_b32_e32 v37, 16, v117
	v_add3_u32 v136, v122, v124, s69
	v_add3_u32 v137, v123, v121, s69
	v_add3_u32 v138, v118, v120, s69
	v_lshrrev_b32_e32 v139, 16, v36
	v_lshrrev_b32_e32 v36, 16, v116
	v_and_or_b32 v37, v89, s70, v37
	v_and_or_b32 v36, v138, s70, v36
	v_add_u32_e32 v88, 64, v88
	v_and_b32_sdwa v89, v44, v115 dst_sel:DWORD dst_unused:UNUSED_PAD src0_sel:WORD_1 src1_sel:DWORD
	v_and_b32_sdwa v116, v40, v115 dst_sel:DWORD dst_unused:UNUSED_PAD src0_sel:WORD_1 src1_sel:DWORD
	v_and_b32_sdwa v117, v45, v115 dst_sel:DWORD dst_unused:UNUSED_PAD src0_sel:WORD_1 src1_sel:DWORD
	v_and_b32_sdwa v118, v83, v115 dst_sel:DWORD dst_unused:UNUSED_PAD src0_sel:WORD_1 src1_sel:DWORD
	v_and_b32_sdwa v119, v82, v115 dst_sel:DWORD dst_unused:UNUSED_PAD src0_sel:WORD_1 src1_sel:DWORD
	v_add3_u32 v89, v44, v89, s69
	v_and_b32_sdwa v121, v80, v115 dst_sel:DWORD dst_unused:UNUSED_PAD src0_sel:WORD_1 src1_sel:DWORD
	v_and_b32_sdwa v122, v87, v115 dst_sel:DWORD dst_unused:UNUSED_PAD src0_sel:WORD_1 src1_sel:DWORD
	v_and_b32_sdwa v123, v86, v115 dst_sel:DWORD dst_unused:UNUSED_PAD src0_sel:WORD_1 src1_sel:DWORD
	v_and_b32_sdwa v120, v81, v115 dst_sel:DWORD dst_unused:UNUSED_PAD src0_sel:WORD_1 src1_sel:DWORD
	v_and_b32_sdwa v124, v41, v115 dst_sel:DWORD dst_unused:UNUSED_PAD src0_sel:WORD_1 src1_sel:DWORD
	v_add3_u32 v141, v40, v116, s69
	v_and_b32_sdwa v116, v85, v115 dst_sel:DWORD dst_unused:UNUSED_PAD src0_sel:WORD_1 src1_sel:DWORD
	v_and_b32_sdwa v125, v84, v115 dst_sel:DWORD dst_unused:UNUSED_PAD src0_sel:WORD_1 src1_sel:DWORD
	v_add3_u32 v117, v45, v117, s69
	v_add3_u32 v130, v83, v118, s69
	v_add3_u32 v119, v82, v119, s69
	v_add3_u32 v143, v80, v121, s69
	v_add3_u32 v121, v87, v122, s69
	v_add3_u32 v131, v86, v123, s69
	v_and_b32_sdwa v128, v47, v115 dst_sel:DWORD dst_unused:UNUSED_PAD src0_sel:WORD_1 src1_sel:DWORD
	v_and_b32_sdwa v129, v46, v115 dst_sel:DWORD dst_unused:UNUSED_PAD src0_sel:WORD_1 src1_sel:DWORD
	v_and_b32_e32 v118, 0xffff0000, v89
	v_add3_u32 v142, v81, v120, s69
	v_add3_u32 v144, v41, v124, s69
	v_add3_u32 v116, v85, v116, s69
	v_add3_u32 v132, v84, v125, s69
	v_and_b32_e32 v123, 0xffff0000, v130
	v_and_b32_e32 v122, 0xffff0000, v119
	v_and_b32_e32 v119, 0xffff0000, v117
	v_and_b32_e32 v125, 0xffff0000, v121
	v_and_b32_e32 v124, 0xffff0000, v131
	v_and_b32_sdwa v126, v43, v115 dst_sel:DWORD dst_unused:UNUSED_PAD src0_sel:WORD_1 src1_sel:DWORD
	v_and_b32_sdwa v127, v42, v115 dst_sel:DWORD dst_unused:UNUSED_PAD src0_sel:WORD_1 src1_sel:DWORD
	v_add3_u32 v133, v47, v128, s69
	v_add3_u32 v134, v46, v129, s69
	v_and_b32_e32 v129, 0xffff0000, v116
	v_or_b32_sdwa v116, v122, v89 dst_sel:DWORD dst_unused:UNUSED_PAD src0_sel:DWORD src1_sel:WORD_1
	v_pk_add_f32 v[44:45], v[44:45], v[118:119] neg_lo:[0,1] neg_hi:[0,1]
	v_or_b32_sdwa v117, v123, v117 dst_sel:DWORD dst_unused:UNUSED_PAD src0_sel:DWORD src1_sel:WORD_1
	v_or_b32_sdwa v118, v124, v143 dst_sel:DWORD dst_unused:UNUSED_PAD src0_sel:DWORD src1_sel:WORD_1
	v_or_b32_sdwa v119, v125, v142 dst_sel:DWORD dst_unused:UNUSED_PAD src0_sel:DWORD src1_sel:WORD_1
	v_add3_u32 v145, v43, v126, s69
	v_add3_u32 v146, v42, v127, s69
	v_and_b32_e32 v127, 0xffff0000, v142
	v_and_b32_e32 v126, 0xffff0000, v143
	v_and_b32_e32 v128, 0xffff0000, v132
	v_and_b32_e32 v131, 0xffff0000, v133
	v_and_b32_e32 v130, 0xffff0000, v134
	v_mfma_f32_32x32x16_bf16 v[0:15], v[32:35], v[116:119], v[0:15]
	v_add_f32_e64 v134, v82, -v122
	v_add_f32_e64 v135, v83, -v123
	v_add_f32_e64 v122, v80, -v126
	v_add_f32_e64 v123, v81, -v127
	v_or_b32_sdwa v80, v128, v141 dst_sel:DWORD dst_unused:UNUSED_PAD src0_sel:DWORD src1_sel:WORD_1
	v_or_b32_sdwa v81, v129, v144 dst_sel:DWORD dst_unused:UNUSED_PAD src0_sel:DWORD src1_sel:WORD_1
	v_or_b32_sdwa v82, v130, v146 dst_sel:DWORD dst_unused:UNUSED_PAD src0_sel:DWORD src1_sel:WORD_1
	v_or_b32_sdwa v83, v131, v145 dst_sel:DWORD dst_unused:UNUSED_PAD src0_sel:DWORD src1_sel:WORD_1
	v_and_b32_e32 v120, 0xffff0000, v141
	v_and_b32_e32 v121, 0xffff0000, v144
	v_mfma_f32_32x32x16_bf16 v[16:31], v[32:35], v[80:83], v[16:31]
	v_and_b32_e32 v133, 0xffff0000, v145
	v_and_b32_e32 v132, 0xffff0000, v146
	v_add_f32_e64 v86, v86, -v124
	v_add_f32_e64 v87, v87, -v125
	v_add_f32_e64 v40, v40, -v120
	v_add_f32_e64 v41, v41, -v121
	v_pk_add_f32 v[84:85], v[84:85], v[128:129] neg_lo:[0,1] neg_hi:[0,1]
	v_pk_add_f32 v[42:43], v[42:43], v[132:133] neg_lo:[0,1] neg_hi:[0,1]
	v_bfe_u32 v89, v87, 16, 1
	v_bfe_u32 v120, v86, 16, 1
	v_bfe_u32 v125, v122, 16, 1
	v_bfe_u32 v126, v123, 16, 1
	v_bfe_u32 v127, v44, 16, 1
	v_bfe_u32 v128, v45, 16, 1
	v_bfe_u32 v121, v135, 16, 1
	v_bfe_u32 v124, v134, 16, 1
	v_bfe_u32 v133, v42, 16, 1
	v_bfe_u32 v142, v40, 16, 1
	v_bfe_u32 v143, v41, 16, 1
	v_add3_u32 v86, v86, v120, s69
	v_add3_u32 v87, v87, v89, s69
	v_add3_u32 v89, v123, v126, s69
	v_add3_u32 v120, v122, v125, s69
	v_add3_u32 v45, v45, v128, s69
	v_add3_u32 v44, v44, v127, s69
	v_pk_add_f32 v[46:47], v[46:47], v[130:131] neg_lo:[0,1] neg_hi:[0,1]
	v_bfe_u32 v141, v43, 16, 1
	v_add3_u32 v124, v134, v124, s69
	v_add3_u32 v121, v135, v121, s69
	v_add3_u32 v42, v42, v133, s69
	v_add3_u32 v123, v41, v143, s69
	v_add3_u32 v125, v40, v142, s69
	v_lshrrev_b32_e32 v40, 16, v120
	v_lshrrev_b32_e32 v41, 16, v89
	v_lshrrev_b32_e32 v44, 16, v44
	v_lshrrev_b32_e32 v45, 16, v45
	v_bfe_u32 v129, v47, 16, 1
	v_bfe_u32 v130, v46, 16, 1
	v_bfe_u32 v131, v85, 16, 1
	v_bfe_u32 v132, v84, 16, 1
	v_add3_u32 v122, v43, v141, s69
	v_lshrrev_b32_e32 v89, 16, v42
	v_and_or_b32 v43, v87, s70, v41
	v_and_or_b32 v42, v86, s70, v40
	v_and_or_b32 v41, v121, s70, v45
	v_and_or_b32 v40, v124, s70, v44
	v_add3_u32 v84, v84, v132, s69
	v_add3_u32 v85, v85, v131, s69
	v_add3_u32 v46, v46, v130, s69
	v_add3_u32 v47, v47, v129, s69
	v_mfma_f32_32x32x16_bf16 v[0:15], v[32:35], v[40:43], v[0:15]
	v_lshrrev_b32_e32 v40, 16, v122
	v_lshrrev_b32_e32 v44, 16, v125
	v_lshrrev_b32_e32 v41, 16, v123
	v_and_or_b32 v43, v47, s70, v40
	v_and_or_b32 v42, v46, s70, v89
	v_and_or_b32 v41, v85, s70, v41
	v_and_or_b32 v40, v84, s70, v44
	s_nop 1
	v_mfma_f32_32x32x16_bf16 v[16:31], v[32:35], v[40:43], v[16:31]
	v_and_or_b32 v35, v137, s70, v140
	v_and_or_b32 v34, v136, s70, v139
	s_nop 1
	v_mfma_f32_32x32x16_bf16 v[0:15], v[34:37], v[116:119], v[0:15]
	v_mfma_f32_32x32x16_bf16 v[16:31], v[34:37], v[80:83], v[16:31]
	s_mul_i32 s50, s52, 17
	s_nop 8
	v_add_u32_e32 v9, s50, v94
	v_lshl_add_u32 v9, v9, 8, v95
	ds_write2_b32 v9, v0, v16 offset1:32
	v_add_u32_e32 v0, s50, v96
	v_lshl_add_u32 v0, v0, 8, v95
	ds_write2_b32 v0, v1, v17 offset1:32
	v_add_u32_e32 v0, s50, v97
	v_lshl_add_u32 v0, v0, 8, v95
	ds_write2_b32 v0, v2, v18 offset1:32
	v_add_u32_e32 v0, s50, v98
	v_lshl_add_u32 v0, v0, 8, v95
	ds_write2_b32 v0, v3, v19 offset1:32
	v_add_u32_e32 v0, s50, v99
	v_lshl_add_u32 v0, v0, 8, v95
	ds_write2_b32 v0, v4, v20 offset1:32
	v_add_u32_e32 v0, s50, v100
	v_lshl_add_u32 v0, v0, 8, v95
	ds_write2_b32 v0, v5, v21 offset1:32
	v_add_u32_e32 v0, s50, v101
	v_lshl_add_u32 v0, v0, 8, v95
	ds_write2_b32 v0, v6, v22 offset1:32
	v_add_u32_e32 v0, s50, v102
	v_lshl_add_u32 v0, v0, 8, v95
	ds_write2_b32 v0, v7, v23 offset1:32
	s_and_saveexec_b64 s[50:51], s[4:5]
	s_mulk_i32 s52, 0x1100
	v_add_u32_e32 v0, s52, v95
	v_add_u32_e32 v0, 0x1000, v0
	ds_write2_b32 v0, v8, v24 offset1:32
	s_or_b64 exec, exec, s[50:51]
	s_waitcnt lgkmcnt(0)
	s_barrier
	s_and_saveexec_b64 s[50:51], s[6:7]
	s_cbranch_execz .LBB0_188
	v_lshl_add_u64 v[0:1], s[48:49], 2, v[56:57]
	s_mov_b64 s[54:55], -1
	v_mov_b32_e32 v2, v48
	s_and_saveexec_b64 s[52:53], s[28:29]
	s_cbranch_execz .LBB0_185
	v_mov_b64_e32 v[2:3], v[48:49]
	s_and_saveexec_b64 s[54:55], s[30:31]
	s_cbranch_execz .LBB0_182
	s_mov_b64 s[56:57], 0
	v_mov_b32_e32 v4, v105
	v_mov_b64_e32 v[2:3], v[48:49]

.LBB0_191:
	s_mov_b32 s101, 0
	s_add_u32 s100, s1, 0x2c200
	v_lshl_add_u64 v[250:251], v[40:41], 0, s[100:101]
	global_load_dword v148, v[250:251], off offset:3136
	s_add_u32 s100, s33, 0x2c200
	v_lshl_add_u64 v[252:253], v[40:41], 0, s[100:101]
	global_load_dword v149, v[252:253], off offset:1024
	s_add_u32 s100, s75, 0x2c200
	v_lshl_add_u64 v[250:251], v[40:41], 0, s[100:101]
	global_load_dword v150, v[250:251], off offset:2144
	s_add_u32 s100, s74, 0x2c200
	v_lshl_add_u64 v[252:253], v[40:41], 0, s[100:101]
	global_load_dword v151, v[252:253], off offset:32
	s_add_u32 s100, s78, 0x2c200
	v_lshl_add_u64 v[250:251], v[40:41], 0, s[100:101]
	global_load_dword v152, v[250:251], off offset:3264
	s_add_u32 s100, s76, 0x2c200
	v_lshl_add_u64 v[252:253], v[40:41], 0, s[100:101]
	global_load_dword v153, v[252:253], off offset:1152
	s_add_u32 s100, s79, 0x2c200
	v_lshl_add_u64 v[250:251], v[40:41], 0, s[100:101]
	global_load_dword v154, v[250:251], off offset:2272
	s_add_u32 s100, s77, 0x2c200
	v_lshl_add_u64 v[252:253], v[40:41], 0, s[100:101]
	global_load_dword v155, v[252:253], off offset:160
	s_add_u32 s100, s1, 0x2c200
	v_lshl_add_u64 v[250:251], v[38:39], 0, s[100:101]
	global_load_dword v156, v[250:251], off offset:3136
	s_add_u32 s100, s33, 0x2c200
	v_lshl_add_u64 v[252:253], v[38:39], 0, s[100:101]
	global_load_dword v157, v[252:253], off offset:1024
	s_add_u32 s100, s75, 0x2c200
	v_lshl_add_u64 v[250:251], v[38:39], 0, s[100:101]
	global_load_dword v158, v[250:251], off offset:2144
	s_add_u32 s100, s74, 0x2c200
	v_lshl_add_u64 v[252:253], v[38:39], 0, s[100:101]
	global_load_dword v159, v[252:253], off offset:32
	s_add_u32 s100, s78, 0x2c200
	v_lshl_add_u64 v[250:251], v[38:39], 0, s[100:101]
	global_load_dword v160, v[250:251], off offset:3264
	s_add_u32 s100, s76, 0x2c200
	v_lshl_add_u64 v[252:253], v[38:39], 0, s[100:101]
	global_load_dword v161, v[252:253], off offset:1152
	s_add_u32 s100, s79, 0x2c200
	v_lshl_add_u64 v[250:251], v[38:39], 0, s[100:101]
	global_load_dword v162, v[250:251], off offset:2272
	s_add_u32 s100, s77, 0x2c200
	v_lshl_add_u64 v[252:253], v[38:39], 0, s[100:101]
	global_load_dword v163, v[252:253], off offset:160
	s_mov_b32 s101, 0
	s_add_u32 s100, s1, 0x58400
	v_lshl_add_u64 v[250:251], v[40:41], 0, s[100:101]
	global_load_dword v164, v[250:251], off offset:3136
	s_add_u32 s100, s33, 0x58400
	v_lshl_add_u64 v[252:253], v[40:41], 0, s[100:101]
	global_load_dword v165, v[252:253], off offset:1024
	s_add_u32 s100, s75, 0x58400
	v_lshl_add_u64 v[250:251], v[40:41], 0, s[100:101]
	global_load_dword v166, v[250:251], off offset:2144
	s_add_u32 s100, s74, 0x58400
	v_lshl_add_u64 v[252:253], v[40:41], 0, s[100:101]
	global_load_dword v167, v[252:253], off offset:32
	s_add_u32 s100, s78, 0x58400
	v_lshl_add_u64 v[250:251], v[40:41], 0, s[100:101]
	global_load_dword v168, v[250:251], off offset:3264
	s_add_u32 s100, s76, 0x58400
	v_lshl_add_u64 v[252:253], v[40:41], 0, s[100:101]
	global_load_dword v169, v[252:253], off offset:1152
	s_add_u32 s100, s79, 0x58400
	v_lshl_add_u64 v[250:251], v[40:41], 0, s[100:101]
	global_load_dword v170, v[250:251], off offset:2272
	s_add_u32 s100, s77, 0x58400
	v_lshl_add_u64 v[252:253], v[40:41], 0, s[100:101]
	global_load_dword v171, v[252:253], off offset:160
	s_add_u32 s100, s1, 0x58400
	v_lshl_add_u64 v[250:251], v[38:39], 0, s[100:101]
	global_load_dword v172, v[250:251], off offset:3136
	s_add_u32 s100, s33, 0x58400
	v_lshl_add_u64 v[252:253], v[38:39], 0, s[100:101]
	global_load_dword v173, v[252:253], off offset:1024
	s_add_u32 s100, s75, 0x58400
	v_lshl_add_u64 v[250:251], v[38:39], 0, s[100:101]
	global_load_dword v174, v[250:251], off offset:2144
	s_add_u32 s100, s74, 0x58400
	v_lshl_add_u64 v[252:253], v[38:39], 0, s[100:101]
	global_load_dword v175, v[252:253], off offset:32
	s_add_u32 s100, s78, 0x58400
	v_lshl_add_u64 v[250:251], v[38:39], 0, s[100:101]
	global_load_dword v176, v[250:251], off offset:3264
	s_add_u32 s100, s76, 0x58400
	v_lshl_add_u64 v[252:253], v[38:39], 0, s[100:101]
	global_load_dword v177, v[252:253], off offset:1152
	s_add_u32 s100, s79, 0x58400
	v_lshl_add_u64 v[250:251], v[38:39], 0, s[100:101]
	global_load_dword v178, v[250:251], off offset:2272
	s_add_u32 s100, s77, 0x58400
	v_lshl_add_u64 v[252:253], v[38:39], 0, s[100:101]
	global_load_dword v179, v[252:253], off offset:160
	s_mov_b32 s101, 0
	s_add_u32 s100, s1, 0x84600
	v_lshl_add_u64 v[250:251], v[40:41], 0, s[100:101]
	global_load_dword v180, v[250:251], off offset:3136
	s_add_u32 s100, s33, 0x84600
	v_lshl_add_u64 v[252:253], v[40:41], 0, s[100:101]
	global_load_dword v181, v[252:253], off offset:1024
	s_add_u32 s100, s75, 0x84600
	v_lshl_add_u64 v[250:251], v[40:41], 0, s[100:101]
	global_load_dword v182, v[250:251], off offset:2144
	s_add_u32 s100, s74, 0x84600
	v_lshl_add_u64 v[252:253], v[40:41], 0, s[100:101]
	global_load_dword v183, v[252:253], off offset:32
	s_add_u32 s100, s78, 0x84600
	v_lshl_add_u64 v[250:251], v[40:41], 0, s[100:101]
	global_load_dword v184, v[250:251], off offset:3264
	s_add_u32 s100, s76, 0x84600
	v_lshl_add_u64 v[252:253], v[40:41], 0, s[100:101]
	global_load_dword v185, v[252:253], off offset:1152
	s_add_u32 s100, s79, 0x84600
	v_lshl_add_u64 v[250:251], v[40:41], 0, s[100:101]
	global_load_dword v186, v[250:251], off offset:2272
	s_add_u32 s100, s77, 0x84600
	v_lshl_add_u64 v[252:253], v[40:41], 0, s[100:101]
	global_load_dword v187, v[252:253], off offset:160
	s_add_u32 s100, s1, 0x84600
	v_lshl_add_u64 v[250:251], v[38:39], 0, s[100:101]
	global_load_dword v188, v[250:251], off offset:3136
	s_add_u32 s100, s33, 0x84600
	v_lshl_add_u64 v[252:253], v[38:39], 0, s[100:101]
	global_load_dword v189, v[252:253], off offset:1024
	s_add_u32 s100, s75, 0x84600
	v_lshl_add_u64 v[250:251], v[38:39], 0, s[100:101]
	global_load_dword v190, v[250:251], off offset:2144
	s_add_u32 s100, s74, 0x84600
	v_lshl_add_u64 v[252:253], v[38:39], 0, s[100:101]
	global_load_dword v191, v[252:253], off offset:32
	s_add_u32 s100, s78, 0x84600
	v_lshl_add_u64 v[250:251], v[38:39], 0, s[100:101]
	global_load_dword v192, v[250:251], off offset:3264
	s_add_u32 s100, s76, 0x84600
	v_lshl_add_u64 v[252:253], v[38:39], 0, s[100:101]
	global_load_dword v193, v[252:253], off offset:1152
	s_add_u32 s100, s79, 0x84600
	v_lshl_add_u64 v[250:251], v[38:39], 0, s[100:101]
	global_load_dword v194, v[250:251], off offset:2272
	s_add_u32 s100, s77, 0x84600
	v_lshl_add_u64 v[252:253], v[38:39], 0, s[100:101]
	global_load_dword v195, v[252:253], off offset:160
	s_mov_b32 s101, 0
	s_add_u32 s100, s1, 0xb0800
	v_lshl_add_u64 v[250:251], v[40:41], 0, s[100:101]
	global_load_dword v196, v[250:251], off offset:3136
	s_add_u32 s100, s33, 0xb0800
	v_lshl_add_u64 v[252:253], v[40:41], 0, s[100:101]
	global_load_dword v197, v[252:253], off offset:1024
	s_add_u32 s100, s75, 0xb0800
	v_lshl_add_u64 v[250:251], v[40:41], 0, s[100:101]
	global_load_dword v198, v[250:251], off offset:2144
	s_add_u32 s100, s74, 0xb0800
	v_lshl_add_u64 v[252:253], v[40:41], 0, s[100:101]
	global_load_dword v199, v[252:253], off offset:32
	s_add_u32 s100, s78, 0xb0800
	v_lshl_add_u64 v[250:251], v[40:41], 0, s[100:101]
	global_load_dword v200, v[250:251], off offset:3264
	s_add_u32 s100, s76, 0xb0800
	v_lshl_add_u64 v[252:253], v[40:41], 0, s[100:101]
	global_load_dword v201, v[252:253], off offset:1152
	s_add_u32 s100, s79, 0xb0800
	v_lshl_add_u64 v[250:251], v[40:41], 0, s[100:101]
	global_load_dword v202, v[250:251], off offset:2272
	s_add_u32 s100, s77, 0xb0800
	v_lshl_add_u64 v[252:253], v[40:41], 0, s[100:101]
	global_load_dword v203, v[252:253], off offset:160
	s_add_u32 s100, s1, 0xb0800
	v_lshl_add_u64 v[250:251], v[38:39], 0, s[100:101]
	global_load_dword v204, v[250:251], off offset:3136
	s_add_u32 s100, s33, 0xb0800
	v_lshl_add_u64 v[252:253], v[38:39], 0, s[100:101]
	global_load_dword v205, v[252:253], off offset:1024
	s_add_u32 s100, s75, 0xb0800
	v_lshl_add_u64 v[250:251], v[38:39], 0, s[100:101]
	global_load_dword v206, v[250:251], off offset:2144
	s_add_u32 s100, s74, 0xb0800
	v_lshl_add_u64 v[252:253], v[38:39], 0, s[100:101]
	global_load_dword v207, v[252:253], off offset:32
	s_add_u32 s100, s78, 0xb0800
	v_lshl_add_u64 v[250:251], v[38:39], 0, s[100:101]
	global_load_dword v208, v[250:251], off offset:3264
	s_add_u32 s100, s76, 0xb0800
	v_lshl_add_u64 v[252:253], v[38:39], 0, s[100:101]
	global_load_dword v209, v[252:253], off offset:1152
	s_add_u32 s100, s79, 0xb0800
	v_lshl_add_u64 v[250:251], v[38:39], 0, s[100:101]
	global_load_dword v210, v[250:251], off offset:2272
	s_add_u32 s100, s77, 0xb0800
	v_lshl_add_u64 v[252:253], v[38:39], 0, s[100:101]
	global_load_dword v211, v[252:253], off offset:160
	s_mov_b32 s101, 0
	s_add_u32 s100, s1, 0xdca00
	v_lshl_add_u64 v[250:251], v[40:41], 0, s[100:101]
	global_load_dword v212, v[250:251], off offset:3136
	s_add_u32 s100, s33, 0xdca00
	v_lshl_add_u64 v[252:253], v[40:41], 0, s[100:101]
	global_load_dword v213, v[252:253], off offset:1024
	s_add_u32 s100, s75, 0xdca00
	v_lshl_add_u64 v[250:251], v[40:41], 0, s[100:101]
	global_load_dword v214, v[250:251], off offset:2144
	s_add_u32 s100, s74, 0xdca00
	v_lshl_add_u64 v[252:253], v[40:41], 0, s[100:101]
	global_load_dword v215, v[252:253], off offset:32
	s_add_u32 s100, s78, 0xdca00
	v_lshl_add_u64 v[250:251], v[40:41], 0, s[100:101]
	global_load_dword v216, v[250:251], off offset:3264
	s_add_u32 s100, s76, 0xdca00
	v_lshl_add_u64 v[252:253], v[40:41], 0, s[100:101]
	global_load_dword v217, v[252:253], off offset:1152
	s_add_u32 s100, s79, 0xdca00
	v_lshl_add_u64 v[250:251], v[40:41], 0, s[100:101]
	global_load_dword v218, v[250:251], off offset:2272
	s_add_u32 s100, s77, 0xdca00
	v_lshl_add_u64 v[252:253], v[40:41], 0, s[100:101]
	global_load_dword v219, v[252:253], off offset:160
	s_add_u32 s100, s1, 0xdca00
	v_lshl_add_u64 v[250:251], v[38:39], 0, s[100:101]
	global_load_dword v220, v[250:251], off offset:3136
	s_add_u32 s100, s33, 0xdca00
	v_lshl_add_u64 v[252:253], v[38:39], 0, s[100:101]
	global_load_dword v221, v[252:253], off offset:1024
	s_add_u32 s100, s75, 0xdca00
	v_lshl_add_u64 v[250:251], v[38:39], 0, s[100:101]
	global_load_dword v222, v[250:251], off offset:2144
	s_add_u32 s100, s74, 0xdca00
	v_lshl_add_u64 v[252:253], v[38:39], 0, s[100:101]
	global_load_dword v223, v[252:253], off offset:32
	s_add_u32 s100, s78, 0xdca00
	v_lshl_add_u64 v[250:251], v[38:39], 0, s[100:101]
	global_load_dword v224, v[250:251], off offset:3264
	s_add_u32 s100, s76, 0xdca00
	v_lshl_add_u64 v[252:253], v[38:39], 0, s[100:101]
	global_load_dword v225, v[252:253], off offset:1152
	s_add_u32 s100, s79, 0xdca00
	v_lshl_add_u64 v[250:251], v[38:39], 0, s[100:101]
	global_load_dword v226, v[250:251], off offset:2272
	s_add_u32 s100, s77, 0xdca00
	v_lshl_add_u64 v[252:253], v[38:39], 0, s[100:101]
	global_load_dword v227, v[252:253], off offset:160
	s_mov_b32 s101, 0
	s_add_u32 s100, s1, 0x108c00
	v_lshl_add_u64 v[250:251], v[40:41], 0, s[100:101]
	global_load_dword v228, v[250:251], off offset:3136
	s_add_u32 s100, s33, 0x108c00
	v_lshl_add_u64 v[252:253], v[40:41], 0, s[100:101]
	global_load_dword v229, v[252:253], off offset:1024
	s_add_u32 s100, s75, 0x108c00
	v_lshl_add_u64 v[250:251], v[40:41], 0, s[100:101]
	global_load_dword v230, v[250:251], off offset:2144
	s_add_u32 s100, s74, 0x108c00
	v_lshl_add_u64 v[252:253], v[40:41], 0, s[100:101]
	global_load_dword v231, v[252:253], off offset:32
	s_add_u32 s100, s78, 0x108c00
	v_lshl_add_u64 v[250:251], v[40:41], 0, s[100:101]
	global_load_dword v232, v[250:251], off offset:3264
	s_add_u32 s100, s76, 0x108c00
	v_lshl_add_u64 v[252:253], v[40:41], 0, s[100:101]
	global_load_dword v233, v[252:253], off offset:1152
	s_add_u32 s100, s79, 0x108c00
	v_lshl_add_u64 v[250:251], v[40:41], 0, s[100:101]
	global_load_dword v234, v[250:251], off offset:2272
	s_add_u32 s100, s77, 0x108c00
	v_lshl_add_u64 v[252:253], v[40:41], 0, s[100:101]
	global_load_dword v235, v[252:253], off offset:160
	s_add_u32 s100, s1, 0x108c00
	v_lshl_add_u64 v[250:251], v[38:39], 0, s[100:101]
	global_load_dword v236, v[250:251], off offset:3136
	s_add_u32 s100, s33, 0x108c00
	v_lshl_add_u64 v[252:253], v[38:39], 0, s[100:101]
	global_load_dword v237, v[252:253], off offset:1024
	s_add_u32 s100, s75, 0x108c00
	v_lshl_add_u64 v[250:251], v[38:39], 0, s[100:101]
	global_load_dword v238, v[250:251], off offset:2144
	s_add_u32 s100, s74, 0x108c00
	v_lshl_add_u64 v[252:253], v[38:39], 0, s[100:101]
	global_load_dword v239, v[252:253], off offset:32
	s_add_u32 s100, s78, 0x108c00
	v_lshl_add_u64 v[250:251], v[38:39], 0, s[100:101]
	global_load_dword v240, v[250:251], off offset:3264
	s_add_u32 s100, s76, 0x108c00
	v_lshl_add_u64 v[252:253], v[38:39], 0, s[100:101]
	global_load_dword v241, v[252:253], off offset:1152
	s_add_u32 s100, s79, 0x108c00
	v_lshl_add_u64 v[250:251], v[38:39], 0, s[100:101]
	global_load_dword v242, v[250:251], off offset:2272
	s_add_u32 s100, s77, 0x108c00
	v_lshl_add_u64 v[252:253], v[38:39], 0, s[100:101]
	global_load_dword v243, v[252:253], off offset:160
	v_lshl_add_u64 v[42:43], v[40:41], 0, s[50:51]
	v_add_co_u32_e32 v44, vcc, s33, v42
	v_lshl_add_u64 v[36:37], v[38:39], 0, s[50:51]
	s_nop 0
	v_addc_co_u32_e32 v45, vcc, 0, v43, vcc
	v_add_co_u32_e32 v82, vcc, s33, v36
	ds_read_b128 v[32:35], v116
	ds_read_b128 v[118:121], v116 offset:16
	v_addc_co_u32_e32 v83, vcc, 0, v37, vcc
	v_add_co_u32_e32 v46, vcc, s74, v42
	s_waitcnt lgkmcnt(1)
	v_cndmask_b32_e64 v35, 0, v35, s[2:3]
	v_addc_co_u32_e32 v47, vcc, 0, v43, vcc
	v_add_co_u32_e32 v122, vcc, s74, v36
	s_waitcnt lgkmcnt(0)
	v_cndmask_b32_e64 v121, 0, v121, s[2:3]
	v_addc_co_u32_e32 v123, vcc, 0, v37, vcc
	v_add_co_u32_e32 v80, vcc, s1, v42
	v_and_b32_sdwa v117, v35, v115 dst_sel:DWORD dst_unused:UNUSED_PAD src0_sel:WORD_1 src1_sel:DWORD
	s_nop 0
	v_addc_co_u32_e32 v81, vcc, 0, v43, vcc
	v_add_co_u32_e32 v84, vcc, s1, v36
	s_nop 0
	v_addc_co_u32_e32 v85, vcc, 0, v37, vcc
	v_add_co_u32_e32 v86, vcc, s75, v42
	s_nop 0
	v_addc_co_u32_e32 v87, vcc, 0, v43, vcc
	v_add_co_u32_e32 v124, vcc, s75, v36
	s_nop 0
	v_addc_co_u32_e32 v125, vcc, 0, v37, vcc
	v_add_co_u32_e32 v126, vcc, s76, v42
	v_add_u32_e32 v116, 64, v116
	s_nop 0
	v_addc_co_u32_e32 v127, vcc, 0, v43, vcc
	v_add_co_u32_e32 v128, vcc, s76, v36
	s_nop 1
	v_addc_co_u32_e32 v129, vcc, 0, v37, vcc
	v_add_co_u32_e32 v130, vcc, s77, v42
	s_nop 1
	v_addc_co_u32_e32 v131, vcc, 0, v43, vcc
	v_add_co_u32_e32 v132, vcc, s77, v36
	s_nop 1
	v_addc_co_u32_e32 v133, vcc, 0, v37, vcc
	v_add_co_u32_e32 v134, vcc, s78, v42
	s_nop 1
	v_addc_co_u32_e32 v135, vcc, 0, v43, vcc
	v_add_co_u32_e32 v136, vcc, s78, v36
	s_nop 1
	v_addc_co_u32_e32 v137, vcc, 0, v37, vcc
	v_add_co_u32_e32 v42, vcc, s79, v42
	s_nop 1
	v_addc_co_u32_e32 v43, vcc, 0, v43, vcc
	v_add_co_u32_e32 v36, vcc, s79, v36
	s_nop 1
	v_addc_co_u32_e32 v37, vcc, 0, v37, vcc
	global_load_dword v81, v[80:81], off offset:3136
	s_nop 0
	global_load_dword v80, v[44:45], off offset:1024
	global_load_dword v89, v[86:87], off offset:2144
	global_load_dword v88, v[46:47], off offset:32
	s_nop 0
	global_load_dword v47, v[134:135], off offset:3264
	global_load_dword v46, v[126:127], off offset:1152
	global_load_dword v87, v[42:43], off offset:2272
	global_load_dword v86, v[130:131], off offset:160
	global_load_dword v45, v[84:85], off offset:3136
	global_load_dword v44, v[82:83], off offset:1024
	s_nop 0
	global_load_dword v85, v[124:125], off offset:2144
	global_load_dword v84, v[122:123], off offset:32
	global_load_dword v43, v[136:137], off offset:3264
	global_load_dword v42, v[128:129], off offset:1152
	global_load_dword v83, v[36:37], off offset:2272
	global_load_dword v82, v[132:133], off offset:160
	v_cndmask_b32_e64 v37, 0, v34, s[2:3]
	v_cndmask_b32_e64 v36, 0, v32, s[2:3]
	v_cndmask_b32_e64 v34, 0, v33, s[2:3]
	v_cndmask_b32_e64 v123, 0, v120, s[2:3]
	v_cndmask_b32_e64 v122, 0, v118, s[2:3]
	v_cndmask_b32_e64 v120, 0, v119, s[2:3]
	v_and_b32_sdwa v32, v37, v115 dst_sel:DWORD dst_unused:UNUSED_PAD src0_sel:WORD_1 src1_sel:DWORD
	v_and_b32_sdwa v33, v36, v115 dst_sel:DWORD dst_unused:UNUSED_PAD src0_sel:WORD_1 src1_sel:DWORD
	v_and_b32_sdwa v118, v34, v115 dst_sel:DWORD dst_unused:UNUSED_PAD src0_sel:WORD_1 src1_sel:DWORD
	v_and_b32_sdwa v119, v123, v115 dst_sel:DWORD dst_unused:UNUSED_PAD src0_sel:WORD_1 src1_sel:DWORD
	v_and_b32_sdwa v124, v122, v115 dst_sel:DWORD dst_unused:UNUSED_PAD src0_sel:WORD_1 src1_sel:DWORD
	v_and_b32_sdwa v125, v121, v115 dst_sel:DWORD dst_unused:UNUSED_PAD src0_sel:WORD_1 src1_sel:DWORD
	v_and_b32_sdwa v126, v120, v115 dst_sel:DWORD dst_unused:UNUSED_PAD src0_sel:WORD_1 src1_sel:DWORD
	v_add3_u32 v130, v37, v32, s69
	v_add3_u32 v32, v36, v33, s69
	v_add3_u32 v33, v35, v117, s69
	v_add3_u32 v117, v34, v118, s69
	v_add3_u32 v131, v123, v119, s69
	v_add3_u32 v132, v122, v124, s69
	v_add3_u32 v127, v121, v125, s69
	v_add3_u32 v126, v120, v126, s69
	v_and_b32_e32 v119, 0xffff0000, v33
	v_and_b32_e32 v118, 0xffff0000, v117
	v_and_b32_e32 v125, 0xffff0000, v130
	v_and_b32_e32 v124, 0xffff0000, v32
	v_and_b32_e32 v129, 0xffff0000, v131
	v_and_b32_e32 v128, 0xffff0000, v132
	v_and_b32_e32 v127, 0xffff0000, v127
	v_and_b32_e32 v126, 0xffff0000, v126
	v_or_b32_sdwa v32, v118, v32 dst_sel:DWORD dst_unused:UNUSED_PAD src0_sel:DWORD src1_sel:WORD_1
	v_pk_add_f32 v[36:37], v[36:37], v[124:125] neg_lo:[0,1] neg_hi:[0,1]
	v_pk_add_f32 v[124:125], v[34:35], v[118:119] neg_lo:[0,1] neg_hi:[0,1]
	v_or_b32_sdwa v33, v119, v130 dst_sel:DWORD dst_unused:UNUSED_PAD src0_sel:DWORD src1_sel:WORD_1
	v_pk_add_f32 v[118:119], v[122:123], v[128:129] neg_lo:[0,1] neg_hi:[0,1]
	v_pk_add_f32 v[120:121], v[120:121], v[126:127] neg_lo:[0,1] neg_hi:[0,1]
	v_bfe_u32 v128, v37, 16, 1
	v_bfe_u32 v130, v119, 16, 1
	v_or_b32_sdwa v35, v127, v131 dst_sel:DWORD dst_unused:UNUSED_PAD src0_sel:DWORD src1_sel:WORD_1
	v_bfe_u32 v117, v121, 16, 1
	v_bfe_u32 v127, v36, 16, 1
	v_bfe_u32 v129, v118, 16, 1
	v_add3_u32 v119, v119, v130, s69
	v_add3_u32 v37, v37, v128, s69
	v_or_b32_sdwa v34, v126, v132 dst_sel:DWORD dst_unused:UNUSED_PAD src0_sel:DWORD src1_sel:WORD_1
	v_bfe_u32 v122, v120, 16, 1
	v_bfe_u32 v123, v125, 16, 1
	v_bfe_u32 v126, v124, 16, 1
	v_add3_u32 v117, v121, v117, s69
	v_add3_u32 v118, v118, v129, s69
	v_add3_u32 v36, v36, v127, s69
	v_lshrrev_b32_e32 v140, 16, v37
	v_lshrrev_b32_e32 v37, 16, v119
	v_add3_u32 v136, v124, v126, s69
	v_add3_u32 v137, v125, v123, s69
	v_add3_u32 v138, v120, v122, s69
	v_lshrrev_b32_e32 v139, 16, v36
	v_lshrrev_b32_e32 v36, 16, v118
	v_and_or_b32 v37, v117, s70, v37
	v_and_or_b32 v36, v138, s70, v36
	s_waitcnt vmcnt(15)
	v_and_b32_sdwa v117, v81, v115 dst_sel:DWORD dst_unused:UNUSED_PAD src0_sel:WORD_1 src1_sel:DWORD
	s_waitcnt vmcnt(14)
	v_and_b32_sdwa v118, v80, v115 dst_sel:DWORD dst_unused:UNUSED_PAD src0_sel:WORD_1 src1_sel:DWORD
	s_waitcnt vmcnt(13)
	v_and_b32_sdwa v119, v89, v115 dst_sel:DWORD dst_unused:UNUSED_PAD src0_sel:WORD_1 src1_sel:DWORD
	s_waitcnt vmcnt(12)
	v_and_b32_sdwa v120, v88, v115 dst_sel:DWORD dst_unused:UNUSED_PAD src0_sel:WORD_1 src1_sel:DWORD
	s_waitcnt vmcnt(11)
	v_and_b32_sdwa v121, v47, v115 dst_sel:DWORD dst_unused:UNUSED_PAD src0_sel:WORD_1 src1_sel:DWORD
	s_waitcnt vmcnt(10)
	v_and_b32_sdwa v122, v46, v115 dst_sel:DWORD dst_unused:UNUSED_PAD src0_sel:WORD_1 src1_sel:DWORD
	s_waitcnt vmcnt(9)
	v_and_b32_sdwa v123, v87, v115 dst_sel:DWORD dst_unused:UNUSED_PAD src0_sel:WORD_1 src1_sel:DWORD
	s_waitcnt vmcnt(8)
	v_and_b32_sdwa v124, v86, v115 dst_sel:DWORD dst_unused:UNUSED_PAD src0_sel:WORD_1 src1_sel:DWORD
	s_waitcnt vmcnt(7)
	v_and_b32_sdwa v125, v45, v115 dst_sel:DWORD dst_unused:UNUSED_PAD src0_sel:WORD_1 src1_sel:DWORD
	v_add3_u32 v117, v81, v117, s69
	v_add3_u32 v118, v80, v118, s69
	v_add3_u32 v119, v89, v119, s69
	v_add3_u32 v120, v88, v120, s69
	v_add3_u32 v133, v87, v123, s69
	v_add3_u32 v124, v86, v124, s69
	s_waitcnt vmcnt(5)
	v_and_b32_sdwa v127, v85, v115 dst_sel:DWORD dst_unused:UNUSED_PAD src0_sel:WORD_1 src1_sel:DWORD
	s_waitcnt vmcnt(4)
	v_and_b32_sdwa v128, v84, v115 dst_sel:DWORD dst_unused:UNUSED_PAD src0_sel:WORD_1 src1_sel:DWORD
	s_waitcnt vmcnt(1)
	v_and_b32_sdwa v131, v83, v115 dst_sel:DWORD dst_unused:UNUSED_PAD src0_sel:WORD_1 src1_sel:DWORD
	s_waitcnt vmcnt(0)
	v_and_b32_sdwa v132, v82, v115 dst_sel:DWORD dst_unused:UNUSED_PAD src0_sel:WORD_1 src1_sel:DWORD
	v_add3_u32 v141, v47, v121, s69
	v_add3_u32 v142, v46, v122, s69
	v_add3_u32 v143, v45, v125, s69
	v_and_b32_e32 v121, 0xffff0000, v119
	v_and_b32_e32 v120, 0xffff0000, v120
	v_and_b32_e32 v123, 0xffff0000, v117
	v_and_b32_e32 v122, 0xffff0000, v118
	v_and_b32_e32 v125, 0xffff0000, v133
	v_and_b32_e32 v124, 0xffff0000, v124
	v_and_b32_sdwa v126, v44, v115 dst_sel:DWORD dst_unused:UNUSED_PAD src0_sel:WORD_1 src1_sel:DWORD
	v_and_b32_sdwa v129, v43, v115 dst_sel:DWORD dst_unused:UNUSED_PAD src0_sel:WORD_1 src1_sel:DWORD
	v_and_b32_sdwa v130, v42, v115 dst_sel:DWORD dst_unused:UNUSED_PAD src0_sel:WORD_1 src1_sel:DWORD
	v_add3_u32 v134, v85, v127, s69
	v_add3_u32 v128, v84, v128, s69
	v_add3_u32 v135, v83, v131, s69
	v_add3_u32 v132, v82, v132, s69
	v_or_b32_sdwa v118, v120, v118 dst_sel:DWORD dst_unused:UNUSED_PAD src0_sel:DWORD src1_sel:WORD_1
	v_pk_add_f32 v[80:81], v[80:81], v[122:123] neg_lo:[0,1] neg_hi:[0,1]
	v_pk_add_f32 v[122:123], v[88:89], v[120:121] neg_lo:[0,1] neg_hi:[0,1]
	v_or_b32_sdwa v119, v121, v117 dst_sel:DWORD dst_unused:UNUSED_PAD src0_sel:DWORD src1_sel:WORD_1
	v_or_b32_sdwa v120, v124, v142 dst_sel:DWORD dst_unused:UNUSED_PAD src0_sel:DWORD src1_sel:WORD_1
	v_or_b32_sdwa v121, v125, v141 dst_sel:DWORD dst_unused:UNUSED_PAD src0_sel:DWORD src1_sel:WORD_1
	v_add3_u32 v144, v44, v126, s69
	v_add3_u32 v145, v43, v129, s69
	v_add3_u32 v146, v42, v130, s69
	v_and_b32_e32 v127, 0xffff0000, v141
	v_and_b32_e32 v126, 0xffff0000, v142
	v_and_b32_e32 v129, 0xffff0000, v134
	v_and_b32_e32 v128, 0xffff0000, v128
	v_and_b32_e32 v133, 0xffff0000, v135
	v_and_b32_e32 v132, 0xffff0000, v132
	v_mfma_f32_32x32x16_bf16 v[0:15], v[32:35], v[118:121], v[0:15]
	v_add_f32_e64 v46, v46, -v126
	v_add_f32_e64 v47, v47, -v127
	v_add_f32_e64 v126, v86, -v124
	v_add_f32_e64 v127, v87, -v125
	v_or_b32_sdwa v86, v128, v144 dst_sel:DWORD dst_unused:UNUSED_PAD src0_sel:DWORD src1_sel:WORD_1
	v_or_b32_sdwa v87, v129, v143 dst_sel:DWORD dst_unused:UNUSED_PAD src0_sel:DWORD src1_sel:WORD_1
	v_or_b32_sdwa v88, v132, v146 dst_sel:DWORD dst_unused:UNUSED_PAD src0_sel:DWORD src1_sel:WORD_1
	v_or_b32_sdwa v89, v133, v145 dst_sel:DWORD dst_unused:UNUSED_PAD src0_sel:DWORD src1_sel:WORD_1
	v_and_b32_e32 v131, 0xffff0000, v143
	v_and_b32_e32 v130, 0xffff0000, v144
	v_mfma_f32_32x32x16_bf16 v[16:31], v[32:35], v[86:89], v[16:31]
	v_and_b32_e32 v135, 0xffff0000, v145
	v_and_b32_e32 v134, 0xffff0000, v146
	v_add_f32_e64 v44, v44, -v130
	v_add_f32_e64 v45, v45, -v131
	v_add_f32_e64 v84, v84, -v128
	v_add_f32_e64 v85, v85, -v129
	v_pk_add_f32 v[42:43], v[42:43], v[134:135] neg_lo:[0,1] neg_hi:[0,1]
	v_pk_add_f32 v[82:83], v[82:83], v[132:133] neg_lo:[0,1] neg_hi:[0,1]
	v_bfe_u32 v129, v80, 16, 1
	v_bfe_u32 v130, v81, 16, 1
	v_bfe_u32 v131, v46, 16, 1
	v_bfe_u32 v132, v47, 16, 1
	v_bfe_u32 v117, v127, 16, 1
	v_bfe_u32 v124, v126, 16, 1
	v_bfe_u32 v125, v123, 16, 1
	v_bfe_u32 v128, v122, 16, 1
	v_bfe_u32 v142, v44, 16, 1
	v_bfe_u32 v143, v45, 16, 1
	v_bfe_u32 v144, v42, 16, 1
	v_bfe_u32 v145, v43, 16, 1
	v_add3_u32 v47, v47, v132, s69
	v_add3_u32 v46, v46, v131, s69
	v_add3_u32 v81, v81, v130, s69
	v_add3_u32 v80, v80, v129, s69
	v_add3_u32 v122, v122, v128, s69
	v_add3_u32 v123, v123, v125, s69
	v_add3_u32 v124, v126, v124, s69
	v_add3_u32 v117, v127, v117, s69
	v_add3_u32 v125, v43, v145, s69
	v_add3_u32 v126, v42, v144, s69
	v_add3_u32 v127, v45, v143, s69
	v_add3_u32 v42, v44, v142, s69
	v_lshrrev_b32_e32 v80, 16, v80
	v_lshrrev_b32_e32 v43, 16, v81
	v_lshrrev_b32_e32 v44, 16, v46
	v_lshrrev_b32_e32 v45, 16, v47
	v_bfe_u32 v133, v83, 16, 1
	v_bfe_u32 v134, v82, 16, 1
	v_bfe_u32 v135, v85, 16, 1
	v_bfe_u32 v141, v84, 16, 1
	v_lshrrev_b32_e32 v46, 16, v42
	v_and_or_b32 v45, v117, s70, v45
	v_and_or_b32 v44, v124, s70, v44
	v_and_or_b32 v43, v123, s70, v43
	v_and_or_b32 v42, v122, s70, v80
	v_add3_u32 v84, v84, v141, s69
	v_add3_u32 v85, v85, v135, s69
	v_add3_u32 v82, v82, v134, s69
	v_add3_u32 v83, v83, v133, s69
	v_mfma_f32_32x32x16_bf16 v[0:15], v[32:35], v[42:45], v[0:15]
	v_lshrrev_b32_e32 v42, 16, v127
	v_lshrrev_b32_e32 v43, 16, v126
	v_lshrrev_b32_e32 v44, 16, v125
	v_and_or_b32 v45, v83, s70, v44
	v_and_or_b32 v44, v82, s70, v43
	v_and_or_b32 v43, v85, s70, v42
	v_and_or_b32 v42, v84, s70, v46
	s_nop 1
	v_mfma_f32_32x32x16_bf16 v[16:31], v[32:35], v[42:45], v[16:31]
	v_and_or_b32 v35, v137, s70, v140
	v_and_or_b32 v34, v136, s70, v139
	s_nop 1
	v_mfma_f32_32x32x16_bf16 v[0:15], v[34:37], v[118:121], v[0:15]
	v_mfma_f32_32x32x16_bf16 v[16:31], v[34:37], v[86:89], v[16:31]
	s_nop 0
	ds_read_b128 v[32:35], v116
	ds_read_b128 v[118:121], v116 offset:16
	s_waitcnt lgkmcnt(1)
	v_cndmask_b32_e64 v35, 0, v35, s[2:3]
	s_waitcnt lgkmcnt(0)
	v_cndmask_b32_e64 v121, 0, v121, s[2:3]
	v_and_b32_sdwa v117, v35, v115 dst_sel:DWORD dst_unused:UNUSED_PAD src0_sel:WORD_1 src1_sel:DWORD
	s_nop 0
	s_nop 0
	s_nop 0
	s_nop 0
	v_add_u32_e32 v116, 64, v116
	s_nop 0
	s_nop 1
	s_nop 1
	s_nop 1
	s_nop 1
	s_nop 1
	s_nop 1
	s_nop 1
	v_mov_b32_e32 v81, v148
	s_nop 0
	v_mov_b32_e32 v80, v149
	v_mov_b32_e32 v89, v150
	v_mov_b32_e32 v88, v151
	s_nop 0
	v_mov_b32_e32 v47, v152
	v_mov_b32_e32 v46, v153
	v_mov_b32_e32 v87, v154
	v_mov_b32_e32 v86, v155
	v_mov_b32_e32 v45, v156
	v_mov_b32_e32 v44, v157
	s_nop 0
	v_mov_b32_e32 v85, v158
	v_mov_b32_e32 v84, v159
	v_mov_b32_e32 v43, v160
	v_mov_b32_e32 v42, v161
	v_mov_b32_e32 v83, v162
	v_mov_b32_e32 v82, v163
	s_mov_b32 s101, 0
	s_add_u32 s100, s1, 0x134e00
	v_lshl_add_u64 v[250:251], v[40:41], 0, s[100:101]
	global_load_dword v148, v[250:251], off offset:3136
	s_add_u32 s100, s33, 0x134e00
	v_lshl_add_u64 v[252:253], v[40:41], 0, s[100:101]
	global_load_dword v149, v[252:253], off offset:1024
	s_add_u32 s100, s75, 0x134e00
	v_lshl_add_u64 v[250:251], v[40:41], 0, s[100:101]
	global_load_dword v150, v[250:251], off offset:2144
	s_add_u32 s100, s74, 0x134e00
	v_lshl_add_u64 v[252:253], v[40:41], 0, s[100:101]
	global_load_dword v151, v[252:253], off offset:32
	s_add_u32 s100, s78, 0x134e00
	v_lshl_add_u64 v[250:251], v[40:41], 0, s[100:101]
	global_load_dword v152, v[250:251], off offset:3264
	s_add_u32 s100, s76, 0x134e00
	v_lshl_add_u64 v[252:253], v[40:41], 0, s[100:101]
	global_load_dword v153, v[252:253], off offset:1152
	s_add_u32 s100, s79, 0x134e00
	v_lshl_add_u64 v[250:251], v[40:41], 0, s[100:101]
	global_load_dword v154, v[250:251], off offset:2272
	s_add_u32 s100, s77, 0x134e00
	v_lshl_add_u64 v[252:253], v[40:41], 0, s[100:101]
	global_load_dword v155, v[252:253], off offset:160
	s_add_u32 s100, s1, 0x134e00
	v_lshl_add_u64 v[250:251], v[38:39], 0, s[100:101]
	global_load_dword v156, v[250:251], off offset:3136
	s_add_u32 s100, s33, 0x134e00
	v_lshl_add_u64 v[252:253], v[38:39], 0, s[100:101]
	global_load_dword v157, v[252:253], off offset:1024
	s_add_u32 s100, s75, 0x134e00
	v_lshl_add_u64 v[250:251], v[38:39], 0, s[100:101]
	global_load_dword v158, v[250:251], off offset:2144
	s_add_u32 s100, s74, 0x134e00
	v_lshl_add_u64 v[252:253], v[38:39], 0, s[100:101]
	global_load_dword v159, v[252:253], off offset:32
	s_add_u32 s100, s78, 0x134e00
	v_lshl_add_u64 v[250:251], v[38:39], 0, s[100:101]
	global_load_dword v160, v[250:251], off offset:3264
	s_add_u32 s100, s76, 0x134e00
	v_lshl_add_u64 v[252:253], v[38:39], 0, s[100:101]
	global_load_dword v161, v[252:253], off offset:1152
	s_add_u32 s100, s79, 0x134e00
	v_lshl_add_u64 v[250:251], v[38:39], 0, s[100:101]
	global_load_dword v162, v[250:251], off offset:2272
	s_add_u32 s100, s77, 0x134e00
	v_lshl_add_u64 v[252:253], v[38:39], 0, s[100:101]
	global_load_dword v163, v[252:253], off offset:160
	v_cndmask_b32_e64 v37, 0, v34, s[2:3]
	v_cndmask_b32_e64 v36, 0, v32, s[2:3]
	v_cndmask_b32_e64 v34, 0, v33, s[2:3]
	v_cndmask_b32_e64 v123, 0, v120, s[2:3]
	v_cndmask_b32_e64 v122, 0, v118, s[2:3]
	v_cndmask_b32_e64 v120, 0, v119, s[2:3]
	v_and_b32_sdwa v32, v37, v115 dst_sel:DWORD dst_unused:UNUSED_PAD src0_sel:WORD_1 src1_sel:DWORD
	v_and_b32_sdwa v33, v36, v115 dst_sel:DWORD dst_unused:UNUSED_PAD src0_sel:WORD_1 src1_sel:DWORD
	v_and_b32_sdwa v118, v34, v115 dst_sel:DWORD dst_unused:UNUSED_PAD src0_sel:WORD_1 src1_sel:DWORD
	v_and_b32_sdwa v119, v123, v115 dst_sel:DWORD dst_unused:UNUSED_PAD src0_sel:WORD_1 src1_sel:DWORD
	v_and_b32_sdwa v124, v122, v115 dst_sel:DWORD dst_unused:UNUSED_PAD src0_sel:WORD_1 src1_sel:DWORD
	v_and_b32_sdwa v125, v121, v115 dst_sel:DWORD dst_unused:UNUSED_PAD src0_sel:WORD_1 src1_sel:DWORD
	v_and_b32_sdwa v126, v120, v115 dst_sel:DWORD dst_unused:UNUSED_PAD src0_sel:WORD_1 src1_sel:DWORD
	v_add3_u32 v130, v37, v32, s69
	v_add3_u32 v32, v36, v33, s69
	v_add3_u32 v33, v35, v117, s69
	v_add3_u32 v117, v34, v118, s69
	v_add3_u32 v131, v123, v119, s69
	v_add3_u32 v132, v122, v124, s69
	v_add3_u32 v127, v121, v125, s69
	v_add3_u32 v126, v120, v126, s69
	v_and_b32_e32 v119, 0xffff0000, v33
	v_and_b32_e32 v118, 0xffff0000, v117
	v_and_b32_e32 v125, 0xffff0000, v130
	v_and_b32_e32 v124, 0xffff0000, v32
	v_and_b32_e32 v129, 0xffff0000, v131
	v_and_b32_e32 v128, 0xffff0000, v132
	v_and_b32_e32 v127, 0xffff0000, v127
	v_and_b32_e32 v126, 0xffff0000, v126
	v_or_b32_sdwa v32, v118, v32 dst_sel:DWORD dst_unused:UNUSED_PAD src0_sel:DWORD src1_sel:WORD_1
	v_pk_add_f32 v[36:37], v[36:37], v[124:125] neg_lo:[0,1] neg_hi:[0,1]
	v_pk_add_f32 v[124:125], v[34:35], v[118:119] neg_lo:[0,1] neg_hi:[0,1]
	v_or_b32_sdwa v33, v119, v130 dst_sel:DWORD dst_unused:UNUSED_PAD src0_sel:DWORD src1_sel:WORD_1
	v_pk_add_f32 v[118:119], v[122:123], v[128:129] neg_lo:[0,1] neg_hi:[0,1]
	v_pk_add_f32 v[120:121], v[120:121], v[126:127] neg_lo:[0,1] neg_hi:[0,1]
	v_bfe_u32 v128, v37, 16, 1
	v_bfe_u32 v130, v119, 16, 1
	v_or_b32_sdwa v35, v127, v131 dst_sel:DWORD dst_unused:UNUSED_PAD src0_sel:DWORD src1_sel:WORD_1
	v_bfe_u32 v117, v121, 16, 1
	v_bfe_u32 v127, v36, 16, 1
	v_bfe_u32 v129, v118, 16, 1
	v_add3_u32 v119, v119, v130, s69
	v_add3_u32 v37, v37, v128, s69
	v_or_b32_sdwa v34, v126, v132 dst_sel:DWORD dst_unused:UNUSED_PAD src0_sel:DWORD src1_sel:WORD_1
	v_bfe_u32 v122, v120, 16, 1
	v_bfe_u32 v123, v125, 16, 1
	v_bfe_u32 v126, v124, 16, 1
	v_add3_u32 v117, v121, v117, s69
	v_add3_u32 v118, v118, v129, s69
	v_add3_u32 v36, v36, v127, s69
	v_lshrrev_b32_e32 v140, 16, v37
	v_lshrrev_b32_e32 v37, 16, v119
	v_add3_u32 v136, v124, v126, s69
	v_add3_u32 v137, v125, v123, s69
	v_add3_u32 v138, v120, v122, s69
	v_lshrrev_b32_e32 v139, 16, v36
	v_lshrrev_b32_e32 v36, 16, v118
	v_and_or_b32 v37, v117, s70, v37
	v_and_or_b32 v36, v138, s70, v36
	v_and_b32_sdwa v117, v81, v115 dst_sel:DWORD dst_unused:UNUSED_PAD src0_sel:WORD_1 src1_sel:DWORD
	v_and_b32_sdwa v118, v80, v115 dst_sel:DWORD dst_unused:UNUSED_PAD src0_sel:WORD_1 src1_sel:DWORD
	v_and_b32_sdwa v119, v89, v115 dst_sel:DWORD dst_unused:UNUSED_PAD src0_sel:WORD_1 src1_sel:DWORD
	v_and_b32_sdwa v120, v88, v115 dst_sel:DWORD dst_unused:UNUSED_PAD src0_sel:WORD_1 src1_sel:DWORD
	v_and_b32_sdwa v121, v47, v115 dst_sel:DWORD dst_unused:UNUSED_PAD src0_sel:WORD_1 src1_sel:DWORD
	v_and_b32_sdwa v122, v46, v115 dst_sel:DWORD dst_unused:UNUSED_PAD src0_sel:WORD_1 src1_sel:DWORD
	v_and_b32_sdwa v123, v87, v115 dst_sel:DWORD dst_unused:UNUSED_PAD src0_sel:WORD_1 src1_sel:DWORD
	v_and_b32_sdwa v124, v86, v115 dst_sel:DWORD dst_unused:UNUSED_PAD src0_sel:WORD_1 src1_sel:DWORD
	v_and_b32_sdwa v125, v45, v115 dst_sel:DWORD dst_unused:UNUSED_PAD src0_sel:WORD_1 src1_sel:DWORD
	v_add3_u32 v117, v81, v117, s69
	v_add3_u32 v118, v80, v118, s69
	v_add3_u32 v119, v89, v119, s69
	v_add3_u32 v120, v88, v120, s69
	v_add3_u32 v133, v87, v123, s69
	v_add3_u32 v124, v86, v124, s69
	v_and_b32_sdwa v127, v85, v115 dst_sel:DWORD dst_unused:UNUSED_PAD src0_sel:WORD_1 src1_sel:DWORD
	v_and_b32_sdwa v128, v84, v115 dst_sel:DWORD dst_unused:UNUSED_PAD src0_sel:WORD_1 src1_sel:DWORD
	v_and_b32_sdwa v131, v83, v115 dst_sel:DWORD dst_unused:UNUSED_PAD src0_sel:WORD_1 src1_sel:DWORD
	v_and_b32_sdwa v132, v82, v115 dst_sel:DWORD dst_unused:UNUSED_PAD src0_sel:WORD_1 src1_sel:DWORD
	v_add3_u32 v141, v47, v121, s69
	v_add3_u32 v142, v46, v122, s69
	v_add3_u32 v143, v45, v125, s69
	v_and_b32_e32 v121, 0xffff0000, v119
	v_and_b32_e32 v120, 0xffff0000, v120
	v_and_b32_e32 v123, 0xffff0000, v117
	v_and_b32_e32 v122, 0xffff0000, v118
	v_and_b32_e32 v125, 0xffff0000, v133
	v_and_b32_e32 v124, 0xffff0000, v124
	v_and_b32_sdwa v126, v44, v115 dst_sel:DWORD dst_unused:UNUSED_PAD src0_sel:WORD_1 src1_sel:DWORD
	v_and_b32_sdwa v129, v43, v115 dst_sel:DWORD dst_unused:UNUSED_PAD src0_sel:WORD_1 src1_sel:DWORD
	v_and_b32_sdwa v130, v42, v115 dst_sel:DWORD dst_unused:UNUSED_PAD src0_sel:WORD_1 src1_sel:DWORD
	v_add3_u32 v134, v85, v127, s69
	v_add3_u32 v128, v84, v128, s69
	v_add3_u32 v135, v83, v131, s69
	v_add3_u32 v132, v82, v132, s69
	v_or_b32_sdwa v118, v120, v118 dst_sel:DWORD dst_unused:UNUSED_PAD src0_sel:DWORD src1_sel:WORD_1
	v_pk_add_f32 v[80:81], v[80:81], v[122:123] neg_lo:[0,1] neg_hi:[0,1]
	v_pk_add_f32 v[122:123], v[88:89], v[120:121] neg_lo:[0,1] neg_hi:[0,1]
	v_or_b32_sdwa v119, v121, v117 dst_sel:DWORD dst_unused:UNUSED_PAD src0_sel:DWORD src1_sel:WORD_1
	v_or_b32_sdwa v120, v124, v142 dst_sel:DWORD dst_unused:UNUSED_PAD src0_sel:DWORD src1_sel:WORD_1
	v_or_b32_sdwa v121, v125, v141 dst_sel:DWORD dst_unused:UNUSED_PAD src0_sel:DWORD src1_sel:WORD_1
	v_add3_u32 v144, v44, v126, s69
	v_add3_u32 v145, v43, v129, s69
	v_add3_u32 v146, v42, v130, s69
	v_and_b32_e32 v127, 0xffff0000, v141
	v_and_b32_e32 v126, 0xffff0000, v142
	v_and_b32_e32 v129, 0xffff0000, v134
	v_and_b32_e32 v128, 0xffff0000, v128
	v_and_b32_e32 v133, 0xffff0000, v135
	v_and_b32_e32 v132, 0xffff0000, v132
	v_mfma_f32_32x32x16_bf16 v[0:15], v[32:35], v[118:121], v[0:15]
	v_add_f32_e64 v46, v46, -v126
	v_add_f32_e64 v47, v47, -v127
	v_add_f32_e64 v126, v86, -v124
	v_add_f32_e64 v127, v87, -v125
	v_or_b32_sdwa v86, v128, v144 dst_sel:DWORD dst_unused:UNUSED_PAD src0_sel:DWORD src1_sel:WORD_1
	v_or_b32_sdwa v87, v129, v143 dst_sel:DWORD dst_unused:UNUSED_PAD src0_sel:DWORD src1_sel:WORD_1
	v_or_b32_sdwa v88, v132, v146 dst_sel:DWORD dst_unused:UNUSED_PAD src0_sel:DWORD src1_sel:WORD_1
	v_or_b32_sdwa v89, v133, v145 dst_sel:DWORD dst_unused:UNUSED_PAD src0_sel:DWORD src1_sel:WORD_1
	v_and_b32_e32 v131, 0xffff0000, v143
	v_and_b32_e32 v130, 0xffff0000, v144
	v_mfma_f32_32x32x16_bf16 v[16:31], v[32:35], v[86:89], v[16:31]
	v_and_b32_e32 v135, 0xffff0000, v145
	v_and_b32_e32 v134, 0xffff0000, v146
	v_add_f32_e64 v44, v44, -v130
	v_add_f32_e64 v45, v45, -v131
	v_add_f32_e64 v84, v84, -v128
	v_add_f32_e64 v85, v85, -v129
	v_pk_add_f32 v[42:43], v[42:43], v[134:135] neg_lo:[0,1] neg_hi:[0,1]
	v_pk_add_f32 v[82:83], v[82:83], v[132:133] neg_lo:[0,1] neg_hi:[0,1]
	v_bfe_u32 v129, v80, 16, 1
	v_bfe_u32 v130, v81, 16, 1
	v_bfe_u32 v131, v46, 16, 1
	v_bfe_u32 v132, v47, 16, 1
	v_bfe_u32 v117, v127, 16, 1
	v_bfe_u32 v124, v126, 16, 1
	v_bfe_u32 v125, v123, 16, 1
	v_bfe_u32 v128, v122, 16, 1
	v_bfe_u32 v142, v44, 16, 1
	v_bfe_u32 v143, v45, 16, 1
	v_bfe_u32 v144, v42, 16, 1
	v_bfe_u32 v145, v43, 16, 1
	v_add3_u32 v47, v47, v132, s69
	v_add3_u32 v46, v46, v131, s69
	v_add3_u32 v81, v81, v130, s69
	v_add3_u32 v80, v80, v129, s69
	v_add3_u32 v122, v122, v128, s69
	v_add3_u32 v123, v123, v125, s69
	v_add3_u32 v124, v126, v124, s69
	v_add3_u32 v117, v127, v117, s69
	v_add3_u32 v125, v43, v145, s69
	v_add3_u32 v126, v42, v144, s69
	v_add3_u32 v127, v45, v143, s69
	v_add3_u32 v42, v44, v142, s69
	v_lshrrev_b32_e32 v80, 16, v80
	v_lshrrev_b32_e32 v43, 16, v81
	v_lshrrev_b32_e32 v44, 16, v46
	v_lshrrev_b32_e32 v45, 16, v47
	v_bfe_u32 v133, v83, 16, 1
	v_bfe_u32 v134, v82, 16, 1
	v_bfe_u32 v135, v85, 16, 1
	v_bfe_u32 v141, v84, 16, 1
	v_lshrrev_b32_e32 v46, 16, v42
	v_and_or_b32 v45, v117, s70, v45
	v_and_or_b32 v44, v124, s70, v44
	v_and_or_b32 v43, v123, s70, v43
	v_and_or_b32 v42, v122, s70, v80
	v_add3_u32 v84, v84, v141, s69
	v_add3_u32 v85, v85, v135, s69
	v_add3_u32 v82, v82, v134, s69
	v_add3_u32 v83, v83, v133, s69
	v_mfma_f32_32x32x16_bf16 v[0:15], v[32:35], v[42:45], v[0:15]
	v_lshrrev_b32_e32 v42, 16, v127
	v_lshrrev_b32_e32 v43, 16, v126
	v_lshrrev_b32_e32 v44, 16, v125
	v_and_or_b32 v45, v83, s70, v44
	v_and_or_b32 v44, v82, s70, v43
	v_and_or_b32 v43, v85, s70, v42
	v_and_or_b32 v42, v84, s70, v46
	s_nop 1
	v_mfma_f32_32x32x16_bf16 v[16:31], v[32:35], v[42:45], v[16:31]
	v_and_or_b32 v35, v137, s70, v140
	v_and_or_b32 v34, v136, s70, v139
	s_nop 1
	v_mfma_f32_32x32x16_bf16 v[0:15], v[34:37], v[118:121], v[0:15]
	v_mfma_f32_32x32x16_bf16 v[16:31], v[34:37], v[86:89], v[16:31]
	s_nop 0
	ds_read_b128 v[32:35], v116
	ds_read_b128 v[118:121], v116 offset:16
	s_waitcnt lgkmcnt(1)
	v_cndmask_b32_e64 v35, 0, v35, s[2:3]
	s_waitcnt lgkmcnt(0)
	v_cndmask_b32_e64 v121, 0, v121, s[2:3]
	v_and_b32_sdwa v117, v35, v115 dst_sel:DWORD dst_unused:UNUSED_PAD src0_sel:WORD_1 src1_sel:DWORD
	s_nop 0
	s_nop 0
	s_nop 0
	s_nop 0
	v_add_u32_e32 v116, 64, v116
	s_nop 0
	s_nop 1
	s_nop 1
	s_nop 1
	s_nop 1
	s_nop 1
	s_nop 1
	s_nop 1
	v_mov_b32_e32 v81, v164
	s_nop 0
	v_mov_b32_e32 v80, v165
	v_mov_b32_e32 v89, v166
	v_mov_b32_e32 v88, v167
	s_nop 0
	v_mov_b32_e32 v47, v168
	v_mov_b32_e32 v46, v169
	v_mov_b32_e32 v87, v170
	v_mov_b32_e32 v86, v171
	v_mov_b32_e32 v45, v172
	v_mov_b32_e32 v44, v173
	s_nop 0
	v_mov_b32_e32 v85, v174
	v_mov_b32_e32 v84, v175
	v_mov_b32_e32 v43, v176
	v_mov_b32_e32 v42, v177
	v_mov_b32_e32 v83, v178
	v_mov_b32_e32 v82, v179
	v_cndmask_b32_e64 v37, 0, v34, s[2:3]
	v_cndmask_b32_e64 v36, 0, v32, s[2:3]
	v_cndmask_b32_e64 v34, 0, v33, s[2:3]
	v_cndmask_b32_e64 v123, 0, v120, s[2:3]
	v_cndmask_b32_e64 v122, 0, v118, s[2:3]
	v_cndmask_b32_e64 v120, 0, v119, s[2:3]
	v_and_b32_sdwa v32, v37, v115 dst_sel:DWORD dst_unused:UNUSED_PAD src0_sel:WORD_1 src1_sel:DWORD
	v_and_b32_sdwa v33, v36, v115 dst_sel:DWORD dst_unused:UNUSED_PAD src0_sel:WORD_1 src1_sel:DWORD
	v_and_b32_sdwa v118, v34, v115 dst_sel:DWORD dst_unused:UNUSED_PAD src0_sel:WORD_1 src1_sel:DWORD
	v_and_b32_sdwa v119, v123, v115 dst_sel:DWORD dst_unused:UNUSED_PAD src0_sel:WORD_1 src1_sel:DWORD
	v_and_b32_sdwa v124, v122, v115 dst_sel:DWORD dst_unused:UNUSED_PAD src0_sel:WORD_1 src1_sel:DWORD
	v_and_b32_sdwa v125, v121, v115 dst_sel:DWORD dst_unused:UNUSED_PAD src0_sel:WORD_1 src1_sel:DWORD
	v_and_b32_sdwa v126, v120, v115 dst_sel:DWORD dst_unused:UNUSED_PAD src0_sel:WORD_1 src1_sel:DWORD
	v_add3_u32 v130, v37, v32, s69
	v_add3_u32 v32, v36, v33, s69
	v_add3_u32 v33, v35, v117, s69
	v_add3_u32 v117, v34, v118, s69
	v_add3_u32 v131, v123, v119, s69
	v_add3_u32 v132, v122, v124, s69
	v_add3_u32 v127, v121, v125, s69
	v_add3_u32 v126, v120, v126, s69
	v_and_b32_e32 v119, 0xffff0000, v33
	v_and_b32_e32 v118, 0xffff0000, v117
	v_and_b32_e32 v125, 0xffff0000, v130
	v_and_b32_e32 v124, 0xffff0000, v32
	v_and_b32_e32 v129, 0xffff0000, v131
	v_and_b32_e32 v128, 0xffff0000, v132
	v_and_b32_e32 v127, 0xffff0000, v127
	v_and_b32_e32 v126, 0xffff0000, v126
	v_or_b32_sdwa v32, v118, v32 dst_sel:DWORD dst_unused:UNUSED_PAD src0_sel:DWORD src1_sel:WORD_1
	v_pk_add_f32 v[36:37], v[36:37], v[124:125] neg_lo:[0,1] neg_hi:[0,1]
	v_pk_add_f32 v[124:125], v[34:35], v[118:119] neg_lo:[0,1] neg_hi:[0,1]
	v_or_b32_sdwa v33, v119, v130 dst_sel:DWORD dst_unused:UNUSED_PAD src0_sel:DWORD src1_sel:WORD_1
	v_pk_add_f32 v[118:119], v[122:123], v[128:129] neg_lo:[0,1] neg_hi:[0,1]
	v_pk_add_f32 v[120:121], v[120:121], v[126:127] neg_lo:[0,1] neg_hi:[0,1]
	v_bfe_u32 v128, v37, 16, 1
	v_bfe_u32 v130, v119, 16, 1
	v_or_b32_sdwa v35, v127, v131 dst_sel:DWORD dst_unused:UNUSED_PAD src0_sel:DWORD src1_sel:WORD_1
	v_bfe_u32 v117, v121, 16, 1
	v_bfe_u32 v127, v36, 16, 1
	v_bfe_u32 v129, v118, 16, 1
	v_add3_u32 v119, v119, v130, s69
	v_add3_u32 v37, v37, v128, s69
	v_or_b32_sdwa v34, v126, v132 dst_sel:DWORD dst_unused:UNUSED_PAD src0_sel:DWORD src1_sel:WORD_1
	v_bfe_u32 v122, v120, 16, 1
	v_bfe_u32 v123, v125, 16, 1
	v_bfe_u32 v126, v124, 16, 1
	v_add3_u32 v117, v121, v117, s69
	v_add3_u32 v118, v118, v129, s69
	v_add3_u32 v36, v36, v127, s69
	v_lshrrev_b32_e32 v140, 16, v37
	v_lshrrev_b32_e32 v37, 16, v119
	v_add3_u32 v136, v124, v126, s69
	v_add3_u32 v137, v125, v123, s69
	v_add3_u32 v138, v120, v122, s69
	v_lshrrev_b32_e32 v139, 16, v36
	v_lshrrev_b32_e32 v36, 16, v118
	v_and_or_b32 v37, v117, s70, v37
	v_and_or_b32 v36, v138, s70, v36
	v_and_b32_sdwa v117, v81, v115 dst_sel:DWORD dst_unused:UNUSED_PAD src0_sel:WORD_1 src1_sel:DWORD
	v_and_b32_sdwa v118, v80, v115 dst_sel:DWORD dst_unused:UNUSED_PAD src0_sel:WORD_1 src1_sel:DWORD
	v_and_b32_sdwa v119, v89, v115 dst_sel:DWORD dst_unused:UNUSED_PAD src0_sel:WORD_1 src1_sel:DWORD
	v_and_b32_sdwa v120, v88, v115 dst_sel:DWORD dst_unused:UNUSED_PAD src0_sel:WORD_1 src1_sel:DWORD
	v_and_b32_sdwa v121, v47, v115 dst_sel:DWORD dst_unused:UNUSED_PAD src0_sel:WORD_1 src1_sel:DWORD
	v_and_b32_sdwa v122, v46, v115 dst_sel:DWORD dst_unused:UNUSED_PAD src0_sel:WORD_1 src1_sel:DWORD
	v_and_b32_sdwa v123, v87, v115 dst_sel:DWORD dst_unused:UNUSED_PAD src0_sel:WORD_1 src1_sel:DWORD
	v_and_b32_sdwa v124, v86, v115 dst_sel:DWORD dst_unused:UNUSED_PAD src0_sel:WORD_1 src1_sel:DWORD
	v_and_b32_sdwa v125, v45, v115 dst_sel:DWORD dst_unused:UNUSED_PAD src0_sel:WORD_1 src1_sel:DWORD
	v_add3_u32 v117, v81, v117, s69
	v_add3_u32 v118, v80, v118, s69
	v_add3_u32 v119, v89, v119, s69
	v_add3_u32 v120, v88, v120, s69
	v_add3_u32 v133, v87, v123, s69
	v_add3_u32 v124, v86, v124, s69
	v_and_b32_sdwa v127, v85, v115 dst_sel:DWORD dst_unused:UNUSED_PAD src0_sel:WORD_1 src1_sel:DWORD
	v_and_b32_sdwa v128, v84, v115 dst_sel:DWORD dst_unused:UNUSED_PAD src0_sel:WORD_1 src1_sel:DWORD
	v_and_b32_sdwa v131, v83, v115 dst_sel:DWORD dst_unused:UNUSED_PAD src0_sel:WORD_1 src1_sel:DWORD
	v_and_b32_sdwa v132, v82, v115 dst_sel:DWORD dst_unused:UNUSED_PAD src0_sel:WORD_1 src1_sel:DWORD
	v_add3_u32 v141, v47, v121, s69
	v_add3_u32 v142, v46, v122, s69
	v_add3_u32 v143, v45, v125, s69
	v_and_b32_e32 v121, 0xffff0000, v119
	v_and_b32_e32 v120, 0xffff0000, v120
	v_and_b32_e32 v123, 0xffff0000, v117
	v_and_b32_e32 v122, 0xffff0000, v118
	v_and_b32_e32 v125, 0xffff0000, v133
	v_and_b32_e32 v124, 0xffff0000, v124
	v_and_b32_sdwa v126, v44, v115 dst_sel:DWORD dst_unused:UNUSED_PAD src0_sel:WORD_1 src1_sel:DWORD
	v_and_b32_sdwa v129, v43, v115 dst_sel:DWORD dst_unused:UNUSED_PAD src0_sel:WORD_1 src1_sel:DWORD
	v_and_b32_sdwa v130, v42, v115 dst_sel:DWORD dst_unused:UNUSED_PAD src0_sel:WORD_1 src1_sel:DWORD
	v_add3_u32 v134, v85, v127, s69
	v_add3_u32 v128, v84, v128, s69
	v_add3_u32 v135, v83, v131, s69
	v_add3_u32 v132, v82, v132, s69
	v_or_b32_sdwa v118, v120, v118 dst_sel:DWORD dst_unused:UNUSED_PAD src0_sel:DWORD src1_sel:WORD_1
	v_pk_add_f32 v[80:81], v[80:81], v[122:123] neg_lo:[0,1] neg_hi:[0,1]
	v_pk_add_f32 v[122:123], v[88:89], v[120:121] neg_lo:[0,1] neg_hi:[0,1]
	v_or_b32_sdwa v119, v121, v117 dst_sel:DWORD dst_unused:UNUSED_PAD src0_sel:DWORD src1_sel:WORD_1
	v_or_b32_sdwa v120, v124, v142 dst_sel:DWORD dst_unused:UNUSED_PAD src0_sel:DWORD src1_sel:WORD_1
	v_or_b32_sdwa v121, v125, v141 dst_sel:DWORD dst_unused:UNUSED_PAD src0_sel:DWORD src1_sel:WORD_1
	v_add3_u32 v144, v44, v126, s69
	v_add3_u32 v145, v43, v129, s69
	v_add3_u32 v146, v42, v130, s69
	v_and_b32_e32 v127, 0xffff0000, v141
	v_and_b32_e32 v126, 0xffff0000, v142
	v_and_b32_e32 v129, 0xffff0000, v134
	v_and_b32_e32 v128, 0xffff0000, v128
	v_and_b32_e32 v133, 0xffff0000, v135
	v_and_b32_e32 v132, 0xffff0000, v132
	v_mfma_f32_32x32x16_bf16 v[0:15], v[32:35], v[118:121], v[0:15]
	v_add_f32_e64 v46, v46, -v126
	v_add_f32_e64 v47, v47, -v127
	v_add_f32_e64 v126, v86, -v124
	v_add_f32_e64 v127, v87, -v125
	v_or_b32_sdwa v86, v128, v144 dst_sel:DWORD dst_unused:UNUSED_PAD src0_sel:DWORD src1_sel:WORD_1
	v_or_b32_sdwa v87, v129, v143 dst_sel:DWORD dst_unused:UNUSED_PAD src0_sel:DWORD src1_sel:WORD_1
	v_or_b32_sdwa v88, v132, v146 dst_sel:DWORD dst_unused:UNUSED_PAD src0_sel:DWORD src1_sel:WORD_1
	v_or_b32_sdwa v89, v133, v145 dst_sel:DWORD dst_unused:UNUSED_PAD src0_sel:DWORD src1_sel:WORD_1
	v_and_b32_e32 v131, 0xffff0000, v143
	v_and_b32_e32 v130, 0xffff0000, v144
	v_mfma_f32_32x32x16_bf16 v[16:31], v[32:35], v[86:89], v[16:31]
	v_and_b32_e32 v135, 0xffff0000, v145
	v_and_b32_e32 v134, 0xffff0000, v146
	v_add_f32_e64 v44, v44, -v130
	v_add_f32_e64 v45, v45, -v131
	v_add_f32_e64 v84, v84, -v128
	v_add_f32_e64 v85, v85, -v129
	v_pk_add_f32 v[42:43], v[42:43], v[134:135] neg_lo:[0,1] neg_hi:[0,1]
	v_pk_add_f32 v[82:83], v[82:83], v[132:133] neg_lo:[0,1] neg_hi:[0,1]
	v_bfe_u32 v129, v80, 16, 1
	v_bfe_u32 v130, v81, 16, 1
	v_bfe_u32 v131, v46, 16, 1
	v_bfe_u32 v132, v47, 16, 1
	v_bfe_u32 v117, v127, 16, 1
	v_bfe_u32 v124, v126, 16, 1
	v_bfe_u32 v125, v123, 16, 1
	v_bfe_u32 v128, v122, 16, 1
	v_bfe_u32 v142, v44, 16, 1
	v_bfe_u32 v143, v45, 16, 1
	v_bfe_u32 v144, v42, 16, 1
	v_bfe_u32 v145, v43, 16, 1
	v_add3_u32 v47, v47, v132, s69
	v_add3_u32 v46, v46, v131, s69
	v_add3_u32 v81, v81, v130, s69
	v_add3_u32 v80, v80, v129, s69
	v_add3_u32 v122, v122, v128, s69
	v_add3_u32 v123, v123, v125, s69
	v_add3_u32 v124, v126, v124, s69
	v_add3_u32 v117, v127, v117, s69
	v_add3_u32 v125, v43, v145, s69
	v_add3_u32 v126, v42, v144, s69
	v_add3_u32 v127, v45, v143, s69
	v_add3_u32 v42, v44, v142, s69
	v_lshrrev_b32_e32 v80, 16, v80
	v_lshrrev_b32_e32 v43, 16, v81
	v_lshrrev_b32_e32 v44, 16, v46
	v_lshrrev_b32_e32 v45, 16, v47
	v_bfe_u32 v133, v83, 16, 1
	v_bfe_u32 v134, v82, 16, 1
	v_bfe_u32 v135, v85, 16, 1
	v_bfe_u32 v141, v84, 16, 1
	v_lshrrev_b32_e32 v46, 16, v42
	v_and_or_b32 v45, v117, s70, v45
	v_and_or_b32 v44, v124, s70, v44
	v_and_or_b32 v43, v123, s70, v43
	v_and_or_b32 v42, v122, s70, v80
	v_add3_u32 v84, v84, v141, s69
	v_add3_u32 v85, v85, v135, s69
	v_add3_u32 v82, v82, v134, s69
	v_add3_u32 v83, v83, v133, s69
	v_mfma_f32_32x32x16_bf16 v[0:15], v[32:35], v[42:45], v[0:15]
	v_lshrrev_b32_e32 v42, 16, v127
	v_lshrrev_b32_e32 v43, 16, v126
	v_lshrrev_b32_e32 v44, 16, v125
	v_and_or_b32 v45, v83, s70, v44
	v_and_or_b32 v44, v82, s70, v43
	v_and_or_b32 v43, v85, s70, v42
	v_and_or_b32 v42, v84, s70, v46
	s_nop 1
	v_mfma_f32_32x32x16_bf16 v[16:31], v[32:35], v[42:45], v[16:31]
	v_and_or_b32 v35, v137, s70, v140
	v_and_or_b32 v34, v136, s70, v139
	s_nop 1
	v_mfma_f32_32x32x16_bf16 v[0:15], v[34:37], v[118:121], v[0:15]
	v_mfma_f32_32x32x16_bf16 v[16:31], v[34:37], v[86:89], v[16:31]
	s_nop 0
	ds_read_b128 v[32:35], v116
	ds_read_b128 v[118:121], v116 offset:16
	s_waitcnt lgkmcnt(1)
	v_cndmask_b32_e64 v35, 0, v35, s[2:3]
	s_waitcnt lgkmcnt(0)
	v_cndmask_b32_e64 v121, 0, v121, s[2:3]
	v_and_b32_sdwa v117, v35, v115 dst_sel:DWORD dst_unused:UNUSED_PAD src0_sel:WORD_1 src1_sel:DWORD
	s_nop 0
	s_nop 0
	s_nop 0
	s_nop 0
	v_add_u32_e32 v116, 64, v116
	s_nop 0
	s_nop 1
	s_nop 1
	s_nop 1
	s_nop 1
	s_nop 1
	s_nop 1
	s_nop 1
	v_mov_b32_e32 v81, v180
	s_nop 0
	v_mov_b32_e32 v80, v181
	v_mov_b32_e32 v89, v182
	v_mov_b32_e32 v88, v183
	s_nop 0
	v_mov_b32_e32 v47, v184
	v_mov_b32_e32 v46, v185
	v_mov_b32_e32 v87, v186
	v_mov_b32_e32 v86, v187
	v_mov_b32_e32 v45, v188
	v_mov_b32_e32 v44, v189
	s_nop 0
	v_mov_b32_e32 v85, v190
	v_mov_b32_e32 v84, v191
	v_mov_b32_e32 v43, v192
	v_mov_b32_e32 v42, v193
	v_mov_b32_e32 v83, v194
	v_mov_b32_e32 v82, v195
	v_cndmask_b32_e64 v37, 0, v34, s[2:3]
	v_cndmask_b32_e64 v36, 0, v32, s[2:3]
	v_cndmask_b32_e64 v34, 0, v33, s[2:3]
	v_cndmask_b32_e64 v123, 0, v120, s[2:3]
	v_cndmask_b32_e64 v122, 0, v118, s[2:3]
	v_cndmask_b32_e64 v120, 0, v119, s[2:3]
	v_and_b32_sdwa v32, v37, v115 dst_sel:DWORD dst_unused:UNUSED_PAD src0_sel:WORD_1 src1_sel:DWORD
	v_and_b32_sdwa v33, v36, v115 dst_sel:DWORD dst_unused:UNUSED_PAD src0_sel:WORD_1 src1_sel:DWORD
	v_and_b32_sdwa v118, v34, v115 dst_sel:DWORD dst_unused:UNUSED_PAD src0_sel:WORD_1 src1_sel:DWORD
	v_and_b32_sdwa v119, v123, v115 dst_sel:DWORD dst_unused:UNUSED_PAD src0_sel:WORD_1 src1_sel:DWORD
	v_and_b32_sdwa v124, v122, v115 dst_sel:DWORD dst_unused:UNUSED_PAD src0_sel:WORD_1 src1_sel:DWORD
	v_and_b32_sdwa v125, v121, v115 dst_sel:DWORD dst_unused:UNUSED_PAD src0_sel:WORD_1 src1_sel:DWORD
	v_and_b32_sdwa v126, v120, v115 dst_sel:DWORD dst_unused:UNUSED_PAD src0_sel:WORD_1 src1_sel:DWORD
	v_add3_u32 v130, v37, v32, s69
	v_add3_u32 v32, v36, v33, s69
	v_add3_u32 v33, v35, v117, s69
	v_add3_u32 v117, v34, v118, s69
	v_add3_u32 v131, v123, v119, s69
	v_add3_u32 v132, v122, v124, s69
	v_add3_u32 v127, v121, v125, s69
	v_add3_u32 v126, v120, v126, s69
	v_and_b32_e32 v119, 0xffff0000, v33
	v_and_b32_e32 v118, 0xffff0000, v117
	v_and_b32_e32 v125, 0xffff0000, v130
	v_and_b32_e32 v124, 0xffff0000, v32
	v_and_b32_e32 v129, 0xffff0000, v131
	v_and_b32_e32 v128, 0xffff0000, v132
	v_and_b32_e32 v127, 0xffff0000, v127
	v_and_b32_e32 v126, 0xffff0000, v126
	v_or_b32_sdwa v32, v118, v32 dst_sel:DWORD dst_unused:UNUSED_PAD src0_sel:DWORD src1_sel:WORD_1
	v_pk_add_f32 v[36:37], v[36:37], v[124:125] neg_lo:[0,1] neg_hi:[0,1]
	v_pk_add_f32 v[124:125], v[34:35], v[118:119] neg_lo:[0,1] neg_hi:[0,1]
	v_or_b32_sdwa v33, v119, v130 dst_sel:DWORD dst_unused:UNUSED_PAD src0_sel:DWORD src1_sel:WORD_1
	v_pk_add_f32 v[118:119], v[122:123], v[128:129] neg_lo:[0,1] neg_hi:[0,1]
	v_pk_add_f32 v[120:121], v[120:121], v[126:127] neg_lo:[0,1] neg_hi:[0,1]
	v_bfe_u32 v128, v37, 16, 1
	v_bfe_u32 v130, v119, 16, 1
	v_or_b32_sdwa v35, v127, v131 dst_sel:DWORD dst_unused:UNUSED_PAD src0_sel:DWORD src1_sel:WORD_1
	v_bfe_u32 v117, v121, 16, 1
	v_bfe_u32 v127, v36, 16, 1
	v_bfe_u32 v129, v118, 16, 1
	v_add3_u32 v119, v119, v130, s69
	v_add3_u32 v37, v37, v128, s69
	v_or_b32_sdwa v34, v126, v132 dst_sel:DWORD dst_unused:UNUSED_PAD src0_sel:DWORD src1_sel:WORD_1
	v_bfe_u32 v122, v120, 16, 1
	v_bfe_u32 v123, v125, 16, 1
	v_bfe_u32 v126, v124, 16, 1
	v_add3_u32 v117, v121, v117, s69
	v_add3_u32 v118, v118, v129, s69
	v_add3_u32 v36, v36, v127, s69
	v_lshrrev_b32_e32 v140, 16, v37
	v_lshrrev_b32_e32 v37, 16, v119
	v_add3_u32 v136, v124, v126, s69
	v_add3_u32 v137, v125, v123, s69
	v_add3_u32 v138, v120, v122, s69
	v_lshrrev_b32_e32 v139, 16, v36
	v_lshrrev_b32_e32 v36, 16, v118
	v_and_or_b32 v37, v117, s70, v37
	v_and_or_b32 v36, v138, s70, v36
	v_and_b32_sdwa v117, v81, v115 dst_sel:DWORD dst_unused:UNUSED_PAD src0_sel:WORD_1 src1_sel:DWORD
	v_and_b32_sdwa v118, v80, v115 dst_sel:DWORD dst_unused:UNUSED_PAD src0_sel:WORD_1 src1_sel:DWORD
	v_and_b32_sdwa v119, v89, v115 dst_sel:DWORD dst_unused:UNUSED_PAD src0_sel:WORD_1 src1_sel:DWORD
	v_and_b32_sdwa v120, v88, v115 dst_sel:DWORD dst_unused:UNUSED_PAD src0_sel:WORD_1 src1_sel:DWORD
	v_and_b32_sdwa v121, v47, v115 dst_sel:DWORD dst_unused:UNUSED_PAD src0_sel:WORD_1 src1_sel:DWORD
	v_and_b32_sdwa v122, v46, v115 dst_sel:DWORD dst_unused:UNUSED_PAD src0_sel:WORD_1 src1_sel:DWORD
	v_and_b32_sdwa v123, v87, v115 dst_sel:DWORD dst_unused:UNUSED_PAD src0_sel:WORD_1 src1_sel:DWORD
	v_and_b32_sdwa v124, v86, v115 dst_sel:DWORD dst_unused:UNUSED_PAD src0_sel:WORD_1 src1_sel:DWORD
	v_and_b32_sdwa v125, v45, v115 dst_sel:DWORD dst_unused:UNUSED_PAD src0_sel:WORD_1 src1_sel:DWORD
	v_add3_u32 v117, v81, v117, s69
	v_add3_u32 v118, v80, v118, s69
	v_add3_u32 v119, v89, v119, s69
	v_add3_u32 v120, v88, v120, s69
	v_add3_u32 v133, v87, v123, s69
	v_add3_u32 v124, v86, v124, s69
	v_and_b32_sdwa v127, v85, v115 dst_sel:DWORD dst_unused:UNUSED_PAD src0_sel:WORD_1 src1_sel:DWORD
	v_and_b32_sdwa v128, v84, v115 dst_sel:DWORD dst_unused:UNUSED_PAD src0_sel:WORD_1 src1_sel:DWORD
	v_and_b32_sdwa v131, v83, v115 dst_sel:DWORD dst_unused:UNUSED_PAD src0_sel:WORD_1 src1_sel:DWORD
	v_and_b32_sdwa v132, v82, v115 dst_sel:DWORD dst_unused:UNUSED_PAD src0_sel:WORD_1 src1_sel:DWORD
	v_add3_u32 v141, v47, v121, s69
	v_add3_u32 v142, v46, v122, s69
	v_add3_u32 v143, v45, v125, s69
	v_and_b32_e32 v121, 0xffff0000, v119
	v_and_b32_e32 v120, 0xffff0000, v120
	v_and_b32_e32 v123, 0xffff0000, v117
	v_and_b32_e32 v122, 0xffff0000, v118
	v_and_b32_e32 v125, 0xffff0000, v133
	v_and_b32_e32 v124, 0xffff0000, v124
	v_and_b32_sdwa v126, v44, v115 dst_sel:DWORD dst_unused:UNUSED_PAD src0_sel:WORD_1 src1_sel:DWORD
	v_and_b32_sdwa v129, v43, v115 dst_sel:DWORD dst_unused:UNUSED_PAD src0_sel:WORD_1 src1_sel:DWORD
	v_and_b32_sdwa v130, v42, v115 dst_sel:DWORD dst_unused:UNUSED_PAD src0_sel:WORD_1 src1_sel:DWORD
	v_add3_u32 v134, v85, v127, s69
	v_add3_u32 v128, v84, v128, s69
	v_add3_u32 v135, v83, v131, s69
	v_add3_u32 v132, v82, v132, s69
	v_or_b32_sdwa v118, v120, v118 dst_sel:DWORD dst_unused:UNUSED_PAD src0_sel:DWORD src1_sel:WORD_1
	v_pk_add_f32 v[80:81], v[80:81], v[122:123] neg_lo:[0,1] neg_hi:[0,1]
	v_pk_add_f32 v[122:123], v[88:89], v[120:121] neg_lo:[0,1] neg_hi:[0,1]
	v_or_b32_sdwa v119, v121, v117 dst_sel:DWORD dst_unused:UNUSED_PAD src0_sel:DWORD src1_sel:WORD_1
	v_or_b32_sdwa v120, v124, v142 dst_sel:DWORD dst_unused:UNUSED_PAD src0_sel:DWORD src1_sel:WORD_1
	v_or_b32_sdwa v121, v125, v141 dst_sel:DWORD dst_unused:UNUSED_PAD src0_sel:DWORD src1_sel:WORD_1
	v_add3_u32 v144, v44, v126, s69
	v_add3_u32 v145, v43, v129, s69
	v_add3_u32 v146, v42, v130, s69
	v_and_b32_e32 v127, 0xffff0000, v141
	v_and_b32_e32 v126, 0xffff0000, v142
	v_and_b32_e32 v129, 0xffff0000, v134
	v_and_b32_e32 v128, 0xffff0000, v128
	v_and_b32_e32 v133, 0xffff0000, v135
	v_and_b32_e32 v132, 0xffff0000, v132
	v_mfma_f32_32x32x16_bf16 v[0:15], v[32:35], v[118:121], v[0:15]
	v_add_f32_e64 v46, v46, -v126
	v_add_f32_e64 v47, v47, -v127
	v_add_f32_e64 v126, v86, -v124
	v_add_f32_e64 v127, v87, -v125
	v_or_b32_sdwa v86, v128, v144 dst_sel:DWORD dst_unused:UNUSED_PAD src0_sel:DWORD src1_sel:WORD_1
	v_or_b32_sdwa v87, v129, v143 dst_sel:DWORD dst_unused:UNUSED_PAD src0_sel:DWORD src1_sel:WORD_1
	v_or_b32_sdwa v88, v132, v146 dst_sel:DWORD dst_unused:UNUSED_PAD src0_sel:DWORD src1_sel:WORD_1
	v_or_b32_sdwa v89, v133, v145 dst_sel:DWORD dst_unused:UNUSED_PAD src0_sel:DWORD src1_sel:WORD_1
	v_and_b32_e32 v131, 0xffff0000, v143
	v_and_b32_e32 v130, 0xffff0000, v144
	v_mfma_f32_32x32x16_bf16 v[16:31], v[32:35], v[86:89], v[16:31]
	v_and_b32_e32 v135, 0xffff0000, v145
	v_and_b32_e32 v134, 0xffff0000, v146
	v_add_f32_e64 v44, v44, -v130
	v_add_f32_e64 v45, v45, -v131
	v_add_f32_e64 v84, v84, -v128
	v_add_f32_e64 v85, v85, -v129
	v_pk_add_f32 v[42:43], v[42:43], v[134:135] neg_lo:[0,1] neg_hi:[0,1]
	v_pk_add_f32 v[82:83], v[82:83], v[132:133] neg_lo:[0,1] neg_hi:[0,1]
	v_bfe_u32 v129, v80, 16, 1
	v_bfe_u32 v130, v81, 16, 1
	v_bfe_u32 v131, v46, 16, 1
	v_bfe_u32 v132, v47, 16, 1
	v_bfe_u32 v117, v127, 16, 1
	v_bfe_u32 v124, v126, 16, 1
	v_bfe_u32 v125, v123, 16, 1
	v_bfe_u32 v128, v122, 16, 1
	v_bfe_u32 v142, v44, 16, 1
	v_bfe_u32 v143, v45, 16, 1
	v_bfe_u32 v144, v42, 16, 1
	v_bfe_u32 v145, v43, 16, 1
	v_add3_u32 v47, v47, v132, s69
	v_add3_u32 v46, v46, v131, s69
	v_add3_u32 v81, v81, v130, s69
	v_add3_u32 v80, v80, v129, s69
	v_add3_u32 v122, v122, v128, s69
	v_add3_u32 v123, v123, v125, s69
	v_add3_u32 v124, v126, v124, s69
	v_add3_u32 v117, v127, v117, s69
	v_add3_u32 v125, v43, v145, s69
	v_add3_u32 v126, v42, v144, s69
	v_add3_u32 v127, v45, v143, s69
	v_add3_u32 v42, v44, v142, s69
	v_lshrrev_b32_e32 v80, 16, v80
	v_lshrrev_b32_e32 v43, 16, v81
	v_lshrrev_b32_e32 v44, 16, v46
	v_lshrrev_b32_e32 v45, 16, v47
	v_bfe_u32 v133, v83, 16, 1
	v_bfe_u32 v134, v82, 16, 1
	v_bfe_u32 v135, v85, 16, 1
	v_bfe_u32 v141, v84, 16, 1
	v_lshrrev_b32_e32 v46, 16, v42
	v_and_or_b32 v45, v117, s70, v45
	v_and_or_b32 v44, v124, s70, v44
	v_and_or_b32 v43, v123, s70, v43
	v_and_or_b32 v42, v122, s70, v80
	v_add3_u32 v84, v84, v141, s69
	v_add3_u32 v85, v85, v135, s69
	v_add3_u32 v82, v82, v134, s69
	v_add3_u32 v83, v83, v133, s69
	v_mfma_f32_32x32x16_bf16 v[0:15], v[32:35], v[42:45], v[0:15]
	v_lshrrev_b32_e32 v42, 16, v127
	v_lshrrev_b32_e32 v43, 16, v126
	v_lshrrev_b32_e32 v44, 16, v125
	v_and_or_b32 v45, v83, s70, v44
	v_and_or_b32 v44, v82, s70, v43
	v_and_or_b32 v43, v85, s70, v42
	v_and_or_b32 v42, v84, s70, v46
	s_nop 1
	v_mfma_f32_32x32x16_bf16 v[16:31], v[32:35], v[42:45], v[16:31]
	v_and_or_b32 v35, v137, s70, v140
	v_and_or_b32 v34, v136, s70, v139
	s_nop 1
	v_mfma_f32_32x32x16_bf16 v[0:15], v[34:37], v[118:121], v[0:15]
	v_mfma_f32_32x32x16_bf16 v[16:31], v[34:37], v[86:89], v[16:31]
	s_nop 0
	ds_read_b128 v[32:35], v116
	ds_read_b128 v[118:121], v116 offset:16
	s_waitcnt lgkmcnt(1)
	v_cndmask_b32_e64 v35, 0, v35, s[2:3]
	s_waitcnt lgkmcnt(0)
	v_cndmask_b32_e64 v121, 0, v121, s[2:3]
	v_and_b32_sdwa v117, v35, v115 dst_sel:DWORD dst_unused:UNUSED_PAD src0_sel:WORD_1 src1_sel:DWORD
	s_nop 0
	s_nop 0
	s_nop 0
	s_nop 0
	v_add_u32_e32 v116, 64, v116
	s_nop 0
	s_nop 1
	s_nop 1
	s_nop 1
	s_nop 1
	s_nop 1
	s_nop 1
	s_nop 1
	v_mov_b32_e32 v81, v196
	s_nop 0
	v_mov_b32_e32 v80, v197
	v_mov_b32_e32 v89, v198
	v_mov_b32_e32 v88, v199
	s_nop 0
	v_mov_b32_e32 v47, v200
	v_mov_b32_e32 v46, v201
	v_mov_b32_e32 v87, v202
	v_mov_b32_e32 v86, v203
	v_mov_b32_e32 v45, v204
	v_mov_b32_e32 v44, v205
	s_nop 0
	v_mov_b32_e32 v85, v206
	v_mov_b32_e32 v84, v207
	v_mov_b32_e32 v43, v208
	v_mov_b32_e32 v42, v209
	v_mov_b32_e32 v83, v210
	v_mov_b32_e32 v82, v211
	v_cndmask_b32_e64 v37, 0, v34, s[2:3]
	v_cndmask_b32_e64 v36, 0, v32, s[2:3]
	v_cndmask_b32_e64 v34, 0, v33, s[2:3]
	v_cndmask_b32_e64 v123, 0, v120, s[2:3]
	v_cndmask_b32_e64 v122, 0, v118, s[2:3]
	v_cndmask_b32_e64 v120, 0, v119, s[2:3]
	v_and_b32_sdwa v32, v37, v115 dst_sel:DWORD dst_unused:UNUSED_PAD src0_sel:WORD_1 src1_sel:DWORD
	v_and_b32_sdwa v33, v36, v115 dst_sel:DWORD dst_unused:UNUSED_PAD src0_sel:WORD_1 src1_sel:DWORD
	v_and_b32_sdwa v118, v34, v115 dst_sel:DWORD dst_unused:UNUSED_PAD src0_sel:WORD_1 src1_sel:DWORD
	v_and_b32_sdwa v119, v123, v115 dst_sel:DWORD dst_unused:UNUSED_PAD src0_sel:WORD_1 src1_sel:DWORD
	v_and_b32_sdwa v124, v122, v115 dst_sel:DWORD dst_unused:UNUSED_PAD src0_sel:WORD_1 src1_sel:DWORD
	v_and_b32_sdwa v125, v121, v115 dst_sel:DWORD dst_unused:UNUSED_PAD src0_sel:WORD_1 src1_sel:DWORD
	v_and_b32_sdwa v126, v120, v115 dst_sel:DWORD dst_unused:UNUSED_PAD src0_sel:WORD_1 src1_sel:DWORD
	v_add3_u32 v130, v37, v32, s69
	v_add3_u32 v32, v36, v33, s69
	v_add3_u32 v33, v35, v117, s69
	v_add3_u32 v117, v34, v118, s69
	v_add3_u32 v131, v123, v119, s69
	v_add3_u32 v132, v122, v124, s69
	v_add3_u32 v127, v121, v125, s69
	v_add3_u32 v126, v120, v126, s69
	v_and_b32_e32 v119, 0xffff0000, v33
	v_and_b32_e32 v118, 0xffff0000, v117
	v_and_b32_e32 v125, 0xffff0000, v130
	v_and_b32_e32 v124, 0xffff0000, v32
	v_and_b32_e32 v129, 0xffff0000, v131
	v_and_b32_e32 v128, 0xffff0000, v132
	v_and_b32_e32 v127, 0xffff0000, v127
	v_and_b32_e32 v126, 0xffff0000, v126
	v_or_b32_sdwa v32, v118, v32 dst_sel:DWORD dst_unused:UNUSED_PAD src0_sel:DWORD src1_sel:WORD_1
	v_pk_add_f32 v[36:37], v[36:37], v[124:125] neg_lo:[0,1] neg_hi:[0,1]
	v_pk_add_f32 v[124:125], v[34:35], v[118:119] neg_lo:[0,1] neg_hi:[0,1]
	v_or_b32_sdwa v33, v119, v130 dst_sel:DWORD dst_unused:UNUSED_PAD src0_sel:DWORD src1_sel:WORD_1
	v_pk_add_f32 v[118:119], v[122:123], v[128:129] neg_lo:[0,1] neg_hi:[0,1]
	v_pk_add_f32 v[120:121], v[120:121], v[126:127] neg_lo:[0,1] neg_hi:[0,1]
	v_bfe_u32 v128, v37, 16, 1
	v_bfe_u32 v130, v119, 16, 1
	v_or_b32_sdwa v35, v127, v131 dst_sel:DWORD dst_unused:UNUSED_PAD src0_sel:DWORD src1_sel:WORD_1
	v_bfe_u32 v117, v121, 16, 1
	v_bfe_u32 v127, v36, 16, 1
	v_bfe_u32 v129, v118, 16, 1
	v_add3_u32 v119, v119, v130, s69
	v_add3_u32 v37, v37, v128, s69
	v_or_b32_sdwa v34, v126, v132 dst_sel:DWORD dst_unused:UNUSED_PAD src0_sel:DWORD src1_sel:WORD_1
	v_bfe_u32 v122, v120, 16, 1
	v_bfe_u32 v123, v125, 16, 1
	v_bfe_u32 v126, v124, 16, 1
	v_add3_u32 v117, v121, v117, s69
	v_add3_u32 v118, v118, v129, s69
	v_add3_u32 v36, v36, v127, s69
	v_lshrrev_b32_e32 v140, 16, v37
	v_lshrrev_b32_e32 v37, 16, v119
	v_add3_u32 v136, v124, v126, s69
	v_add3_u32 v137, v125, v123, s69
	v_add3_u32 v138, v120, v122, s69
	v_lshrrev_b32_e32 v139, 16, v36
	v_lshrrev_b32_e32 v36, 16, v118
	v_and_or_b32 v37, v117, s70, v37
	v_and_or_b32 v36, v138, s70, v36
	v_and_b32_sdwa v117, v81, v115 dst_sel:DWORD dst_unused:UNUSED_PAD src0_sel:WORD_1 src1_sel:DWORD
	v_and_b32_sdwa v118, v80, v115 dst_sel:DWORD dst_unused:UNUSED_PAD src0_sel:WORD_1 src1_sel:DWORD
	v_and_b32_sdwa v119, v89, v115 dst_sel:DWORD dst_unused:UNUSED_PAD src0_sel:WORD_1 src1_sel:DWORD
	v_and_b32_sdwa v120, v88, v115 dst_sel:DWORD dst_unused:UNUSED_PAD src0_sel:WORD_1 src1_sel:DWORD
	v_and_b32_sdwa v121, v47, v115 dst_sel:DWORD dst_unused:UNUSED_PAD src0_sel:WORD_1 src1_sel:DWORD
	v_and_b32_sdwa v122, v46, v115 dst_sel:DWORD dst_unused:UNUSED_PAD src0_sel:WORD_1 src1_sel:DWORD
	v_and_b32_sdwa v123, v87, v115 dst_sel:DWORD dst_unused:UNUSED_PAD src0_sel:WORD_1 src1_sel:DWORD
	v_and_b32_sdwa v124, v86, v115 dst_sel:DWORD dst_unused:UNUSED_PAD src0_sel:WORD_1 src1_sel:DWORD
	v_and_b32_sdwa v125, v45, v115 dst_sel:DWORD dst_unused:UNUSED_PAD src0_sel:WORD_1 src1_sel:DWORD
	v_add3_u32 v117, v81, v117, s69
	v_add3_u32 v118, v80, v118, s69
	v_add3_u32 v119, v89, v119, s69
	v_add3_u32 v120, v88, v120, s69
	v_add3_u32 v133, v87, v123, s69
	v_add3_u32 v124, v86, v124, s69
	v_and_b32_sdwa v127, v85, v115 dst_sel:DWORD dst_unused:UNUSED_PAD src0_sel:WORD_1 src1_sel:DWORD
	v_and_b32_sdwa v128, v84, v115 dst_sel:DWORD dst_unused:UNUSED_PAD src0_sel:WORD_1 src1_sel:DWORD
	v_and_b32_sdwa v131, v83, v115 dst_sel:DWORD dst_unused:UNUSED_PAD src0_sel:WORD_1 src1_sel:DWORD
	v_and_b32_sdwa v132, v82, v115 dst_sel:DWORD dst_unused:UNUSED_PAD src0_sel:WORD_1 src1_sel:DWORD
	v_add3_u32 v141, v47, v121, s69
	v_add3_u32 v142, v46, v122, s69
	v_add3_u32 v143, v45, v125, s69
	v_and_b32_e32 v121, 0xffff0000, v119
	v_and_b32_e32 v120, 0xffff0000, v120
	v_and_b32_e32 v123, 0xffff0000, v117
	v_and_b32_e32 v122, 0xffff0000, v118
	v_and_b32_e32 v125, 0xffff0000, v133
	v_and_b32_e32 v124, 0xffff0000, v124
	v_and_b32_sdwa v126, v44, v115 dst_sel:DWORD dst_unused:UNUSED_PAD src0_sel:WORD_1 src1_sel:DWORD
	v_and_b32_sdwa v129, v43, v115 dst_sel:DWORD dst_unused:UNUSED_PAD src0_sel:WORD_1 src1_sel:DWORD
	v_and_b32_sdwa v130, v42, v115 dst_sel:DWORD dst_unused:UNUSED_PAD src0_sel:WORD_1 src1_sel:DWORD
	v_add3_u32 v134, v85, v127, s69
	v_add3_u32 v128, v84, v128, s69
	v_add3_u32 v135, v83, v131, s69
	v_add3_u32 v132, v82, v132, s69
	v_or_b32_sdwa v118, v120, v118 dst_sel:DWORD dst_unused:UNUSED_PAD src0_sel:DWORD src1_sel:WORD_1
	v_pk_add_f32 v[80:81], v[80:81], v[122:123] neg_lo:[0,1] neg_hi:[0,1]
	v_pk_add_f32 v[122:123], v[88:89], v[120:121] neg_lo:[0,1] neg_hi:[0,1]
	v_or_b32_sdwa v119, v121, v117 dst_sel:DWORD dst_unused:UNUSED_PAD src0_sel:DWORD src1_sel:WORD_1
	v_or_b32_sdwa v120, v124, v142 dst_sel:DWORD dst_unused:UNUSED_PAD src0_sel:DWORD src1_sel:WORD_1
	v_or_b32_sdwa v121, v125, v141 dst_sel:DWORD dst_unused:UNUSED_PAD src0_sel:DWORD src1_sel:WORD_1
	v_add3_u32 v144, v44, v126, s69
	v_add3_u32 v145, v43, v129, s69
	v_add3_u32 v146, v42, v130, s69
	v_and_b32_e32 v127, 0xffff0000, v141
	v_and_b32_e32 v126, 0xffff0000, v142
	v_and_b32_e32 v129, 0xffff0000, v134
	v_and_b32_e32 v128, 0xffff0000, v128
	v_and_b32_e32 v133, 0xffff0000, v135
	v_and_b32_e32 v132, 0xffff0000, v132
	v_mfma_f32_32x32x16_bf16 v[0:15], v[32:35], v[118:121], v[0:15]
	v_add_f32_e64 v46, v46, -v126
	v_add_f32_e64 v47, v47, -v127
	v_add_f32_e64 v126, v86, -v124
	v_add_f32_e64 v127, v87, -v125
	v_or_b32_sdwa v86, v128, v144 dst_sel:DWORD dst_unused:UNUSED_PAD src0_sel:DWORD src1_sel:WORD_1
	v_or_b32_sdwa v87, v129, v143 dst_sel:DWORD dst_unused:UNUSED_PAD src0_sel:DWORD src1_sel:WORD_1
	v_or_b32_sdwa v88, v132, v146 dst_sel:DWORD dst_unused:UNUSED_PAD src0_sel:DWORD src1_sel:WORD_1
	v_or_b32_sdwa v89, v133, v145 dst_sel:DWORD dst_unused:UNUSED_PAD src0_sel:DWORD src1_sel:WORD_1
	v_and_b32_e32 v131, 0xffff0000, v143
	v_and_b32_e32 v130, 0xffff0000, v144
	v_mfma_f32_32x32x16_bf16 v[16:31], v[32:35], v[86:89], v[16:31]
	v_and_b32_e32 v135, 0xffff0000, v145
	v_and_b32_e32 v134, 0xffff0000, v146
	v_add_f32_e64 v44, v44, -v130
	v_add_f32_e64 v45, v45, -v131
	v_add_f32_e64 v84, v84, -v128
	v_add_f32_e64 v85, v85, -v129
	v_pk_add_f32 v[42:43], v[42:43], v[134:135] neg_lo:[0,1] neg_hi:[0,1]
	v_pk_add_f32 v[82:83], v[82:83], v[132:133] neg_lo:[0,1] neg_hi:[0,1]
	v_bfe_u32 v129, v80, 16, 1
	v_bfe_u32 v130, v81, 16, 1
	v_bfe_u32 v131, v46, 16, 1
	v_bfe_u32 v132, v47, 16, 1
	v_bfe_u32 v117, v127, 16, 1
	v_bfe_u32 v124, v126, 16, 1
	v_bfe_u32 v125, v123, 16, 1
	v_bfe_u32 v128, v122, 16, 1
	v_bfe_u32 v142, v44, 16, 1
	v_bfe_u32 v143, v45, 16, 1
	v_bfe_u32 v144, v42, 16, 1
	v_bfe_u32 v145, v43, 16, 1
	v_add3_u32 v47, v47, v132, s69
	v_add3_u32 v46, v46, v131, s69
	v_add3_u32 v81, v81, v130, s69
	v_add3_u32 v80, v80, v129, s69
	v_add3_u32 v122, v122, v128, s69
	v_add3_u32 v123, v123, v125, s69
	v_add3_u32 v124, v126, v124, s69
	v_add3_u32 v117, v127, v117, s69
	v_add3_u32 v125, v43, v145, s69
	v_add3_u32 v126, v42, v144, s69
	v_add3_u32 v127, v45, v143, s69
	v_add3_u32 v42, v44, v142, s69
	v_lshrrev_b32_e32 v80, 16, v80
	v_lshrrev_b32_e32 v43, 16, v81
	v_lshrrev_b32_e32 v44, 16, v46
	v_lshrrev_b32_e32 v45, 16, v47
	v_bfe_u32 v133, v83, 16, 1
	v_bfe_u32 v134, v82, 16, 1
	v_bfe_u32 v135, v85, 16, 1
	v_bfe_u32 v141, v84, 16, 1
	v_lshrrev_b32_e32 v46, 16, v42
	v_and_or_b32 v45, v117, s70, v45
	v_and_or_b32 v44, v124, s70, v44
	v_and_or_b32 v43, v123, s70, v43
	v_and_or_b32 v42, v122, s70, v80
	v_add3_u32 v84, v84, v141, s69
	v_add3_u32 v85, v85, v135, s69
	v_add3_u32 v82, v82, v134, s69
	v_add3_u32 v83, v83, v133, s69
	v_mfma_f32_32x32x16_bf16 v[0:15], v[32:35], v[42:45], v[0:15]
	v_lshrrev_b32_e32 v42, 16, v127
	v_lshrrev_b32_e32 v43, 16, v126
	v_lshrrev_b32_e32 v44, 16, v125
	v_and_or_b32 v45, v83, s70, v44
	v_and_or_b32 v44, v82, s70, v43
	v_and_or_b32 v43, v85, s70, v42
	v_and_or_b32 v42, v84, s70, v46
	s_nop 1
	v_mfma_f32_32x32x16_bf16 v[16:31], v[32:35], v[42:45], v[16:31]
	v_and_or_b32 v35, v137, s70, v140
	v_and_or_b32 v34, v136, s70, v139
	s_nop 1
	v_mfma_f32_32x32x16_bf16 v[0:15], v[34:37], v[118:121], v[0:15]
	v_mfma_f32_32x32x16_bf16 v[16:31], v[34:37], v[86:89], v[16:31]
	s_nop 0
	ds_read_b128 v[32:35], v116
	ds_read_b128 v[118:121], v116 offset:16
	s_waitcnt lgkmcnt(1)
	v_cndmask_b32_e64 v35, 0, v35, s[2:3]
	s_waitcnt lgkmcnt(0)
	v_cndmask_b32_e64 v121, 0, v121, s[2:3]
	v_and_b32_sdwa v117, v35, v115 dst_sel:DWORD dst_unused:UNUSED_PAD src0_sel:WORD_1 src1_sel:DWORD
	s_nop 0
	s_nop 0
	s_nop 0
	s_nop 0
	v_add_u32_e32 v116, 64, v116
	s_nop 0
	s_nop 1
	s_nop 1
	s_nop 1
	s_nop 1
	s_nop 1
	s_nop 1
	s_nop 1
	v_mov_b32_e32 v81, v212
	s_nop 0
	v_mov_b32_e32 v80, v213
	v_mov_b32_e32 v89, v214
	v_mov_b32_e32 v88, v215
	s_nop 0
	v_mov_b32_e32 v47, v216
	v_mov_b32_e32 v46, v217
	v_mov_b32_e32 v87, v218
	v_mov_b32_e32 v86, v219
	v_mov_b32_e32 v45, v220
	v_mov_b32_e32 v44, v221
	s_nop 0
	v_mov_b32_e32 v85, v222
	v_mov_b32_e32 v84, v223
	v_mov_b32_e32 v43, v224
	v_mov_b32_e32 v42, v225
	v_mov_b32_e32 v83, v226
	v_mov_b32_e32 v82, v227
	v_cndmask_b32_e64 v37, 0, v34, s[2:3]
	v_cndmask_b32_e64 v36, 0, v32, s[2:3]
	v_cndmask_b32_e64 v34, 0, v33, s[2:3]
	v_cndmask_b32_e64 v123, 0, v120, s[2:3]
	v_cndmask_b32_e64 v122, 0, v118, s[2:3]
	v_cndmask_b32_e64 v120, 0, v119, s[2:3]
	v_and_b32_sdwa v32, v37, v115 dst_sel:DWORD dst_unused:UNUSED_PAD src0_sel:WORD_1 src1_sel:DWORD
	v_and_b32_sdwa v33, v36, v115 dst_sel:DWORD dst_unused:UNUSED_PAD src0_sel:WORD_1 src1_sel:DWORD
	v_and_b32_sdwa v118, v34, v115 dst_sel:DWORD dst_unused:UNUSED_PAD src0_sel:WORD_1 src1_sel:DWORD
	v_and_b32_sdwa v119, v123, v115 dst_sel:DWORD dst_unused:UNUSED_PAD src0_sel:WORD_1 src1_sel:DWORD
	v_and_b32_sdwa v124, v122, v115 dst_sel:DWORD dst_unused:UNUSED_PAD src0_sel:WORD_1 src1_sel:DWORD
	v_and_b32_sdwa v125, v121, v115 dst_sel:DWORD dst_unused:UNUSED_PAD src0_sel:WORD_1 src1_sel:DWORD
	v_and_b32_sdwa v126, v120, v115 dst_sel:DWORD dst_unused:UNUSED_PAD src0_sel:WORD_1 src1_sel:DWORD
	v_add3_u32 v130, v37, v32, s69
	v_add3_u32 v32, v36, v33, s69
	v_add3_u32 v33, v35, v117, s69
	v_add3_u32 v117, v34, v118, s69
	v_add3_u32 v131, v123, v119, s69
	v_add3_u32 v132, v122, v124, s69
	v_add3_u32 v127, v121, v125, s69
	v_add3_u32 v126, v120, v126, s69
	v_and_b32_e32 v119, 0xffff0000, v33
	v_and_b32_e32 v118, 0xffff0000, v117
	v_and_b32_e32 v125, 0xffff0000, v130
	v_and_b32_e32 v124, 0xffff0000, v32
	v_and_b32_e32 v129, 0xffff0000, v131
	v_and_b32_e32 v128, 0xffff0000, v132
	v_and_b32_e32 v127, 0xffff0000, v127
	v_and_b32_e32 v126, 0xffff0000, v126
	v_or_b32_sdwa v32, v118, v32 dst_sel:DWORD dst_unused:UNUSED_PAD src0_sel:DWORD src1_sel:WORD_1
	v_pk_add_f32 v[36:37], v[36:37], v[124:125] neg_lo:[0,1] neg_hi:[0,1]
	v_pk_add_f32 v[124:125], v[34:35], v[118:119] neg_lo:[0,1] neg_hi:[0,1]
	v_or_b32_sdwa v33, v119, v130 dst_sel:DWORD dst_unused:UNUSED_PAD src0_sel:DWORD src1_sel:WORD_1
	v_pk_add_f32 v[118:119], v[122:123], v[128:129] neg_lo:[0,1] neg_hi:[0,1]
	v_pk_add_f32 v[120:121], v[120:121], v[126:127] neg_lo:[0,1] neg_hi:[0,1]
	v_bfe_u32 v128, v37, 16, 1
	v_bfe_u32 v130, v119, 16, 1
	v_or_b32_sdwa v35, v127, v131 dst_sel:DWORD dst_unused:UNUSED_PAD src0_sel:DWORD src1_sel:WORD_1
	v_bfe_u32 v117, v121, 16, 1
	v_bfe_u32 v127, v36, 16, 1
	v_bfe_u32 v129, v118, 16, 1
	v_add3_u32 v119, v119, v130, s69
	v_add3_u32 v37, v37, v128, s69
	v_or_b32_sdwa v34, v126, v132 dst_sel:DWORD dst_unused:UNUSED_PAD src0_sel:DWORD src1_sel:WORD_1
	v_bfe_u32 v122, v120, 16, 1
	v_bfe_u32 v123, v125, 16, 1
	v_bfe_u32 v126, v124, 16, 1
	v_add3_u32 v117, v121, v117, s69
	v_add3_u32 v118, v118, v129, s69
	v_add3_u32 v36, v36, v127, s69
	v_lshrrev_b32_e32 v140, 16, v37
	v_lshrrev_b32_e32 v37, 16, v119
	v_add3_u32 v136, v124, v126, s69
	v_add3_u32 v137, v125, v123, s69
	v_add3_u32 v138, v120, v122, s69
	v_lshrrev_b32_e32 v139, 16, v36
	v_lshrrev_b32_e32 v36, 16, v118
	v_and_or_b32 v37, v117, s70, v37
	v_and_or_b32 v36, v138, s70, v36
	v_and_b32_sdwa v117, v81, v115 dst_sel:DWORD dst_unused:UNUSED_PAD src0_sel:WORD_1 src1_sel:DWORD
	v_and_b32_sdwa v118, v80, v115 dst_sel:DWORD dst_unused:UNUSED_PAD src0_sel:WORD_1 src1_sel:DWORD
	v_and_b32_sdwa v119, v89, v115 dst_sel:DWORD dst_unused:UNUSED_PAD src0_sel:WORD_1 src1_sel:DWORD
	v_and_b32_sdwa v120, v88, v115 dst_sel:DWORD dst_unused:UNUSED_PAD src0_sel:WORD_1 src1_sel:DWORD
	v_and_b32_sdwa v121, v47, v115 dst_sel:DWORD dst_unused:UNUSED_PAD src0_sel:WORD_1 src1_sel:DWORD
	v_and_b32_sdwa v122, v46, v115 dst_sel:DWORD dst_unused:UNUSED_PAD src0_sel:WORD_1 src1_sel:DWORD
	v_and_b32_sdwa v123, v87, v115 dst_sel:DWORD dst_unused:UNUSED_PAD src0_sel:WORD_1 src1_sel:DWORD
	v_and_b32_sdwa v124, v86, v115 dst_sel:DWORD dst_unused:UNUSED_PAD src0_sel:WORD_1 src1_sel:DWORD
	v_and_b32_sdwa v125, v45, v115 dst_sel:DWORD dst_unused:UNUSED_PAD src0_sel:WORD_1 src1_sel:DWORD
	v_add3_u32 v117, v81, v117, s69
	v_add3_u32 v118, v80, v118, s69
	v_add3_u32 v119, v89, v119, s69
	v_add3_u32 v120, v88, v120, s69
	v_add3_u32 v133, v87, v123, s69
	v_add3_u32 v124, v86, v124, s69
	v_and_b32_sdwa v127, v85, v115 dst_sel:DWORD dst_unused:UNUSED_PAD src0_sel:WORD_1 src1_sel:DWORD
	v_and_b32_sdwa v128, v84, v115 dst_sel:DWORD dst_unused:UNUSED_PAD src0_sel:WORD_1 src1_sel:DWORD
	v_and_b32_sdwa v131, v83, v115 dst_sel:DWORD dst_unused:UNUSED_PAD src0_sel:WORD_1 src1_sel:DWORD
	v_and_b32_sdwa v132, v82, v115 dst_sel:DWORD dst_unused:UNUSED_PAD src0_sel:WORD_1 src1_sel:DWORD
	v_add3_u32 v141, v47, v121, s69
	v_add3_u32 v142, v46, v122, s69
	v_add3_u32 v143, v45, v125, s69
	v_and_b32_e32 v121, 0xffff0000, v119
	v_and_b32_e32 v120, 0xffff0000, v120
	v_and_b32_e32 v123, 0xffff0000, v117
	v_and_b32_e32 v122, 0xffff0000, v118
	v_and_b32_e32 v125, 0xffff0000, v133
	v_and_b32_e32 v124, 0xffff0000, v124
	v_and_b32_sdwa v126, v44, v115 dst_sel:DWORD dst_unused:UNUSED_PAD src0_sel:WORD_1 src1_sel:DWORD
	v_and_b32_sdwa v129, v43, v115 dst_sel:DWORD dst_unused:UNUSED_PAD src0_sel:WORD_1 src1_sel:DWORD
	v_and_b32_sdwa v130, v42, v115 dst_sel:DWORD dst_unused:UNUSED_PAD src0_sel:WORD_1 src1_sel:DWORD
	v_add3_u32 v134, v85, v127, s69
	v_add3_u32 v128, v84, v128, s69
	v_add3_u32 v135, v83, v131, s69
	v_add3_u32 v132, v82, v132, s69
	v_or_b32_sdwa v118, v120, v118 dst_sel:DWORD dst_unused:UNUSED_PAD src0_sel:DWORD src1_sel:WORD_1
	v_pk_add_f32 v[80:81], v[80:81], v[122:123] neg_lo:[0,1] neg_hi:[0,1]
	v_pk_add_f32 v[122:123], v[88:89], v[120:121] neg_lo:[0,1] neg_hi:[0,1]
	v_or_b32_sdwa v119, v121, v117 dst_sel:DWORD dst_unused:UNUSED_PAD src0_sel:DWORD src1_sel:WORD_1
	v_or_b32_sdwa v120, v124, v142 dst_sel:DWORD dst_unused:UNUSED_PAD src0_sel:DWORD src1_sel:WORD_1
	v_or_b32_sdwa v121, v125, v141 dst_sel:DWORD dst_unused:UNUSED_PAD src0_sel:DWORD src1_sel:WORD_1
	v_add3_u32 v144, v44, v126, s69
	v_add3_u32 v145, v43, v129, s69
	v_add3_u32 v146, v42, v130, s69
	v_and_b32_e32 v127, 0xffff0000, v141
	v_and_b32_e32 v126, 0xffff0000, v142
	v_and_b32_e32 v129, 0xffff0000, v134
	v_and_b32_e32 v128, 0xffff0000, v128
	v_and_b32_e32 v133, 0xffff0000, v135
	v_and_b32_e32 v132, 0xffff0000, v132
	v_mfma_f32_32x32x16_bf16 v[0:15], v[32:35], v[118:121], v[0:15]
	v_add_f32_e64 v46, v46, -v126
	v_add_f32_e64 v47, v47, -v127
	v_add_f32_e64 v126, v86, -v124
	v_add_f32_e64 v127, v87, -v125
	v_or_b32_sdwa v86, v128, v144 dst_sel:DWORD dst_unused:UNUSED_PAD src0_sel:DWORD src1_sel:WORD_1
	v_or_b32_sdwa v87, v129, v143 dst_sel:DWORD dst_unused:UNUSED_PAD src0_sel:DWORD src1_sel:WORD_1
	v_or_b32_sdwa v88, v132, v146 dst_sel:DWORD dst_unused:UNUSED_PAD src0_sel:DWORD src1_sel:WORD_1
	v_or_b32_sdwa v89, v133, v145 dst_sel:DWORD dst_unused:UNUSED_PAD src0_sel:DWORD src1_sel:WORD_1
	v_and_b32_e32 v131, 0xffff0000, v143
	v_and_b32_e32 v130, 0xffff0000, v144
	v_mfma_f32_32x32x16_bf16 v[16:31], v[32:35], v[86:89], v[16:31]
	v_and_b32_e32 v135, 0xffff0000, v145
	v_and_b32_e32 v134, 0xffff0000, v146
	v_add_f32_e64 v44, v44, -v130
	v_add_f32_e64 v45, v45, -v131
	v_add_f32_e64 v84, v84, -v128
	v_add_f32_e64 v85, v85, -v129
	v_pk_add_f32 v[42:43], v[42:43], v[134:135] neg_lo:[0,1] neg_hi:[0,1]
	v_pk_add_f32 v[82:83], v[82:83], v[132:133] neg_lo:[0,1] neg_hi:[0,1]
	v_bfe_u32 v129, v80, 16, 1
	v_bfe_u32 v130, v81, 16, 1
	v_bfe_u32 v131, v46, 16, 1
	v_bfe_u32 v132, v47, 16, 1
	v_bfe_u32 v117, v127, 16, 1
	v_bfe_u32 v124, v126, 16, 1
	v_bfe_u32 v125, v123, 16, 1
	v_bfe_u32 v128, v122, 16, 1
	v_bfe_u32 v142, v44, 16, 1
	v_bfe_u32 v143, v45, 16, 1
	v_bfe_u32 v144, v42, 16, 1
	v_bfe_u32 v145, v43, 16, 1
	v_add3_u32 v47, v47, v132, s69
	v_add3_u32 v46, v46, v131, s69
	v_add3_u32 v81, v81, v130, s69
	v_add3_u32 v80, v80, v129, s69
	v_add3_u32 v122, v122, v128, s69
	v_add3_u32 v123, v123, v125, s69
	v_add3_u32 v124, v126, v124, s69
	v_add3_u32 v117, v127, v117, s69
	v_add3_u32 v125, v43, v145, s69
	v_add3_u32 v126, v42, v144, s69
	v_add3_u32 v127, v45, v143, s69
	v_add3_u32 v42, v44, v142, s69
	v_lshrrev_b32_e32 v80, 16, v80
	v_lshrrev_b32_e32 v43, 16, v81
	v_lshrrev_b32_e32 v44, 16, v46
	v_lshrrev_b32_e32 v45, 16, v47
	v_bfe_u32 v133, v83, 16, 1
	v_bfe_u32 v134, v82, 16, 1
	v_bfe_u32 v135, v85, 16, 1
	v_bfe_u32 v141, v84, 16, 1
	v_lshrrev_b32_e32 v46, 16, v42
	v_and_or_b32 v45, v117, s70, v45
	v_and_or_b32 v44, v124, s70, v44
	v_and_or_b32 v43, v123, s70, v43
	v_and_or_b32 v42, v122, s70, v80
	v_add3_u32 v84, v84, v141, s69
	v_add3_u32 v85, v85, v135, s69
	v_add3_u32 v82, v82, v134, s69
	v_add3_u32 v83, v83, v133, s69
	v_mfma_f32_32x32x16_bf16 v[0:15], v[32:35], v[42:45], v[0:15]
	v_lshrrev_b32_e32 v42, 16, v127
	v_lshrrev_b32_e32 v43, 16, v126
	v_lshrrev_b32_e32 v44, 16, v125
	v_and_or_b32 v45, v83, s70, v44
	v_and_or_b32 v44, v82, s70, v43
	v_and_or_b32 v43, v85, s70, v42
	v_and_or_b32 v42, v84, s70, v46
	s_nop 1
	v_mfma_f32_32x32x16_bf16 v[16:31], v[32:35], v[42:45], v[16:31]
	v_and_or_b32 v35, v137, s70, v140
	v_and_or_b32 v34, v136, s70, v139
	s_nop 1
	v_mfma_f32_32x32x16_bf16 v[0:15], v[34:37], v[118:121], v[0:15]
	v_mfma_f32_32x32x16_bf16 v[16:31], v[34:37], v[86:89], v[16:31]
	s_nop 0
	ds_read_b128 v[32:35], v116
	ds_read_b128 v[118:121], v116 offset:16
	s_waitcnt lgkmcnt(1)
	v_cndmask_b32_e64 v35, 0, v35, s[2:3]
	s_waitcnt lgkmcnt(0)
	v_cndmask_b32_e64 v121, 0, v121, s[2:3]
	v_and_b32_sdwa v117, v35, v115 dst_sel:DWORD dst_unused:UNUSED_PAD src0_sel:WORD_1 src1_sel:DWORD
	s_nop 0
	s_nop 0
	s_nop 0
	s_nop 0
	v_add_u32_e32 v116, 64, v116
	s_nop 0
	s_nop 1
	s_nop 1
	s_nop 1
	s_nop 1
	s_nop 1
	s_nop 1
	s_nop 1
	v_mov_b32_e32 v81, v228
	s_nop 0
	v_mov_b32_e32 v80, v229
	v_mov_b32_e32 v89, v230
	v_mov_b32_e32 v88, v231
	s_nop 0
	v_mov_b32_e32 v47, v232
	v_mov_b32_e32 v46, v233
	v_mov_b32_e32 v87, v234
	v_mov_b32_e32 v86, v235
	v_mov_b32_e32 v45, v236
	v_mov_b32_e32 v44, v237
	s_nop 0
	v_mov_b32_e32 v85, v238
	v_mov_b32_e32 v84, v239
	v_mov_b32_e32 v43, v240
	v_mov_b32_e32 v42, v241
	v_mov_b32_e32 v83, v242
	v_mov_b32_e32 v82, v243
	v_cndmask_b32_e64 v37, 0, v34, s[2:3]
	v_cndmask_b32_e64 v36, 0, v32, s[2:3]
	v_cndmask_b32_e64 v34, 0, v33, s[2:3]
	v_cndmask_b32_e64 v123, 0, v120, s[2:3]
	v_cndmask_b32_e64 v122, 0, v118, s[2:3]
	v_cndmask_b32_e64 v120, 0, v119, s[2:3]
	v_and_b32_sdwa v32, v37, v115 dst_sel:DWORD dst_unused:UNUSED_PAD src0_sel:WORD_1 src1_sel:DWORD
	v_and_b32_sdwa v33, v36, v115 dst_sel:DWORD dst_unused:UNUSED_PAD src0_sel:WORD_1 src1_sel:DWORD
	v_and_b32_sdwa v118, v34, v115 dst_sel:DWORD dst_unused:UNUSED_PAD src0_sel:WORD_1 src1_sel:DWORD
	v_and_b32_sdwa v119, v123, v115 dst_sel:DWORD dst_unused:UNUSED_PAD src0_sel:WORD_1 src1_sel:DWORD
	v_and_b32_sdwa v124, v122, v115 dst_sel:DWORD dst_unused:UNUSED_PAD src0_sel:WORD_1 src1_sel:DWORD
	v_and_b32_sdwa v125, v121, v115 dst_sel:DWORD dst_unused:UNUSED_PAD src0_sel:WORD_1 src1_sel:DWORD
	v_and_b32_sdwa v126, v120, v115 dst_sel:DWORD dst_unused:UNUSED_PAD src0_sel:WORD_1 src1_sel:DWORD
	v_add3_u32 v130, v37, v32, s69
	v_add3_u32 v32, v36, v33, s69
	v_add3_u32 v33, v35, v117, s69
	v_add3_u32 v117, v34, v118, s69
	v_add3_u32 v131, v123, v119, s69
	v_add3_u32 v132, v122, v124, s69
	v_add3_u32 v127, v121, v125, s69
	v_add3_u32 v126, v120, v126, s69
	v_and_b32_e32 v119, 0xffff0000, v33
	v_and_b32_e32 v118, 0xffff0000, v117
	v_and_b32_e32 v125, 0xffff0000, v130
	v_and_b32_e32 v124, 0xffff0000, v32
	v_and_b32_e32 v129, 0xffff0000, v131
	v_and_b32_e32 v128, 0xffff0000, v132
	v_and_b32_e32 v127, 0xffff0000, v127
	v_and_b32_e32 v126, 0xffff0000, v126
	v_or_b32_sdwa v32, v118, v32 dst_sel:DWORD dst_unused:UNUSED_PAD src0_sel:DWORD src1_sel:WORD_1
	v_pk_add_f32 v[36:37], v[36:37], v[124:125] neg_lo:[0,1] neg_hi:[0,1]
	v_pk_add_f32 v[124:125], v[34:35], v[118:119] neg_lo:[0,1] neg_hi:[0,1]
	v_or_b32_sdwa v33, v119, v130 dst_sel:DWORD dst_unused:UNUSED_PAD src0_sel:DWORD src1_sel:WORD_1
	v_pk_add_f32 v[118:119], v[122:123], v[128:129] neg_lo:[0,1] neg_hi:[0,1]
	v_pk_add_f32 v[120:121], v[120:121], v[126:127] neg_lo:[0,1] neg_hi:[0,1]
	v_bfe_u32 v128, v37, 16, 1
	v_bfe_u32 v130, v119, 16, 1
	v_or_b32_sdwa v35, v127, v131 dst_sel:DWORD dst_unused:UNUSED_PAD src0_sel:DWORD src1_sel:WORD_1
	v_bfe_u32 v117, v121, 16, 1
	v_bfe_u32 v127, v36, 16, 1
	v_bfe_u32 v129, v118, 16, 1
	v_add3_u32 v119, v119, v130, s69
	v_add3_u32 v37, v37, v128, s69
	v_or_b32_sdwa v34, v126, v132 dst_sel:DWORD dst_unused:UNUSED_PAD src0_sel:DWORD src1_sel:WORD_1
	v_bfe_u32 v122, v120, 16, 1
	v_bfe_u32 v123, v125, 16, 1
	v_bfe_u32 v126, v124, 16, 1
	v_add3_u32 v117, v121, v117, s69
	v_add3_u32 v118, v118, v129, s69
	v_add3_u32 v36, v36, v127, s69
	v_lshrrev_b32_e32 v140, 16, v37
	v_lshrrev_b32_e32 v37, 16, v119
	v_add3_u32 v136, v124, v126, s69
	v_add3_u32 v137, v125, v123, s69
	v_add3_u32 v138, v120, v122, s69
	v_lshrrev_b32_e32 v139, 16, v36
	v_lshrrev_b32_e32 v36, 16, v118
	v_and_or_b32 v37, v117, s70, v37
	v_and_or_b32 v36, v138, s70, v36
	v_and_b32_sdwa v117, v81, v115 dst_sel:DWORD dst_unused:UNUSED_PAD src0_sel:WORD_1 src1_sel:DWORD
	v_and_b32_sdwa v118, v80, v115 dst_sel:DWORD dst_unused:UNUSED_PAD src0_sel:WORD_1 src1_sel:DWORD
	v_and_b32_sdwa v119, v89, v115 dst_sel:DWORD dst_unused:UNUSED_PAD src0_sel:WORD_1 src1_sel:DWORD
	v_and_b32_sdwa v120, v88, v115 dst_sel:DWORD dst_unused:UNUSED_PAD src0_sel:WORD_1 src1_sel:DWORD
	v_and_b32_sdwa v121, v47, v115 dst_sel:DWORD dst_unused:UNUSED_PAD src0_sel:WORD_1 src1_sel:DWORD
	v_and_b32_sdwa v122, v46, v115 dst_sel:DWORD dst_unused:UNUSED_PAD src0_sel:WORD_1 src1_sel:DWORD
	v_and_b32_sdwa v123, v87, v115 dst_sel:DWORD dst_unused:UNUSED_PAD src0_sel:WORD_1 src1_sel:DWORD
	v_and_b32_sdwa v124, v86, v115 dst_sel:DWORD dst_unused:UNUSED_PAD src0_sel:WORD_1 src1_sel:DWORD
	v_and_b32_sdwa v125, v45, v115 dst_sel:DWORD dst_unused:UNUSED_PAD src0_sel:WORD_1 src1_sel:DWORD
	v_add3_u32 v117, v81, v117, s69
	v_add3_u32 v118, v80, v118, s69
	v_add3_u32 v119, v89, v119, s69
	v_add3_u32 v120, v88, v120, s69
	v_add3_u32 v133, v87, v123, s69
	v_add3_u32 v124, v86, v124, s69
	v_and_b32_sdwa v127, v85, v115 dst_sel:DWORD dst_unused:UNUSED_PAD src0_sel:WORD_1 src1_sel:DWORD
	v_and_b32_sdwa v128, v84, v115 dst_sel:DWORD dst_unused:UNUSED_PAD src0_sel:WORD_1 src1_sel:DWORD
	v_and_b32_sdwa v131, v83, v115 dst_sel:DWORD dst_unused:UNUSED_PAD src0_sel:WORD_1 src1_sel:DWORD
	v_and_b32_sdwa v132, v82, v115 dst_sel:DWORD dst_unused:UNUSED_PAD src0_sel:WORD_1 src1_sel:DWORD
	v_add3_u32 v141, v47, v121, s69
	v_add3_u32 v142, v46, v122, s69
	v_add3_u32 v143, v45, v125, s69
	v_and_b32_e32 v121, 0xffff0000, v119
	v_and_b32_e32 v120, 0xffff0000, v120
	v_and_b32_e32 v123, 0xffff0000, v117
	v_and_b32_e32 v122, 0xffff0000, v118
	v_and_b32_e32 v125, 0xffff0000, v133
	v_and_b32_e32 v124, 0xffff0000, v124
	v_and_b32_sdwa v126, v44, v115 dst_sel:DWORD dst_unused:UNUSED_PAD src0_sel:WORD_1 src1_sel:DWORD
	v_and_b32_sdwa v129, v43, v115 dst_sel:DWORD dst_unused:UNUSED_PAD src0_sel:WORD_1 src1_sel:DWORD
	v_and_b32_sdwa v130, v42, v115 dst_sel:DWORD dst_unused:UNUSED_PAD src0_sel:WORD_1 src1_sel:DWORD
	v_add3_u32 v134, v85, v127, s69
	v_add3_u32 v128, v84, v128, s69
	v_add3_u32 v135, v83, v131, s69
	v_add3_u32 v132, v82, v132, s69
	v_or_b32_sdwa v118, v120, v118 dst_sel:DWORD dst_unused:UNUSED_PAD src0_sel:DWORD src1_sel:WORD_1
	v_pk_add_f32 v[80:81], v[80:81], v[122:123] neg_lo:[0,1] neg_hi:[0,1]
	v_pk_add_f32 v[122:123], v[88:89], v[120:121] neg_lo:[0,1] neg_hi:[0,1]
	v_or_b32_sdwa v119, v121, v117 dst_sel:DWORD dst_unused:UNUSED_PAD src0_sel:DWORD src1_sel:WORD_1
	v_or_b32_sdwa v120, v124, v142 dst_sel:DWORD dst_unused:UNUSED_PAD src0_sel:DWORD src1_sel:WORD_1
	v_or_b32_sdwa v121, v125, v141 dst_sel:DWORD dst_unused:UNUSED_PAD src0_sel:DWORD src1_sel:WORD_1
	v_add3_u32 v144, v44, v126, s69
	v_add3_u32 v145, v43, v129, s69
	v_add3_u32 v146, v42, v130, s69
	v_and_b32_e32 v127, 0xffff0000, v141
	v_and_b32_e32 v126, 0xffff0000, v142
	v_and_b32_e32 v129, 0xffff0000, v134
	v_and_b32_e32 v128, 0xffff0000, v128
	v_and_b32_e32 v133, 0xffff0000, v135
	v_and_b32_e32 v132, 0xffff0000, v132
	v_mfma_f32_32x32x16_bf16 v[0:15], v[32:35], v[118:121], v[0:15]
	v_add_f32_e64 v46, v46, -v126
	v_add_f32_e64 v47, v47, -v127
	v_add_f32_e64 v126, v86, -v124
	v_add_f32_e64 v127, v87, -v125
	v_or_b32_sdwa v86, v128, v144 dst_sel:DWORD dst_unused:UNUSED_PAD src0_sel:DWORD src1_sel:WORD_1
	v_or_b32_sdwa v87, v129, v143 dst_sel:DWORD dst_unused:UNUSED_PAD src0_sel:DWORD src1_sel:WORD_1
	v_or_b32_sdwa v88, v132, v146 dst_sel:DWORD dst_unused:UNUSED_PAD src0_sel:DWORD src1_sel:WORD_1
	v_or_b32_sdwa v89, v133, v145 dst_sel:DWORD dst_unused:UNUSED_PAD src0_sel:DWORD src1_sel:WORD_1
	v_and_b32_e32 v131, 0xffff0000, v143
	v_and_b32_e32 v130, 0xffff0000, v144
	v_mfma_f32_32x32x16_bf16 v[16:31], v[32:35], v[86:89], v[16:31]
	v_and_b32_e32 v135, 0xffff0000, v145
	v_and_b32_e32 v134, 0xffff0000, v146
	v_add_f32_e64 v44, v44, -v130
	v_add_f32_e64 v45, v45, -v131
	v_add_f32_e64 v84, v84, -v128
	v_add_f32_e64 v85, v85, -v129
	v_pk_add_f32 v[42:43], v[42:43], v[134:135] neg_lo:[0,1] neg_hi:[0,1]
	v_pk_add_f32 v[82:83], v[82:83], v[132:133] neg_lo:[0,1] neg_hi:[0,1]
	v_bfe_u32 v129, v80, 16, 1
	v_bfe_u32 v130, v81, 16, 1
	v_bfe_u32 v131, v46, 16, 1
	v_bfe_u32 v132, v47, 16, 1
	v_bfe_u32 v117, v127, 16, 1
	v_bfe_u32 v124, v126, 16, 1
	v_bfe_u32 v125, v123, 16, 1
	v_bfe_u32 v128, v122, 16, 1
	v_bfe_u32 v142, v44, 16, 1
	v_bfe_u32 v143, v45, 16, 1
	v_bfe_u32 v144, v42, 16, 1
	v_bfe_u32 v145, v43, 16, 1
	v_add3_u32 v47, v47, v132, s69
	v_add3_u32 v46, v46, v131, s69
	v_add3_u32 v81, v81, v130, s69
	v_add3_u32 v80, v80, v129, s69
	v_add3_u32 v122, v122, v128, s69
	v_add3_u32 v123, v123, v125, s69
	v_add3_u32 v124, v126, v124, s69
	v_add3_u32 v117, v127, v117, s69
	v_add3_u32 v125, v43, v145, s69
	v_add3_u32 v126, v42, v144, s69
	v_add3_u32 v127, v45, v143, s69
	v_add3_u32 v42, v44, v142, s69
	v_lshrrev_b32_e32 v80, 16, v80
	v_lshrrev_b32_e32 v43, 16, v81
	v_lshrrev_b32_e32 v44, 16, v46
	v_lshrrev_b32_e32 v45, 16, v47
	v_bfe_u32 v133, v83, 16, 1
	v_bfe_u32 v134, v82, 16, 1
	v_bfe_u32 v135, v85, 16, 1
	v_bfe_u32 v141, v84, 16, 1
	v_lshrrev_b32_e32 v46, 16, v42
	v_and_or_b32 v45, v117, s70, v45
	v_and_or_b32 v44, v124, s70, v44
	v_and_or_b32 v43, v123, s70, v43
	v_and_or_b32 v42, v122, s70, v80
	v_add3_u32 v84, v84, v141, s69
	v_add3_u32 v85, v85, v135, s69
	v_add3_u32 v82, v82, v134, s69
	v_add3_u32 v83, v83, v133, s69
	v_mfma_f32_32x32x16_bf16 v[0:15], v[32:35], v[42:45], v[0:15]
	v_lshrrev_b32_e32 v42, 16, v127
	v_lshrrev_b32_e32 v43, 16, v126
	v_lshrrev_b32_e32 v44, 16, v125
	v_and_or_b32 v45, v83, s70, v44
	v_and_or_b32 v44, v82, s70, v43
	v_and_or_b32 v43, v85, s70, v42
	v_and_or_b32 v42, v84, s70, v46
	s_nop 1
	v_mfma_f32_32x32x16_bf16 v[16:31], v[32:35], v[42:45], v[16:31]
	v_and_or_b32 v35, v137, s70, v140
	v_and_or_b32 v34, v136, s70, v139
	s_nop 1
	v_mfma_f32_32x32x16_bf16 v[0:15], v[34:37], v[118:121], v[0:15]
	v_mfma_f32_32x32x16_bf16 v[16:31], v[34:37], v[86:89], v[16:31]
	s_nop 0
	ds_read_b128 v[32:35], v116
	ds_read_b128 v[118:121], v116 offset:16
	s_waitcnt lgkmcnt(1)
	v_cndmask_b32_e64 v35, 0, v35, s[2:3]
	s_waitcnt lgkmcnt(0)
	v_cndmask_b32_e64 v121, 0, v121, s[2:3]
	v_and_b32_sdwa v117, v35, v115 dst_sel:DWORD dst_unused:UNUSED_PAD src0_sel:WORD_1 src1_sel:DWORD
	s_nop 0
	s_nop 0
	s_nop 0
	s_nop 0
	v_add_u32_e32 v116, 64, v116
	s_nop 0
	s_nop 1
	s_nop 1
	s_nop 1
	s_nop 1
	s_nop 1
	s_nop 1
	s_nop 1
	s_waitcnt vmcnt(0)
	v_mov_b32_e32 v81, v148
	s_nop 0
	v_mov_b32_e32 v80, v149
	v_mov_b32_e32 v89, v150
	v_mov_b32_e32 v88, v151
	s_nop 0
	v_mov_b32_e32 v47, v152
	v_mov_b32_e32 v46, v153
	v_mov_b32_e32 v87, v154
	v_mov_b32_e32 v86, v155
	v_mov_b32_e32 v45, v156
	v_mov_b32_e32 v44, v157
	s_nop 0
	v_mov_b32_e32 v85, v158
	v_mov_b32_e32 v84, v159
	v_mov_b32_e32 v43, v160
	v_mov_b32_e32 v42, v161
	v_mov_b32_e32 v83, v162
	v_mov_b32_e32 v82, v163
	v_cndmask_b32_e64 v37, 0, v34, s[2:3]
	v_cndmask_b32_e64 v36, 0, v32, s[2:3]
	v_cndmask_b32_e64 v34, 0, v33, s[2:3]
	v_cndmask_b32_e64 v123, 0, v120, s[2:3]
	v_cndmask_b32_e64 v122, 0, v118, s[2:3]
	v_cndmask_b32_e64 v120, 0, v119, s[2:3]
	v_and_b32_sdwa v32, v37, v115 dst_sel:DWORD dst_unused:UNUSED_PAD src0_sel:WORD_1 src1_sel:DWORD
	v_and_b32_sdwa v33, v36, v115 dst_sel:DWORD dst_unused:UNUSED_PAD src0_sel:WORD_1 src1_sel:DWORD
	v_and_b32_sdwa v118, v34, v115 dst_sel:DWORD dst_unused:UNUSED_PAD src0_sel:WORD_1 src1_sel:DWORD
	v_and_b32_sdwa v119, v123, v115 dst_sel:DWORD dst_unused:UNUSED_PAD src0_sel:WORD_1 src1_sel:DWORD
	v_and_b32_sdwa v124, v122, v115 dst_sel:DWORD dst_unused:UNUSED_PAD src0_sel:WORD_1 src1_sel:DWORD
	v_and_b32_sdwa v125, v121, v115 dst_sel:DWORD dst_unused:UNUSED_PAD src0_sel:WORD_1 src1_sel:DWORD
	v_and_b32_sdwa v126, v120, v115 dst_sel:DWORD dst_unused:UNUSED_PAD src0_sel:WORD_1 src1_sel:DWORD
	v_add3_u32 v130, v37, v32, s69
	v_add3_u32 v32, v36, v33, s69
	v_add3_u32 v33, v35, v117, s69
	v_add3_u32 v117, v34, v118, s69
	v_add3_u32 v131, v123, v119, s69
	v_add3_u32 v132, v122, v124, s69
	v_add3_u32 v127, v121, v125, s69
	v_add3_u32 v126, v120, v126, s69
	v_and_b32_e32 v119, 0xffff0000, v33
	v_and_b32_e32 v118, 0xffff0000, v117
	v_and_b32_e32 v125, 0xffff0000, v130
	v_and_b32_e32 v124, 0xffff0000, v32
	v_and_b32_e32 v129, 0xffff0000, v131
	v_and_b32_e32 v128, 0xffff0000, v132
	v_and_b32_e32 v127, 0xffff0000, v127
	v_and_b32_e32 v126, 0xffff0000, v126
	v_or_b32_sdwa v32, v118, v32 dst_sel:DWORD dst_unused:UNUSED_PAD src0_sel:DWORD src1_sel:WORD_1
	v_pk_add_f32 v[36:37], v[36:37], v[124:125] neg_lo:[0,1] neg_hi:[0,1]
	v_pk_add_f32 v[124:125], v[34:35], v[118:119] neg_lo:[0,1] neg_hi:[0,1]
	v_or_b32_sdwa v33, v119, v130 dst_sel:DWORD dst_unused:UNUSED_PAD src0_sel:DWORD src1_sel:WORD_1
	v_pk_add_f32 v[118:119], v[122:123], v[128:129] neg_lo:[0,1] neg_hi:[0,1]
	v_pk_add_f32 v[120:121], v[120:121], v[126:127] neg_lo:[0,1] neg_hi:[0,1]
	v_bfe_u32 v128, v37, 16, 1
	v_bfe_u32 v130, v119, 16, 1
	v_or_b32_sdwa v35, v127, v131 dst_sel:DWORD dst_unused:UNUSED_PAD src0_sel:DWORD src1_sel:WORD_1
	v_bfe_u32 v117, v121, 16, 1
	v_bfe_u32 v127, v36, 16, 1
	v_bfe_u32 v129, v118, 16, 1
	v_add3_u32 v119, v119, v130, s69
	v_add3_u32 v37, v37, v128, s69
	v_or_b32_sdwa v34, v126, v132 dst_sel:DWORD dst_unused:UNUSED_PAD src0_sel:DWORD src1_sel:WORD_1
	v_bfe_u32 v122, v120, 16, 1
	v_bfe_u32 v123, v125, 16, 1
	v_bfe_u32 v126, v124, 16, 1
	v_add3_u32 v117, v121, v117, s69
	v_add3_u32 v118, v118, v129, s69
	v_add3_u32 v36, v36, v127, s69
	v_lshrrev_b32_e32 v140, 16, v37
	v_lshrrev_b32_e32 v37, 16, v119
	v_add3_u32 v136, v124, v126, s69
	v_add3_u32 v137, v125, v123, s69
	v_add3_u32 v138, v120, v122, s69
	v_lshrrev_b32_e32 v139, 16, v36
	v_lshrrev_b32_e32 v36, 16, v118
	v_and_or_b32 v37, v117, s70, v37
	v_and_or_b32 v36, v138, s70, v36
	v_and_b32_sdwa v117, v81, v115 dst_sel:DWORD dst_unused:UNUSED_PAD src0_sel:WORD_1 src1_sel:DWORD
	v_and_b32_sdwa v118, v80, v115 dst_sel:DWORD dst_unused:UNUSED_PAD src0_sel:WORD_1 src1_sel:DWORD
	v_and_b32_sdwa v119, v89, v115 dst_sel:DWORD dst_unused:UNUSED_PAD src0_sel:WORD_1 src1_sel:DWORD
	v_and_b32_sdwa v120, v88, v115 dst_sel:DWORD dst_unused:UNUSED_PAD src0_sel:WORD_1 src1_sel:DWORD
	v_and_b32_sdwa v121, v47, v115 dst_sel:DWORD dst_unused:UNUSED_PAD src0_sel:WORD_1 src1_sel:DWORD
	v_and_b32_sdwa v122, v46, v115 dst_sel:DWORD dst_unused:UNUSED_PAD src0_sel:WORD_1 src1_sel:DWORD
	v_and_b32_sdwa v123, v87, v115 dst_sel:DWORD dst_unused:UNUSED_PAD src0_sel:WORD_1 src1_sel:DWORD
	v_and_b32_sdwa v124, v86, v115 dst_sel:DWORD dst_unused:UNUSED_PAD src0_sel:WORD_1 src1_sel:DWORD
	v_and_b32_sdwa v125, v45, v115 dst_sel:DWORD dst_unused:UNUSED_PAD src0_sel:WORD_1 src1_sel:DWORD
	v_add3_u32 v117, v81, v117, s69
	v_add3_u32 v118, v80, v118, s69
	v_add3_u32 v119, v89, v119, s69
	v_add3_u32 v120, v88, v120, s69
	v_add3_u32 v133, v87, v123, s69
	v_add3_u32 v124, v86, v124, s69
	v_and_b32_sdwa v127, v85, v115 dst_sel:DWORD dst_unused:UNUSED_PAD src0_sel:WORD_1 src1_sel:DWORD
	v_and_b32_sdwa v128, v84, v115 dst_sel:DWORD dst_unused:UNUSED_PAD src0_sel:WORD_1 src1_sel:DWORD
	v_and_b32_sdwa v131, v83, v115 dst_sel:DWORD dst_unused:UNUSED_PAD src0_sel:WORD_1 src1_sel:DWORD
	v_and_b32_sdwa v132, v82, v115 dst_sel:DWORD dst_unused:UNUSED_PAD src0_sel:WORD_1 src1_sel:DWORD
	v_add3_u32 v141, v47, v121, s69
	v_add3_u32 v142, v46, v122, s69
	v_add3_u32 v143, v45, v125, s69
	v_and_b32_e32 v121, 0xffff0000, v119
	v_and_b32_e32 v120, 0xffff0000, v120
	v_and_b32_e32 v123, 0xffff0000, v117
	v_and_b32_e32 v122, 0xffff0000, v118
	v_and_b32_e32 v125, 0xffff0000, v133
	v_and_b32_e32 v124, 0xffff0000, v124
	v_and_b32_sdwa v126, v44, v115 dst_sel:DWORD dst_unused:UNUSED_PAD src0_sel:WORD_1 src1_sel:DWORD
	v_and_b32_sdwa v129, v43, v115 dst_sel:DWORD dst_unused:UNUSED_PAD src0_sel:WORD_1 src1_sel:DWORD
	v_and_b32_sdwa v130, v42, v115 dst_sel:DWORD dst_unused:UNUSED_PAD src0_sel:WORD_1 src1_sel:DWORD
	v_add3_u32 v134, v85, v127, s69
	v_add3_u32 v128, v84, v128, s69
	v_add3_u32 v135, v83, v131, s69
	v_add3_u32 v132, v82, v132, s69
	v_or_b32_sdwa v118, v120, v118 dst_sel:DWORD dst_unused:UNUSED_PAD src0_sel:DWORD src1_sel:WORD_1
	v_pk_add_f32 v[80:81], v[80:81], v[122:123] neg_lo:[0,1] neg_hi:[0,1]
	v_pk_add_f32 v[122:123], v[88:89], v[120:121] neg_lo:[0,1] neg_hi:[0,1]
	v_or_b32_sdwa v119, v121, v117 dst_sel:DWORD dst_unused:UNUSED_PAD src0_sel:DWORD src1_sel:WORD_1
	v_or_b32_sdwa v120, v124, v142 dst_sel:DWORD dst_unused:UNUSED_PAD src0_sel:DWORD src1_sel:WORD_1
	v_or_b32_sdwa v121, v125, v141 dst_sel:DWORD dst_unused:UNUSED_PAD src0_sel:DWORD src1_sel:WORD_1
	v_add3_u32 v144, v44, v126, s69
	v_add3_u32 v145, v43, v129, s69
	v_add3_u32 v146, v42, v130, s69
	v_and_b32_e32 v127, 0xffff0000, v141
	v_and_b32_e32 v126, 0xffff0000, v142
	v_and_b32_e32 v129, 0xffff0000, v134
	v_and_b32_e32 v128, 0xffff0000, v128
	v_and_b32_e32 v133, 0xffff0000, v135
	v_and_b32_e32 v132, 0xffff0000, v132
	v_mfma_f32_32x32x16_bf16 v[0:15], v[32:35], v[118:121], v[0:15]
	v_add_f32_e64 v46, v46, -v126
	v_add_f32_e64 v47, v47, -v127
	v_add_f32_e64 v126, v86, -v124
	v_add_f32_e64 v127, v87, -v125
	v_or_b32_sdwa v86, v128, v144 dst_sel:DWORD dst_unused:UNUSED_PAD src0_sel:DWORD src1_sel:WORD_1
	v_or_b32_sdwa v87, v129, v143 dst_sel:DWORD dst_unused:UNUSED_PAD src0_sel:DWORD src1_sel:WORD_1
	v_or_b32_sdwa v88, v132, v146 dst_sel:DWORD dst_unused:UNUSED_PAD src0_sel:DWORD src1_sel:WORD_1
	v_or_b32_sdwa v89, v133, v145 dst_sel:DWORD dst_unused:UNUSED_PAD src0_sel:DWORD src1_sel:WORD_1
	v_and_b32_e32 v131, 0xffff0000, v143
	v_and_b32_e32 v130, 0xffff0000, v144
	v_mfma_f32_32x32x16_bf16 v[16:31], v[32:35], v[86:89], v[16:31]
	v_and_b32_e32 v135, 0xffff0000, v145
	v_and_b32_e32 v134, 0xffff0000, v146
	v_add_f32_e64 v44, v44, -v130
	v_add_f32_e64 v45, v45, -v131
	v_add_f32_e64 v84, v84, -v128
	v_add_f32_e64 v85, v85, -v129
	v_pk_add_f32 v[42:43], v[42:43], v[134:135] neg_lo:[0,1] neg_hi:[0,1]
	v_pk_add_f32 v[82:83], v[82:83], v[132:133] neg_lo:[0,1] neg_hi:[0,1]
	v_bfe_u32 v129, v80, 16, 1
	v_bfe_u32 v130, v81, 16, 1
	v_bfe_u32 v131, v46, 16, 1
	v_bfe_u32 v132, v47, 16, 1
	v_bfe_u32 v117, v127, 16, 1
	v_bfe_u32 v124, v126, 16, 1
	v_bfe_u32 v125, v123, 16, 1
	v_bfe_u32 v128, v122, 16, 1
	v_bfe_u32 v142, v44, 16, 1
	v_bfe_u32 v143, v45, 16, 1
	v_bfe_u32 v144, v42, 16, 1
	v_bfe_u32 v145, v43, 16, 1
	v_add3_u32 v47, v47, v132, s69
	v_add3_u32 v46, v46, v131, s69
	v_add3_u32 v81, v81, v130, s69
	v_add3_u32 v80, v80, v129, s69
	v_add3_u32 v122, v122, v128, s69
	v_add3_u32 v123, v123, v125, s69
	v_add3_u32 v124, v126, v124, s69
	v_add3_u32 v117, v127, v117, s69
	v_add3_u32 v125, v43, v145, s69
	v_add3_u32 v126, v42, v144, s69
	v_add3_u32 v127, v45, v143, s69
	v_add3_u32 v42, v44, v142, s69
	v_lshrrev_b32_e32 v80, 16, v80
	v_lshrrev_b32_e32 v43, 16, v81
	v_lshrrev_b32_e32 v44, 16, v46
	v_lshrrev_b32_e32 v45, 16, v47
	v_bfe_u32 v133, v83, 16, 1
	v_bfe_u32 v134, v82, 16, 1
	v_bfe_u32 v135, v85, 16, 1
	v_bfe_u32 v141, v84, 16, 1
	v_lshrrev_b32_e32 v46, 16, v42
	v_and_or_b32 v45, v117, s70, v45
	v_and_or_b32 v44, v124, s70, v44
	v_and_or_b32 v43, v123, s70, v43
	v_and_or_b32 v42, v122, s70, v80
	v_add3_u32 v84, v84, v141, s69
	v_add3_u32 v85, v85, v135, s69
	v_add3_u32 v82, v82, v134, s69
	v_add3_u32 v83, v83, v133, s69
	v_mfma_f32_32x32x16_bf16 v[0:15], v[32:35], v[42:45], v[0:15]
	v_lshrrev_b32_e32 v42, 16, v127
	v_lshrrev_b32_e32 v43, 16, v126
	v_lshrrev_b32_e32 v44, 16, v125
	v_and_or_b32 v45, v83, s70, v44
	v_and_or_b32 v44, v82, s70, v43
	v_and_or_b32 v43, v85, s70, v42
	v_and_or_b32 v42, v84, s70, v46
	s_nop 1
	v_mfma_f32_32x32x16_bf16 v[16:31], v[32:35], v[42:45], v[16:31]
	v_and_or_b32 v35, v137, s70, v140
	v_and_or_b32 v34, v136, s70, v139
	s_nop 1
	v_mfma_f32_32x32x16_bf16 v[0:15], v[34:37], v[118:121], v[0:15]
	v_mfma_f32_32x32x16_bf16 v[16:31], v[34:37], v[86:89], v[16:31]
	s_mul_i32 s50, s48, 17
	s_nop 8
	v_add_u32_e32 v9, s50, v94
	v_lshl_add_u32 v9, v9, 8, v95
	ds_write2_b32 v9, v0, v16 offset1:32
	v_add_u32_e32 v0, s50, v96
	v_lshl_add_u32 v0, v0, 8, v95
	ds_write2_b32 v0, v1, v17 offset1:32
	v_add_u32_e32 v0, s50, v97
	v_lshl_add_u32 v0, v0, 8, v95
	ds_write2_b32 v0, v2, v18 offset1:32
	v_add_u32_e32 v0, s50, v98
	v_lshl_add_u32 v0, v0, 8, v95
	ds_write2_b32 v0, v3, v19 offset1:32
	v_add_u32_e32 v0, s50, v99
	v_lshl_add_u32 v0, v0, 8, v95
	ds_write2_b32 v0, v4, v20 offset1:32
	v_add_u32_e32 v0, s50, v100
	v_lshl_add_u32 v0, v0, 8, v95
	ds_write2_b32 v0, v5, v21 offset1:32
	v_add_u32_e32 v0, s50, v101
	v_lshl_add_u32 v0, v0, 8, v95
	ds_write2_b32 v0, v6, v22 offset1:32
	v_add_u32_e32 v0, s50, v102
	v_lshl_add_u32 v0, v0, 8, v95
	ds_write2_b32 v0, v7, v23 offset1:32
	s_and_saveexec_b64 s[50:51], s[4:5]
	s_mulk_i32 s48, 0x1100
	v_add_u32_e32 v0, s48, v95
	v_add_u32_e32 v0, 0x1000, v0
	ds_write2_b32 v0, v8, v24 offset1:32
	s_or_b64 exec, exec, s[50:51]
	s_waitcnt lgkmcnt(0)
	s_barrier
	s_and_saveexec_b64 s[50:51], s[6:7]
	s_cbranch_execz .LBB0_214
	v_mov_b32_e32 v0, v48
	s_and_saveexec_b64 s[52:53], s[38:39]
	s_cbranch_execz .LBB0_209
	s_mov_b64 s[54:55], 0
	v_mov_b32_e32 v1, v106
	v_mov_b32_e32 v0, v48
	s_branch .LBB0_198

.LBB0_218:
	s_mov_b32 s101, 0
	s_mov_b32 s100, 0x2c200
	v_lshl_add_u64 v[250:251], v[80:81], 0, s[100:101]
	global_load_dword v138, v[250:251], off
	global_load_dword v139, v[250:251], off offset:128
	s_add_u32 s100, s62, 0x2c200
	v_lshl_add_u64 v[252:253], v[80:81], 0, s[100:101]
	global_load_dword v140, v[252:253], off offset:3104
	global_load_dword v141, v[252:253], off offset:3232
	s_add_u32 s100, s63, 0x2c200
	v_lshl_add_u64 v[250:251], v[80:81], 0, s[100:101]
	global_load_dword v142, v[250:251], off offset:2112
	global_load_dword v143, v[250:251], off offset:2240
	s_add_u32 s100, s64, 0x2c200
	v_lshl_add_u64 v[252:253], v[80:81], 0, s[100:101]
	global_load_dword v144, v[252:253], off offset:1120
	global_load_dword v145, v[252:253], off offset:1248
	s_add_u32 s100, s65, 0x2c200
	v_lshl_add_u64 v[250:251], v[80:81], 0, s[100:101]
	global_load_dword v146, v[250:251], off offset:128
	global_load_dword v147, v[250:251], off offset:256
	s_add_u32 s100, s66, 0x2c200
	v_lshl_add_u64 v[252:253], v[80:81], 0, s[100:101]
	global_load_dword v148, v[252:253], off offset:3232
	global_load_dword v149, v[252:253], off offset:3360
	s_add_u32 s100, s67, 0x2c200
	v_lshl_add_u64 v[250:251], v[80:81], 0, s[100:101]
	global_load_dword v150, v[250:251], off offset:2240
	global_load_dword v151, v[250:251], off offset:2368
	s_add_u32 s100, s68, 0x2c200
	v_lshl_add_u64 v[252:253], v[80:81], 0, s[100:101]
	global_load_dword v152, v[252:253], off offset:1248
	global_load_dword v153, v[252:253], off offset:1376
	s_mov_b32 s101, 0
	s_mov_b32 s100, 0x58400
	v_lshl_add_u64 v[250:251], v[80:81], 0, s[100:101]
	global_load_dword v154, v[250:251], off
	global_load_dword v155, v[250:251], off offset:128
	s_add_u32 s100, s62, 0x58400
	v_lshl_add_u64 v[252:253], v[80:81], 0, s[100:101]
	global_load_dword v156, v[252:253], off offset:3104
	global_load_dword v157, v[252:253], off offset:3232
	s_add_u32 s100, s63, 0x58400
	v_lshl_add_u64 v[250:251], v[80:81], 0, s[100:101]
	global_load_dword v158, v[250:251], off offset:2112
	global_load_dword v159, v[250:251], off offset:2240
	s_add_u32 s100, s64, 0x58400
	v_lshl_add_u64 v[252:253], v[80:81], 0, s[100:101]
	global_load_dword v160, v[252:253], off offset:1120
	global_load_dword v161, v[252:253], off offset:1248
	s_add_u32 s100, s65, 0x58400
	v_lshl_add_u64 v[250:251], v[80:81], 0, s[100:101]
	global_load_dword v162, v[250:251], off offset:128
	global_load_dword v163, v[250:251], off offset:256
	s_add_u32 s100, s66, 0x58400
	v_lshl_add_u64 v[252:253], v[80:81], 0, s[100:101]
	global_load_dword v164, v[252:253], off offset:3232
	global_load_dword v165, v[252:253], off offset:3360
	s_add_u32 s100, s67, 0x58400
	v_lshl_add_u64 v[250:251], v[80:81], 0, s[100:101]
	global_load_dword v166, v[250:251], off offset:2240
	global_load_dword v167, v[250:251], off offset:2368
	s_add_u32 s100, s68, 0x58400
	v_lshl_add_u64 v[252:253], v[80:81], 0, s[100:101]
	global_load_dword v168, v[252:253], off offset:1248
	global_load_dword v169, v[252:253], off offset:1376
	s_mov_b32 s101, 0
	s_mov_b32 s100, 0x84600
	v_lshl_add_u64 v[250:251], v[80:81], 0, s[100:101]
	global_load_dword v170, v[250:251], off
	global_load_dword v171, v[250:251], off offset:128
	s_add_u32 s100, s62, 0x84600
	v_lshl_add_u64 v[252:253], v[80:81], 0, s[100:101]
	global_load_dword v172, v[252:253], off offset:3104
	global_load_dword v173, v[252:253], off offset:3232
	s_add_u32 s100, s63, 0x84600
	v_lshl_add_u64 v[250:251], v[80:81], 0, s[100:101]
	global_load_dword v174, v[250:251], off offset:2112
	global_load_dword v175, v[250:251], off offset:2240
	s_add_u32 s100, s64, 0x84600
	v_lshl_add_u64 v[252:253], v[80:81], 0, s[100:101]
	global_load_dword v176, v[252:253], off offset:1120
	global_load_dword v177, v[252:253], off offset:1248
	s_add_u32 s100, s65, 0x84600
	v_lshl_add_u64 v[250:251], v[80:81], 0, s[100:101]
	global_load_dword v178, v[250:251], off offset:128
	global_load_dword v179, v[250:251], off offset:256
	s_add_u32 s100, s66, 0x84600
	v_lshl_add_u64 v[252:253], v[80:81], 0, s[100:101]
	global_load_dword v180, v[252:253], off offset:3232
	global_load_dword v181, v[252:253], off offset:3360
	s_add_u32 s100, s67, 0x84600
	v_lshl_add_u64 v[250:251], v[80:81], 0, s[100:101]
	global_load_dword v182, v[250:251], off offset:2240
	global_load_dword v183, v[250:251], off offset:2368
	s_add_u32 s100, s68, 0x84600
	v_lshl_add_u64 v[252:253], v[80:81], 0, s[100:101]
	global_load_dword v184, v[252:253], off offset:1248
	global_load_dword v185, v[252:253], off offset:1376
	s_mov_b32 s101, 0
	s_mov_b32 s100, 0xb0800
	v_lshl_add_u64 v[250:251], v[80:81], 0, s[100:101]
	global_load_dword v186, v[250:251], off
	global_load_dword v187, v[250:251], off offset:128
	s_add_u32 s100, s62, 0xb0800
	v_lshl_add_u64 v[252:253], v[80:81], 0, s[100:101]
	global_load_dword v188, v[252:253], off offset:3104
	global_load_dword v189, v[252:253], off offset:3232
	s_add_u32 s100, s63, 0xb0800
	v_lshl_add_u64 v[250:251], v[80:81], 0, s[100:101]
	global_load_dword v190, v[250:251], off offset:2112
	global_load_dword v191, v[250:251], off offset:2240
	s_add_u32 s100, s64, 0xb0800
	v_lshl_add_u64 v[252:253], v[80:81], 0, s[100:101]
	global_load_dword v192, v[252:253], off offset:1120
	global_load_dword v193, v[252:253], off offset:1248
	s_add_u32 s100, s65, 0xb0800
	v_lshl_add_u64 v[250:251], v[80:81], 0, s[100:101]
	global_load_dword v194, v[250:251], off offset:128
	global_load_dword v195, v[250:251], off offset:256
	s_add_u32 s100, s66, 0xb0800
	v_lshl_add_u64 v[252:253], v[80:81], 0, s[100:101]
	global_load_dword v196, v[252:253], off offset:3232
	global_load_dword v197, v[252:253], off offset:3360
	s_add_u32 s100, s67, 0xb0800
	v_lshl_add_u64 v[250:251], v[80:81], 0, s[100:101]
	global_load_dword v198, v[250:251], off offset:2240
	global_load_dword v199, v[250:251], off offset:2368
	s_add_u32 s100, s68, 0xb0800
	v_lshl_add_u64 v[252:253], v[80:81], 0, s[100:101]
	global_load_dword v200, v[252:253], off offset:1248
	global_load_dword v201, v[252:253], off offset:1376
	s_mov_b32 s101, 0
	s_mov_b32 s100, 0xdca00
	v_lshl_add_u64 v[250:251], v[80:81], 0, s[100:101]
	global_load_dword v202, v[250:251], off
	global_load_dword v203, v[250:251], off offset:128
	s_add_u32 s100, s62, 0xdca00
	v_lshl_add_u64 v[252:253], v[80:81], 0, s[100:101]
	global_load_dword v204, v[252:253], off offset:3104
	global_load_dword v205, v[252:253], off offset:3232
	s_add_u32 s100, s63, 0xdca00
	v_lshl_add_u64 v[250:251], v[80:81], 0, s[100:101]
	global_load_dword v206, v[250:251], off offset:2112
	global_load_dword v207, v[250:251], off offset:2240
	s_add_u32 s100, s64, 0xdca00
	v_lshl_add_u64 v[252:253], v[80:81], 0, s[100:101]
	global_load_dword v208, v[252:253], off offset:1120
	global_load_dword v209, v[252:253], off offset:1248
	s_add_u32 s100, s65, 0xdca00
	v_lshl_add_u64 v[250:251], v[80:81], 0, s[100:101]
	global_load_dword v210, v[250:251], off offset:128
	global_load_dword v211, v[250:251], off offset:256
	s_add_u32 s100, s66, 0xdca00
	v_lshl_add_u64 v[252:253], v[80:81], 0, s[100:101]
	global_load_dword v212, v[252:253], off offset:3232
	global_load_dword v213, v[252:253], off offset:3360
	s_add_u32 s100, s67, 0xdca00
	v_lshl_add_u64 v[250:251], v[80:81], 0, s[100:101]
	global_load_dword v214, v[250:251], off offset:2240
	global_load_dword v215, v[250:251], off offset:2368
	s_add_u32 s100, s68, 0xdca00
	v_lshl_add_u64 v[252:253], v[80:81], 0, s[100:101]
	global_load_dword v216, v[252:253], off offset:1248
	global_load_dword v217, v[252:253], off offset:1376
	s_mov_b32 s101, 0
	s_mov_b32 s100, 0x108c00
	v_lshl_add_u64 v[250:251], v[80:81], 0, s[100:101]
	global_load_dword v218, v[250:251], off
	global_load_dword v219, v[250:251], off offset:128
	s_add_u32 s100, s62, 0x108c00
	v_lshl_add_u64 v[252:253], v[80:81], 0, s[100:101]
	global_load_dword v220, v[252:253], off offset:3104
	global_load_dword v221, v[252:253], off offset:3232
	s_add_u32 s100, s63, 0x108c00
	v_lshl_add_u64 v[250:251], v[80:81], 0, s[100:101]
	global_load_dword v222, v[250:251], off offset:2112
	global_load_dword v223, v[250:251], off offset:2240
	s_add_u32 s100, s64, 0x108c00
	v_lshl_add_u64 v[252:253], v[80:81], 0, s[100:101]
	global_load_dword v224, v[252:253], off offset:1120
	global_load_dword v225, v[252:253], off offset:1248
	s_add_u32 s100, s65, 0x108c00
	v_lshl_add_u64 v[250:251], v[80:81], 0, s[100:101]
	global_load_dword v226, v[250:251], off offset:128
	global_load_dword v227, v[250:251], off offset:256
	s_add_u32 s100, s66, 0x108c00
	v_lshl_add_u64 v[252:253], v[80:81], 0, s[100:101]
	global_load_dword v228, v[252:253], off offset:3232
	global_load_dword v229, v[252:253], off offset:3360
	s_add_u32 s100, s67, 0x108c00
	v_lshl_add_u64 v[250:251], v[80:81], 0, s[100:101]
	global_load_dword v230, v[250:251], off offset:2240
	global_load_dword v231, v[250:251], off offset:2368
	s_add_u32 s100, s68, 0x108c00
	v_lshl_add_u64 v[252:253], v[80:81], 0, s[100:101]
	global_load_dword v232, v[252:253], off offset:1248
	global_load_dword v233, v[252:253], off offset:1376
	s_mov_b32 s101, 0
	s_mov_b32 s100, 0x134e00
	v_lshl_add_u64 v[250:251], v[80:81], 0, s[100:101]
	global_load_dword v234, v[250:251], off
	global_load_dword v235, v[250:251], off offset:128
	s_add_u32 s100, s62, 0x134e00
	v_lshl_add_u64 v[252:253], v[80:81], 0, s[100:101]
	global_load_dword v236, v[252:253], off offset:3104
	global_load_dword v237, v[252:253], off offset:3232
	s_add_u32 s100, s63, 0x134e00
	v_lshl_add_u64 v[250:251], v[80:81], 0, s[100:101]
	global_load_dword v238, v[250:251], off offset:2112
	global_load_dword v239, v[250:251], off offset:2240
	s_add_u32 s100, s64, 0x134e00
	v_lshl_add_u64 v[252:253], v[80:81], 0, s[100:101]
	global_load_dword v240, v[252:253], off offset:1120
	global_load_dword v241, v[252:253], off offset:1248
	s_add_u32 s100, s65, 0x134e00
	v_lshl_add_u64 v[250:251], v[80:81], 0, s[100:101]
	global_load_dword v242, v[250:251], off offset:128
	global_load_dword v243, v[250:251], off offset:256
	s_add_u32 s100, s66, 0x134e00
	v_lshl_add_u64 v[252:253], v[80:81], 0, s[100:101]
	global_load_dword v244, v[252:253], off offset:3232
	global_load_dword v245, v[252:253], off offset:3360
	s_add_u32 s100, s67, 0x134e00
	v_lshl_add_u64 v[250:251], v[80:81], 0, s[100:101]
	global_load_dword v246, v[250:251], off offset:2240
	global_load_dword v247, v[250:251], off offset:2368
	s_add_u32 s100, s68, 0x134e00
	v_lshl_add_u64 v[252:253], v[80:81], 0, s[100:101]
	global_load_dword v248, v[252:253], off offset:1248
	global_load_dword v249, v[252:253], off offset:1376
	v_lshl_add_u64 v[40:41], v[80:81], 0, s[52:53]
	v_add_co_u32_e32 v44, vcc, s62, v40
	ds_read_b128 v[32:35], v116
	ds_read_b128 v[36:39], v116 offset:16
	v_addc_co_u32_e32 v45, vcc, 0, v41, vcc
	global_load_dword v42, v[40:41], off
	global_load_dword v86, v[40:41], off offset:128
	global_load_dword v46, v[44:45], off offset:3104
	global_load_dword v88, v[44:45], off offset:3232
	v_add_co_u32_e32 v44, vcc, s63, v40
	s_waitcnt lgkmcnt(1)
	v_cndmask_b32_e64 v35, 0, v35, s[2:3]
	v_addc_co_u32_e32 v45, vcc, 0, v41, vcc
	global_load_dword v43, v[44:45], off offset:2112
	global_load_dword v87, v[44:45], off offset:2240
	v_add_co_u32_e32 v44, vcc, s64, v40
	s_waitcnt lgkmcnt(0)
	v_cndmask_b32_e64 v39, 0, v39, s[2:3]
	v_addc_co_u32_e32 v45, vcc, 0, v41, vcc
	global_load_dword v47, v[44:45], off offset:1120
	global_load_dword v89, v[44:45], off offset:1248
	v_add_co_u32_e32 v44, vcc, s65, v40
	s_nop 0
	v_addc_co_u32_e32 v45, vcc, 0, v41, vcc
	global_load_dword v118, v[44:45], off offset:128
	global_load_dword v82, v[44:45], off offset:256
	v_add_co_u32_e32 v44, vcc, s66, v40
	s_nop 0
	v_addc_co_u32_e32 v45, vcc, 0, v41, vcc
	global_load_dword v120, v[44:45], off offset:3232
	global_load_dword v84, v[44:45], off offset:3360
	v_add_co_u32_e32 v44, vcc, s67, v40
	v_add_u32_e32 v116, 64, v116
	s_nop 0
	v_addc_co_u32_e32 v45, vcc, 0, v41, vcc
	v_add_co_u32_e32 v40, vcc, s68, v40
	global_load_dword v119, v[44:45], off offset:2240
	global_load_dword v83, v[44:45], off offset:2368
	v_addc_co_u32_e32 v41, vcc, 0, v41, vcc
	global_load_dword v121, v[40:41], off offset:1248
	global_load_dword v85, v[40:41], off offset:1376
	v_cndmask_b32_e64 v41, 0, v34, s[2:3]
	v_cndmask_b32_e64 v40, 0, v32, s[2:3]
	v_cndmask_b32_e64 v34, 0, v33, s[2:3]
	v_and_b32_sdwa v32, v41, v115 dst_sel:DWORD dst_unused:UNUSED_PAD src0_sel:WORD_1 src1_sel:DWORD
	v_and_b32_sdwa v33, v40, v115 dst_sel:DWORD dst_unused:UNUSED_PAD src0_sel:WORD_1 src1_sel:DWORD
	v_add3_u32 v117, v41, v32, s69
	v_and_b32_sdwa v32, v35, v115 dst_sel:DWORD dst_unused:UNUSED_PAD src0_sel:WORD_1 src1_sel:DWORD
	v_and_b32_sdwa v44, v34, v115 dst_sel:DWORD dst_unused:UNUSED_PAD src0_sel:WORD_1 src1_sel:DWORD
	v_add3_u32 v33, v40, v33, s69
	v_add3_u32 v32, v35, v32, s69
	v_add3_u32 v44, v34, v44, s69
	v_and_b32_e32 v45, 0xffff0000, v32
	v_and_b32_e32 v44, 0xffff0000, v44
	v_and_b32_e32 v123, 0xffff0000, v117
	v_and_b32_e32 v122, 0xffff0000, v33
	v_or_b32_sdwa v32, v44, v33 dst_sel:DWORD dst_unused:UNUSED_PAD src0_sel:DWORD src1_sel:WORD_1
	v_pk_add_f32 v[40:41], v[40:41], v[122:123] neg_lo:[0,1] neg_hi:[0,1]
	v_pk_add_f32 v[122:123], v[34:35], v[44:45] neg_lo:[0,1] neg_hi:[0,1]
	v_or_b32_sdwa v33, v45, v117 dst_sel:DWORD dst_unused:UNUSED_PAD src0_sel:DWORD src1_sel:WORD_1
	v_cndmask_b32_e64 v45, 0, v38, s[2:3]
	v_cndmask_b32_e64 v38, 0, v37, s[2:3]
	v_and_b32_sdwa v34, v45, v115 dst_sel:DWORD dst_unused:UNUSED_PAD src0_sel:WORD_1 src1_sel:DWORD
	v_cndmask_b32_e64 v44, 0, v36, s[2:3]
	v_add3_u32 v117, v45, v34, s69
	v_and_b32_sdwa v34, v39, v115 dst_sel:DWORD dst_unused:UNUSED_PAD src0_sel:WORD_1 src1_sel:DWORD
	v_and_b32_sdwa v36, v38, v115 dst_sel:DWORD dst_unused:UNUSED_PAD src0_sel:WORD_1 src1_sel:DWORD
	v_and_b32_sdwa v35, v44, v115 dst_sel:DWORD dst_unused:UNUSED_PAD src0_sel:WORD_1 src1_sel:DWORD
	v_add3_u32 v34, v39, v34, s69
	v_add3_u32 v36, v38, v36, s69
	v_add3_u32 v35, v44, v35, s69
	v_and_b32_e32 v37, 0xffff0000, v34
	v_and_b32_e32 v36, 0xffff0000, v36
	v_and_b32_e32 v125, 0xffff0000, v117
	v_and_b32_e32 v124, 0xffff0000, v35
	v_pk_add_f32 v[38:39], v[38:39], v[36:37] neg_lo:[0,1] neg_hi:[0,1]
	v_or_b32_sdwa v34, v36, v35 dst_sel:DWORD dst_unused:UNUSED_PAD src0_sel:DWORD src1_sel:WORD_1
	v_pk_add_f32 v[44:45], v[44:45], v[124:125] neg_lo:[0,1] neg_hi:[0,1]
	v_or_b32_sdwa v35, v37, v117 dst_sel:DWORD dst_unused:UNUSED_PAD src0_sel:DWORD src1_sel:WORD_1
	v_bfe_u32 v36, v39, 16, 1
	v_bfe_u32 v37, v38, 16, 1
	v_bfe_u32 v117, v123, 16, 1
	v_bfe_u32 v124, v122, 16, 1
	v_add3_u32 v122, v122, v124, s69
	v_add3_u32 v117, v123, v117, s69
	v_add3_u32 v37, v38, v37, s69
	v_add3_u32 v36, v39, v36, s69
	v_bfe_u32 v38, v40, 16, 1
	v_bfe_u32 v39, v41, 16, 1
	v_bfe_u32 v123, v44, 16, 1
	v_bfe_u32 v124, v45, 16, 1
	v_add3_u32 v45, v45, v124, s69
	v_add3_u32 v44, v44, v123, s69
	v_add3_u32 v39, v41, v39, s69
	v_add3_u32 v38, v40, v38, s69
	v_lshrrev_b32_e32 v40, 16, v38
	v_lshrrev_b32_e32 v41, 16, v39
	v_lshrrev_b32_e32 v38, 16, v44
	v_lshrrev_b32_e32 v39, 16, v45
	v_and_or_b32 v39, v36, s70, v39
	v_and_or_b32 v38, v37, s70, v38
	v_and_or_b32 v37, v117, s70, v41
	v_and_or_b32 v36, v122, s70, v40
	s_waitcnt vmcnt(11)
	v_and_b32_sdwa v40, v43, v115 dst_sel:DWORD dst_unused:UNUSED_PAD src0_sel:WORD_1 src1_sel:DWORD
	v_and_b32_sdwa v41, v42, v115 dst_sel:DWORD dst_unused:UNUSED_PAD src0_sel:WORD_1 src1_sel:DWORD
	v_add3_u32 v117, v43, v40, s69
	v_add3_u32 v41, v42, v41, s69
	s_waitcnt vmcnt(9)
	v_and_b32_sdwa v40, v47, v115 dst_sel:DWORD dst_unused:UNUSED_PAD src0_sel:WORD_1 src1_sel:DWORD
	v_and_b32_sdwa v44, v46, v115 dst_sel:DWORD dst_unused:UNUSED_PAD src0_sel:WORD_1 src1_sel:DWORD
	v_add3_u32 v40, v47, v40, s69
	v_add3_u32 v44, v46, v44, s69
	v_and_b32_e32 v123, 0xffff0000, v117
	v_and_b32_e32 v122, 0xffff0000, v41
	v_and_b32_e32 v45, 0xffff0000, v40
	v_and_b32_e32 v44, 0xffff0000, v44
	v_pk_add_f32 v[122:123], v[42:43], v[122:123] neg_lo:[0,1] neg_hi:[0,1]
	s_waitcnt vmcnt(3)
	v_and_b32_sdwa v42, v119, v115 dst_sel:DWORD dst_unused:UNUSED_PAD src0_sel:WORD_1 src1_sel:DWORD
	v_or_b32_sdwa v40, v44, v41 dst_sel:DWORD dst_unused:UNUSED_PAD src0_sel:DWORD src1_sel:WORD_1
	v_pk_add_f32 v[46:47], v[46:47], v[44:45] neg_lo:[0,1] neg_hi:[0,1]
	v_or_b32_sdwa v41, v45, v117 dst_sel:DWORD dst_unused:UNUSED_PAD src0_sel:DWORD src1_sel:WORD_1
	v_add3_u32 v117, v119, v42, s69
	s_waitcnt vmcnt(1)
	v_and_b32_sdwa v42, v121, v115 dst_sel:DWORD dst_unused:UNUSED_PAD src0_sel:WORD_1 src1_sel:DWORD
	v_and_b32_sdwa v44, v120, v115 dst_sel:DWORD dst_unused:UNUSED_PAD src0_sel:WORD_1 src1_sel:DWORD
	v_and_b32_sdwa v43, v118, v115 dst_sel:DWORD dst_unused:UNUSED_PAD src0_sel:WORD_1 src1_sel:DWORD
	v_add3_u32 v42, v121, v42, s69
	v_add3_u32 v44, v120, v44, s69
	v_add3_u32 v43, v118, v43, s69
	v_and_b32_e32 v45, 0xffff0000, v42
	v_and_b32_e32 v44, 0xffff0000, v44
	v_and_b32_e32 v125, 0xffff0000, v117
	v_and_b32_e32 v124, 0xffff0000, v43
	v_pk_add_f32 v[120:121], v[120:121], v[44:45] neg_lo:[0,1] neg_hi:[0,1]
	v_or_b32_sdwa v42, v44, v43 dst_sel:DWORD dst_unused:UNUSED_PAD src0_sel:DWORD src1_sel:WORD_1
	v_pk_add_f32 v[118:119], v[118:119], v[124:125] neg_lo:[0,1] neg_hi:[0,1]
	v_bfe_u32 v44, v121, 16, 1
	v_bfe_u32 v124, v46, 16, 1
	v_or_b32_sdwa v43, v45, v117 dst_sel:DWORD dst_unused:UNUSED_PAD src0_sel:DWORD src1_sel:WORD_1
	v_bfe_u32 v45, v120, 16, 1
	v_bfe_u32 v117, v47, 16, 1
	v_add3_u32 v124, v46, v124, s69
	v_add3_u32 v44, v121, v44, s69
	v_bfe_u32 v46, v118, 16, 1
	v_bfe_u32 v121, v123, 16, 1
	v_add3_u32 v117, v47, v117, s69
	v_add3_u32 v45, v120, v45, s69
	v_bfe_u32 v47, v119, 16, 1
	v_bfe_u32 v120, v122, 16, 1
	v_add3_u32 v46, v118, v46, s69
	v_add3_u32 v118, v123, v121, s69
	v_add3_u32 v47, v119, v47, s69
	v_add3_u32 v119, v122, v120, s69
	v_lshrrev_b32_e32 v46, 16, v46
	v_lshrrev_b32_e32 v118, 16, v118
	v_lshrrev_b32_e32 v47, 16, v47
	v_lshrrev_b32_e32 v119, 16, v119
	v_and_or_b32 v46, v45, s70, v46
	v_and_or_b32 v45, v117, s70, v118
	v_and_b32_sdwa v118, v86, v115 dst_sel:DWORD dst_unused:UNUSED_PAD src0_sel:WORD_1 src1_sel:DWORD
	v_and_or_b32 v47, v44, s70, v47
	v_and_or_b32 v44, v124, s70, v119
	v_add3_u32 v119, v86, v118, s69
	v_and_b32_sdwa v118, v89, v115 dst_sel:DWORD dst_unused:UNUSED_PAD src0_sel:WORD_1 src1_sel:DWORD
	v_and_b32_sdwa v120, v88, v115 dst_sel:DWORD dst_unused:UNUSED_PAD src0_sel:WORD_1 src1_sel:DWORD
	v_and_b32_sdwa v117, v87, v115 dst_sel:DWORD dst_unused:UNUSED_PAD src0_sel:WORD_1 src1_sel:DWORD
	v_add3_u32 v118, v89, v118, s69
	v_add3_u32 v120, v88, v120, s69
	v_add3_u32 v117, v87, v117, s69
	v_and_b32_e32 v121, 0xffff0000, v118
	v_and_b32_e32 v120, 0xffff0000, v120
	v_or_b32_sdwa v118, v120, v119 dst_sel:DWORD dst_unused:UNUSED_PAD src0_sel:DWORD src1_sel:WORD_1
	v_and_b32_e32 v123, 0xffff0000, v117
	v_and_b32_e32 v122, 0xffff0000, v119
	v_pk_add_f32 v[88:89], v[88:89], v[120:121] neg_lo:[0,1] neg_hi:[0,1]
	v_and_b32_sdwa v120, v82, v115 dst_sel:DWORD dst_unused:UNUSED_PAD src0_sel:WORD_1 src1_sel:DWORD
	v_pk_add_f32 v[86:87], v[86:87], v[122:123] neg_lo:[0,1] neg_hi:[0,1]
	v_or_b32_sdwa v119, v121, v117 dst_sel:DWORD dst_unused:UNUSED_PAD src0_sel:DWORD src1_sel:WORD_1
	v_add3_u32 v121, v82, v120, s69
	s_waitcnt vmcnt(0)
	v_and_b32_sdwa v120, v85, v115 dst_sel:DWORD dst_unused:UNUSED_PAD src0_sel:WORD_1 src1_sel:DWORD
	v_and_b32_sdwa v122, v84, v115 dst_sel:DWORD dst_unused:UNUSED_PAD src0_sel:WORD_1 src1_sel:DWORD
	v_and_b32_sdwa v117, v83, v115 dst_sel:DWORD dst_unused:UNUSED_PAD src0_sel:WORD_1 src1_sel:DWORD
	v_add3_u32 v120, v85, v120, s69
	v_add3_u32 v122, v84, v122, s69
	v_add3_u32 v117, v83, v117, s69
	v_and_b32_e32 v123, 0xffff0000, v120
	v_and_b32_e32 v122, 0xffff0000, v122
	v_or_b32_sdwa v120, v122, v121 dst_sel:DWORD dst_unused:UNUSED_PAD src0_sel:DWORD src1_sel:WORD_1
	v_and_b32_e32 v124, 0xffff0000, v121
	v_or_b32_sdwa v121, v123, v117 dst_sel:DWORD dst_unused:UNUSED_PAD src0_sel:DWORD src1_sel:WORD_1
	v_mfma_f32_32x32x16_bf16 v[0:15], v[32:35], v[40:43], v[0:15]
	v_and_b32_e32 v125, 0xffff0000, v117
	v_add_f32_e64 v84, v84, -v122
	v_add_f32_e64 v85, v85, -v123
	v_add_f32_e64 v82, v82, -v124
	v_add_f32_e64 v83, v83, -v125
	v_bfe_u32 v117, v85, 16, 1
	v_bfe_u32 v122, v84, 16, 1
	v_bfe_u32 v123, v89, 16, 1
	v_bfe_u32 v124, v88, 16, 1
	v_mfma_f32_32x32x16_bf16 v[16:31], v[32:35], v[118:121], v[16:31]
	v_add3_u32 v88, v88, v124, s69
	v_add3_u32 v89, v89, v123, s69
	v_add3_u32 v84, v84, v122, s69
	v_add3_u32 v85, v85, v117, s69
	v_bfe_u32 v117, v82, 16, 1
	v_bfe_u32 v122, v83, 16, 1
	v_bfe_u32 v123, v86, 16, 1
	v_bfe_u32 v124, v87, 16, 1
	v_add3_u32 v83, v83, v122, s69
	v_add3_u32 v82, v82, v117, s69
	v_add3_u32 v87, v87, v124, s69
	v_add3_u32 v86, v86, v123, s69
	v_lshrrev_b32_e32 v82, 16, v82
	v_lshrrev_b32_e32 v83, 16, v83
	v_lshrrev_b32_e32 v86, 16, v86
	v_lshrrev_b32_e32 v87, 16, v87
	v_and_or_b32 v85, v85, s70, v83
	v_and_or_b32 v84, v84, s70, v82
	v_and_or_b32 v83, v89, s70, v87
	v_and_or_b32 v82, v88, s70, v86
	v_mfma_f32_32x32x16_bf16 v[0:15], v[32:35], v[44:47], v[0:15]
	v_mfma_f32_32x32x16_bf16 v[16:31], v[32:35], v[82:85], v[16:31]
	v_mfma_f32_32x32x16_bf16 v[0:15], v[36:39], v[40:43], v[0:15]
	v_mfma_f32_32x32x16_bf16 v[16:31], v[36:39], v[118:121], v[16:31]
	ds_read_b128 v[32:35], v116
	ds_read_b128 v[36:39], v116 offset:16
	v_mov_b32_e32 v42, v138
	v_mov_b32_e32 v86, v139
	v_mov_b32_e32 v46, v140
	v_mov_b32_e32 v88, v141
	s_waitcnt lgkmcnt(1)
	v_cndmask_b32_e64 v35, 0, v35, s[2:3]
	v_mov_b32_e32 v43, v142
	v_mov_b32_e32 v87, v143
	s_waitcnt lgkmcnt(0)
	v_cndmask_b32_e64 v39, 0, v39, s[2:3]
	v_mov_b32_e32 v47, v144
	v_mov_b32_e32 v89, v145
	s_nop 0
	v_mov_b32_e32 v118, v146
	v_mov_b32_e32 v82, v147
	s_nop 0
	v_mov_b32_e32 v120, v148
	v_mov_b32_e32 v84, v149
	v_add_u32_e32 v116, 64, v116
	s_nop 0
	v_mov_b32_e32 v119, v150
	v_mov_b32_e32 v83, v151
	v_mov_b32_e32 v121, v152
	v_mov_b32_e32 v85, v153
	v_cndmask_b32_e64 v41, 0, v34, s[2:3]
	v_cndmask_b32_e64 v40, 0, v32, s[2:3]
	v_cndmask_b32_e64 v34, 0, v33, s[2:3]
	v_and_b32_sdwa v32, v41, v115 dst_sel:DWORD dst_unused:UNUSED_PAD src0_sel:WORD_1 src1_sel:DWORD
	v_and_b32_sdwa v33, v40, v115 dst_sel:DWORD dst_unused:UNUSED_PAD src0_sel:WORD_1 src1_sel:DWORD
	v_add3_u32 v117, v41, v32, s69
	v_and_b32_sdwa v32, v35, v115 dst_sel:DWORD dst_unused:UNUSED_PAD src0_sel:WORD_1 src1_sel:DWORD
	v_and_b32_sdwa v44, v34, v115 dst_sel:DWORD dst_unused:UNUSED_PAD src0_sel:WORD_1 src1_sel:DWORD
	v_add3_u32 v33, v40, v33, s69
	v_add3_u32 v32, v35, v32, s69
	v_add3_u32 v44, v34, v44, s69
	v_and_b32_e32 v45, 0xffff0000, v32
	v_and_b32_e32 v44, 0xffff0000, v44
	v_and_b32_e32 v123, 0xffff0000, v117
	v_and_b32_e32 v122, 0xffff0000, v33
	v_or_b32_sdwa v32, v44, v33 dst_sel:DWORD dst_unused:UNUSED_PAD src0_sel:DWORD src1_sel:WORD_1
	v_pk_add_f32 v[40:41], v[40:41], v[122:123] neg_lo:[0,1] neg_hi:[0,1]
	v_pk_add_f32 v[122:123], v[34:35], v[44:45] neg_lo:[0,1] neg_hi:[0,1]
	v_or_b32_sdwa v33, v45, v117 dst_sel:DWORD dst_unused:UNUSED_PAD src0_sel:DWORD src1_sel:WORD_1
	v_cndmask_b32_e64 v45, 0, v38, s[2:3]
	v_cndmask_b32_e64 v38, 0, v37, s[2:3]
	v_and_b32_sdwa v34, v45, v115 dst_sel:DWORD dst_unused:UNUSED_PAD src0_sel:WORD_1 src1_sel:DWORD
	v_cndmask_b32_e64 v44, 0, v36, s[2:3]
	v_add3_u32 v117, v45, v34, s69
	v_and_b32_sdwa v34, v39, v115 dst_sel:DWORD dst_unused:UNUSED_PAD src0_sel:WORD_1 src1_sel:DWORD
	v_and_b32_sdwa v36, v38, v115 dst_sel:DWORD dst_unused:UNUSED_PAD src0_sel:WORD_1 src1_sel:DWORD
	v_and_b32_sdwa v35, v44, v115 dst_sel:DWORD dst_unused:UNUSED_PAD src0_sel:WORD_1 src1_sel:DWORD
	v_add3_u32 v34, v39, v34, s69
	v_add3_u32 v36, v38, v36, s69
	v_add3_u32 v35, v44, v35, s69
	v_and_b32_e32 v37, 0xffff0000, v34
	v_and_b32_e32 v36, 0xffff0000, v36
	v_and_b32_e32 v125, 0xffff0000, v117
	v_and_b32_e32 v124, 0xffff0000, v35
	v_pk_add_f32 v[38:39], v[38:39], v[36:37] neg_lo:[0,1] neg_hi:[0,1]
	v_or_b32_sdwa v34, v36, v35 dst_sel:DWORD dst_unused:UNUSED_PAD src0_sel:DWORD src1_sel:WORD_1
	v_pk_add_f32 v[44:45], v[44:45], v[124:125] neg_lo:[0,1] neg_hi:[0,1]
	v_or_b32_sdwa v35, v37, v117 dst_sel:DWORD dst_unused:UNUSED_PAD src0_sel:DWORD src1_sel:WORD_1
	v_bfe_u32 v36, v39, 16, 1
	v_bfe_u32 v37, v38, 16, 1
	v_bfe_u32 v117, v123, 16, 1
	v_bfe_u32 v124, v122, 16, 1
	v_add3_u32 v122, v122, v124, s69
	v_add3_u32 v117, v123, v117, s69
	v_add3_u32 v37, v38, v37, s69
	v_add3_u32 v36, v39, v36, s69
	v_bfe_u32 v38, v40, 16, 1
	v_bfe_u32 v39, v41, 16, 1
	v_bfe_u32 v123, v44, 16, 1
	v_bfe_u32 v124, v45, 16, 1
	v_add3_u32 v45, v45, v124, s69
	v_add3_u32 v44, v44, v123, s69
	v_add3_u32 v39, v41, v39, s69
	v_add3_u32 v38, v40, v38, s69
	v_lshrrev_b32_e32 v40, 16, v38
	v_lshrrev_b32_e32 v41, 16, v39
	v_lshrrev_b32_e32 v38, 16, v44
	v_lshrrev_b32_e32 v39, 16, v45
	v_and_or_b32 v39, v36, s70, v39
	v_and_or_b32 v38, v37, s70, v38
	v_and_or_b32 v37, v117, s70, v41
	v_and_or_b32 v36, v122, s70, v40
	v_and_b32_sdwa v40, v43, v115 dst_sel:DWORD dst_unused:UNUSED_PAD src0_sel:WORD_1 src1_sel:DWORD
	v_and_b32_sdwa v41, v42, v115 dst_sel:DWORD dst_unused:UNUSED_PAD src0_sel:WORD_1 src1_sel:DWORD
	v_add3_u32 v117, v43, v40, s69
	v_add3_u32 v41, v42, v41, s69
	v_and_b32_sdwa v40, v47, v115 dst_sel:DWORD dst_unused:UNUSED_PAD src0_sel:WORD_1 src1_sel:DWORD
	v_and_b32_sdwa v44, v46, v115 dst_sel:DWORD dst_unused:UNUSED_PAD src0_sel:WORD_1 src1_sel:DWORD
	v_add3_u32 v40, v47, v40, s69
	v_add3_u32 v44, v46, v44, s69
	v_and_b32_e32 v123, 0xffff0000, v117
	v_and_b32_e32 v122, 0xffff0000, v41
	v_and_b32_e32 v45, 0xffff0000, v40
	v_and_b32_e32 v44, 0xffff0000, v44
	v_pk_add_f32 v[122:123], v[42:43], v[122:123] neg_lo:[0,1] neg_hi:[0,1]
	v_and_b32_sdwa v42, v119, v115 dst_sel:DWORD dst_unused:UNUSED_PAD src0_sel:WORD_1 src1_sel:DWORD
	v_or_b32_sdwa v40, v44, v41 dst_sel:DWORD dst_unused:UNUSED_PAD src0_sel:DWORD src1_sel:WORD_1
	v_pk_add_f32 v[46:47], v[46:47], v[44:45] neg_lo:[0,1] neg_hi:[0,1]
	v_or_b32_sdwa v41, v45, v117 dst_sel:DWORD dst_unused:UNUSED_PAD src0_sel:DWORD src1_sel:WORD_1
	v_add3_u32 v117, v119, v42, s69
	v_and_b32_sdwa v42, v121, v115 dst_sel:DWORD dst_unused:UNUSED_PAD src0_sel:WORD_1 src1_sel:DWORD
	v_and_b32_sdwa v44, v120, v115 dst_sel:DWORD dst_unused:UNUSED_PAD src0_sel:WORD_1 src1_sel:DWORD
	v_and_b32_sdwa v43, v118, v115 dst_sel:DWORD dst_unused:UNUSED_PAD src0_sel:WORD_1 src1_sel:DWORD
	v_add3_u32 v42, v121, v42, s69
	v_add3_u32 v44, v120, v44, s69
	v_add3_u32 v43, v118, v43, s69
	v_and_b32_e32 v45, 0xffff0000, v42
	v_and_b32_e32 v44, 0xffff0000, v44
	v_and_b32_e32 v125, 0xffff0000, v117
	v_and_b32_e32 v124, 0xffff0000, v43
	v_pk_add_f32 v[120:121], v[120:121], v[44:45] neg_lo:[0,1] neg_hi:[0,1]
	v_or_b32_sdwa v42, v44, v43 dst_sel:DWORD dst_unused:UNUSED_PAD src0_sel:DWORD src1_sel:WORD_1
	v_pk_add_f32 v[118:119], v[118:119], v[124:125] neg_lo:[0,1] neg_hi:[0,1]
	v_bfe_u32 v44, v121, 16, 1
	v_bfe_u32 v124, v46, 16, 1
	v_or_b32_sdwa v43, v45, v117 dst_sel:DWORD dst_unused:UNUSED_PAD src0_sel:DWORD src1_sel:WORD_1
	v_bfe_u32 v45, v120, 16, 1
	v_bfe_u32 v117, v47, 16, 1
	v_add3_u32 v124, v46, v124, s69
	v_add3_u32 v44, v121, v44, s69
	v_bfe_u32 v46, v118, 16, 1
	v_bfe_u32 v121, v123, 16, 1
	v_add3_u32 v117, v47, v117, s69
	v_add3_u32 v45, v120, v45, s69
	v_bfe_u32 v47, v119, 16, 1
	v_bfe_u32 v120, v122, 16, 1
	v_add3_u32 v46, v118, v46, s69
	v_add3_u32 v118, v123, v121, s69
	v_add3_u32 v47, v119, v47, s69
	v_add3_u32 v119, v122, v120, s69
	v_lshrrev_b32_e32 v46, 16, v46
	v_lshrrev_b32_e32 v118, 16, v118
	v_lshrrev_b32_e32 v47, 16, v47
	v_lshrrev_b32_e32 v119, 16, v119
	v_and_or_b32 v46, v45, s70, v46
	v_and_or_b32 v45, v117, s70, v118
	v_and_b32_sdwa v118, v86, v115 dst_sel:DWORD dst_unused:UNUSED_PAD src0_sel:WORD_1 src1_sel:DWORD
	v_and_or_b32 v47, v44, s70, v47
	v_and_or_b32 v44, v124, s70, v119
	v_add3_u32 v119, v86, v118, s69
	v_and_b32_sdwa v118, v89, v115 dst_sel:DWORD dst_unused:UNUSED_PAD src0_sel:WORD_1 src1_sel:DWORD
	v_and_b32_sdwa v120, v88, v115 dst_sel:DWORD dst_unused:UNUSED_PAD src0_sel:WORD_1 src1_sel:DWORD
	v_and_b32_sdwa v117, v87, v115 dst_sel:DWORD dst_unused:UNUSED_PAD src0_sel:WORD_1 src1_sel:DWORD
	v_add3_u32 v118, v89, v118, s69
	v_add3_u32 v120, v88, v120, s69
	v_add3_u32 v117, v87, v117, s69
	v_and_b32_e32 v121, 0xffff0000, v118
	v_and_b32_e32 v120, 0xffff0000, v120
	v_or_b32_sdwa v118, v120, v119 dst_sel:DWORD dst_unused:UNUSED_PAD src0_sel:DWORD src1_sel:WORD_1
	v_and_b32_e32 v123, 0xffff0000, v117
	v_and_b32_e32 v122, 0xffff0000, v119
	v_pk_add_f32 v[88:89], v[88:89], v[120:121] neg_lo:[0,1] neg_hi:[0,1]
	v_and_b32_sdwa v120, v82, v115 dst_sel:DWORD dst_unused:UNUSED_PAD src0_sel:WORD_1 src1_sel:DWORD
	v_pk_add_f32 v[86:87], v[86:87], v[122:123] neg_lo:[0,1] neg_hi:[0,1]
	v_or_b32_sdwa v119, v121, v117 dst_sel:DWORD dst_unused:UNUSED_PAD src0_sel:DWORD src1_sel:WORD_1
	v_add3_u32 v121, v82, v120, s69
	v_and_b32_sdwa v120, v85, v115 dst_sel:DWORD dst_unused:UNUSED_PAD src0_sel:WORD_1 src1_sel:DWORD
	v_and_b32_sdwa v122, v84, v115 dst_sel:DWORD dst_unused:UNUSED_PAD src0_sel:WORD_1 src1_sel:DWORD
	v_and_b32_sdwa v117, v83, v115 dst_sel:DWORD dst_unused:UNUSED_PAD src0_sel:WORD_1 src1_sel:DWORD
	v_add3_u32 v120, v85, v120, s69
	v_add3_u32 v122, v84, v122, s69
	v_add3_u32 v117, v83, v117, s69
	v_and_b32_e32 v123, 0xffff0000, v120
	v_and_b32_e32 v122, 0xffff0000, v122
	v_or_b32_sdwa v120, v122, v121 dst_sel:DWORD dst_unused:UNUSED_PAD src0_sel:DWORD src1_sel:WORD_1
	v_and_b32_e32 v124, 0xffff0000, v121
	v_or_b32_sdwa v121, v123, v117 dst_sel:DWORD dst_unused:UNUSED_PAD src0_sel:DWORD src1_sel:WORD_1
	v_mfma_f32_32x32x16_bf16 v[0:15], v[32:35], v[40:43], v[0:15]
	v_and_b32_e32 v125, 0xffff0000, v117
	v_add_f32_e64 v84, v84, -v122
	v_add_f32_e64 v85, v85, -v123
	v_add_f32_e64 v82, v82, -v124
	v_add_f32_e64 v83, v83, -v125
	v_bfe_u32 v117, v85, 16, 1
	v_bfe_u32 v122, v84, 16, 1
	v_bfe_u32 v123, v89, 16, 1
	v_bfe_u32 v124, v88, 16, 1
	v_mfma_f32_32x32x16_bf16 v[16:31], v[32:35], v[118:121], v[16:31]
	v_add3_u32 v88, v88, v124, s69
	v_add3_u32 v89, v89, v123, s69
	v_add3_u32 v84, v84, v122, s69
	v_add3_u32 v85, v85, v117, s69
	v_bfe_u32 v117, v82, 16, 1
	v_bfe_u32 v122, v83, 16, 1
	v_bfe_u32 v123, v86, 16, 1
	v_bfe_u32 v124, v87, 16, 1
	v_add3_u32 v83, v83, v122, s69
	v_add3_u32 v82, v82, v117, s69
	v_add3_u32 v87, v87, v124, s69
	v_add3_u32 v86, v86, v123, s69
	v_lshrrev_b32_e32 v82, 16, v82
	v_lshrrev_b32_e32 v83, 16, v83
	v_lshrrev_b32_e32 v86, 16, v86
	v_lshrrev_b32_e32 v87, 16, v87
	v_and_or_b32 v85, v85, s70, v83
	v_and_or_b32 v84, v84, s70, v82
	v_and_or_b32 v83, v89, s70, v87
	v_and_or_b32 v82, v88, s70, v86
	v_mfma_f32_32x32x16_bf16 v[0:15], v[32:35], v[44:47], v[0:15]
	v_mfma_f32_32x32x16_bf16 v[16:31], v[32:35], v[82:85], v[16:31]
	v_mfma_f32_32x32x16_bf16 v[0:15], v[36:39], v[40:43], v[0:15]
	v_mfma_f32_32x32x16_bf16 v[16:31], v[36:39], v[118:121], v[16:31]
	ds_read_b128 v[32:35], v116
	ds_read_b128 v[36:39], v116 offset:16
	v_mov_b32_e32 v42, v154
	v_mov_b32_e32 v86, v155
	v_mov_b32_e32 v46, v156
	v_mov_b32_e32 v88, v157
	s_waitcnt lgkmcnt(1)
	v_cndmask_b32_e64 v35, 0, v35, s[2:3]
	v_mov_b32_e32 v43, v158
	v_mov_b32_e32 v87, v159
	s_waitcnt lgkmcnt(0)
	v_cndmask_b32_e64 v39, 0, v39, s[2:3]
	v_mov_b32_e32 v47, v160
	v_mov_b32_e32 v89, v161
	s_nop 0
	v_mov_b32_e32 v118, v162
	v_mov_b32_e32 v82, v163
	s_nop 0
	v_mov_b32_e32 v120, v164
	v_mov_b32_e32 v84, v165
	v_add_u32_e32 v116, 64, v116
	s_nop 0
	v_mov_b32_e32 v119, v166
	v_mov_b32_e32 v83, v167
	v_mov_b32_e32 v121, v168
	v_mov_b32_e32 v85, v169
	v_cndmask_b32_e64 v41, 0, v34, s[2:3]
	v_cndmask_b32_e64 v40, 0, v32, s[2:3]
	v_cndmask_b32_e64 v34, 0, v33, s[2:3]
	v_and_b32_sdwa v32, v41, v115 dst_sel:DWORD dst_unused:UNUSED_PAD src0_sel:WORD_1 src1_sel:DWORD
	v_and_b32_sdwa v33, v40, v115 dst_sel:DWORD dst_unused:UNUSED_PAD src0_sel:WORD_1 src1_sel:DWORD
	v_add3_u32 v117, v41, v32, s69
	v_and_b32_sdwa v32, v35, v115 dst_sel:DWORD dst_unused:UNUSED_PAD src0_sel:WORD_1 src1_sel:DWORD
	v_and_b32_sdwa v44, v34, v115 dst_sel:DWORD dst_unused:UNUSED_PAD src0_sel:WORD_1 src1_sel:DWORD
	v_add3_u32 v33, v40, v33, s69
	v_add3_u32 v32, v35, v32, s69
	v_add3_u32 v44, v34, v44, s69
	v_and_b32_e32 v45, 0xffff0000, v32
	v_and_b32_e32 v44, 0xffff0000, v44
	v_and_b32_e32 v123, 0xffff0000, v117
	v_and_b32_e32 v122, 0xffff0000, v33
	v_or_b32_sdwa v32, v44, v33 dst_sel:DWORD dst_unused:UNUSED_PAD src0_sel:DWORD src1_sel:WORD_1
	v_pk_add_f32 v[40:41], v[40:41], v[122:123] neg_lo:[0,1] neg_hi:[0,1]
	v_pk_add_f32 v[122:123], v[34:35], v[44:45] neg_lo:[0,1] neg_hi:[0,1]
	v_or_b32_sdwa v33, v45, v117 dst_sel:DWORD dst_unused:UNUSED_PAD src0_sel:DWORD src1_sel:WORD_1
	v_cndmask_b32_e64 v45, 0, v38, s[2:3]
	v_cndmask_b32_e64 v38, 0, v37, s[2:3]
	v_and_b32_sdwa v34, v45, v115 dst_sel:DWORD dst_unused:UNUSED_PAD src0_sel:WORD_1 src1_sel:DWORD
	v_cndmask_b32_e64 v44, 0, v36, s[2:3]
	v_add3_u32 v117, v45, v34, s69
	v_and_b32_sdwa v34, v39, v115 dst_sel:DWORD dst_unused:UNUSED_PAD src0_sel:WORD_1 src1_sel:DWORD
	v_and_b32_sdwa v36, v38, v115 dst_sel:DWORD dst_unused:UNUSED_PAD src0_sel:WORD_1 src1_sel:DWORD
	v_and_b32_sdwa v35, v44, v115 dst_sel:DWORD dst_unused:UNUSED_PAD src0_sel:WORD_1 src1_sel:DWORD
	v_add3_u32 v34, v39, v34, s69
	v_add3_u32 v36, v38, v36, s69
	v_add3_u32 v35, v44, v35, s69
	v_and_b32_e32 v37, 0xffff0000, v34
	v_and_b32_e32 v36, 0xffff0000, v36
	v_and_b32_e32 v125, 0xffff0000, v117
	v_and_b32_e32 v124, 0xffff0000, v35
	v_pk_add_f32 v[38:39], v[38:39], v[36:37] neg_lo:[0,1] neg_hi:[0,1]
	v_or_b32_sdwa v34, v36, v35 dst_sel:DWORD dst_unused:UNUSED_PAD src0_sel:DWORD src1_sel:WORD_1
	v_pk_add_f32 v[44:45], v[44:45], v[124:125] neg_lo:[0,1] neg_hi:[0,1]
	v_or_b32_sdwa v35, v37, v117 dst_sel:DWORD dst_unused:UNUSED_PAD src0_sel:DWORD src1_sel:WORD_1
	v_bfe_u32 v36, v39, 16, 1
	v_bfe_u32 v37, v38, 16, 1
	v_bfe_u32 v117, v123, 16, 1
	v_bfe_u32 v124, v122, 16, 1
	v_add3_u32 v122, v122, v124, s69
	v_add3_u32 v117, v123, v117, s69
	v_add3_u32 v37, v38, v37, s69
	v_add3_u32 v36, v39, v36, s69
	v_bfe_u32 v38, v40, 16, 1
	v_bfe_u32 v39, v41, 16, 1
	v_bfe_u32 v123, v44, 16, 1
	v_bfe_u32 v124, v45, 16, 1
	v_add3_u32 v45, v45, v124, s69
	v_add3_u32 v44, v44, v123, s69
	v_add3_u32 v39, v41, v39, s69
	v_add3_u32 v38, v40, v38, s69
	v_lshrrev_b32_e32 v40, 16, v38
	v_lshrrev_b32_e32 v41, 16, v39
	v_lshrrev_b32_e32 v38, 16, v44
	v_lshrrev_b32_e32 v39, 16, v45
	v_and_or_b32 v39, v36, s70, v39
	v_and_or_b32 v38, v37, s70, v38
	v_and_or_b32 v37, v117, s70, v41
	v_and_or_b32 v36, v122, s70, v40
	v_and_b32_sdwa v40, v43, v115 dst_sel:DWORD dst_unused:UNUSED_PAD src0_sel:WORD_1 src1_sel:DWORD
	v_and_b32_sdwa v41, v42, v115 dst_sel:DWORD dst_unused:UNUSED_PAD src0_sel:WORD_1 src1_sel:DWORD
	v_add3_u32 v117, v43, v40, s69
	v_add3_u32 v41, v42, v41, s69
	v_and_b32_sdwa v40, v47, v115 dst_sel:DWORD dst_unused:UNUSED_PAD src0_sel:WORD_1 src1_sel:DWORD
	v_and_b32_sdwa v44, v46, v115 dst_sel:DWORD dst_unused:UNUSED_PAD src0_sel:WORD_1 src1_sel:DWORD
	v_add3_u32 v40, v47, v40, s69
	v_add3_u32 v44, v46, v44, s69
	v_and_b32_e32 v123, 0xffff0000, v117
	v_and_b32_e32 v122, 0xffff0000, v41
	v_and_b32_e32 v45, 0xffff0000, v40
	v_and_b32_e32 v44, 0xffff0000, v44
	v_pk_add_f32 v[122:123], v[42:43], v[122:123] neg_lo:[0,1] neg_hi:[0,1]
	v_and_b32_sdwa v42, v119, v115 dst_sel:DWORD dst_unused:UNUSED_PAD src0_sel:WORD_1 src1_sel:DWORD
	v_or_b32_sdwa v40, v44, v41 dst_sel:DWORD dst_unused:UNUSED_PAD src0_sel:DWORD src1_sel:WORD_1
	v_pk_add_f32 v[46:47], v[46:47], v[44:45] neg_lo:[0,1] neg_hi:[0,1]
	v_or_b32_sdwa v41, v45, v117 dst_sel:DWORD dst_unused:UNUSED_PAD src0_sel:DWORD src1_sel:WORD_1
	v_add3_u32 v117, v119, v42, s69
	v_and_b32_sdwa v42, v121, v115 dst_sel:DWORD dst_unused:UNUSED_PAD src0_sel:WORD_1 src1_sel:DWORD
	v_and_b32_sdwa v44, v120, v115 dst_sel:DWORD dst_unused:UNUSED_PAD src0_sel:WORD_1 src1_sel:DWORD
	v_and_b32_sdwa v43, v118, v115 dst_sel:DWORD dst_unused:UNUSED_PAD src0_sel:WORD_1 src1_sel:DWORD
	v_add3_u32 v42, v121, v42, s69
	v_add3_u32 v44, v120, v44, s69
	v_add3_u32 v43, v118, v43, s69
	v_and_b32_e32 v45, 0xffff0000, v42
	v_and_b32_e32 v44, 0xffff0000, v44
	v_and_b32_e32 v125, 0xffff0000, v117
	v_and_b32_e32 v124, 0xffff0000, v43
	v_pk_add_f32 v[120:121], v[120:121], v[44:45] neg_lo:[0,1] neg_hi:[0,1]
	v_or_b32_sdwa v42, v44, v43 dst_sel:DWORD dst_unused:UNUSED_PAD src0_sel:DWORD src1_sel:WORD_1
	v_pk_add_f32 v[118:119], v[118:119], v[124:125] neg_lo:[0,1] neg_hi:[0,1]
	v_bfe_u32 v44, v121, 16, 1
	v_bfe_u32 v124, v46, 16, 1
	v_or_b32_sdwa v43, v45, v117 dst_sel:DWORD dst_unused:UNUSED_PAD src0_sel:DWORD src1_sel:WORD_1
	v_bfe_u32 v45, v120, 16, 1
	v_bfe_u32 v117, v47, 16, 1
	v_add3_u32 v124, v46, v124, s69
	v_add3_u32 v44, v121, v44, s69
	v_bfe_u32 v46, v118, 16, 1
	v_bfe_u32 v121, v123, 16, 1
	v_add3_u32 v117, v47, v117, s69
	v_add3_u32 v45, v120, v45, s69
	v_bfe_u32 v47, v119, 16, 1
	v_bfe_u32 v120, v122, 16, 1
	v_add3_u32 v46, v118, v46, s69
	v_add3_u32 v118, v123, v121, s69
	v_add3_u32 v47, v119, v47, s69
	v_add3_u32 v119, v122, v120, s69
	v_lshrrev_b32_e32 v46, 16, v46
	v_lshrrev_b32_e32 v118, 16, v118
	v_lshrrev_b32_e32 v47, 16, v47
	v_lshrrev_b32_e32 v119, 16, v119
	v_and_or_b32 v46, v45, s70, v46
	v_and_or_b32 v45, v117, s70, v118
	v_and_b32_sdwa v118, v86, v115 dst_sel:DWORD dst_unused:UNUSED_PAD src0_sel:WORD_1 src1_sel:DWORD
	v_and_or_b32 v47, v44, s70, v47
	v_and_or_b32 v44, v124, s70, v119
	v_add3_u32 v119, v86, v118, s69
	v_and_b32_sdwa v118, v89, v115 dst_sel:DWORD dst_unused:UNUSED_PAD src0_sel:WORD_1 src1_sel:DWORD
	v_and_b32_sdwa v120, v88, v115 dst_sel:DWORD dst_unused:UNUSED_PAD src0_sel:WORD_1 src1_sel:DWORD
	v_and_b32_sdwa v117, v87, v115 dst_sel:DWORD dst_unused:UNUSED_PAD src0_sel:WORD_1 src1_sel:DWORD
	v_add3_u32 v118, v89, v118, s69
	v_add3_u32 v120, v88, v120, s69
	v_add3_u32 v117, v87, v117, s69
	v_and_b32_e32 v121, 0xffff0000, v118
	v_and_b32_e32 v120, 0xffff0000, v120
	v_or_b32_sdwa v118, v120, v119 dst_sel:DWORD dst_unused:UNUSED_PAD src0_sel:DWORD src1_sel:WORD_1
	v_and_b32_e32 v123, 0xffff0000, v117
	v_and_b32_e32 v122, 0xffff0000, v119
	v_pk_add_f32 v[88:89], v[88:89], v[120:121] neg_lo:[0,1] neg_hi:[0,1]
	v_and_b32_sdwa v120, v82, v115 dst_sel:DWORD dst_unused:UNUSED_PAD src0_sel:WORD_1 src1_sel:DWORD
	v_pk_add_f32 v[86:87], v[86:87], v[122:123] neg_lo:[0,1] neg_hi:[0,1]
	v_or_b32_sdwa v119, v121, v117 dst_sel:DWORD dst_unused:UNUSED_PAD src0_sel:DWORD src1_sel:WORD_1
	v_add3_u32 v121, v82, v120, s69
	v_and_b32_sdwa v120, v85, v115 dst_sel:DWORD dst_unused:UNUSED_PAD src0_sel:WORD_1 src1_sel:DWORD
	v_and_b32_sdwa v122, v84, v115 dst_sel:DWORD dst_unused:UNUSED_PAD src0_sel:WORD_1 src1_sel:DWORD
	v_and_b32_sdwa v117, v83, v115 dst_sel:DWORD dst_unused:UNUSED_PAD src0_sel:WORD_1 src1_sel:DWORD
	v_add3_u32 v120, v85, v120, s69
	v_add3_u32 v122, v84, v122, s69
	v_add3_u32 v117, v83, v117, s69
	v_and_b32_e32 v123, 0xffff0000, v120
	v_and_b32_e32 v122, 0xffff0000, v122
	v_or_b32_sdwa v120, v122, v121 dst_sel:DWORD dst_unused:UNUSED_PAD src0_sel:DWORD src1_sel:WORD_1
	v_and_b32_e32 v124, 0xffff0000, v121
	v_or_b32_sdwa v121, v123, v117 dst_sel:DWORD dst_unused:UNUSED_PAD src0_sel:DWORD src1_sel:WORD_1
	v_mfma_f32_32x32x16_bf16 v[0:15], v[32:35], v[40:43], v[0:15]
	v_and_b32_e32 v125, 0xffff0000, v117
	v_add_f32_e64 v84, v84, -v122
	v_add_f32_e64 v85, v85, -v123
	v_add_f32_e64 v82, v82, -v124
	v_add_f32_e64 v83, v83, -v125
	v_bfe_u32 v117, v85, 16, 1
	v_bfe_u32 v122, v84, 16, 1
	v_bfe_u32 v123, v89, 16, 1
	v_bfe_u32 v124, v88, 16, 1
	v_mfma_f32_32x32x16_bf16 v[16:31], v[32:35], v[118:121], v[16:31]
	v_add3_u32 v88, v88, v124, s69
	v_add3_u32 v89, v89, v123, s69
	v_add3_u32 v84, v84, v122, s69
	v_add3_u32 v85, v85, v117, s69
	v_bfe_u32 v117, v82, 16, 1
	v_bfe_u32 v122, v83, 16, 1
	v_bfe_u32 v123, v86, 16, 1
	v_bfe_u32 v124, v87, 16, 1
	v_add3_u32 v83, v83, v122, s69
	v_add3_u32 v82, v82, v117, s69
	v_add3_u32 v87, v87, v124, s69
	v_add3_u32 v86, v86, v123, s69
	v_lshrrev_b32_e32 v82, 16, v82
	v_lshrrev_b32_e32 v83, 16, v83
	v_lshrrev_b32_e32 v86, 16, v86
	v_lshrrev_b32_e32 v87, 16, v87
	v_and_or_b32 v85, v85, s70, v83
	v_and_or_b32 v84, v84, s70, v82
	v_and_or_b32 v83, v89, s70, v87
	v_and_or_b32 v82, v88, s70, v86
	v_mfma_f32_32x32x16_bf16 v[0:15], v[32:35], v[44:47], v[0:15]
	v_mfma_f32_32x32x16_bf16 v[16:31], v[32:35], v[82:85], v[16:31]
	v_mfma_f32_32x32x16_bf16 v[0:15], v[36:39], v[40:43], v[0:15]
	v_mfma_f32_32x32x16_bf16 v[16:31], v[36:39], v[118:121], v[16:31]
	ds_read_b128 v[32:35], v116
	ds_read_b128 v[36:39], v116 offset:16
	v_mov_b32_e32 v42, v170
	v_mov_b32_e32 v86, v171
	v_mov_b32_e32 v46, v172
	v_mov_b32_e32 v88, v173
	s_waitcnt lgkmcnt(1)
	v_cndmask_b32_e64 v35, 0, v35, s[2:3]
	v_mov_b32_e32 v43, v174
	v_mov_b32_e32 v87, v175
	s_waitcnt lgkmcnt(0)
	v_cndmask_b32_e64 v39, 0, v39, s[2:3]
	v_mov_b32_e32 v47, v176
	v_mov_b32_e32 v89, v177
	s_nop 0
	v_mov_b32_e32 v118, v178
	v_mov_b32_e32 v82, v179
	s_nop 0
	v_mov_b32_e32 v120, v180
	v_mov_b32_e32 v84, v181
	v_add_u32_e32 v116, 64, v116
	s_nop 0
	v_mov_b32_e32 v119, v182
	v_mov_b32_e32 v83, v183
	v_mov_b32_e32 v121, v184
	v_mov_b32_e32 v85, v185
	v_cndmask_b32_e64 v41, 0, v34, s[2:3]
	v_cndmask_b32_e64 v40, 0, v32, s[2:3]
	v_cndmask_b32_e64 v34, 0, v33, s[2:3]
	v_and_b32_sdwa v32, v41, v115 dst_sel:DWORD dst_unused:UNUSED_PAD src0_sel:WORD_1 src1_sel:DWORD
	v_and_b32_sdwa v33, v40, v115 dst_sel:DWORD dst_unused:UNUSED_PAD src0_sel:WORD_1 src1_sel:DWORD
	v_add3_u32 v117, v41, v32, s69
	v_and_b32_sdwa v32, v35, v115 dst_sel:DWORD dst_unused:UNUSED_PAD src0_sel:WORD_1 src1_sel:DWORD
	v_and_b32_sdwa v44, v34, v115 dst_sel:DWORD dst_unused:UNUSED_PAD src0_sel:WORD_1 src1_sel:DWORD
	v_add3_u32 v33, v40, v33, s69
	v_add3_u32 v32, v35, v32, s69
	v_add3_u32 v44, v34, v44, s69
	v_and_b32_e32 v45, 0xffff0000, v32
	v_and_b32_e32 v44, 0xffff0000, v44
	v_and_b32_e32 v123, 0xffff0000, v117
	v_and_b32_e32 v122, 0xffff0000, v33
	v_or_b32_sdwa v32, v44, v33 dst_sel:DWORD dst_unused:UNUSED_PAD src0_sel:DWORD src1_sel:WORD_1
	v_pk_add_f32 v[40:41], v[40:41], v[122:123] neg_lo:[0,1] neg_hi:[0,1]
	v_pk_add_f32 v[122:123], v[34:35], v[44:45] neg_lo:[0,1] neg_hi:[0,1]
	v_or_b32_sdwa v33, v45, v117 dst_sel:DWORD dst_unused:UNUSED_PAD src0_sel:DWORD src1_sel:WORD_1
	v_cndmask_b32_e64 v45, 0, v38, s[2:3]
	v_cndmask_b32_e64 v38, 0, v37, s[2:3]
	v_and_b32_sdwa v34, v45, v115 dst_sel:DWORD dst_unused:UNUSED_PAD src0_sel:WORD_1 src1_sel:DWORD
	v_cndmask_b32_e64 v44, 0, v36, s[2:3]
	v_add3_u32 v117, v45, v34, s69
	v_and_b32_sdwa v34, v39, v115 dst_sel:DWORD dst_unused:UNUSED_PAD src0_sel:WORD_1 src1_sel:DWORD
	v_and_b32_sdwa v36, v38, v115 dst_sel:DWORD dst_unused:UNUSED_PAD src0_sel:WORD_1 src1_sel:DWORD
	v_and_b32_sdwa v35, v44, v115 dst_sel:DWORD dst_unused:UNUSED_PAD src0_sel:WORD_1 src1_sel:DWORD
	v_add3_u32 v34, v39, v34, s69
	v_add3_u32 v36, v38, v36, s69
	v_add3_u32 v35, v44, v35, s69
	v_and_b32_e32 v37, 0xffff0000, v34
	v_and_b32_e32 v36, 0xffff0000, v36
	v_and_b32_e32 v125, 0xffff0000, v117
	v_and_b32_e32 v124, 0xffff0000, v35
	v_pk_add_f32 v[38:39], v[38:39], v[36:37] neg_lo:[0,1] neg_hi:[0,1]
	v_or_b32_sdwa v34, v36, v35 dst_sel:DWORD dst_unused:UNUSED_PAD src0_sel:DWORD src1_sel:WORD_1
	v_pk_add_f32 v[44:45], v[44:45], v[124:125] neg_lo:[0,1] neg_hi:[0,1]
	v_or_b32_sdwa v35, v37, v117 dst_sel:DWORD dst_unused:UNUSED_PAD src0_sel:DWORD src1_sel:WORD_1
	v_bfe_u32 v36, v39, 16, 1
	v_bfe_u32 v37, v38, 16, 1
	v_bfe_u32 v117, v123, 16, 1
	v_bfe_u32 v124, v122, 16, 1
	v_add3_u32 v122, v122, v124, s69
	v_add3_u32 v117, v123, v117, s69
	v_add3_u32 v37, v38, v37, s69
	v_add3_u32 v36, v39, v36, s69
	v_bfe_u32 v38, v40, 16, 1
	v_bfe_u32 v39, v41, 16, 1
	v_bfe_u32 v123, v44, 16, 1
	v_bfe_u32 v124, v45, 16, 1
	v_add3_u32 v45, v45, v124, s69
	v_add3_u32 v44, v44, v123, s69
	v_add3_u32 v39, v41, v39, s69
	v_add3_u32 v38, v40, v38, s69
	v_lshrrev_b32_e32 v40, 16, v38
	v_lshrrev_b32_e32 v41, 16, v39
	v_lshrrev_b32_e32 v38, 16, v44
	v_lshrrev_b32_e32 v39, 16, v45
	v_and_or_b32 v39, v36, s70, v39
	v_and_or_b32 v38, v37, s70, v38
	v_and_or_b32 v37, v117, s70, v41
	v_and_or_b32 v36, v122, s70, v40
	v_and_b32_sdwa v40, v43, v115 dst_sel:DWORD dst_unused:UNUSED_PAD src0_sel:WORD_1 src1_sel:DWORD
	v_and_b32_sdwa v41, v42, v115 dst_sel:DWORD dst_unused:UNUSED_PAD src0_sel:WORD_1 src1_sel:DWORD
	v_add3_u32 v117, v43, v40, s69
	v_add3_u32 v41, v42, v41, s69
	v_and_b32_sdwa v40, v47, v115 dst_sel:DWORD dst_unused:UNUSED_PAD src0_sel:WORD_1 src1_sel:DWORD
	v_and_b32_sdwa v44, v46, v115 dst_sel:DWORD dst_unused:UNUSED_PAD src0_sel:WORD_1 src1_sel:DWORD
	v_add3_u32 v40, v47, v40, s69
	v_add3_u32 v44, v46, v44, s69
	v_and_b32_e32 v123, 0xffff0000, v117
	v_and_b32_e32 v122, 0xffff0000, v41
	v_and_b32_e32 v45, 0xffff0000, v40
	v_and_b32_e32 v44, 0xffff0000, v44
	v_pk_add_f32 v[122:123], v[42:43], v[122:123] neg_lo:[0,1] neg_hi:[0,1]
	v_and_b32_sdwa v42, v119, v115 dst_sel:DWORD dst_unused:UNUSED_PAD src0_sel:WORD_1 src1_sel:DWORD
	v_or_b32_sdwa v40, v44, v41 dst_sel:DWORD dst_unused:UNUSED_PAD src0_sel:DWORD src1_sel:WORD_1
	v_pk_add_f32 v[46:47], v[46:47], v[44:45] neg_lo:[0,1] neg_hi:[0,1]
	v_or_b32_sdwa v41, v45, v117 dst_sel:DWORD dst_unused:UNUSED_PAD src0_sel:DWORD src1_sel:WORD_1
	v_add3_u32 v117, v119, v42, s69
	v_and_b32_sdwa v42, v121, v115 dst_sel:DWORD dst_unused:UNUSED_PAD src0_sel:WORD_1 src1_sel:DWORD
	v_and_b32_sdwa v44, v120, v115 dst_sel:DWORD dst_unused:UNUSED_PAD src0_sel:WORD_1 src1_sel:DWORD
	v_and_b32_sdwa v43, v118, v115 dst_sel:DWORD dst_unused:UNUSED_PAD src0_sel:WORD_1 src1_sel:DWORD
	v_add3_u32 v42, v121, v42, s69
	v_add3_u32 v44, v120, v44, s69
	v_add3_u32 v43, v118, v43, s69
	v_and_b32_e32 v45, 0xffff0000, v42
	v_and_b32_e32 v44, 0xffff0000, v44
	v_and_b32_e32 v125, 0xffff0000, v117
	v_and_b32_e32 v124, 0xffff0000, v43
	v_pk_add_f32 v[120:121], v[120:121], v[44:45] neg_lo:[0,1] neg_hi:[0,1]
	v_or_b32_sdwa v42, v44, v43 dst_sel:DWORD dst_unused:UNUSED_PAD src0_sel:DWORD src1_sel:WORD_1
	v_pk_add_f32 v[118:119], v[118:119], v[124:125] neg_lo:[0,1] neg_hi:[0,1]
	v_bfe_u32 v44, v121, 16, 1
	v_bfe_u32 v124, v46, 16, 1
	v_or_b32_sdwa v43, v45, v117 dst_sel:DWORD dst_unused:UNUSED_PAD src0_sel:DWORD src1_sel:WORD_1
	v_bfe_u32 v45, v120, 16, 1
	v_bfe_u32 v117, v47, 16, 1
	v_add3_u32 v124, v46, v124, s69
	v_add3_u32 v44, v121, v44, s69
	v_bfe_u32 v46, v118, 16, 1
	v_bfe_u32 v121, v123, 16, 1
	v_add3_u32 v117, v47, v117, s69
	v_add3_u32 v45, v120, v45, s69
	v_bfe_u32 v47, v119, 16, 1
	v_bfe_u32 v120, v122, 16, 1
	v_add3_u32 v46, v118, v46, s69
	v_add3_u32 v118, v123, v121, s69
	v_add3_u32 v47, v119, v47, s69
	v_add3_u32 v119, v122, v120, s69
	v_lshrrev_b32_e32 v46, 16, v46
	v_lshrrev_b32_e32 v118, 16, v118
	v_lshrrev_b32_e32 v47, 16, v47
	v_lshrrev_b32_e32 v119, 16, v119
	v_and_or_b32 v46, v45, s70, v46
	v_and_or_b32 v45, v117, s70, v118
	v_and_b32_sdwa v118, v86, v115 dst_sel:DWORD dst_unused:UNUSED_PAD src0_sel:WORD_1 src1_sel:DWORD
	v_and_or_b32 v47, v44, s70, v47
	v_and_or_b32 v44, v124, s70, v119
	v_add3_u32 v119, v86, v118, s69
	v_and_b32_sdwa v118, v89, v115 dst_sel:DWORD dst_unused:UNUSED_PAD src0_sel:WORD_1 src1_sel:DWORD
	v_and_b32_sdwa v120, v88, v115 dst_sel:DWORD dst_unused:UNUSED_PAD src0_sel:WORD_1 src1_sel:DWORD
	v_and_b32_sdwa v117, v87, v115 dst_sel:DWORD dst_unused:UNUSED_PAD src0_sel:WORD_1 src1_sel:DWORD
	v_add3_u32 v118, v89, v118, s69
	v_add3_u32 v120, v88, v120, s69
	v_add3_u32 v117, v87, v117, s69
	v_and_b32_e32 v121, 0xffff0000, v118
	v_and_b32_e32 v120, 0xffff0000, v120
	v_or_b32_sdwa v118, v120, v119 dst_sel:DWORD dst_unused:UNUSED_PAD src0_sel:DWORD src1_sel:WORD_1
	v_and_b32_e32 v123, 0xffff0000, v117
	v_and_b32_e32 v122, 0xffff0000, v119
	v_pk_add_f32 v[88:89], v[88:89], v[120:121] neg_lo:[0,1] neg_hi:[0,1]
	v_and_b32_sdwa v120, v82, v115 dst_sel:DWORD dst_unused:UNUSED_PAD src0_sel:WORD_1 src1_sel:DWORD
	v_pk_add_f32 v[86:87], v[86:87], v[122:123] neg_lo:[0,1] neg_hi:[0,1]
	v_or_b32_sdwa v119, v121, v117 dst_sel:DWORD dst_unused:UNUSED_PAD src0_sel:DWORD src1_sel:WORD_1
	v_add3_u32 v121, v82, v120, s69
	v_and_b32_sdwa v120, v85, v115 dst_sel:DWORD dst_unused:UNUSED_PAD src0_sel:WORD_1 src1_sel:DWORD
	v_and_b32_sdwa v122, v84, v115 dst_sel:DWORD dst_unused:UNUSED_PAD src0_sel:WORD_1 src1_sel:DWORD
	v_and_b32_sdwa v117, v83, v115 dst_sel:DWORD dst_unused:UNUSED_PAD src0_sel:WORD_1 src1_sel:DWORD
	v_add3_u32 v120, v85, v120, s69
	v_add3_u32 v122, v84, v122, s69
	v_add3_u32 v117, v83, v117, s69
	v_and_b32_e32 v123, 0xffff0000, v120
	v_and_b32_e32 v122, 0xffff0000, v122
	v_or_b32_sdwa v120, v122, v121 dst_sel:DWORD dst_unused:UNUSED_PAD src0_sel:DWORD src1_sel:WORD_1
	v_and_b32_e32 v124, 0xffff0000, v121
	v_or_b32_sdwa v121, v123, v117 dst_sel:DWORD dst_unused:UNUSED_PAD src0_sel:DWORD src1_sel:WORD_1
	v_mfma_f32_32x32x16_bf16 v[0:15], v[32:35], v[40:43], v[0:15]
	v_and_b32_e32 v125, 0xffff0000, v117
	v_add_f32_e64 v84, v84, -v122
	v_add_f32_e64 v85, v85, -v123
	v_add_f32_e64 v82, v82, -v124
	v_add_f32_e64 v83, v83, -v125
	v_bfe_u32 v117, v85, 16, 1
	v_bfe_u32 v122, v84, 16, 1
	v_bfe_u32 v123, v89, 16, 1
	v_bfe_u32 v124, v88, 16, 1
	v_mfma_f32_32x32x16_bf16 v[16:31], v[32:35], v[118:121], v[16:31]
	v_add3_u32 v88, v88, v124, s69
	v_add3_u32 v89, v89, v123, s69
	v_add3_u32 v84, v84, v122, s69
	v_add3_u32 v85, v85, v117, s69
	v_bfe_u32 v117, v82, 16, 1
	v_bfe_u32 v122, v83, 16, 1
	v_bfe_u32 v123, v86, 16, 1
	v_bfe_u32 v124, v87, 16, 1
	v_add3_u32 v83, v83, v122, s69
	v_add3_u32 v82, v82, v117, s69
	v_add3_u32 v87, v87, v124, s69
	v_add3_u32 v86, v86, v123, s69
	v_lshrrev_b32_e32 v82, 16, v82
	v_lshrrev_b32_e32 v83, 16, v83
	v_lshrrev_b32_e32 v86, 16, v86
	v_lshrrev_b32_e32 v87, 16, v87
	v_and_or_b32 v85, v85, s70, v83
	v_and_or_b32 v84, v84, s70, v82
	v_and_or_b32 v83, v89, s70, v87
	v_and_or_b32 v82, v88, s70, v86
	v_mfma_f32_32x32x16_bf16 v[0:15], v[32:35], v[44:47], v[0:15]
	v_mfma_f32_32x32x16_bf16 v[16:31], v[32:35], v[82:85], v[16:31]
	v_mfma_f32_32x32x16_bf16 v[0:15], v[36:39], v[40:43], v[0:15]
	v_mfma_f32_32x32x16_bf16 v[16:31], v[36:39], v[118:121], v[16:31]
	ds_read_b128 v[32:35], v116
	ds_read_b128 v[36:39], v116 offset:16
	v_mov_b32_e32 v42, v186
	v_mov_b32_e32 v86, v187
	v_mov_b32_e32 v46, v188
	v_mov_b32_e32 v88, v189
	s_waitcnt lgkmcnt(1)
	v_cndmask_b32_e64 v35, 0, v35, s[2:3]
	v_mov_b32_e32 v43, v190
	v_mov_b32_e32 v87, v191
	s_waitcnt lgkmcnt(0)
	v_cndmask_b32_e64 v39, 0, v39, s[2:3]
	v_mov_b32_e32 v47, v192
	v_mov_b32_e32 v89, v193
	s_nop 0
	v_mov_b32_e32 v118, v194
	v_mov_b32_e32 v82, v195
	s_nop 0
	v_mov_b32_e32 v120, v196
	v_mov_b32_e32 v84, v197
	v_add_u32_e32 v116, 64, v116
	s_nop 0
	v_mov_b32_e32 v119, v198
	v_mov_b32_e32 v83, v199
	v_mov_b32_e32 v121, v200
	v_mov_b32_e32 v85, v201
	v_cndmask_b32_e64 v41, 0, v34, s[2:3]
	v_cndmask_b32_e64 v40, 0, v32, s[2:3]
	v_cndmask_b32_e64 v34, 0, v33, s[2:3]
	v_and_b32_sdwa v32, v41, v115 dst_sel:DWORD dst_unused:UNUSED_PAD src0_sel:WORD_1 src1_sel:DWORD
	v_and_b32_sdwa v33, v40, v115 dst_sel:DWORD dst_unused:UNUSED_PAD src0_sel:WORD_1 src1_sel:DWORD
	v_add3_u32 v117, v41, v32, s69
	v_and_b32_sdwa v32, v35, v115 dst_sel:DWORD dst_unused:UNUSED_PAD src0_sel:WORD_1 src1_sel:DWORD
	v_and_b32_sdwa v44, v34, v115 dst_sel:DWORD dst_unused:UNUSED_PAD src0_sel:WORD_1 src1_sel:DWORD
	v_add3_u32 v33, v40, v33, s69
	v_add3_u32 v32, v35, v32, s69
	v_add3_u32 v44, v34, v44, s69
	v_and_b32_e32 v45, 0xffff0000, v32
	v_and_b32_e32 v44, 0xffff0000, v44
	v_and_b32_e32 v123, 0xffff0000, v117
	v_and_b32_e32 v122, 0xffff0000, v33
	v_or_b32_sdwa v32, v44, v33 dst_sel:DWORD dst_unused:UNUSED_PAD src0_sel:DWORD src1_sel:WORD_1
	v_pk_add_f32 v[40:41], v[40:41], v[122:123] neg_lo:[0,1] neg_hi:[0,1]
	v_pk_add_f32 v[122:123], v[34:35], v[44:45] neg_lo:[0,1] neg_hi:[0,1]
	v_or_b32_sdwa v33, v45, v117 dst_sel:DWORD dst_unused:UNUSED_PAD src0_sel:DWORD src1_sel:WORD_1
	v_cndmask_b32_e64 v45, 0, v38, s[2:3]
	v_cndmask_b32_e64 v38, 0, v37, s[2:3]
	v_and_b32_sdwa v34, v45, v115 dst_sel:DWORD dst_unused:UNUSED_PAD src0_sel:WORD_1 src1_sel:DWORD
	v_cndmask_b32_e64 v44, 0, v36, s[2:3]
	v_add3_u32 v117, v45, v34, s69
	v_and_b32_sdwa v34, v39, v115 dst_sel:DWORD dst_unused:UNUSED_PAD src0_sel:WORD_1 src1_sel:DWORD
	v_and_b32_sdwa v36, v38, v115 dst_sel:DWORD dst_unused:UNUSED_PAD src0_sel:WORD_1 src1_sel:DWORD
	v_and_b32_sdwa v35, v44, v115 dst_sel:DWORD dst_unused:UNUSED_PAD src0_sel:WORD_1 src1_sel:DWORD
	v_add3_u32 v34, v39, v34, s69
	v_add3_u32 v36, v38, v36, s69
	v_add3_u32 v35, v44, v35, s69
	v_and_b32_e32 v37, 0xffff0000, v34
	v_and_b32_e32 v36, 0xffff0000, v36
	v_and_b32_e32 v125, 0xffff0000, v117
	v_and_b32_e32 v124, 0xffff0000, v35
	v_pk_add_f32 v[38:39], v[38:39], v[36:37] neg_lo:[0,1] neg_hi:[0,1]
	v_or_b32_sdwa v34, v36, v35 dst_sel:DWORD dst_unused:UNUSED_PAD src0_sel:DWORD src1_sel:WORD_1
	v_pk_add_f32 v[44:45], v[44:45], v[124:125] neg_lo:[0,1] neg_hi:[0,1]
	v_or_b32_sdwa v35, v37, v117 dst_sel:DWORD dst_unused:UNUSED_PAD src0_sel:DWORD src1_sel:WORD_1
	v_bfe_u32 v36, v39, 16, 1
	v_bfe_u32 v37, v38, 16, 1
	v_bfe_u32 v117, v123, 16, 1
	v_bfe_u32 v124, v122, 16, 1
	v_add3_u32 v122, v122, v124, s69
	v_add3_u32 v117, v123, v117, s69
	v_add3_u32 v37, v38, v37, s69
	v_add3_u32 v36, v39, v36, s69
	v_bfe_u32 v38, v40, 16, 1
	v_bfe_u32 v39, v41, 16, 1
	v_bfe_u32 v123, v44, 16, 1
	v_bfe_u32 v124, v45, 16, 1
	v_add3_u32 v45, v45, v124, s69
	v_add3_u32 v44, v44, v123, s69
	v_add3_u32 v39, v41, v39, s69
	v_add3_u32 v38, v40, v38, s69
	v_lshrrev_b32_e32 v40, 16, v38
	v_lshrrev_b32_e32 v41, 16, v39
	v_lshrrev_b32_e32 v38, 16, v44
	v_lshrrev_b32_e32 v39, 16, v45
	v_and_or_b32 v39, v36, s70, v39
	v_and_or_b32 v38, v37, s70, v38
	v_and_or_b32 v37, v117, s70, v41
	v_and_or_b32 v36, v122, s70, v40
	v_and_b32_sdwa v40, v43, v115 dst_sel:DWORD dst_unused:UNUSED_PAD src0_sel:WORD_1 src1_sel:DWORD
	v_and_b32_sdwa v41, v42, v115 dst_sel:DWORD dst_unused:UNUSED_PAD src0_sel:WORD_1 src1_sel:DWORD
	v_add3_u32 v117, v43, v40, s69
	v_add3_u32 v41, v42, v41, s69
	v_and_b32_sdwa v40, v47, v115 dst_sel:DWORD dst_unused:UNUSED_PAD src0_sel:WORD_1 src1_sel:DWORD
	v_and_b32_sdwa v44, v46, v115 dst_sel:DWORD dst_unused:UNUSED_PAD src0_sel:WORD_1 src1_sel:DWORD
	v_add3_u32 v40, v47, v40, s69
	v_add3_u32 v44, v46, v44, s69
	v_and_b32_e32 v123, 0xffff0000, v117
	v_and_b32_e32 v122, 0xffff0000, v41
	v_and_b32_e32 v45, 0xffff0000, v40
	v_and_b32_e32 v44, 0xffff0000, v44
	v_pk_add_f32 v[122:123], v[42:43], v[122:123] neg_lo:[0,1] neg_hi:[0,1]
	v_and_b32_sdwa v42, v119, v115 dst_sel:DWORD dst_unused:UNUSED_PAD src0_sel:WORD_1 src1_sel:DWORD
	v_or_b32_sdwa v40, v44, v41 dst_sel:DWORD dst_unused:UNUSED_PAD src0_sel:DWORD src1_sel:WORD_1
	v_pk_add_f32 v[46:47], v[46:47], v[44:45] neg_lo:[0,1] neg_hi:[0,1]
	v_or_b32_sdwa v41, v45, v117 dst_sel:DWORD dst_unused:UNUSED_PAD src0_sel:DWORD src1_sel:WORD_1
	v_add3_u32 v117, v119, v42, s69
	v_and_b32_sdwa v42, v121, v115 dst_sel:DWORD dst_unused:UNUSED_PAD src0_sel:WORD_1 src1_sel:DWORD
	v_and_b32_sdwa v44, v120, v115 dst_sel:DWORD dst_unused:UNUSED_PAD src0_sel:WORD_1 src1_sel:DWORD
	v_and_b32_sdwa v43, v118, v115 dst_sel:DWORD dst_unused:UNUSED_PAD src0_sel:WORD_1 src1_sel:DWORD
	v_add3_u32 v42, v121, v42, s69
	v_add3_u32 v44, v120, v44, s69
	v_add3_u32 v43, v118, v43, s69
	v_and_b32_e32 v45, 0xffff0000, v42
	v_and_b32_e32 v44, 0xffff0000, v44
	v_and_b32_e32 v125, 0xffff0000, v117
	v_and_b32_e32 v124, 0xffff0000, v43
	v_pk_add_f32 v[120:121], v[120:121], v[44:45] neg_lo:[0,1] neg_hi:[0,1]
	v_or_b32_sdwa v42, v44, v43 dst_sel:DWORD dst_unused:UNUSED_PAD src0_sel:DWORD src1_sel:WORD_1
	v_pk_add_f32 v[118:119], v[118:119], v[124:125] neg_lo:[0,1] neg_hi:[0,1]
	v_bfe_u32 v44, v121, 16, 1
	v_bfe_u32 v124, v46, 16, 1
	v_or_b32_sdwa v43, v45, v117 dst_sel:DWORD dst_unused:UNUSED_PAD src0_sel:DWORD src1_sel:WORD_1
	v_bfe_u32 v45, v120, 16, 1
	v_bfe_u32 v117, v47, 16, 1
	v_add3_u32 v124, v46, v124, s69
	v_add3_u32 v44, v121, v44, s69
	v_bfe_u32 v46, v118, 16, 1
	v_bfe_u32 v121, v123, 16, 1
	v_add3_u32 v117, v47, v117, s69
	v_add3_u32 v45, v120, v45, s69
	v_bfe_u32 v47, v119, 16, 1
	v_bfe_u32 v120, v122, 16, 1
	v_add3_u32 v46, v118, v46, s69
	v_add3_u32 v118, v123, v121, s69
	v_add3_u32 v47, v119, v47, s69
	v_add3_u32 v119, v122, v120, s69
	v_lshrrev_b32_e32 v46, 16, v46
	v_lshrrev_b32_e32 v118, 16, v118
	v_lshrrev_b32_e32 v47, 16, v47
	v_lshrrev_b32_e32 v119, 16, v119
	v_and_or_b32 v46, v45, s70, v46
	v_and_or_b32 v45, v117, s70, v118
	v_and_b32_sdwa v118, v86, v115 dst_sel:DWORD dst_unused:UNUSED_PAD src0_sel:WORD_1 src1_sel:DWORD
	v_and_or_b32 v47, v44, s70, v47
	v_and_or_b32 v44, v124, s70, v119
	v_add3_u32 v119, v86, v118, s69
	v_and_b32_sdwa v118, v89, v115 dst_sel:DWORD dst_unused:UNUSED_PAD src0_sel:WORD_1 src1_sel:DWORD
	v_and_b32_sdwa v120, v88, v115 dst_sel:DWORD dst_unused:UNUSED_PAD src0_sel:WORD_1 src1_sel:DWORD
	v_and_b32_sdwa v117, v87, v115 dst_sel:DWORD dst_unused:UNUSED_PAD src0_sel:WORD_1 src1_sel:DWORD
	v_add3_u32 v118, v89, v118, s69
	v_add3_u32 v120, v88, v120, s69
	v_add3_u32 v117, v87, v117, s69
	v_and_b32_e32 v121, 0xffff0000, v118
	v_and_b32_e32 v120, 0xffff0000, v120
	v_or_b32_sdwa v118, v120, v119 dst_sel:DWORD dst_unused:UNUSED_PAD src0_sel:DWORD src1_sel:WORD_1
	v_and_b32_e32 v123, 0xffff0000, v117
	v_and_b32_e32 v122, 0xffff0000, v119
	v_pk_add_f32 v[88:89], v[88:89], v[120:121] neg_lo:[0,1] neg_hi:[0,1]
	v_and_b32_sdwa v120, v82, v115 dst_sel:DWORD dst_unused:UNUSED_PAD src0_sel:WORD_1 src1_sel:DWORD
	v_pk_add_f32 v[86:87], v[86:87], v[122:123] neg_lo:[0,1] neg_hi:[0,1]
	v_or_b32_sdwa v119, v121, v117 dst_sel:DWORD dst_unused:UNUSED_PAD src0_sel:DWORD src1_sel:WORD_1
	v_add3_u32 v121, v82, v120, s69
	v_and_b32_sdwa v120, v85, v115 dst_sel:DWORD dst_unused:UNUSED_PAD src0_sel:WORD_1 src1_sel:DWORD
	v_and_b32_sdwa v122, v84, v115 dst_sel:DWORD dst_unused:UNUSED_PAD src0_sel:WORD_1 src1_sel:DWORD
	v_and_b32_sdwa v117, v83, v115 dst_sel:DWORD dst_unused:UNUSED_PAD src0_sel:WORD_1 src1_sel:DWORD
	v_add3_u32 v120, v85, v120, s69
	v_add3_u32 v122, v84, v122, s69
	v_add3_u32 v117, v83, v117, s69
	v_and_b32_e32 v123, 0xffff0000, v120
	v_and_b32_e32 v122, 0xffff0000, v122
	v_or_b32_sdwa v120, v122, v121 dst_sel:DWORD dst_unused:UNUSED_PAD src0_sel:DWORD src1_sel:WORD_1
	v_and_b32_e32 v124, 0xffff0000, v121
	v_or_b32_sdwa v121, v123, v117 dst_sel:DWORD dst_unused:UNUSED_PAD src0_sel:DWORD src1_sel:WORD_1
	v_mfma_f32_32x32x16_bf16 v[0:15], v[32:35], v[40:43], v[0:15]
	v_and_b32_e32 v125, 0xffff0000, v117
	v_add_f32_e64 v84, v84, -v122
	v_add_f32_e64 v85, v85, -v123
	v_add_f32_e64 v82, v82, -v124
	v_add_f32_e64 v83, v83, -v125
	v_bfe_u32 v117, v85, 16, 1
	v_bfe_u32 v122, v84, 16, 1
	v_bfe_u32 v123, v89, 16, 1
	v_bfe_u32 v124, v88, 16, 1
	v_mfma_f32_32x32x16_bf16 v[16:31], v[32:35], v[118:121], v[16:31]
	v_add3_u32 v88, v88, v124, s69
	v_add3_u32 v89, v89, v123, s69
	v_add3_u32 v84, v84, v122, s69
	v_add3_u32 v85, v85, v117, s69
	v_bfe_u32 v117, v82, 16, 1
	v_bfe_u32 v122, v83, 16, 1
	v_bfe_u32 v123, v86, 16, 1
	v_bfe_u32 v124, v87, 16, 1
	v_add3_u32 v83, v83, v122, s69
	v_add3_u32 v82, v82, v117, s69
	v_add3_u32 v87, v87, v124, s69
	v_add3_u32 v86, v86, v123, s69
	v_lshrrev_b32_e32 v82, 16, v82
	v_lshrrev_b32_e32 v83, 16, v83
	v_lshrrev_b32_e32 v86, 16, v86
	v_lshrrev_b32_e32 v87, 16, v87
	v_and_or_b32 v85, v85, s70, v83
	v_and_or_b32 v84, v84, s70, v82
	v_and_or_b32 v83, v89, s70, v87
	v_and_or_b32 v82, v88, s70, v86
	v_mfma_f32_32x32x16_bf16 v[0:15], v[32:35], v[44:47], v[0:15]
	v_mfma_f32_32x32x16_bf16 v[16:31], v[32:35], v[82:85], v[16:31]
	v_mfma_f32_32x32x16_bf16 v[0:15], v[36:39], v[40:43], v[0:15]
	v_mfma_f32_32x32x16_bf16 v[16:31], v[36:39], v[118:121], v[16:31]
	ds_read_b128 v[32:35], v116
	ds_read_b128 v[36:39], v116 offset:16
	v_mov_b32_e32 v42, v202
	v_mov_b32_e32 v86, v203
	v_mov_b32_e32 v46, v204
	v_mov_b32_e32 v88, v205
	s_waitcnt lgkmcnt(1)
	v_cndmask_b32_e64 v35, 0, v35, s[2:3]
	v_mov_b32_e32 v43, v206
	v_mov_b32_e32 v87, v207
	s_waitcnt lgkmcnt(0)
	v_cndmask_b32_e64 v39, 0, v39, s[2:3]
	v_mov_b32_e32 v47, v208
	v_mov_b32_e32 v89, v209
	s_nop 0
	v_mov_b32_e32 v118, v210
	v_mov_b32_e32 v82, v211
	s_nop 0
	v_mov_b32_e32 v120, v212
	v_mov_b32_e32 v84, v213
	v_add_u32_e32 v116, 64, v116
	s_nop 0
	v_mov_b32_e32 v119, v214
	v_mov_b32_e32 v83, v215
	v_mov_b32_e32 v121, v216
	v_mov_b32_e32 v85, v217
	v_cndmask_b32_e64 v41, 0, v34, s[2:3]
	v_cndmask_b32_e64 v40, 0, v32, s[2:3]
	v_cndmask_b32_e64 v34, 0, v33, s[2:3]
	v_and_b32_sdwa v32, v41, v115 dst_sel:DWORD dst_unused:UNUSED_PAD src0_sel:WORD_1 src1_sel:DWORD
	v_and_b32_sdwa v33, v40, v115 dst_sel:DWORD dst_unused:UNUSED_PAD src0_sel:WORD_1 src1_sel:DWORD
	v_add3_u32 v117, v41, v32, s69
	v_and_b32_sdwa v32, v35, v115 dst_sel:DWORD dst_unused:UNUSED_PAD src0_sel:WORD_1 src1_sel:DWORD
	v_and_b32_sdwa v44, v34, v115 dst_sel:DWORD dst_unused:UNUSED_PAD src0_sel:WORD_1 src1_sel:DWORD
	v_add3_u32 v33, v40, v33, s69
	v_add3_u32 v32, v35, v32, s69
	v_add3_u32 v44, v34, v44, s69
	v_and_b32_e32 v45, 0xffff0000, v32
	v_and_b32_e32 v44, 0xffff0000, v44
	v_and_b32_e32 v123, 0xffff0000, v117
	v_and_b32_e32 v122, 0xffff0000, v33
	v_or_b32_sdwa v32, v44, v33 dst_sel:DWORD dst_unused:UNUSED_PAD src0_sel:DWORD src1_sel:WORD_1
	v_pk_add_f32 v[40:41], v[40:41], v[122:123] neg_lo:[0,1] neg_hi:[0,1]
	v_pk_add_f32 v[122:123], v[34:35], v[44:45] neg_lo:[0,1] neg_hi:[0,1]
	v_or_b32_sdwa v33, v45, v117 dst_sel:DWORD dst_unused:UNUSED_PAD src0_sel:DWORD src1_sel:WORD_1
	v_cndmask_b32_e64 v45, 0, v38, s[2:3]
	v_cndmask_b32_e64 v38, 0, v37, s[2:3]
	v_and_b32_sdwa v34, v45, v115 dst_sel:DWORD dst_unused:UNUSED_PAD src0_sel:WORD_1 src1_sel:DWORD
	v_cndmask_b32_e64 v44, 0, v36, s[2:3]
	v_add3_u32 v117, v45, v34, s69
	v_and_b32_sdwa v34, v39, v115 dst_sel:DWORD dst_unused:UNUSED_PAD src0_sel:WORD_1 src1_sel:DWORD
	v_and_b32_sdwa v36, v38, v115 dst_sel:DWORD dst_unused:UNUSED_PAD src0_sel:WORD_1 src1_sel:DWORD
	v_and_b32_sdwa v35, v44, v115 dst_sel:DWORD dst_unused:UNUSED_PAD src0_sel:WORD_1 src1_sel:DWORD
	v_add3_u32 v34, v39, v34, s69
	v_add3_u32 v36, v38, v36, s69
	v_add3_u32 v35, v44, v35, s69
	v_and_b32_e32 v37, 0xffff0000, v34
	v_and_b32_e32 v36, 0xffff0000, v36
	v_and_b32_e32 v125, 0xffff0000, v117
	v_and_b32_e32 v124, 0xffff0000, v35
	v_pk_add_f32 v[38:39], v[38:39], v[36:37] neg_lo:[0,1] neg_hi:[0,1]
	v_or_b32_sdwa v34, v36, v35 dst_sel:DWORD dst_unused:UNUSED_PAD src0_sel:DWORD src1_sel:WORD_1
	v_pk_add_f32 v[44:45], v[44:45], v[124:125] neg_lo:[0,1] neg_hi:[0,1]
	v_or_b32_sdwa v35, v37, v117 dst_sel:DWORD dst_unused:UNUSED_PAD src0_sel:DWORD src1_sel:WORD_1
	v_bfe_u32 v36, v39, 16, 1
	v_bfe_u32 v37, v38, 16, 1
	v_bfe_u32 v117, v123, 16, 1
	v_bfe_u32 v124, v122, 16, 1
	v_add3_u32 v122, v122, v124, s69
	v_add3_u32 v117, v123, v117, s69
	v_add3_u32 v37, v38, v37, s69
	v_add3_u32 v36, v39, v36, s69
	v_bfe_u32 v38, v40, 16, 1
	v_bfe_u32 v39, v41, 16, 1
	v_bfe_u32 v123, v44, 16, 1
	v_bfe_u32 v124, v45, 16, 1
	v_add3_u32 v45, v45, v124, s69
	v_add3_u32 v44, v44, v123, s69
	v_add3_u32 v39, v41, v39, s69
	v_add3_u32 v38, v40, v38, s69
	v_lshrrev_b32_e32 v40, 16, v38
	v_lshrrev_b32_e32 v41, 16, v39
	v_lshrrev_b32_e32 v38, 16, v44
	v_lshrrev_b32_e32 v39, 16, v45
	v_and_or_b32 v39, v36, s70, v39
	v_and_or_b32 v38, v37, s70, v38
	v_and_or_b32 v37, v117, s70, v41
	v_and_or_b32 v36, v122, s70, v40
	v_and_b32_sdwa v40, v43, v115 dst_sel:DWORD dst_unused:UNUSED_PAD src0_sel:WORD_1 src1_sel:DWORD
	v_and_b32_sdwa v41, v42, v115 dst_sel:DWORD dst_unused:UNUSED_PAD src0_sel:WORD_1 src1_sel:DWORD
	v_add3_u32 v117, v43, v40, s69
	v_add3_u32 v41, v42, v41, s69
	v_and_b32_sdwa v40, v47, v115 dst_sel:DWORD dst_unused:UNUSED_PAD src0_sel:WORD_1 src1_sel:DWORD
	v_and_b32_sdwa v44, v46, v115 dst_sel:DWORD dst_unused:UNUSED_PAD src0_sel:WORD_1 src1_sel:DWORD
	v_add3_u32 v40, v47, v40, s69
	v_add3_u32 v44, v46, v44, s69
	v_and_b32_e32 v123, 0xffff0000, v117
	v_and_b32_e32 v122, 0xffff0000, v41
	v_and_b32_e32 v45, 0xffff0000, v40
	v_and_b32_e32 v44, 0xffff0000, v44
	v_pk_add_f32 v[122:123], v[42:43], v[122:123] neg_lo:[0,1] neg_hi:[0,1]
	v_and_b32_sdwa v42, v119, v115 dst_sel:DWORD dst_unused:UNUSED_PAD src0_sel:WORD_1 src1_sel:DWORD
	v_or_b32_sdwa v40, v44, v41 dst_sel:DWORD dst_unused:UNUSED_PAD src0_sel:DWORD src1_sel:WORD_1
	v_pk_add_f32 v[46:47], v[46:47], v[44:45] neg_lo:[0,1] neg_hi:[0,1]
	v_or_b32_sdwa v41, v45, v117 dst_sel:DWORD dst_unused:UNUSED_PAD src0_sel:DWORD src1_sel:WORD_1
	v_add3_u32 v117, v119, v42, s69
	v_and_b32_sdwa v42, v121, v115 dst_sel:DWORD dst_unused:UNUSED_PAD src0_sel:WORD_1 src1_sel:DWORD
	v_and_b32_sdwa v44, v120, v115 dst_sel:DWORD dst_unused:UNUSED_PAD src0_sel:WORD_1 src1_sel:DWORD
	v_and_b32_sdwa v43, v118, v115 dst_sel:DWORD dst_unused:UNUSED_PAD src0_sel:WORD_1 src1_sel:DWORD
	v_add3_u32 v42, v121, v42, s69
	v_add3_u32 v44, v120, v44, s69
	v_add3_u32 v43, v118, v43, s69
	v_and_b32_e32 v45, 0xffff0000, v42
	v_and_b32_e32 v44, 0xffff0000, v44
	v_and_b32_e32 v125, 0xffff0000, v117
	v_and_b32_e32 v124, 0xffff0000, v43
	v_pk_add_f32 v[120:121], v[120:121], v[44:45] neg_lo:[0,1] neg_hi:[0,1]
	v_or_b32_sdwa v42, v44, v43 dst_sel:DWORD dst_unused:UNUSED_PAD src0_sel:DWORD src1_sel:WORD_1
	v_pk_add_f32 v[118:119], v[118:119], v[124:125] neg_lo:[0,1] neg_hi:[0,1]
	v_bfe_u32 v44, v121, 16, 1
	v_bfe_u32 v124, v46, 16, 1
	v_or_b32_sdwa v43, v45, v117 dst_sel:DWORD dst_unused:UNUSED_PAD src0_sel:DWORD src1_sel:WORD_1
	v_bfe_u32 v45, v120, 16, 1
	v_bfe_u32 v117, v47, 16, 1
	v_add3_u32 v124, v46, v124, s69
	v_add3_u32 v44, v121, v44, s69
	v_bfe_u32 v46, v118, 16, 1
	v_bfe_u32 v121, v123, 16, 1
	v_add3_u32 v117, v47, v117, s69
	v_add3_u32 v45, v120, v45, s69
	v_bfe_u32 v47, v119, 16, 1
	v_bfe_u32 v120, v122, 16, 1
	v_add3_u32 v46, v118, v46, s69
	v_add3_u32 v118, v123, v121, s69
	v_add3_u32 v47, v119, v47, s69
	v_add3_u32 v119, v122, v120, s69
	v_lshrrev_b32_e32 v46, 16, v46
	v_lshrrev_b32_e32 v118, 16, v118
	v_lshrrev_b32_e32 v47, 16, v47
	v_lshrrev_b32_e32 v119, 16, v119
	v_and_or_b32 v46, v45, s70, v46
	v_and_or_b32 v45, v117, s70, v118
	v_and_b32_sdwa v118, v86, v115 dst_sel:DWORD dst_unused:UNUSED_PAD src0_sel:WORD_1 src1_sel:DWORD
	v_and_or_b32 v47, v44, s70, v47
	v_and_or_b32 v44, v124, s70, v119
	v_add3_u32 v119, v86, v118, s69
	v_and_b32_sdwa v118, v89, v115 dst_sel:DWORD dst_unused:UNUSED_PAD src0_sel:WORD_1 src1_sel:DWORD
	v_and_b32_sdwa v120, v88, v115 dst_sel:DWORD dst_unused:UNUSED_PAD src0_sel:WORD_1 src1_sel:DWORD
	v_and_b32_sdwa v117, v87, v115 dst_sel:DWORD dst_unused:UNUSED_PAD src0_sel:WORD_1 src1_sel:DWORD
	v_add3_u32 v118, v89, v118, s69
	v_add3_u32 v120, v88, v120, s69
	v_add3_u32 v117, v87, v117, s69
	v_and_b32_e32 v121, 0xffff0000, v118
	v_and_b32_e32 v120, 0xffff0000, v120
	v_or_b32_sdwa v118, v120, v119 dst_sel:DWORD dst_unused:UNUSED_PAD src0_sel:DWORD src1_sel:WORD_1
	v_and_b32_e32 v123, 0xffff0000, v117
	v_and_b32_e32 v122, 0xffff0000, v119
	v_pk_add_f32 v[88:89], v[88:89], v[120:121] neg_lo:[0,1] neg_hi:[0,1]
	v_and_b32_sdwa v120, v82, v115 dst_sel:DWORD dst_unused:UNUSED_PAD src0_sel:WORD_1 src1_sel:DWORD
	v_pk_add_f32 v[86:87], v[86:87], v[122:123] neg_lo:[0,1] neg_hi:[0,1]
	v_or_b32_sdwa v119, v121, v117 dst_sel:DWORD dst_unused:UNUSED_PAD src0_sel:DWORD src1_sel:WORD_1
	v_add3_u32 v121, v82, v120, s69
	v_and_b32_sdwa v120, v85, v115 dst_sel:DWORD dst_unused:UNUSED_PAD src0_sel:WORD_1 src1_sel:DWORD
	v_and_b32_sdwa v122, v84, v115 dst_sel:DWORD dst_unused:UNUSED_PAD src0_sel:WORD_1 src1_sel:DWORD
	v_and_b32_sdwa v117, v83, v115 dst_sel:DWORD dst_unused:UNUSED_PAD src0_sel:WORD_1 src1_sel:DWORD
	v_add3_u32 v120, v85, v120, s69
	v_add3_u32 v122, v84, v122, s69
	v_add3_u32 v117, v83, v117, s69
	v_and_b32_e32 v123, 0xffff0000, v120
	v_and_b32_e32 v122, 0xffff0000, v122
	v_or_b32_sdwa v120, v122, v121 dst_sel:DWORD dst_unused:UNUSED_PAD src0_sel:DWORD src1_sel:WORD_1
	v_and_b32_e32 v124, 0xffff0000, v121
	v_or_b32_sdwa v121, v123, v117 dst_sel:DWORD dst_unused:UNUSED_PAD src0_sel:DWORD src1_sel:WORD_1
	v_mfma_f32_32x32x16_bf16 v[0:15], v[32:35], v[40:43], v[0:15]
	v_and_b32_e32 v125, 0xffff0000, v117
	v_add_f32_e64 v84, v84, -v122
	v_add_f32_e64 v85, v85, -v123
	v_add_f32_e64 v82, v82, -v124
	v_add_f32_e64 v83, v83, -v125
	v_bfe_u32 v117, v85, 16, 1
	v_bfe_u32 v122, v84, 16, 1
	v_bfe_u32 v123, v89, 16, 1
	v_bfe_u32 v124, v88, 16, 1
	v_mfma_f32_32x32x16_bf16 v[16:31], v[32:35], v[118:121], v[16:31]
	v_add3_u32 v88, v88, v124, s69
	v_add3_u32 v89, v89, v123, s69
	v_add3_u32 v84, v84, v122, s69
	v_add3_u32 v85, v85, v117, s69
	v_bfe_u32 v117, v82, 16, 1
	v_bfe_u32 v122, v83, 16, 1
	v_bfe_u32 v123, v86, 16, 1
	v_bfe_u32 v124, v87, 16, 1
	v_add3_u32 v83, v83, v122, s69
	v_add3_u32 v82, v82, v117, s69
	v_add3_u32 v87, v87, v124, s69
	v_add3_u32 v86, v86, v123, s69
	v_lshrrev_b32_e32 v82, 16, v82
	v_lshrrev_b32_e32 v83, 16, v83
	v_lshrrev_b32_e32 v86, 16, v86
	v_lshrrev_b32_e32 v87, 16, v87
	v_and_or_b32 v85, v85, s70, v83
	v_and_or_b32 v84, v84, s70, v82
	v_and_or_b32 v83, v89, s70, v87
	v_and_or_b32 v82, v88, s70, v86
	v_mfma_f32_32x32x16_bf16 v[0:15], v[32:35], v[44:47], v[0:15]
	v_mfma_f32_32x32x16_bf16 v[16:31], v[32:35], v[82:85], v[16:31]
	v_mfma_f32_32x32x16_bf16 v[0:15], v[36:39], v[40:43], v[0:15]
	v_mfma_f32_32x32x16_bf16 v[16:31], v[36:39], v[118:121], v[16:31]
	ds_read_b128 v[32:35], v116
	ds_read_b128 v[36:39], v116 offset:16
	v_mov_b32_e32 v42, v218
	v_mov_b32_e32 v86, v219
	v_mov_b32_e32 v46, v220
	v_mov_b32_e32 v88, v221
	s_waitcnt lgkmcnt(1)
	v_cndmask_b32_e64 v35, 0, v35, s[2:3]
	v_mov_b32_e32 v43, v222
	v_mov_b32_e32 v87, v223
	s_waitcnt lgkmcnt(0)
	v_cndmask_b32_e64 v39, 0, v39, s[2:3]
	v_mov_b32_e32 v47, v224
	v_mov_b32_e32 v89, v225
	s_nop 0
	v_mov_b32_e32 v118, v226
	v_mov_b32_e32 v82, v227
	s_nop 0
	v_mov_b32_e32 v120, v228
	v_mov_b32_e32 v84, v229
	v_add_u32_e32 v116, 64, v116
	s_nop 0
	v_mov_b32_e32 v119, v230
	v_mov_b32_e32 v83, v231
	v_mov_b32_e32 v121, v232
	v_mov_b32_e32 v85, v233
	v_cndmask_b32_e64 v41, 0, v34, s[2:3]
	v_cndmask_b32_e64 v40, 0, v32, s[2:3]
	v_cndmask_b32_e64 v34, 0, v33, s[2:3]
	v_and_b32_sdwa v32, v41, v115 dst_sel:DWORD dst_unused:UNUSED_PAD src0_sel:WORD_1 src1_sel:DWORD
	v_and_b32_sdwa v33, v40, v115 dst_sel:DWORD dst_unused:UNUSED_PAD src0_sel:WORD_1 src1_sel:DWORD
	v_add3_u32 v117, v41, v32, s69
	v_and_b32_sdwa v32, v35, v115 dst_sel:DWORD dst_unused:UNUSED_PAD src0_sel:WORD_1 src1_sel:DWORD
	v_and_b32_sdwa v44, v34, v115 dst_sel:DWORD dst_unused:UNUSED_PAD src0_sel:WORD_1 src1_sel:DWORD
	v_add3_u32 v33, v40, v33, s69
	v_add3_u32 v32, v35, v32, s69
	v_add3_u32 v44, v34, v44, s69
	v_and_b32_e32 v45, 0xffff0000, v32
	v_and_b32_e32 v44, 0xffff0000, v44
	v_and_b32_e32 v123, 0xffff0000, v117
	v_and_b32_e32 v122, 0xffff0000, v33
	v_or_b32_sdwa v32, v44, v33 dst_sel:DWORD dst_unused:UNUSED_PAD src0_sel:DWORD src1_sel:WORD_1
	v_pk_add_f32 v[40:41], v[40:41], v[122:123] neg_lo:[0,1] neg_hi:[0,1]
	v_pk_add_f32 v[122:123], v[34:35], v[44:45] neg_lo:[0,1] neg_hi:[0,1]
	v_or_b32_sdwa v33, v45, v117 dst_sel:DWORD dst_unused:UNUSED_PAD src0_sel:DWORD src1_sel:WORD_1
	v_cndmask_b32_e64 v45, 0, v38, s[2:3]
	v_cndmask_b32_e64 v38, 0, v37, s[2:3]
	v_and_b32_sdwa v34, v45, v115 dst_sel:DWORD dst_unused:UNUSED_PAD src0_sel:WORD_1 src1_sel:DWORD
	v_cndmask_b32_e64 v44, 0, v36, s[2:3]
	v_add3_u32 v117, v45, v34, s69
	v_and_b32_sdwa v34, v39, v115 dst_sel:DWORD dst_unused:UNUSED_PAD src0_sel:WORD_1 src1_sel:DWORD
	v_and_b32_sdwa v36, v38, v115 dst_sel:DWORD dst_unused:UNUSED_PAD src0_sel:WORD_1 src1_sel:DWORD
	v_and_b32_sdwa v35, v44, v115 dst_sel:DWORD dst_unused:UNUSED_PAD src0_sel:WORD_1 src1_sel:DWORD
	v_add3_u32 v34, v39, v34, s69
	v_add3_u32 v36, v38, v36, s69
	v_add3_u32 v35, v44, v35, s69
	v_and_b32_e32 v37, 0xffff0000, v34
	v_and_b32_e32 v36, 0xffff0000, v36
	v_and_b32_e32 v125, 0xffff0000, v117
	v_and_b32_e32 v124, 0xffff0000, v35
	v_pk_add_f32 v[38:39], v[38:39], v[36:37] neg_lo:[0,1] neg_hi:[0,1]
	v_or_b32_sdwa v34, v36, v35 dst_sel:DWORD dst_unused:UNUSED_PAD src0_sel:DWORD src1_sel:WORD_1
	v_pk_add_f32 v[44:45], v[44:45], v[124:125] neg_lo:[0,1] neg_hi:[0,1]
	v_or_b32_sdwa v35, v37, v117 dst_sel:DWORD dst_unused:UNUSED_PAD src0_sel:DWORD src1_sel:WORD_1
	v_bfe_u32 v36, v39, 16, 1
	v_bfe_u32 v37, v38, 16, 1
	v_bfe_u32 v117, v123, 16, 1
	v_bfe_u32 v124, v122, 16, 1
	v_add3_u32 v122, v122, v124, s69
	v_add3_u32 v117, v123, v117, s69
	v_add3_u32 v37, v38, v37, s69
	v_add3_u32 v36, v39, v36, s69
	v_bfe_u32 v38, v40, 16, 1
	v_bfe_u32 v39, v41, 16, 1
	v_bfe_u32 v123, v44, 16, 1
	v_bfe_u32 v124, v45, 16, 1
	v_add3_u32 v45, v45, v124, s69
	v_add3_u32 v44, v44, v123, s69
	v_add3_u32 v39, v41, v39, s69
	v_add3_u32 v38, v40, v38, s69
	v_lshrrev_b32_e32 v40, 16, v38
	v_lshrrev_b32_e32 v41, 16, v39
	v_lshrrev_b32_e32 v38, 16, v44
	v_lshrrev_b32_e32 v39, 16, v45
	v_and_or_b32 v39, v36, s70, v39
	v_and_or_b32 v38, v37, s70, v38
	v_and_or_b32 v37, v117, s70, v41
	v_and_or_b32 v36, v122, s70, v40
	v_and_b32_sdwa v40, v43, v115 dst_sel:DWORD dst_unused:UNUSED_PAD src0_sel:WORD_1 src1_sel:DWORD
	v_and_b32_sdwa v41, v42, v115 dst_sel:DWORD dst_unused:UNUSED_PAD src0_sel:WORD_1 src1_sel:DWORD
	v_add3_u32 v117, v43, v40, s69
	v_add3_u32 v41, v42, v41, s69
	v_and_b32_sdwa v40, v47, v115 dst_sel:DWORD dst_unused:UNUSED_PAD src0_sel:WORD_1 src1_sel:DWORD
	v_and_b32_sdwa v44, v46, v115 dst_sel:DWORD dst_unused:UNUSED_PAD src0_sel:WORD_1 src1_sel:DWORD
	v_add3_u32 v40, v47, v40, s69
	v_add3_u32 v44, v46, v44, s69
	v_and_b32_e32 v123, 0xffff0000, v117
	v_and_b32_e32 v122, 0xffff0000, v41
	v_and_b32_e32 v45, 0xffff0000, v40
	v_and_b32_e32 v44, 0xffff0000, v44
	v_pk_add_f32 v[122:123], v[42:43], v[122:123] neg_lo:[0,1] neg_hi:[0,1]
	v_and_b32_sdwa v42, v119, v115 dst_sel:DWORD dst_unused:UNUSED_PAD src0_sel:WORD_1 src1_sel:DWORD
	v_or_b32_sdwa v40, v44, v41 dst_sel:DWORD dst_unused:UNUSED_PAD src0_sel:DWORD src1_sel:WORD_1
	v_pk_add_f32 v[46:47], v[46:47], v[44:45] neg_lo:[0,1] neg_hi:[0,1]
	v_or_b32_sdwa v41, v45, v117 dst_sel:DWORD dst_unused:UNUSED_PAD src0_sel:DWORD src1_sel:WORD_1
	v_add3_u32 v117, v119, v42, s69
	v_and_b32_sdwa v42, v121, v115 dst_sel:DWORD dst_unused:UNUSED_PAD src0_sel:WORD_1 src1_sel:DWORD
	v_and_b32_sdwa v44, v120, v115 dst_sel:DWORD dst_unused:UNUSED_PAD src0_sel:WORD_1 src1_sel:DWORD
	v_and_b32_sdwa v43, v118, v115 dst_sel:DWORD dst_unused:UNUSED_PAD src0_sel:WORD_1 src1_sel:DWORD
	v_add3_u32 v42, v121, v42, s69
	v_add3_u32 v44, v120, v44, s69
	v_add3_u32 v43, v118, v43, s69
	v_and_b32_e32 v45, 0xffff0000, v42
	v_and_b32_e32 v44, 0xffff0000, v44
	v_and_b32_e32 v125, 0xffff0000, v117
	v_and_b32_e32 v124, 0xffff0000, v43
	v_pk_add_f32 v[120:121], v[120:121], v[44:45] neg_lo:[0,1] neg_hi:[0,1]
	v_or_b32_sdwa v42, v44, v43 dst_sel:DWORD dst_unused:UNUSED_PAD src0_sel:DWORD src1_sel:WORD_1
	v_pk_add_f32 v[118:119], v[118:119], v[124:125] neg_lo:[0,1] neg_hi:[0,1]
	v_bfe_u32 v44, v121, 16, 1
	v_bfe_u32 v124, v46, 16, 1
	v_or_b32_sdwa v43, v45, v117 dst_sel:DWORD dst_unused:UNUSED_PAD src0_sel:DWORD src1_sel:WORD_1
	v_bfe_u32 v45, v120, 16, 1
	v_bfe_u32 v117, v47, 16, 1
	v_add3_u32 v124, v46, v124, s69
	v_add3_u32 v44, v121, v44, s69
	v_bfe_u32 v46, v118, 16, 1
	v_bfe_u32 v121, v123, 16, 1
	v_add3_u32 v117, v47, v117, s69
	v_add3_u32 v45, v120, v45, s69
	v_bfe_u32 v47, v119, 16, 1
	v_bfe_u32 v120, v122, 16, 1
	v_add3_u32 v46, v118, v46, s69
	v_add3_u32 v118, v123, v121, s69
	v_add3_u32 v47, v119, v47, s69
	v_add3_u32 v119, v122, v120, s69
	v_lshrrev_b32_e32 v46, 16, v46
	v_lshrrev_b32_e32 v118, 16, v118
	v_lshrrev_b32_e32 v47, 16, v47
	v_lshrrev_b32_e32 v119, 16, v119
	v_and_or_b32 v46, v45, s70, v46
	v_and_or_b32 v45, v117, s70, v118
	v_and_b32_sdwa v118, v86, v115 dst_sel:DWORD dst_unused:UNUSED_PAD src0_sel:WORD_1 src1_sel:DWORD
	v_and_or_b32 v47, v44, s70, v47
	v_and_or_b32 v44, v124, s70, v119
	v_add3_u32 v119, v86, v118, s69
	v_and_b32_sdwa v118, v89, v115 dst_sel:DWORD dst_unused:UNUSED_PAD src0_sel:WORD_1 src1_sel:DWORD
	v_and_b32_sdwa v120, v88, v115 dst_sel:DWORD dst_unused:UNUSED_PAD src0_sel:WORD_1 src1_sel:DWORD
	v_and_b32_sdwa v117, v87, v115 dst_sel:DWORD dst_unused:UNUSED_PAD src0_sel:WORD_1 src1_sel:DWORD
	v_add3_u32 v118, v89, v118, s69
	v_add3_u32 v120, v88, v120, s69
	v_add3_u32 v117, v87, v117, s69
	v_and_b32_e32 v121, 0xffff0000, v118
	v_and_b32_e32 v120, 0xffff0000, v120
	v_or_b32_sdwa v118, v120, v119 dst_sel:DWORD dst_unused:UNUSED_PAD src0_sel:DWORD src1_sel:WORD_1
	v_and_b32_e32 v123, 0xffff0000, v117
	v_and_b32_e32 v122, 0xffff0000, v119
	v_pk_add_f32 v[88:89], v[88:89], v[120:121] neg_lo:[0,1] neg_hi:[0,1]
	v_and_b32_sdwa v120, v82, v115 dst_sel:DWORD dst_unused:UNUSED_PAD src0_sel:WORD_1 src1_sel:DWORD
	v_pk_add_f32 v[86:87], v[86:87], v[122:123] neg_lo:[0,1] neg_hi:[0,1]
	v_or_b32_sdwa v119, v121, v117 dst_sel:DWORD dst_unused:UNUSED_PAD src0_sel:DWORD src1_sel:WORD_1
	v_add3_u32 v121, v82, v120, s69
	v_and_b32_sdwa v120, v85, v115 dst_sel:DWORD dst_unused:UNUSED_PAD src0_sel:WORD_1 src1_sel:DWORD
	v_and_b32_sdwa v122, v84, v115 dst_sel:DWORD dst_unused:UNUSED_PAD src0_sel:WORD_1 src1_sel:DWORD
	v_and_b32_sdwa v117, v83, v115 dst_sel:DWORD dst_unused:UNUSED_PAD src0_sel:WORD_1 src1_sel:DWORD
	v_add3_u32 v120, v85, v120, s69
	v_add3_u32 v122, v84, v122, s69
	v_add3_u32 v117, v83, v117, s69
	v_and_b32_e32 v123, 0xffff0000, v120
	v_and_b32_e32 v122, 0xffff0000, v122
	v_or_b32_sdwa v120, v122, v121 dst_sel:DWORD dst_unused:UNUSED_PAD src0_sel:DWORD src1_sel:WORD_1
	v_and_b32_e32 v124, 0xffff0000, v121
	v_or_b32_sdwa v121, v123, v117 dst_sel:DWORD dst_unused:UNUSED_PAD src0_sel:DWORD src1_sel:WORD_1
	v_mfma_f32_32x32x16_bf16 v[0:15], v[32:35], v[40:43], v[0:15]
	v_and_b32_e32 v125, 0xffff0000, v117
	v_add_f32_e64 v84, v84, -v122
	v_add_f32_e64 v85, v85, -v123
	v_add_f32_e64 v82, v82, -v124
	v_add_f32_e64 v83, v83, -v125
	v_bfe_u32 v117, v85, 16, 1
	v_bfe_u32 v122, v84, 16, 1
	v_bfe_u32 v123, v89, 16, 1
	v_bfe_u32 v124, v88, 16, 1
	v_mfma_f32_32x32x16_bf16 v[16:31], v[32:35], v[118:121], v[16:31]
	v_add3_u32 v88, v88, v124, s69
	v_add3_u32 v89, v89, v123, s69
	v_add3_u32 v84, v84, v122, s69
	v_add3_u32 v85, v85, v117, s69
	v_bfe_u32 v117, v82, 16, 1
	v_bfe_u32 v122, v83, 16, 1
	v_bfe_u32 v123, v86, 16, 1
	v_bfe_u32 v124, v87, 16, 1
	v_add3_u32 v83, v83, v122, s69
	v_add3_u32 v82, v82, v117, s69
	v_add3_u32 v87, v87, v124, s69
	v_add3_u32 v86, v86, v123, s69
	v_lshrrev_b32_e32 v82, 16, v82
	v_lshrrev_b32_e32 v83, 16, v83
	v_lshrrev_b32_e32 v86, 16, v86
	v_lshrrev_b32_e32 v87, 16, v87
	v_and_or_b32 v85, v85, s70, v83
	v_and_or_b32 v84, v84, s70, v82
	v_and_or_b32 v83, v89, s70, v87
	v_and_or_b32 v82, v88, s70, v86
	v_mfma_f32_32x32x16_bf16 v[0:15], v[32:35], v[44:47], v[0:15]
	v_mfma_f32_32x32x16_bf16 v[16:31], v[32:35], v[82:85], v[16:31]
	v_mfma_f32_32x32x16_bf16 v[0:15], v[36:39], v[40:43], v[0:15]
	v_mfma_f32_32x32x16_bf16 v[16:31], v[36:39], v[118:121], v[16:31]
	ds_read_b128 v[32:35], v116
	ds_read_b128 v[36:39], v116 offset:16
	v_mov_b32_e32 v42, v234
	v_mov_b32_e32 v86, v235
	v_mov_b32_e32 v46, v236
	v_mov_b32_e32 v88, v237
	s_waitcnt lgkmcnt(1)
	v_cndmask_b32_e64 v35, 0, v35, s[2:3]
	v_mov_b32_e32 v43, v238
	v_mov_b32_e32 v87, v239
	s_waitcnt lgkmcnt(0)
	v_cndmask_b32_e64 v39, 0, v39, s[2:3]
	v_mov_b32_e32 v47, v240
	v_mov_b32_e32 v89, v241
	s_nop 0
	v_mov_b32_e32 v118, v242
	v_mov_b32_e32 v82, v243
	s_nop 0
	v_mov_b32_e32 v120, v244
	v_mov_b32_e32 v84, v245
	v_add_u32_e32 v116, 64, v116
	s_nop 0
	v_mov_b32_e32 v119, v246
	v_mov_b32_e32 v83, v247
	v_mov_b32_e32 v121, v248
	v_mov_b32_e32 v85, v249
	v_cndmask_b32_e64 v41, 0, v34, s[2:3]
	v_cndmask_b32_e64 v40, 0, v32, s[2:3]
	v_cndmask_b32_e64 v34, 0, v33, s[2:3]
	v_and_b32_sdwa v32, v41, v115 dst_sel:DWORD dst_unused:UNUSED_PAD src0_sel:WORD_1 src1_sel:DWORD
	v_and_b32_sdwa v33, v40, v115 dst_sel:DWORD dst_unused:UNUSED_PAD src0_sel:WORD_1 src1_sel:DWORD
	v_add3_u32 v117, v41, v32, s69
	v_and_b32_sdwa v32, v35, v115 dst_sel:DWORD dst_unused:UNUSED_PAD src0_sel:WORD_1 src1_sel:DWORD
	v_and_b32_sdwa v44, v34, v115 dst_sel:DWORD dst_unused:UNUSED_PAD src0_sel:WORD_1 src1_sel:DWORD
	v_add3_u32 v33, v40, v33, s69
	v_add3_u32 v32, v35, v32, s69
	v_add3_u32 v44, v34, v44, s69
	v_and_b32_e32 v45, 0xffff0000, v32
	v_and_b32_e32 v44, 0xffff0000, v44
	v_and_b32_e32 v123, 0xffff0000, v117
	v_and_b32_e32 v122, 0xffff0000, v33
	v_or_b32_sdwa v32, v44, v33 dst_sel:DWORD dst_unused:UNUSED_PAD src0_sel:DWORD src1_sel:WORD_1
	v_pk_add_f32 v[40:41], v[40:41], v[122:123] neg_lo:[0,1] neg_hi:[0,1]
	v_pk_add_f32 v[122:123], v[34:35], v[44:45] neg_lo:[0,1] neg_hi:[0,1]
	v_or_b32_sdwa v33, v45, v117 dst_sel:DWORD dst_unused:UNUSED_PAD src0_sel:DWORD src1_sel:WORD_1
	v_cndmask_b32_e64 v45, 0, v38, s[2:3]
	v_cndmask_b32_e64 v38, 0, v37, s[2:3]
	v_and_b32_sdwa v34, v45, v115 dst_sel:DWORD dst_unused:UNUSED_PAD src0_sel:WORD_1 src1_sel:DWORD
	v_cndmask_b32_e64 v44, 0, v36, s[2:3]
	v_add3_u32 v117, v45, v34, s69
	v_and_b32_sdwa v34, v39, v115 dst_sel:DWORD dst_unused:UNUSED_PAD src0_sel:WORD_1 src1_sel:DWORD
	v_and_b32_sdwa v36, v38, v115 dst_sel:DWORD dst_unused:UNUSED_PAD src0_sel:WORD_1 src1_sel:DWORD
	v_and_b32_sdwa v35, v44, v115 dst_sel:DWORD dst_unused:UNUSED_PAD src0_sel:WORD_1 src1_sel:DWORD
	v_add3_u32 v34, v39, v34, s69
	v_add3_u32 v36, v38, v36, s69
	v_add3_u32 v35, v44, v35, s69
	v_and_b32_e32 v37, 0xffff0000, v34
	v_and_b32_e32 v36, 0xffff0000, v36
	v_and_b32_e32 v125, 0xffff0000, v117
	v_and_b32_e32 v124, 0xffff0000, v35
	v_pk_add_f32 v[38:39], v[38:39], v[36:37] neg_lo:[0,1] neg_hi:[0,1]
	v_or_b32_sdwa v34, v36, v35 dst_sel:DWORD dst_unused:UNUSED_PAD src0_sel:DWORD src1_sel:WORD_1
	v_pk_add_f32 v[44:45], v[44:45], v[124:125] neg_lo:[0,1] neg_hi:[0,1]
	v_or_b32_sdwa v35, v37, v117 dst_sel:DWORD dst_unused:UNUSED_PAD src0_sel:DWORD src1_sel:WORD_1
	v_bfe_u32 v36, v39, 16, 1
	v_bfe_u32 v37, v38, 16, 1
	v_bfe_u32 v117, v123, 16, 1
	v_bfe_u32 v124, v122, 16, 1
	v_add3_u32 v122, v122, v124, s69
	v_add3_u32 v117, v123, v117, s69
	v_add3_u32 v37, v38, v37, s69
	v_add3_u32 v36, v39, v36, s69
	v_bfe_u32 v38, v40, 16, 1
	v_bfe_u32 v39, v41, 16, 1
	v_bfe_u32 v123, v44, 16, 1
	v_bfe_u32 v124, v45, 16, 1
	v_add3_u32 v45, v45, v124, s69
	v_add3_u32 v44, v44, v123, s69
	v_add3_u32 v39, v41, v39, s69
	v_add3_u32 v38, v40, v38, s69
	v_lshrrev_b32_e32 v40, 16, v38
	v_lshrrev_b32_e32 v41, 16, v39
	v_lshrrev_b32_e32 v38, 16, v44
	v_lshrrev_b32_e32 v39, 16, v45
	v_and_or_b32 v39, v36, s70, v39
	v_and_or_b32 v38, v37, s70, v38
	v_and_or_b32 v37, v117, s70, v41
	v_and_or_b32 v36, v122, s70, v40
	v_and_b32_sdwa v40, v43, v115 dst_sel:DWORD dst_unused:UNUSED_PAD src0_sel:WORD_1 src1_sel:DWORD
	v_and_b32_sdwa v41, v42, v115 dst_sel:DWORD dst_unused:UNUSED_PAD src0_sel:WORD_1 src1_sel:DWORD
	v_add3_u32 v117, v43, v40, s69
	v_add3_u32 v41, v42, v41, s69
	v_and_b32_sdwa v40, v47, v115 dst_sel:DWORD dst_unused:UNUSED_PAD src0_sel:WORD_1 src1_sel:DWORD
	v_and_b32_sdwa v44, v46, v115 dst_sel:DWORD dst_unused:UNUSED_PAD src0_sel:WORD_1 src1_sel:DWORD
	v_add3_u32 v40, v47, v40, s69
	v_add3_u32 v44, v46, v44, s69
	v_and_b32_e32 v123, 0xffff0000, v117
	v_and_b32_e32 v122, 0xffff0000, v41
	v_and_b32_e32 v45, 0xffff0000, v40
	v_and_b32_e32 v44, 0xffff0000, v44
	v_pk_add_f32 v[122:123], v[42:43], v[122:123] neg_lo:[0,1] neg_hi:[0,1]
	v_and_b32_sdwa v42, v119, v115 dst_sel:DWORD dst_unused:UNUSED_PAD src0_sel:WORD_1 src1_sel:DWORD
	v_or_b32_sdwa v40, v44, v41 dst_sel:DWORD dst_unused:UNUSED_PAD src0_sel:DWORD src1_sel:WORD_1
	v_pk_add_f32 v[46:47], v[46:47], v[44:45] neg_lo:[0,1] neg_hi:[0,1]
	v_or_b32_sdwa v41, v45, v117 dst_sel:DWORD dst_unused:UNUSED_PAD src0_sel:DWORD src1_sel:WORD_1
	v_add3_u32 v117, v119, v42, s69
	v_and_b32_sdwa v42, v121, v115 dst_sel:DWORD dst_unused:UNUSED_PAD src0_sel:WORD_1 src1_sel:DWORD
	v_and_b32_sdwa v44, v120, v115 dst_sel:DWORD dst_unused:UNUSED_PAD src0_sel:WORD_1 src1_sel:DWORD
	v_and_b32_sdwa v43, v118, v115 dst_sel:DWORD dst_unused:UNUSED_PAD src0_sel:WORD_1 src1_sel:DWORD
	v_add3_u32 v42, v121, v42, s69
	v_add3_u32 v44, v120, v44, s69
	v_add3_u32 v43, v118, v43, s69
	v_and_b32_e32 v45, 0xffff0000, v42
	v_and_b32_e32 v44, 0xffff0000, v44
	v_and_b32_e32 v125, 0xffff0000, v117
	v_and_b32_e32 v124, 0xffff0000, v43
	v_pk_add_f32 v[120:121], v[120:121], v[44:45] neg_lo:[0,1] neg_hi:[0,1]
	v_or_b32_sdwa v42, v44, v43 dst_sel:DWORD dst_unused:UNUSED_PAD src0_sel:DWORD src1_sel:WORD_1
	v_pk_add_f32 v[118:119], v[118:119], v[124:125] neg_lo:[0,1] neg_hi:[0,1]
	v_bfe_u32 v44, v121, 16, 1
	v_bfe_u32 v124, v46, 16, 1
	v_or_b32_sdwa v43, v45, v117 dst_sel:DWORD dst_unused:UNUSED_PAD src0_sel:DWORD src1_sel:WORD_1
	v_bfe_u32 v45, v120, 16, 1
	v_bfe_u32 v117, v47, 16, 1
	v_add3_u32 v124, v46, v124, s69
	v_add3_u32 v44, v121, v44, s69
	v_bfe_u32 v46, v118, 16, 1
	v_bfe_u32 v121, v123, 16, 1
	v_add3_u32 v117, v47, v117, s69
	v_add3_u32 v45, v120, v45, s69
	v_bfe_u32 v47, v119, 16, 1
	v_bfe_u32 v120, v122, 16, 1
	v_add3_u32 v46, v118, v46, s69
	v_add3_u32 v118, v123, v121, s69
	v_add3_u32 v47, v119, v47, s69
	v_add3_u32 v119, v122, v120, s69
	v_lshrrev_b32_e32 v46, 16, v46
	v_lshrrev_b32_e32 v118, 16, v118
	v_lshrrev_b32_e32 v47, 16, v47
	v_lshrrev_b32_e32 v119, 16, v119
	v_and_or_b32 v46, v45, s70, v46
	v_and_or_b32 v45, v117, s70, v118
	v_and_b32_sdwa v118, v86, v115 dst_sel:DWORD dst_unused:UNUSED_PAD src0_sel:WORD_1 src1_sel:DWORD
	v_and_or_b32 v47, v44, s70, v47
	v_and_or_b32 v44, v124, s70, v119
	v_add3_u32 v119, v86, v118, s69
	v_and_b32_sdwa v118, v89, v115 dst_sel:DWORD dst_unused:UNUSED_PAD src0_sel:WORD_1 src1_sel:DWORD
	v_and_b32_sdwa v120, v88, v115 dst_sel:DWORD dst_unused:UNUSED_PAD src0_sel:WORD_1 src1_sel:DWORD
	v_and_b32_sdwa v117, v87, v115 dst_sel:DWORD dst_unused:UNUSED_PAD src0_sel:WORD_1 src1_sel:DWORD
	v_add3_u32 v118, v89, v118, s69
	v_add3_u32 v120, v88, v120, s69
	v_add3_u32 v117, v87, v117, s69
	v_and_b32_e32 v121, 0xffff0000, v118
	v_and_b32_e32 v120, 0xffff0000, v120
	v_or_b32_sdwa v118, v120, v119 dst_sel:DWORD dst_unused:UNUSED_PAD src0_sel:DWORD src1_sel:WORD_1
	v_and_b32_e32 v123, 0xffff0000, v117
	v_and_b32_e32 v122, 0xffff0000, v119
	v_pk_add_f32 v[88:89], v[88:89], v[120:121] neg_lo:[0,1] neg_hi:[0,1]
	v_and_b32_sdwa v120, v82, v115 dst_sel:DWORD dst_unused:UNUSED_PAD src0_sel:WORD_1 src1_sel:DWORD
	v_pk_add_f32 v[86:87], v[86:87], v[122:123] neg_lo:[0,1] neg_hi:[0,1]
	v_or_b32_sdwa v119, v121, v117 dst_sel:DWORD dst_unused:UNUSED_PAD src0_sel:DWORD src1_sel:WORD_1
	v_add3_u32 v121, v82, v120, s69
	v_and_b32_sdwa v120, v85, v115 dst_sel:DWORD dst_unused:UNUSED_PAD src0_sel:WORD_1 src1_sel:DWORD
	v_and_b32_sdwa v122, v84, v115 dst_sel:DWORD dst_unused:UNUSED_PAD src0_sel:WORD_1 src1_sel:DWORD
	v_and_b32_sdwa v117, v83, v115 dst_sel:DWORD dst_unused:UNUSED_PAD src0_sel:WORD_1 src1_sel:DWORD
	v_add3_u32 v120, v85, v120, s69
	v_add3_u32 v122, v84, v122, s69
	v_add3_u32 v117, v83, v117, s69
	v_and_b32_e32 v123, 0xffff0000, v120
	v_and_b32_e32 v122, 0xffff0000, v122
	v_or_b32_sdwa v120, v122, v121 dst_sel:DWORD dst_unused:UNUSED_PAD src0_sel:DWORD src1_sel:WORD_1
	v_and_b32_e32 v124, 0xffff0000, v121
	v_or_b32_sdwa v121, v123, v117 dst_sel:DWORD dst_unused:UNUSED_PAD src0_sel:DWORD src1_sel:WORD_1
	v_mfma_f32_32x32x16_bf16 v[0:15], v[32:35], v[40:43], v[0:15]
	v_and_b32_e32 v125, 0xffff0000, v117
	v_add_f32_e64 v84, v84, -v122
	v_add_f32_e64 v85, v85, -v123
	v_add_f32_e64 v82, v82, -v124
	v_add_f32_e64 v83, v83, -v125
	v_bfe_u32 v117, v85, 16, 1
	v_bfe_u32 v122, v84, 16, 1
	v_bfe_u32 v123, v89, 16, 1
	v_bfe_u32 v124, v88, 16, 1
	v_mfma_f32_32x32x16_bf16 v[16:31], v[32:35], v[118:121], v[16:31]
	v_add3_u32 v88, v88, v124, s69
	v_add3_u32 v89, v89, v123, s69
	v_add3_u32 v84, v84, v122, s69
	v_add3_u32 v85, v85, v117, s69
	v_bfe_u32 v117, v82, 16, 1
	v_bfe_u32 v122, v83, 16, 1
	v_bfe_u32 v123, v86, 16, 1
	v_bfe_u32 v124, v87, 16, 1
	v_add3_u32 v83, v83, v122, s69
	v_add3_u32 v82, v82, v117, s69
	v_add3_u32 v87, v87, v124, s69
	v_add3_u32 v86, v86, v123, s69
	v_lshrrev_b32_e32 v82, 16, v82
	v_lshrrev_b32_e32 v83, 16, v83
	v_lshrrev_b32_e32 v86, 16, v86
	v_lshrrev_b32_e32 v87, 16, v87
	v_and_or_b32 v85, v85, s70, v83
	v_and_or_b32 v84, v84, s70, v82
	v_and_or_b32 v83, v89, s70, v87
	v_and_or_b32 v82, v88, s70, v86
	v_mfma_f32_32x32x16_bf16 v[0:15], v[32:35], v[44:47], v[0:15]
	v_mfma_f32_32x32x16_bf16 v[16:31], v[32:35], v[82:85], v[16:31]
	v_mfma_f32_32x32x16_bf16 v[0:15], v[36:39], v[40:43], v[0:15]
	v_mfma_f32_32x32x16_bf16 v[16:31], v[36:39], v[118:121], v[16:31]
	s_mul_i32 s51, s48, 17
	s_nop 8
	v_add_u32_e32 v9, s51, v94
	v_lshl_add_u32 v9, v9, 8, v95
	ds_write2_b32 v9, v0, v16 offset1:32
	v_add_u32_e32 v0, s51, v96
	v_lshl_add_u32 v0, v0, 8, v95
	ds_write2_b32 v0, v1, v17 offset1:32
	v_add_u32_e32 v0, s51, v97
	v_lshl_add_u32 v0, v0, 8, v95
	ds_write2_b32 v0, v2, v18 offset1:32
	v_add_u32_e32 v0, s51, v98
	v_lshl_add_u32 v0, v0, 8, v95
	ds_write2_b32 v0, v3, v19 offset1:32
	v_add_u32_e32 v0, s51, v99
	v_lshl_add_u32 v0, v0, 8, v95
	ds_write2_b32 v0, v4, v20 offset1:32
	v_add_u32_e32 v0, s51, v100
	v_lshl_add_u32 v0, v0, 8, v95
	ds_write2_b32 v0, v5, v21 offset1:32
	v_add_u32_e32 v0, s51, v101
	v_lshl_add_u32 v0, v0, 8, v95
	ds_write2_b32 v0, v6, v22 offset1:32
	v_add_u32_e32 v0, s51, v102
	v_lshl_add_u32 v0, v0, 8, v95
	ds_write2_b32 v0, v7, v23 offset1:32
	s_and_saveexec_b64 s[52:53], s[4:5]
	s_mulk_i32 s48, 0x1100
	v_add_u32_e32 v0, s48, v95
	v_add_u32_e32 v0, 0x1000, v0
	ds_write2_b32 v0, v8, v24 offset1:32
	s_or_b64 exec, exec, s[52:53]
	s_waitcnt lgkmcnt(0)
	s_barrier
	s_and_saveexec_b64 s[52:53], s[6:7]
	s_cbranch_execz .LBB0_158
	s_ashr_i32 s51, s50, 31
	v_lshl_add_u64 v[0:1], s[50:51], 2, v[60:61]
	s_mov_b64 s[54:55], -1
	v_mov_b32_e32 v2, v48
	s_and_saveexec_b64 s[50:51], s[28:29]
	s_cbranch_execz .LBB0_230
	v_mov_b64_e32 v[2:3], v[48:49]
	s_and_saveexec_b64 s[54:55], s[30:31]
	s_cbranch_execz .LBB0_227
	s_mov_b64 s[56:57], 0
	v_mov_b32_e32 v4, v105
	v_mov_b64_e32 v[2:3], v[48:49]
